# removed all s_setprio flips from the 8 GEMM K loops (peeled iteration and loop body): the MFMA wave no longer raises its priority over the loading wave
# speedup vs baseline: 1.0012x; 1.0012x over previous
; #define PG8_STAGE(bufoff, gbase, voff) do { _Pragma("unroll") for (int _i = 0; _i < 2; ++_i) \
;         __builtin_amdgcn_global_load_lds((const unsigned*)((const char*)(gbase) + (voff)[_i]), (LAS unsigned*)(lds + (bufoff) + ldsw + _i * 8192), 16, 0, 0); } while (0)
; #define PG8_LDA(dst, b, h) do { _Pragma("unroll") for (int m = 0; m < 4; ++m) _Pragma("unroll") for (int k = 0; k < 2; ++k) dst[m][k] = *(const LAS bf16x8*)(lds + PG8_SA(b, h) + aoff + m * 2048 + k * 1024); } while (0)
; #define PG8_LDB(dst, b, h) do { _Pragma("unroll") for (int n = 0; n < 2; ++n) _Pragma("unroll") for (int k = 0; k < 2; ++k) dst[n][k] = *(const LAS bf16x8*)(lds + PG8_SB(b, h) + boff + n * 2048 + k * 1024); } while (0)
; #define PG8_MMA(ai, bj, At, Bt) do { __builtin_amdgcn_s_setprio(3); _Pragma("unroll") for (int m = 0; m < 4; ++m) _Pragma("unroll") for (int n = 0; n < 2; ++n) _Pragma("unroll") for (int k = 0; k < 2; ++k) \
;         acc[ai][bj][m][n] = __builtin_amdgcn_mfma_f32_16x16x32_bf16(Bt[n][k], At[m][k], acc[ai][bj][m][n], 0, 0, 0); __builtin_amdgcn_s_setprio(0); } while (0)
; #define PG8_WAIT_V(n) asm volatile("s_waitcnt vmcnt(" #n ")" ::: "memory")
; #define PG8_BAR __builtin_amdgcn_s_barrier()
; template <class Epi, bool ALIGN_EPI>
; __device__ __forceinline__ void gemm_phase(LAS unsigned char* lds, const Gemm g, const StaticOrder& S, const Epi& E) {
;     ...
;             PG8_LDB(B0, 0, 0); PG8_LDB(B1, 0, 1); PG8_SCHED; PG8_LDA(At, 0, 0); PG8_STAGE(PG8_SA(1, 1), a1 + hstep, voffA);
;             PG8_WAIT_V(8); PG8_WAIT_L(0); PG8_BAR; PG8_MMA(0, 0, At, B0); PG8_MMA(0, 1, At, B1); PG8_BAR; PG8_SCHED;
;             PG8_LDA(At, 0, 1); PG8_STAGE(PG8_SB(0, 0), b2, voffB); PG8_STAGE(PG8_SB(0, 1), b2 + hstep, voffB); PG8_STAGE(PG8_SA(0, 0), a2, voffA);
;             PG8_WAIT_V(8); PG8_WAIT_L(0); PG8_BAR; PG8_MMA(1, 0, At, B0); PG8_MMA(1, 1, At, B1); PG8_BAR; PG8_SCHED;
;             PG8_LDB(B0, 1, 0); PG8_LDB(B1, 1, 1); PG8_SCHED; PG8_LDA(At, 1, 0); PG8_STAGE(PG8_SA(0, 1), a2 + hstep, voffA);
;             PG8_WAIT_V(8); PG8_WAIT_L(0); PG8_BAR; PG8_MMA(0, 0, At, B0); PG8_MMA(0, 1, At, B1); PG8_BAR; PG8_SCHED;
;             PG8_LDA(At, 1, 1); PG8_STAGE(PG8_SB(1, 0), b3, voffB); PG8_STAGE(PG8_SB(1, 1), b3 + hstep, voffB); PG8_STAGE(PG8_SA(1, 0), a3, voffA);
;             PG8_WAIT_V(8); PG8_WAIT_L(0); PG8_BAR; PG8_MMA(1, 0, At, B0); PG8_MMA(1, 1, At, B1); PG8_BAR; PG8_SCHED;
.Lmy_rw_293_0:
	s_waitcnt lgkmcnt(0)
	s_barrier
	s_waitcnt lgkmcnt(0)
	v_mfma_f32_16x16x32_bf16 v[118:121], v[148:151], v[180:183], 0
	v_mfma_f32_16x16x32_bf16 v[114:117], v[156:159], v[180:183], 0
	v_mfma_f32_16x16x32_bf16 v[102:105], v[148:151], v[200:203], 0
	v_mfma_f32_16x16x32_bf16 v[98:101], v[156:159], v[200:203], 0
	v_mfma_f32_16x16x32_bf16 v[86:89], v[148:151], v[208:211], 0
	v_mfma_f32_16x16x32_bf16 v[82:85], v[156:159], v[208:211], 0
	v_mfma_f32_16x16x32_bf16 v[70:73], v[148:151], v[216:219], 0
	v_mfma_f32_16x16x32_bf16 v[66:69], v[156:159], v[216:219], 0
	v_mfma_f32_16x16x32_bf16 v[118:121], v[152:155], v[196:199], v[118:121]
	v_mfma_f32_16x16x32_bf16 v[114:117], v[160:163], v[196:199], v[114:117]
	v_mfma_f32_16x16x32_bf16 v[102:105], v[152:155], v[204:207], v[102:105]
	v_mfma_f32_16x16x32_bf16 v[98:101], v[160:163], v[204:207], v[98:101]
	v_mfma_f32_16x16x32_bf16 v[86:89], v[152:155], v[212:215], v[86:89]
	v_mfma_f32_16x16x32_bf16 v[82:85], v[160:163], v[212:215], v[82:85]
	v_mfma_f32_16x16x32_bf16 v[70:73], v[152:155], v[220:223], v[70:73]
	v_mfma_f32_16x16x32_bf16 v[66:69], v[160:163], v[220:223], v[66:69]
	v_mfma_f32_16x16x32_bf16 v[126:129], v[164:167], v[180:183], 0
	v_mfma_f32_16x16x32_bf16 v[122:125], v[172:175], v[180:183], 0
	v_mfma_f32_16x16x32_bf16 v[110:113], v[164:167], v[200:203], 0
	v_mfma_f32_16x16x32_bf16 v[106:109], v[172:175], v[200:203], 0
	v_mfma_f32_16x16x32_bf16 v[94:97], v[164:167], v[208:211], 0
	v_mfma_f32_16x16x32_bf16 v[90:93], v[172:175], v[208:211], 0
	v_mfma_f32_16x16x32_bf16 v[78:81], v[164:167], v[216:219], 0
	v_mfma_f32_16x16x32_bf16 v[74:77], v[172:175], v[216:219], 0
	v_mfma_f32_16x16x32_bf16 v[126:129], v[168:171], v[196:199], v[126:129]
	v_mfma_f32_16x16x32_bf16 v[122:125], v[176:179], v[196:199], v[122:125]
	v_mfma_f32_16x16x32_bf16 v[110:113], v[168:171], v[204:207], v[110:113]
	v_mfma_f32_16x16x32_bf16 v[106:109], v[176:179], v[204:207], v[106:109]
	v_mfma_f32_16x16x32_bf16 v[94:97], v[168:171], v[212:215], v[94:97]
	v_mfma_f32_16x16x32_bf16 v[90:93], v[176:179], v[212:215], v[90:93]
	v_mfma_f32_16x16x32_bf16 v[78:81], v[168:171], v[220:223], v[78:81]
	v_mfma_f32_16x16x32_bf16 v[74:77], v[176:179], v[220:223], v[74:77]
	s_barrier
	s_add_i32 s9, s95, s33
	v_lshl_add_u64 v[224:225], s[82:83], 0, v[132:133]
	s_mov_b32 m0, s9
	ds_read_b128 v[180:183], v194 offset:16384
	ds_read_b128 v[196:199], v194 offset:17408
	ds_read_b128 v[200:203], v194 offset:18432
	ds_read_b128 v[204:207], v194 offset:19456
	ds_read_b128 v[208:211], v194 offset:20480
	ds_read_b128 v[212:215], v194 offset:21504
	ds_read_b128 v[216:219], v194 offset:22528
	ds_read_b128 v[220:223], v194 offset:23552
	global_load_lds_dwordx4 v[224:225], off
	s_add_i32 m0, s9, 0x2000
	s_add_u32 s50, s82, 0x40000
	v_lshl_add_u64 v[226:227], s[82:83], 0, v[136:137]
	s_addc_u32 s51, s83, 0
	s_add_i32 s9, s96, s33
	global_load_lds_dwordx4 v[226:227], off
	v_lshl_add_u64 v[228:229], s[50:51], 0, v[132:133]
	s_mov_b32 m0, s9
	v_lshl_add_u64 v[230:231], s[84:85], 0, v[134:135]
	global_load_lds_dwordx4 v[228:229], off
	v_lshl_add_u64 v[228:229], s[50:51], 0, v[136:137]
	s_add_i32 m0, s9, 0x2000
	s_nop 0
	global_load_lds_dwordx4 v[228:229], off
	v_lshl_add_u64 v[228:229], s[84:85], 0, v[130:131]
	s_mov_b32 m0, s76
	s_nop 0
	global_load_lds_dwordx4 v[228:229], off
	s_mov_b32 m0, s77
	s_nop 0
	global_load_lds_dwordx4 v[230:231], off
	s_cmp_lg_u32 s98, 0
	s_cbranch_scc1 .Lmy_rw_293_1
	s_waitcnt vmcnt(8)
.Lmy_rw_293_1:
	s_waitcnt lgkmcnt(0)
	s_barrier
	s_waitcnt lgkmcnt(0)
	v_mfma_f32_16x16x32_bf16 v[54:57], v[148:151], v[180:183], 0
	v_mfma_f32_16x16x32_bf16 v[50:53], v[156:159], v[180:183], 0
	v_mfma_f32_16x16x32_bf16 v[38:41], v[148:151], v[200:203], 0
	v_mfma_f32_16x16x32_bf16 v[34:37], v[156:159], v[200:203], 0
	v_mfma_f32_16x16x32_bf16 v[22:25], v[148:151], v[208:211], 0
	v_mfma_f32_16x16x32_bf16 v[18:21], v[156:159], v[208:211], 0
	v_mfma_f32_16x16x32_bf16 v[6:9], v[148:151], v[216:219], 0
	v_mfma_f32_16x16x32_bf16 v[2:5], v[156:159], v[216:219], 0
	v_mfma_f32_16x16x32_bf16 v[54:57], v[152:155], v[196:199], v[54:57]
	v_mfma_f32_16x16x32_bf16 v[50:53], v[160:163], v[196:199], v[50:53]
	v_mfma_f32_16x16x32_bf16 v[38:41], v[152:155], v[204:207], v[38:41]
	v_mfma_f32_16x16x32_bf16 v[34:37], v[160:163], v[204:207], v[34:37]
	v_mfma_f32_16x16x32_bf16 v[22:25], v[152:155], v[212:215], v[22:25]
	v_mfma_f32_16x16x32_bf16 v[18:21], v[160:163], v[212:215], v[18:21]
	v_mfma_f32_16x16x32_bf16 v[6:9], v[152:155], v[220:223], v[6:9]
	v_mfma_f32_16x16x32_bf16 v[2:5], v[160:163], v[220:223], v[2:5]
	v_mfma_f32_16x16x32_bf16 v[62:65], v[164:167], v[180:183], 0
	v_mfma_f32_16x16x32_bf16 v[58:61], v[172:175], v[180:183], 0
	v_mfma_f32_16x16x32_bf16 v[46:49], v[164:167], v[200:203], 0
	v_mfma_f32_16x16x32_bf16 v[42:45], v[172:175], v[200:203], 0
	v_mfma_f32_16x16x32_bf16 v[30:33], v[164:167], v[208:211], 0
	v_mfma_f32_16x16x32_bf16 v[26:29], v[172:175], v[208:211], 0
	v_mfma_f32_16x16x32_bf16 v[14:17], v[164:167], v[216:219], 0
	v_mfma_f32_16x16x32_bf16 v[10:13], v[172:175], v[216:219], 0
	v_mfma_f32_16x16x32_bf16 v[62:65], v[168:171], v[196:199], v[62:65]
	v_mfma_f32_16x16x32_bf16 v[58:61], v[176:179], v[196:199], v[58:61]
	v_mfma_f32_16x16x32_bf16 v[46:49], v[168:171], v[204:207], v[46:49]
	v_mfma_f32_16x16x32_bf16 v[42:45], v[176:179], v[204:207], v[42:45]
	v_mfma_f32_16x16x32_bf16 v[30:33], v[168:171], v[212:215], v[30:33]
	v_mfma_f32_16x16x32_bf16 v[26:29], v[176:179], v[212:215], v[26:29]
	v_mfma_f32_16x16x32_bf16 v[14:17], v[168:171], v[220:223], v[14:17]
	v_mfma_f32_16x16x32_bf16 v[10:13], v[176:179], v[220:223], v[10:13]
	s_barrier
; #define PG8_STAGE(bufoff, gbase, voff) do { _Pragma("unroll") for (int _i = 0; _i < 2; ++_i) \
;         __builtin_amdgcn_global_load_lds((const unsigned*)((const char*)(gbase) + (voff)[_i]), (LAS unsigned*)(lds + (bufoff) + ldsw + _i * 8192), 16, 0, 0); } while (0)
; #define PG8_LDA(dst, b, h) do { _Pragma("unroll") for (int m = 0; m < 4; ++m) _Pragma("unroll") for (int k = 0; k < 2; ++k) dst[m][k] = *(const LAS bf16x8*)(lds + PG8_SA(b, h) + aoff + m * 2048 + k * 1024); } while (0)
; #define PG8_LDB(dst, b, h) do { _Pragma("unroll") for (int n = 0; n < 2; ++n) _Pragma("unroll") for (int k = 0; k < 2; ++k) dst[n][k] = *(const LAS bf16x8*)(lds + PG8_SB(b, h) + boff + n * 2048 + k * 1024); } while (0)
; #define PG8_MMA(ai, bj, At, Bt) do { __builtin_amdgcn_s_setprio(3); _Pragma("unroll") for (int m = 0; m < 4; ++m) _Pragma("unroll") for (int n = 0; n < 2; ++n) _Pragma("unroll") for (int k = 0; k < 2; ++k) \
;         acc[ai][bj][m][n] = __builtin_amdgcn_mfma_f32_16x16x32_bf16(Bt[n][k], At[m][k], acc[ai][bj][m][n], 0, 0, 0); __builtin_amdgcn_s_setprio(0); } while (0)
; #define PG8_WAIT_V(n) asm volatile("s_waitcnt vmcnt(" #n ")" ::: "memory")
; #define PG8_WAIT_L(n) asm volatile("s_waitcnt lgkmcnt(" #n ")" ::: "memory")
; #define PG8_BAR __builtin_amdgcn_s_barrier()
; #define PG8_SCHED __builtin_amdgcn_sched_barrier(0)
; template <class Epi, bool ALIGN_EPI>
; __device__ __forceinline__ void gemm_phase(LAS unsigned char* lds, const Gemm g, const StaticOrder& S, const Epi& E) {
;     ...
;             PG8_LDB(B0, 1, 0); PG8_LDB(B1, 1, 1); PG8_SCHED; PG8_LDA(At, 1, 0); PG8_STAGE(PG8_SA(0, 1), a2 + hstep, voffA);
;             PG8_WAIT_V(8); PG8_WAIT_L(0); PG8_BAR; PG8_MMA(0, 0, At, B0); PG8_MMA(0, 1, At, B1); PG8_BAR; PG8_SCHED;
;             PG8_LDA(At, 1, 1); PG8_STAGE(PG8_SB(1, 0), b3, voffB); PG8_STAGE(PG8_SB(1, 1), b3 + hstep, voffB); PG8_STAGE(PG8_SA(1, 0), a3, voffA);
;             PG8_WAIT_V(8); PG8_WAIT_L(0); PG8_BAR; PG8_MMA(1, 0, At, B0); PG8_MMA(1, 1, At, B1); PG8_BAR; PG8_SCHED;
	s_add_i32 s9, 0, 0x18000
	v_add_u32_e32 v138, s9, v189
	s_add_i32 s89, 0, 0x1c000
	ds_read_b128 v[148:151], v138
	ds_read_b128 v[152:155], v138 offset:1024
	ds_read_b128 v[156:159], v138 offset:2048
	ds_read_b128 v[160:163], v138 offset:3072
	v_add_u32_e32 v138, s89, v189
	ds_read_b128 v[164:167], v138
	ds_read_b128 v[168:171], v138 offset:1024
	ds_read_b128 v[172:175], v138 offset:2048
	ds_read_b128 v[176:179], v138 offset:3072
	s_add_u32 s50, s84, 0x40000
	s_addc_u32 s51, s85, 0
	s_mov_b32 m0, s86
	v_lshl_add_u64 v[232:233], s[50:51], 0, v[130:131]
	ds_read_b128 v[180:183], v194 offset:32768
	ds_read_b128 v[196:199], v194 offset:33792
	ds_read_b128 v[200:203], v194 offset:34816
	ds_read_b128 v[204:207], v194 offset:35840
	ds_read_b128 v[208:211], v194 offset:36864
	ds_read_b128 v[212:215], v194 offset:37888
	ds_read_b128 v[216:219], v194 offset:38912
	ds_read_b128 v[220:223], v194 offset:39936
	global_load_lds_dwordx4 v[232:233], off
	v_lshl_add_u64 v[232:233], s[50:51], 0, v[134:135]
	s_mov_b32 m0, s87
	s_nop 0
	global_load_lds_dwordx4 v[232:233], off
	s_waitcnt vmcnt(8)
	s_waitcnt lgkmcnt(0)
	s_barrier
	s_waitcnt lgkmcnt(0)
	v_mfma_f32_16x16x32_bf16 v[118:121], v[148:151], v[180:183], v[118:121]
	v_mfma_f32_16x16x32_bf16 v[114:117], v[156:159], v[180:183], v[114:117]
	v_mfma_f32_16x16x32_bf16 v[102:105], v[148:151], v[200:203], v[102:105]
	v_mfma_f32_16x16x32_bf16 v[98:101], v[156:159], v[200:203], v[98:101]
	v_mfma_f32_16x16x32_bf16 v[86:89], v[148:151], v[208:211], v[86:89]
	v_mfma_f32_16x16x32_bf16 v[82:85], v[156:159], v[208:211], v[82:85]
	v_mfma_f32_16x16x32_bf16 v[70:73], v[148:151], v[216:219], v[70:73]
	v_mfma_f32_16x16x32_bf16 v[66:69], v[156:159], v[216:219], v[66:69]
	v_mfma_f32_16x16x32_bf16 v[118:121], v[152:155], v[196:199], v[118:121]
	v_mfma_f32_16x16x32_bf16 v[114:117], v[160:163], v[196:199], v[114:117]
	v_mfma_f32_16x16x32_bf16 v[102:105], v[152:155], v[204:207], v[102:105]
	v_mfma_f32_16x16x32_bf16 v[98:101], v[160:163], v[204:207], v[98:101]
	v_mfma_f32_16x16x32_bf16 v[86:89], v[152:155], v[212:215], v[86:89]
	v_mfma_f32_16x16x32_bf16 v[82:85], v[160:163], v[212:215], v[82:85]
	v_mfma_f32_16x16x32_bf16 v[70:73], v[152:155], v[220:223], v[70:73]
	v_mfma_f32_16x16x32_bf16 v[66:69], v[160:163], v[220:223], v[66:69]
	v_mfma_f32_16x16x32_bf16 v[126:129], v[164:167], v[180:183], v[126:129]
	v_mfma_f32_16x16x32_bf16 v[122:125], v[172:175], v[180:183], v[122:125]
	v_mfma_f32_16x16x32_bf16 v[110:113], v[164:167], v[200:203], v[110:113]
	v_mfma_f32_16x16x32_bf16 v[106:109], v[172:175], v[200:203], v[106:109]
	v_mfma_f32_16x16x32_bf16 v[94:97], v[164:167], v[208:211], v[94:97]
	v_mfma_f32_16x16x32_bf16 v[90:93], v[172:175], v[208:211], v[90:93]
	v_mfma_f32_16x16x32_bf16 v[78:81], v[164:167], v[216:219], v[78:81]
	v_mfma_f32_16x16x32_bf16 v[74:77], v[172:175], v[216:219], v[74:77]
	v_mfma_f32_16x16x32_bf16 v[126:129], v[168:171], v[196:199], v[126:129]
	v_mfma_f32_16x16x32_bf16 v[122:125], v[176:179], v[196:199], v[122:125]
	v_mfma_f32_16x16x32_bf16 v[110:113], v[168:171], v[204:207], v[110:113]
	v_mfma_f32_16x16x32_bf16 v[106:109], v[176:179], v[204:207], v[106:109]
	v_mfma_f32_16x16x32_bf16 v[94:97], v[168:171], v[212:215], v[94:97]
	v_mfma_f32_16x16x32_bf16 v[90:93], v[176:179], v[212:215], v[90:93]
	v_mfma_f32_16x16x32_bf16 v[78:81], v[168:171], v[220:223], v[78:81]
	v_mfma_f32_16x16x32_bf16 v[74:77], v[176:179], v[220:223], v[74:77]
	s_barrier
	s_add_i32 s9, s9, s33
	v_lshl_add_u64 v[224:225], v[224:225], 0, s[62:63]
	s_mov_b32 m0, s9
	ds_read_b128 v[180:183], v194 offset:49152
	ds_read_b128 v[196:199], v194 offset:50176
	ds_read_b128 v[200:203], v194 offset:51200
	ds_read_b128 v[204:207], v194 offset:52224
	ds_read_b128 v[208:211], v194 offset:53248
	ds_read_b128 v[212:215], v194 offset:54272
	ds_read_b128 v[216:219], v194 offset:55296
	ds_read_b128 v[220:223], v194 offset:56320
	global_load_lds_dwordx4 v[224:225], off
	s_add_i32 m0, s9, 0x2000
	s_add_u32 s50, s82, 0x40080
	v_lshl_add_u64 v[224:225], v[226:227], 0, s[62:63]
	s_addc_u32 s51, s83, 0
	s_add_i32 s9, s89, s33
	global_load_lds_dwordx4 v[224:225], off
	v_lshl_add_u64 v[224:225], s[50:51], 0, v[132:133]
	s_mov_b32 m0, s9
	s_nop 0
	global_load_lds_dwordx4 v[224:225], off
	v_lshl_add_u64 v[224:225], s[50:51], 0, v[136:137]
	s_add_i32 m0, s9, 0x2000
	s_nop 0
	global_load_lds_dwordx4 v[224:225], off
	v_lshl_add_u64 v[224:225], v[228:229], 0, s[62:63]
	s_mov_b32 m0, s93
	s_nop 0
	global_load_lds_dwordx4 v[224:225], off
	v_lshl_add_u64 v[224:225], v[230:231], 0, s[62:63]
	s_mov_b32 m0, s94
	s_nop 0
	global_load_lds_dwordx4 v[224:225], off
	s_waitcnt vmcnt(8)
	s_waitcnt lgkmcnt(0)
	s_barrier
	s_waitcnt lgkmcnt(0)
	v_mfma_f32_16x16x32_bf16 v[54:57], v[148:151], v[180:183], v[54:57]
	v_mfma_f32_16x16x32_bf16 v[50:53], v[156:159], v[180:183], v[50:53]
	v_mfma_f32_16x16x32_bf16 v[38:41], v[148:151], v[200:203], v[38:41]
	v_mfma_f32_16x16x32_bf16 v[34:37], v[156:159], v[200:203], v[34:37]
	v_mfma_f32_16x16x32_bf16 v[22:25], v[148:151], v[208:211], v[22:25]
	v_mfma_f32_16x16x32_bf16 v[18:21], v[156:159], v[208:211], v[18:21]
	v_mfma_f32_16x16x32_bf16 v[6:9], v[148:151], v[216:219], v[6:9]
	v_mfma_f32_16x16x32_bf16 v[2:5], v[156:159], v[216:219], v[2:5]
	v_mfma_f32_16x16x32_bf16 v[54:57], v[152:155], v[196:199], v[54:57]
	v_mfma_f32_16x16x32_bf16 v[50:53], v[160:163], v[196:199], v[50:53]
	v_mfma_f32_16x16x32_bf16 v[38:41], v[152:155], v[204:207], v[38:41]
	v_mfma_f32_16x16x32_bf16 v[34:37], v[160:163], v[204:207], v[34:37]
	v_mfma_f32_16x16x32_bf16 v[22:25], v[152:155], v[212:215], v[22:25]
	v_mfma_f32_16x16x32_bf16 v[18:21], v[160:163], v[212:215], v[18:21]
	v_mfma_f32_16x16x32_bf16 v[6:9], v[152:155], v[220:223], v[6:9]
	v_mfma_f32_16x16x32_bf16 v[2:5], v[160:163], v[220:223], v[2:5]
	v_mfma_f32_16x16x32_bf16 v[62:65], v[164:167], v[180:183], v[62:65]
	v_mfma_f32_16x16x32_bf16 v[58:61], v[172:175], v[180:183], v[58:61]
	v_mfma_f32_16x16x32_bf16 v[46:49], v[164:167], v[200:203], v[46:49]
	v_mfma_f32_16x16x32_bf16 v[42:45], v[172:175], v[200:203], v[42:45]
	v_mfma_f32_16x16x32_bf16 v[30:33], v[164:167], v[208:211], v[30:33]
	v_mfma_f32_16x16x32_bf16 v[26:29], v[172:175], v[208:211], v[26:29]
	v_mfma_f32_16x16x32_bf16 v[14:17], v[164:167], v[216:219], v[14:17]
	v_mfma_f32_16x16x32_bf16 v[10:13], v[172:175], v[216:219], v[10:13]
	v_mfma_f32_16x16x32_bf16 v[62:65], v[168:171], v[196:199], v[62:65]
	v_mfma_f32_16x16x32_bf16 v[58:61], v[176:179], v[196:199], v[58:61]
	v_mfma_f32_16x16x32_bf16 v[46:49], v[168:171], v[204:207], v[46:49]
	v_mfma_f32_16x16x32_bf16 v[42:45], v[176:179], v[204:207], v[42:45]
	v_mfma_f32_16x16x32_bf16 v[30:33], v[168:171], v[212:215], v[30:33]
	v_mfma_f32_16x16x32_bf16 v[26:29], v[176:179], v[212:215], v[26:29]
	v_mfma_f32_16x16x32_bf16 v[14:17], v[168:171], v[220:223], v[14:17]
	v_mfma_f32_16x16x32_bf16 v[10:13], v[176:179], v[220:223], v[10:13]
	s_barrier
	s_add_i32 s8, s8, 2
	s_add_u32 s80, s80, 0x100
	s_addc_u32 s81, s81, 0
	s_add_u32 vcc_lo, vcc_lo, 0x100
	s_addc_u32 vcc_hi, vcc_hi, 0
; #define PG8_STAGE(bufoff, gbase, voff) do { _Pragma("unroll") for (int _i = 0; _i < 2; ++_i) \
;         __builtin_amdgcn_global_load_lds((const unsigned*)((const char*)(gbase) + (voff)[_i]), (LAS unsigned*)(lds + (bufoff) + ldsw + _i * 8192), 16, 0, 0); } while (0)
; #define PG8_LDA(dst, b, h) do { _Pragma("unroll") for (int m = 0; m < 4; ++m) _Pragma("unroll") for (int k = 0; k < 2; ++k) dst[m][k] = *(const LAS bf16x8*)(lds + PG8_SA(b, h) + aoff + m * 2048 + k * 1024); } while (0)
; #define PG8_LDB(dst, b, h) do { _Pragma("unroll") for (int n = 0; n < 2; ++n) _Pragma("unroll") for (int k = 0; k < 2; ++k) dst[n][k] = *(const LAS bf16x8*)(lds + PG8_SB(b, h) + boff + n * 2048 + k * 1024); } while (0)
; #define PG8_MMA(ai, bj, At, Bt) do { __builtin_amdgcn_s_setprio(3); _Pragma("unroll") for (int m = 0; m < 4; ++m) _Pragma("unroll") for (int n = 0; n < 2; ++n) _Pragma("unroll") for (int k = 0; k < 2; ++k) \
;         acc[ai][bj][m][n] = __builtin_amdgcn_mfma_f32_16x16x32_bf16(Bt[n][k], At[m][k], acc[ai][bj][m][n], 0, 0, 0); __builtin_amdgcn_s_setprio(0); } while (0)
; #define PG8_WAIT_V(n) asm volatile("s_waitcnt vmcnt(" #n ")" ::: "memory")
; #define PG8_WAIT_L(n) asm volatile("s_waitcnt lgkmcnt(" #n ")" ::: "memory")
; #define PG8_BAR __builtin_amdgcn_s_barrier()
; #define PG8_SCHED __builtin_amdgcn_sched_barrier(0)
; template <class Epi, bool ALIGN_EPI>
; __device__ __forceinline__ void gemm_phase(LAS unsigned char* lds, const Gemm g, const StaticOrder& S, const Epi& E) {
;     ...
;         for (int t = 0; t < nt; t += 2) {
;             const bool last = (t == nt - 2);
;             const char* a1 = cA + (size_t)(t + 1) * kstep;
;             const char* a2 = last ? nA : cA + (size_t)(t + 2) * kstep; const char* b2 = last ? nB : cB + (size_t)(t + 2) * kstep;
;             const char* a3 = a2 + kstep; const char* b3 = b2 + kstep;
;             PG8_LDB(B0, 0, 0); PG8_LDB(B1, 0, 1); PG8_SCHED; PG8_LDA(At, 0, 0); PG8_STAGE(PG8_SA(1, 1), a1 + hstep, voffA);
;             PG8_WAIT_V(8); PG8_WAIT_L(0); PG8_BAR; PG8_MMA(0, 0, At, B0); PG8_MMA(0, 1, At, B1); PG8_BAR; PG8_SCHED;
;             PG8_LDA(At, 0, 1); PG8_STAGE(PG8_SB(0, 0), b2, voffB); PG8_STAGE(PG8_SB(0, 1), b2 + hstep, voffB); PG8_STAGE(PG8_SA(0, 0), a2, voffA);
;             PG8_WAIT_V(8); PG8_WAIT_L(0); PG8_BAR; PG8_MMA(1, 0, At, B0); PG8_MMA(1, 1, At, B1); PG8_BAR; PG8_SCHED;
.LBB0_293:
	ds_read_b128 v[148:151], v192
	ds_read_b128 v[152:155], v192 offset:1024
	ds_read_b128 v[156:159], v192 offset:2048
	ds_read_b128 v[160:163], v192 offset:3072
	ds_read_b128 v[164:167], v193
	ds_read_b128 v[168:171], v193 offset:1024
	ds_read_b128 v[172:175], v193 offset:2048
	ds_read_b128 v[176:179], v193 offset:3072
	s_add_u32 s9, s80, 0xfffc0080
	s_addc_u32 s50, s81, -1
	s_cmp_eq_u32 s8, 12
	s_cselect_b32 s85, s5, s50
	s_cselect_b32 s84, s69, s9
	s_cselect_b32 s83, s67, vcc_hi
	s_cselect_b32 s82, s79, vcc_lo
	v_lshl_add_u64 v[224:225], s[80:81], 0, v[140:141]
	s_add_i32 m0, s76, 0xc000
	ds_read_b128 v[180:183], v194
	ds_read_b128 v[196:199], v194 offset:1024
	ds_read_b128 v[200:203], v194 offset:2048
	ds_read_b128 v[204:207], v194 offset:3072
	ds_read_b128 v[208:211], v194 offset:4096
	ds_read_b128 v[212:215], v194 offset:5120
	ds_read_b128 v[216:219], v194 offset:6144
	ds_read_b128 v[220:223], v194 offset:7168
	global_load_lds_dwordx4 v[224:225], off
	v_lshl_add_u64 v[224:225], s[80:81], 0, v[142:143]
	s_add_i32 m0, s76, 0xe000
	s_nop 0
	global_load_lds_dwordx4 v[224:225], off
	s_waitcnt vmcnt(8)
	s_waitcnt lgkmcnt(0)
	s_barrier
	s_waitcnt lgkmcnt(0)
	v_mfma_f32_16x16x32_bf16 v[118:121], v[148:151], v[180:183], v[118:121]
	v_mfma_f32_16x16x32_bf16 v[114:117], v[156:159], v[180:183], v[114:117]
	v_mfma_f32_16x16x32_bf16 v[102:105], v[148:151], v[200:203], v[102:105]
	v_mfma_f32_16x16x32_bf16 v[98:101], v[156:159], v[200:203], v[98:101]
	v_mfma_f32_16x16x32_bf16 v[86:89], v[148:151], v[208:211], v[86:89]
	v_mfma_f32_16x16x32_bf16 v[82:85], v[156:159], v[208:211], v[82:85]
	v_mfma_f32_16x16x32_bf16 v[70:73], v[148:151], v[216:219], v[70:73]
	v_mfma_f32_16x16x32_bf16 v[66:69], v[156:159], v[216:219], v[66:69]
	v_mfma_f32_16x16x32_bf16 v[118:121], v[152:155], v[196:199], v[118:121]
	v_mfma_f32_16x16x32_bf16 v[114:117], v[160:163], v[196:199], v[114:117]
	v_mfma_f32_16x16x32_bf16 v[102:105], v[152:155], v[204:207], v[102:105]
	v_mfma_f32_16x16x32_bf16 v[98:101], v[160:163], v[204:207], v[98:101]
	v_mfma_f32_16x16x32_bf16 v[86:89], v[152:155], v[212:215], v[86:89]
	v_mfma_f32_16x16x32_bf16 v[82:85], v[160:163], v[212:215], v[82:85]
	v_mfma_f32_16x16x32_bf16 v[70:73], v[152:155], v[220:223], v[70:73]
	v_mfma_f32_16x16x32_bf16 v[66:69], v[160:163], v[220:223], v[66:69]
	v_mfma_f32_16x16x32_bf16 v[126:129], v[164:167], v[180:183], v[126:129]
	v_mfma_f32_16x16x32_bf16 v[122:125], v[172:175], v[180:183], v[122:125]
	v_mfma_f32_16x16x32_bf16 v[110:113], v[164:167], v[200:203], v[110:113]
	v_mfma_f32_16x16x32_bf16 v[106:109], v[172:175], v[200:203], v[106:109]
	v_mfma_f32_16x16x32_bf16 v[94:97], v[164:167], v[208:211], v[94:97]
	v_mfma_f32_16x16x32_bf16 v[90:93], v[172:175], v[208:211], v[90:93]
	v_mfma_f32_16x16x32_bf16 v[78:81], v[164:167], v[216:219], v[78:81]
	v_mfma_f32_16x16x32_bf16 v[74:77], v[172:175], v[216:219], v[74:77]
	v_mfma_f32_16x16x32_bf16 v[126:129], v[168:171], v[196:199], v[126:129]
	v_mfma_f32_16x16x32_bf16 v[122:125], v[176:179], v[196:199], v[122:125]
	v_mfma_f32_16x16x32_bf16 v[110:113], v[168:171], v[204:207], v[110:113]
	v_mfma_f32_16x16x32_bf16 v[106:109], v[176:179], v[204:207], v[106:109]
	v_mfma_f32_16x16x32_bf16 v[94:97], v[168:171], v[212:215], v[94:97]
	v_mfma_f32_16x16x32_bf16 v[90:93], v[176:179], v[212:215], v[90:93]
	v_mfma_f32_16x16x32_bf16 v[78:81], v[168:171], v[220:223], v[78:81]
	v_mfma_f32_16x16x32_bf16 v[74:77], v[176:179], v[220:223], v[74:77]
	s_barrier
	s_add_i32 s9, s95, s33
	v_lshl_add_u64 v[224:225], s[82:83], 0, v[132:133]
	s_mov_b32 m0, s9
	ds_read_b128 v[180:183], v194 offset:16384
	ds_read_b128 v[196:199], v194 offset:17408
	ds_read_b128 v[200:203], v194 offset:18432
	ds_read_b128 v[204:207], v194 offset:19456
	ds_read_b128 v[208:211], v194 offset:20480
	ds_read_b128 v[212:215], v194 offset:21504
	ds_read_b128 v[216:219], v194 offset:22528
	ds_read_b128 v[220:223], v194 offset:23552
	global_load_lds_dwordx4 v[224:225], off
	s_add_i32 m0, s9, 0x2000
	s_add_u32 s50, s82, 0x40000
	v_lshl_add_u64 v[226:227], s[82:83], 0, v[136:137]
	s_addc_u32 s51, s83, 0
	s_add_i32 s9, s96, s33
	global_load_lds_dwordx4 v[226:227], off
	v_lshl_add_u64 v[228:229], s[50:51], 0, v[132:133]
	s_mov_b32 m0, s9
	v_lshl_add_u64 v[230:231], s[84:85], 0, v[134:135]
	global_load_lds_dwordx4 v[228:229], off
	v_lshl_add_u64 v[228:229], s[50:51], 0, v[136:137]
	s_add_i32 m0, s9, 0x2000
	s_nop 0
	global_load_lds_dwordx4 v[228:229], off
	v_lshl_add_u64 v[228:229], s[84:85], 0, v[130:131]
	s_mov_b32 m0, s76
	s_nop 0
	global_load_lds_dwordx4 v[228:229], off
	s_mov_b32 m0, s77
	s_nop 0
	global_load_lds_dwordx4 v[230:231], off
	s_waitcnt vmcnt(8)
	s_waitcnt lgkmcnt(0)
	s_barrier
; #define PG8_STAGE(bufoff, gbase, voff) do { _Pragma("unroll") for (int _i = 0; _i < 2; ++_i) \
;         __builtin_amdgcn_global_load_lds((const unsigned*)((const char*)(gbase) + (voff)[_i]), (LAS unsigned*)(lds + (bufoff) + ldsw + _i * 8192), 16, 0, 0); } while (0)
; #define PG8_LDA(dst, b, h) do { _Pragma("unroll") for (int m = 0; m < 4; ++m) _Pragma("unroll") for (int k = 0; k < 2; ++k) dst[m][k] = *(const LAS bf16x8*)(lds + PG8_SA(b, h) + aoff + m * 2048 + k * 1024); } while (0)
; #define PG8_LDB(dst, b, h) do { _Pragma("unroll") for (int n = 0; n < 2; ++n) _Pragma("unroll") for (int k = 0; k < 2; ++k) dst[n][k] = *(const LAS bf16x8*)(lds + PG8_SB(b, h) + boff + n * 2048 + k * 1024); } while (0)
; #define PG8_MMA(ai, bj, At, Bt) do { __builtin_amdgcn_s_setprio(3); _Pragma("unroll") for (int m = 0; m < 4; ++m) _Pragma("unroll") for (int n = 0; n < 2; ++n) _Pragma("unroll") for (int k = 0; k < 2; ++k) \
;         acc[ai][bj][m][n] = __builtin_amdgcn_mfma_f32_16x16x32_bf16(Bt[n][k], At[m][k], acc[ai][bj][m][n], 0, 0, 0); __builtin_amdgcn_s_setprio(0); } while (0)
; #define PG8_WAIT_V(n) asm volatile("s_waitcnt vmcnt(" #n ")" ::: "memory")
; #define PG8_WAIT_L(n) asm volatile("s_waitcnt lgkmcnt(" #n ")" ::: "memory")
; #define PG8_BAR __builtin_amdgcn_s_barrier()
; #define PG8_SCHED __builtin_amdgcn_sched_barrier(0)
; template <class Epi, bool ALIGN_EPI>
; __device__ __forceinline__ void gemm_phase(LAS unsigned char* lds, const Gemm g, const StaticOrder& S, const Epi& E) {
;     ...
;             PG8_WAIT_V(8); PG8_WAIT_L(0); PG8_BAR; PG8_MMA(1, 0, At, B0); PG8_MMA(1, 1, At, B1); PG8_BAR; PG8_SCHED;
;             PG8_LDB(B0, 1, 0); PG8_LDB(B1, 1, 1); PG8_SCHED; PG8_LDA(At, 1, 0); PG8_STAGE(PG8_SA(0, 1), a2 + hstep, voffA);
;             PG8_WAIT_V(8); PG8_WAIT_L(0); PG8_BAR; PG8_MMA(0, 0, At, B0); PG8_MMA(0, 1, At, B1); PG8_BAR; PG8_SCHED;
	s_waitcnt lgkmcnt(0)
	v_mfma_f32_16x16x32_bf16 v[54:57], v[148:151], v[180:183], v[54:57]
	v_mfma_f32_16x16x32_bf16 v[50:53], v[156:159], v[180:183], v[50:53]
	v_mfma_f32_16x16x32_bf16 v[38:41], v[148:151], v[200:203], v[38:41]
	v_mfma_f32_16x16x32_bf16 v[34:37], v[156:159], v[200:203], v[34:37]
	v_mfma_f32_16x16x32_bf16 v[22:25], v[148:151], v[208:211], v[22:25]
	v_mfma_f32_16x16x32_bf16 v[18:21], v[156:159], v[208:211], v[18:21]
	v_mfma_f32_16x16x32_bf16 v[6:9], v[148:151], v[216:219], v[6:9]
	v_mfma_f32_16x16x32_bf16 v[2:5], v[156:159], v[216:219], v[2:5]
	v_mfma_f32_16x16x32_bf16 v[54:57], v[152:155], v[196:199], v[54:57]
	v_mfma_f32_16x16x32_bf16 v[50:53], v[160:163], v[196:199], v[50:53]
	v_mfma_f32_16x16x32_bf16 v[38:41], v[152:155], v[204:207], v[38:41]
	v_mfma_f32_16x16x32_bf16 v[34:37], v[160:163], v[204:207], v[34:37]
	v_mfma_f32_16x16x32_bf16 v[22:25], v[152:155], v[212:215], v[22:25]
	v_mfma_f32_16x16x32_bf16 v[18:21], v[160:163], v[212:215], v[18:21]
	v_mfma_f32_16x16x32_bf16 v[6:9], v[152:155], v[220:223], v[6:9]
	v_mfma_f32_16x16x32_bf16 v[2:5], v[160:163], v[220:223], v[2:5]
	v_mfma_f32_16x16x32_bf16 v[62:65], v[164:167], v[180:183], v[62:65]
	v_mfma_f32_16x16x32_bf16 v[58:61], v[172:175], v[180:183], v[58:61]
	v_mfma_f32_16x16x32_bf16 v[46:49], v[164:167], v[200:203], v[46:49]
	v_mfma_f32_16x16x32_bf16 v[42:45], v[172:175], v[200:203], v[42:45]
	v_mfma_f32_16x16x32_bf16 v[30:33], v[164:167], v[208:211], v[30:33]
	v_mfma_f32_16x16x32_bf16 v[26:29], v[172:175], v[208:211], v[26:29]
	v_mfma_f32_16x16x32_bf16 v[14:17], v[164:167], v[216:219], v[14:17]
	v_mfma_f32_16x16x32_bf16 v[10:13], v[172:175], v[216:219], v[10:13]
	v_mfma_f32_16x16x32_bf16 v[62:65], v[168:171], v[196:199], v[62:65]
	v_mfma_f32_16x16x32_bf16 v[58:61], v[176:179], v[196:199], v[58:61]
	v_mfma_f32_16x16x32_bf16 v[46:49], v[168:171], v[204:207], v[46:49]
	v_mfma_f32_16x16x32_bf16 v[42:45], v[176:179], v[204:207], v[42:45]
	v_mfma_f32_16x16x32_bf16 v[30:33], v[168:171], v[212:215], v[30:33]
	v_mfma_f32_16x16x32_bf16 v[26:29], v[176:179], v[212:215], v[26:29]
	v_mfma_f32_16x16x32_bf16 v[14:17], v[168:171], v[220:223], v[14:17]
	v_mfma_f32_16x16x32_bf16 v[10:13], v[176:179], v[220:223], v[10:13]
	s_barrier
	s_add_i32 s9, 0, 0x18000
	v_add_u32_e32 v138, s9, v189
	s_add_i32 s89, 0, 0x1c000
	ds_read_b128 v[148:151], v138
	ds_read_b128 v[152:155], v138 offset:1024
	ds_read_b128 v[156:159], v138 offset:2048
	ds_read_b128 v[160:163], v138 offset:3072
	v_add_u32_e32 v138, s89, v189
	ds_read_b128 v[164:167], v138
	ds_read_b128 v[168:171], v138 offset:1024
	ds_read_b128 v[172:175], v138 offset:2048
	ds_read_b128 v[176:179], v138 offset:3072
	s_add_u32 s50, s84, 0x40000
	s_addc_u32 s51, s85, 0
	s_mov_b32 m0, s86
	v_lshl_add_u64 v[232:233], s[50:51], 0, v[130:131]
	ds_read_b128 v[180:183], v194 offset:32768
	ds_read_b128 v[196:199], v194 offset:33792
	ds_read_b128 v[200:203], v194 offset:34816
	ds_read_b128 v[204:207], v194 offset:35840
	ds_read_b128 v[208:211], v194 offset:36864
	ds_read_b128 v[212:215], v194 offset:37888
	ds_read_b128 v[216:219], v194 offset:38912
	ds_read_b128 v[220:223], v194 offset:39936
	global_load_lds_dwordx4 v[232:233], off
	v_lshl_add_u64 v[232:233], s[50:51], 0, v[134:135]
	s_mov_b32 m0, s87
	s_nop 0
	global_load_lds_dwordx4 v[232:233], off
	s_waitcnt vmcnt(8)
	s_waitcnt lgkmcnt(0)
	s_barrier
	s_waitcnt lgkmcnt(0)
	v_mfma_f32_16x16x32_bf16 v[118:121], v[148:151], v[180:183], v[118:121]
	v_mfma_f32_16x16x32_bf16 v[114:117], v[156:159], v[180:183], v[114:117]
	v_mfma_f32_16x16x32_bf16 v[102:105], v[148:151], v[200:203], v[102:105]
	v_mfma_f32_16x16x32_bf16 v[98:101], v[156:159], v[200:203], v[98:101]
	v_mfma_f32_16x16x32_bf16 v[86:89], v[148:151], v[208:211], v[86:89]
	v_mfma_f32_16x16x32_bf16 v[82:85], v[156:159], v[208:211], v[82:85]
	v_mfma_f32_16x16x32_bf16 v[70:73], v[148:151], v[216:219], v[70:73]
	v_mfma_f32_16x16x32_bf16 v[66:69], v[156:159], v[216:219], v[66:69]
	v_mfma_f32_16x16x32_bf16 v[118:121], v[152:155], v[196:199], v[118:121]
	v_mfma_f32_16x16x32_bf16 v[114:117], v[160:163], v[196:199], v[114:117]
	v_mfma_f32_16x16x32_bf16 v[102:105], v[152:155], v[204:207], v[102:105]
	v_mfma_f32_16x16x32_bf16 v[98:101], v[160:163], v[204:207], v[98:101]
	v_mfma_f32_16x16x32_bf16 v[86:89], v[152:155], v[212:215], v[86:89]
	v_mfma_f32_16x16x32_bf16 v[82:85], v[160:163], v[212:215], v[82:85]
	v_mfma_f32_16x16x32_bf16 v[70:73], v[152:155], v[220:223], v[70:73]
	v_mfma_f32_16x16x32_bf16 v[66:69], v[160:163], v[220:223], v[66:69]
	v_mfma_f32_16x16x32_bf16 v[126:129], v[164:167], v[180:183], v[126:129]
	v_mfma_f32_16x16x32_bf16 v[122:125], v[172:175], v[180:183], v[122:125]
	v_mfma_f32_16x16x32_bf16 v[110:113], v[164:167], v[200:203], v[110:113]
	v_mfma_f32_16x16x32_bf16 v[106:109], v[172:175], v[200:203], v[106:109]
	v_mfma_f32_16x16x32_bf16 v[94:97], v[164:167], v[208:211], v[94:97]
	v_mfma_f32_16x16x32_bf16 v[90:93], v[172:175], v[208:211], v[90:93]
	v_mfma_f32_16x16x32_bf16 v[78:81], v[164:167], v[216:219], v[78:81]
	v_mfma_f32_16x16x32_bf16 v[74:77], v[172:175], v[216:219], v[74:77]
	v_mfma_f32_16x16x32_bf16 v[126:129], v[168:171], v[196:199], v[126:129]
	v_mfma_f32_16x16x32_bf16 v[122:125], v[176:179], v[196:199], v[122:125]
	v_mfma_f32_16x16x32_bf16 v[110:113], v[168:171], v[204:207], v[110:113]
	v_mfma_f32_16x16x32_bf16 v[106:109], v[176:179], v[204:207], v[106:109]
	v_mfma_f32_16x16x32_bf16 v[94:97], v[168:171], v[212:215], v[94:97]
	v_mfma_f32_16x16x32_bf16 v[90:93], v[176:179], v[212:215], v[90:93]
	v_mfma_f32_16x16x32_bf16 v[78:81], v[168:171], v[220:223], v[78:81]
	v_mfma_f32_16x16x32_bf16 v[74:77], v[176:179], v[220:223], v[74:77]
	s_barrier
; #define PG8_STAGE(bufoff, gbase, voff) do { _Pragma("unroll") for (int _i = 0; _i < 2; ++_i) \
;         __builtin_amdgcn_global_load_lds((const unsigned*)((const char*)(gbase) + (voff)[_i]), (LAS unsigned*)(lds + (bufoff) + ldsw + _i * 8192), 16, 0, 0); } while (0)
; #define PG8_LDA(dst, b, h) do { _Pragma("unroll") for (int m = 0; m < 4; ++m) _Pragma("unroll") for (int k = 0; k < 2; ++k) dst[m][k] = *(const LAS bf16x8*)(lds + PG8_SA(b, h) + aoff + m * 2048 + k * 1024); } while (0)
; #define PG8_MMA(ai, bj, At, Bt) do { __builtin_amdgcn_s_setprio(3); _Pragma("unroll") for (int m = 0; m < 4; ++m) _Pragma("unroll") for (int n = 0; n < 2; ++n) _Pragma("unroll") for (int k = 0; k < 2; ++k) \
;         acc[ai][bj][m][n] = __builtin_amdgcn_mfma_f32_16x16x32_bf16(Bt[n][k], At[m][k], acc[ai][bj][m][n], 0, 0, 0); __builtin_amdgcn_s_setprio(0); } while (0)
; #define PG8_WAIT_V(n) asm volatile("s_waitcnt vmcnt(" #n ")" ::: "memory")
; #define PG8_WAIT_L(n) asm volatile("s_waitcnt lgkmcnt(" #n ")" ::: "memory")
; #define PG8_BAR __builtin_amdgcn_s_barrier()
; #define PG8_SCHED __builtin_amdgcn_sched_barrier(0)
; template <class Epi, bool ALIGN_EPI>
; __device__ __forceinline__ void gemm_phase(LAS unsigned char* lds, const Gemm g, const StaticOrder& S, const Epi& E) {
;     ...
;             PG8_LDA(At, 1, 1); PG8_STAGE(PG8_SB(1, 0), b3, voffB); PG8_STAGE(PG8_SB(1, 1), b3 + hstep, voffB); PG8_STAGE(PG8_SA(1, 0), a3, voffA);
;             PG8_WAIT_V(8); PG8_WAIT_L(0); PG8_BAR; PG8_MMA(1, 0, At, B0); PG8_MMA(1, 1, At, B1); PG8_BAR; PG8_SCHED;
;         }
;         if constexpr (ALIGN_EPI) { if (wr == 0) PG8_BAR; }
;         E(acc, cur, wr, wc, fr, fq);
;         if (!has_next) break;
	s_add_i32 s9, s9, s33
	v_lshl_add_u64 v[224:225], v[224:225], 0, s[62:63]
	s_mov_b32 m0, s9
	ds_read_b128 v[180:183], v194 offset:49152
	ds_read_b128 v[196:199], v194 offset:50176
	ds_read_b128 v[200:203], v194 offset:51200
	ds_read_b128 v[204:207], v194 offset:52224
	ds_read_b128 v[208:211], v194 offset:53248
	ds_read_b128 v[212:215], v194 offset:54272
	ds_read_b128 v[216:219], v194 offset:55296
	ds_read_b128 v[220:223], v194 offset:56320
	global_load_lds_dwordx4 v[224:225], off
	s_add_i32 m0, s9, 0x2000
	s_add_u32 s50, s82, 0x40080
	v_lshl_add_u64 v[224:225], v[226:227], 0, s[62:63]
	s_addc_u32 s51, s83, 0
	s_add_i32 s9, s89, s33
	global_load_lds_dwordx4 v[224:225], off
	v_lshl_add_u64 v[224:225], s[50:51], 0, v[132:133]
	s_mov_b32 m0, s9
	s_nop 0
	global_load_lds_dwordx4 v[224:225], off
	v_lshl_add_u64 v[224:225], s[50:51], 0, v[136:137]
	s_add_i32 m0, s9, 0x2000
	s_nop 0
	global_load_lds_dwordx4 v[224:225], off
	v_lshl_add_u64 v[224:225], v[228:229], 0, s[62:63]
	s_mov_b32 m0, s93
	s_nop 0
	global_load_lds_dwordx4 v[224:225], off
	v_lshl_add_u64 v[224:225], v[230:231], 0, s[62:63]
	s_mov_b32 m0, s94
	s_nop 0
	global_load_lds_dwordx4 v[224:225], off
	s_waitcnt vmcnt(8)
	s_waitcnt lgkmcnt(0)
	s_barrier
	s_waitcnt lgkmcnt(0)
	v_mfma_f32_16x16x32_bf16 v[54:57], v[148:151], v[180:183], v[54:57]
	v_mfma_f32_16x16x32_bf16 v[50:53], v[156:159], v[180:183], v[50:53]
	v_mfma_f32_16x16x32_bf16 v[38:41], v[148:151], v[200:203], v[38:41]
	v_mfma_f32_16x16x32_bf16 v[34:37], v[156:159], v[200:203], v[34:37]
	v_mfma_f32_16x16x32_bf16 v[22:25], v[148:151], v[208:211], v[22:25]
	v_mfma_f32_16x16x32_bf16 v[18:21], v[156:159], v[208:211], v[18:21]
	v_mfma_f32_16x16x32_bf16 v[6:9], v[148:151], v[216:219], v[6:9]
	v_mfma_f32_16x16x32_bf16 v[2:5], v[156:159], v[216:219], v[2:5]
	v_mfma_f32_16x16x32_bf16 v[54:57], v[152:155], v[196:199], v[54:57]
	v_mfma_f32_16x16x32_bf16 v[50:53], v[160:163], v[196:199], v[50:53]
	v_mfma_f32_16x16x32_bf16 v[38:41], v[152:155], v[204:207], v[38:41]
	v_mfma_f32_16x16x32_bf16 v[34:37], v[160:163], v[204:207], v[34:37]
	v_mfma_f32_16x16x32_bf16 v[22:25], v[152:155], v[212:215], v[22:25]
	v_mfma_f32_16x16x32_bf16 v[18:21], v[160:163], v[212:215], v[18:21]
	v_mfma_f32_16x16x32_bf16 v[6:9], v[152:155], v[220:223], v[6:9]
	v_mfma_f32_16x16x32_bf16 v[2:5], v[160:163], v[220:223], v[2:5]
	v_mfma_f32_16x16x32_bf16 v[62:65], v[164:167], v[180:183], v[62:65]
	v_mfma_f32_16x16x32_bf16 v[58:61], v[172:175], v[180:183], v[58:61]
	v_mfma_f32_16x16x32_bf16 v[46:49], v[164:167], v[200:203], v[46:49]
	v_mfma_f32_16x16x32_bf16 v[42:45], v[172:175], v[200:203], v[42:45]
	v_mfma_f32_16x16x32_bf16 v[30:33], v[164:167], v[208:211], v[30:33]
	v_mfma_f32_16x16x32_bf16 v[26:29], v[172:175], v[208:211], v[26:29]
	v_mfma_f32_16x16x32_bf16 v[14:17], v[164:167], v[216:219], v[14:17]
	v_mfma_f32_16x16x32_bf16 v[10:13], v[172:175], v[216:219], v[10:13]
	v_mfma_f32_16x16x32_bf16 v[62:65], v[168:171], v[196:199], v[62:65]
	v_mfma_f32_16x16x32_bf16 v[58:61], v[176:179], v[196:199], v[58:61]
	v_mfma_f32_16x16x32_bf16 v[46:49], v[168:171], v[204:207], v[46:49]
	v_mfma_f32_16x16x32_bf16 v[42:45], v[176:179], v[204:207], v[42:45]
	v_mfma_f32_16x16x32_bf16 v[30:33], v[168:171], v[212:215], v[30:33]
	v_mfma_f32_16x16x32_bf16 v[26:29], v[176:179], v[212:215], v[26:29]
	v_mfma_f32_16x16x32_bf16 v[14:17], v[168:171], v[220:223], v[14:17]
	v_mfma_f32_16x16x32_bf16 v[10:13], v[176:179], v[220:223], v[10:13]
	s_barrier
	s_add_i32 s8, s8, 2
	s_add_u32 s80, s80, 0x100
	s_addc_u32 s81, s81, 0
	s_add_u32 vcc_lo, vcc_lo, 0x100
	s_addc_u32 vcc_hi, vcc_hi, 0
	s_cmp_gt_u32 s8, 13
	s_cbranch_scc0 .LBB0_293
	s_and_b64 vcc, exec, s[64:65]
	s_cbranch_vccz .LBB0_296
	s_barrier

; #define PG8_STAGE(bufoff, gbase, voff) do { _Pragma("unroll") for (int _i = 0; _i < 2; ++_i) \
;         __builtin_amdgcn_global_load_lds((const unsigned*)((const char*)(gbase) + (voff)[_i]), (LAS unsigned*)(lds + (bufoff) + ldsw + _i * 8192), 16, 0, 0); } while (0)
; #define PG8_LDA(dst, b, h) do { _Pragma("unroll") for (int m = 0; m < 4; ++m) _Pragma("unroll") for (int k = 0; k < 2; ++k) dst[m][k] = *(const LAS bf16x8*)(lds + PG8_SA(b, h) + aoff + m * 2048 + k * 1024); } while (0)
; #define PG8_LDB(dst, b, h) do { _Pragma("unroll") for (int n = 0; n < 2; ++n) _Pragma("unroll") for (int k = 0; k < 2; ++k) dst[n][k] = *(const LAS bf16x8*)(lds + PG8_SB(b, h) + boff + n * 2048 + k * 1024); } while (0)
; #define PG8_MMA(ai, bj, At, Bt) do { __builtin_amdgcn_s_setprio(3); _Pragma("unroll") for (int m = 0; m < 4; ++m) _Pragma("unroll") for (int n = 0; n < 2; ++n) _Pragma("unroll") for (int k = 0; k < 2; ++k) \
;         acc[ai][bj][m][n] = __builtin_amdgcn_mfma_f32_16x16x32_bf16(Bt[n][k], At[m][k], acc[ai][bj][m][n], 0, 0, 0); __builtin_amdgcn_s_setprio(0); } while (0)
; #define PG8_WAIT_V(n) asm volatile("s_waitcnt vmcnt(" #n ")" ::: "memory")
; #define PG8_WAIT_L(n) asm volatile("s_waitcnt lgkmcnt(" #n ")" ::: "memory")
; #define PG8_BAR __builtin_amdgcn_s_barrier()
; #define PG8_SCHED __builtin_amdgcn_sched_barrier(0)
; template <class Epi, bool ALIGN_EPI>
; __device__ __forceinline__ void gemm_phase(LAS unsigned char* lds, const Gemm g, const StaticOrder& S, const Epi& E) {
;     ...
;             PG8_LDB(B0, 0, 0); PG8_LDB(B1, 0, 1); PG8_SCHED; PG8_LDA(At, 0, 0); PG8_STAGE(PG8_SA(1, 1), a1 + hstep, voffA);
;             PG8_WAIT_V(8); PG8_WAIT_L(0); PG8_BAR; PG8_MMA(0, 0, At, B0); PG8_MMA(0, 1, At, B1); PG8_BAR; PG8_SCHED;
;             PG8_LDA(At, 0, 1); PG8_STAGE(PG8_SB(0, 0), b2, voffB); PG8_STAGE(PG8_SB(0, 1), b2 + hstep, voffB); PG8_STAGE(PG8_SA(0, 0), a2, voffA);
;             PG8_WAIT_V(8); PG8_WAIT_L(0); PG8_BAR; PG8_MMA(1, 0, At, B0); PG8_MMA(1, 1, At, B1); PG8_BAR; PG8_SCHED;
.Lmy_rw_520_0:
	s_waitcnt lgkmcnt(0)
	s_barrier
	s_waitcnt lgkmcnt(0)
	v_mfma_f32_16x16x32_bf16 v[126:129], v[130:133], v[162:165], 0
	v_mfma_f32_16x16x32_bf16 v[122:125], v[138:141], v[162:165], 0
	v_mfma_f32_16x16x32_bf16 v[110:113], v[130:133], v[170:173], 0
	v_mfma_f32_16x16x32_bf16 v[106:109], v[138:141], v[170:173], 0
	v_mfma_f32_16x16x32_bf16 v[94:97], v[130:133], v[194:197], 0
	v_mfma_f32_16x16x32_bf16 v[90:93], v[138:141], v[194:197], 0
	v_mfma_f32_16x16x32_bf16 v[78:81], v[130:133], v[202:205], 0
	v_mfma_f32_16x16x32_bf16 v[74:77], v[138:141], v[202:205], 0
	v_mfma_f32_16x16x32_bf16 v[126:129], v[134:137], v[166:169], v[126:129]
	v_mfma_f32_16x16x32_bf16 v[122:125], v[142:145], v[166:169], v[122:125]
	v_mfma_f32_16x16x32_bf16 v[110:113], v[134:137], v[174:177], v[110:113]
	v_mfma_f32_16x16x32_bf16 v[106:109], v[142:145], v[174:177], v[106:109]
	v_mfma_f32_16x16x32_bf16 v[94:97], v[134:137], v[198:201], v[94:97]
	v_mfma_f32_16x16x32_bf16 v[90:93], v[142:145], v[198:201], v[90:93]
	v_mfma_f32_16x16x32_bf16 v[78:81], v[134:137], v[218:221], v[78:81]
	v_mfma_f32_16x16x32_bf16 v[74:77], v[142:145], v[218:221], v[74:77]
	v_mfma_f32_16x16x32_bf16 v[118:121], v[146:149], v[162:165], 0
	v_mfma_f32_16x16x32_bf16 v[114:117], v[154:157], v[162:165], 0
	v_mfma_f32_16x16x32_bf16 v[102:105], v[146:149], v[170:173], 0
	v_mfma_f32_16x16x32_bf16 v[98:101], v[154:157], v[170:173], 0
	v_mfma_f32_16x16x32_bf16 v[86:89], v[146:149], v[194:197], 0
	v_mfma_f32_16x16x32_bf16 v[82:85], v[154:157], v[194:197], 0
	v_mfma_f32_16x16x32_bf16 v[70:73], v[146:149], v[202:205], 0
	v_mfma_f32_16x16x32_bf16 v[66:69], v[154:157], v[202:205], 0
	v_mfma_f32_16x16x32_bf16 v[118:121], v[150:153], v[166:169], v[118:121]
	v_mfma_f32_16x16x32_bf16 v[114:117], v[158:161], v[166:169], v[114:117]
	v_mfma_f32_16x16x32_bf16 v[102:105], v[150:153], v[174:177], v[102:105]
	v_mfma_f32_16x16x32_bf16 v[98:101], v[158:161], v[174:177], v[98:101]
	v_mfma_f32_16x16x32_bf16 v[86:89], v[150:153], v[198:201], v[86:89]
	v_mfma_f32_16x16x32_bf16 v[82:85], v[158:161], v[198:201], v[82:85]
	v_mfma_f32_16x16x32_bf16 v[70:73], v[150:153], v[218:221], v[70:73]
	v_mfma_f32_16x16x32_bf16 v[66:69], v[158:161], v[218:221], v[66:69]
	s_barrier
	s_add_i32 s86, s80, s33
	v_lshl_add_u64 v[222:223], s[66:67], 0, v[180:181]
	s_mov_b32 m0, s86
	ds_read_b128 v[162:165], v216 offset:16384
	ds_read_b128 v[166:169], v216 offset:17408
	ds_read_b128 v[170:173], v216 offset:18432
	ds_read_b128 v[174:177], v216 offset:19456
	ds_read_b128 v[194:197], v216 offset:20480
	ds_read_b128 v[198:201], v216 offset:21504
	ds_read_b128 v[202:205], v216 offset:22528
	ds_read_b128 v[218:221], v216 offset:23552
	global_load_lds_dwordx4 v[222:223], off
	s_add_i32 m0, s86, 0x2000
	s_add_u32 s86, s66, 0x40000
	v_lshl_add_u64 v[224:225], s[66:67], 0, v[184:185]
	s_addc_u32 s87, s67, 0
	s_add_i32 s88, s81, s33
	global_load_lds_dwordx4 v[224:225], off
	v_lshl_add_u64 v[226:227], s[86:87], 0, v[180:181]
	s_mov_b32 m0, s88
	v_lshl_add_u64 v[228:229], s[68:69], 0, v[182:183]
	global_load_lds_dwordx4 v[226:227], off
	v_lshl_add_u64 v[226:227], s[86:87], 0, v[184:185]
	s_add_i32 m0, s88, 0x2000
	s_nop 0
	global_load_lds_dwordx4 v[226:227], off
	v_lshl_add_u64 v[226:227], s[68:69], 0, v[178:179]
	s_mov_b32 m0, s63
	s_nop 0
	global_load_lds_dwordx4 v[226:227], off
	s_mov_b32 m0, s70
	s_nop 0
	global_load_lds_dwordx4 v[228:229], off
	s_cmp_lg_u32 s98, 0
	s_cbranch_scc1 .Lmy_rw_520_1
	s_waitcnt vmcnt(8)
.Lmy_rw_520_1:
	s_waitcnt lgkmcnt(0)
	s_barrier
	s_waitcnt lgkmcnt(0)
	v_mfma_f32_16x16x32_bf16 v[62:65], v[130:133], v[162:165], 0
	v_mfma_f32_16x16x32_bf16 v[58:61], v[138:141], v[162:165], 0
	v_mfma_f32_16x16x32_bf16 v[46:49], v[130:133], v[170:173], 0
	v_mfma_f32_16x16x32_bf16 v[42:45], v[138:141], v[170:173], 0
	v_mfma_f32_16x16x32_bf16 v[30:33], v[130:133], v[194:197], 0
	v_mfma_f32_16x16x32_bf16 v[26:29], v[138:141], v[194:197], 0
	v_mfma_f32_16x16x32_bf16 v[14:17], v[130:133], v[202:205], 0
	v_mfma_f32_16x16x32_bf16 v[10:13], v[138:141], v[202:205], 0
	v_mfma_f32_16x16x32_bf16 v[62:65], v[134:137], v[166:169], v[62:65]
	v_mfma_f32_16x16x32_bf16 v[58:61], v[142:145], v[166:169], v[58:61]
	v_mfma_f32_16x16x32_bf16 v[46:49], v[134:137], v[174:177], v[46:49]
	v_mfma_f32_16x16x32_bf16 v[42:45], v[142:145], v[174:177], v[42:45]
	v_mfma_f32_16x16x32_bf16 v[30:33], v[134:137], v[198:201], v[30:33]
	v_mfma_f32_16x16x32_bf16 v[26:29], v[142:145], v[198:201], v[26:29]
	v_mfma_f32_16x16x32_bf16 v[14:17], v[134:137], v[218:221], v[14:17]
	v_mfma_f32_16x16x32_bf16 v[10:13], v[142:145], v[218:221], v[10:13]
	v_mfma_f32_16x16x32_bf16 v[54:57], v[146:149], v[162:165], 0
	v_mfma_f32_16x16x32_bf16 v[50:53], v[154:157], v[162:165], 0
	v_mfma_f32_16x16x32_bf16 v[38:41], v[146:149], v[170:173], 0
	v_mfma_f32_16x16x32_bf16 v[34:37], v[154:157], v[170:173], 0
	v_mfma_f32_16x16x32_bf16 v[22:25], v[146:149], v[194:197], 0
	v_mfma_f32_16x16x32_bf16 v[18:21], v[154:157], v[194:197], 0
	v_mfma_f32_16x16x32_bf16 v[6:9], v[146:149], v[202:205], 0
	v_mfma_f32_16x16x32_bf16 v[2:5], v[154:157], v[202:205], 0
	v_mfma_f32_16x16x32_bf16 v[54:57], v[150:153], v[166:169], v[54:57]
	v_mfma_f32_16x16x32_bf16 v[50:53], v[158:161], v[166:169], v[50:53]
	v_mfma_f32_16x16x32_bf16 v[38:41], v[150:153], v[174:177], v[38:41]
	v_mfma_f32_16x16x32_bf16 v[34:37], v[158:161], v[174:177], v[34:37]
	v_mfma_f32_16x16x32_bf16 v[22:25], v[150:153], v[198:201], v[22:25]
	v_mfma_f32_16x16x32_bf16 v[18:21], v[158:161], v[198:201], v[18:21]
	v_mfma_f32_16x16x32_bf16 v[6:9], v[150:153], v[218:221], v[6:9]
	v_mfma_f32_16x16x32_bf16 v[2:5], v[158:161], v[218:221], v[2:5]
	s_barrier
; #define PG8_STAGE(bufoff, gbase, voff) do { _Pragma("unroll") for (int _i = 0; _i < 2; ++_i) \
;         __builtin_amdgcn_global_load_lds((const unsigned*)((const char*)(gbase) + (voff)[_i]), (LAS unsigned*)(lds + (bufoff) + ldsw + _i * 8192), 16, 0, 0); } while (0)
; #define PG8_LDA(dst, b, h) do { _Pragma("unroll") for (int m = 0; m < 4; ++m) _Pragma("unroll") for (int k = 0; k < 2; ++k) dst[m][k] = *(const LAS bf16x8*)(lds + PG8_SA(b, h) + aoff + m * 2048 + k * 1024); } while (0)
; #define PG8_LDB(dst, b, h) do { _Pragma("unroll") for (int n = 0; n < 2; ++n) _Pragma("unroll") for (int k = 0; k < 2; ++k) dst[n][k] = *(const LAS bf16x8*)(lds + PG8_SB(b, h) + boff + n * 2048 + k * 1024); } while (0)
; #define PG8_MMA(ai, bj, At, Bt) do { __builtin_amdgcn_s_setprio(3); _Pragma("unroll") for (int m = 0; m < 4; ++m) _Pragma("unroll") for (int n = 0; n < 2; ++n) _Pragma("unroll") for (int k = 0; k < 2; ++k) \
;         acc[ai][bj][m][n] = __builtin_amdgcn_mfma_f32_16x16x32_bf16(Bt[n][k], At[m][k], acc[ai][bj][m][n], 0, 0, 0); __builtin_amdgcn_s_setprio(0); } while (0)
; #define PG8_WAIT_V(n) asm volatile("s_waitcnt vmcnt(" #n ")" ::: "memory")
; #define PG8_WAIT_L(n) asm volatile("s_waitcnt lgkmcnt(" #n ")" ::: "memory")
; #define PG8_BAR __builtin_amdgcn_s_barrier()
; #define PG8_SCHED __builtin_amdgcn_sched_barrier(0)
; template <class Epi, bool ALIGN_EPI>
; __device__ __forceinline__ void gemm_phase(LAS unsigned char* lds, const Gemm g, const StaticOrder& S, const Epi& E) {
;     ...
;             PG8_LDB(B0, 1, 0); PG8_LDB(B1, 1, 1); PG8_SCHED; PG8_LDA(At, 1, 0); PG8_STAGE(PG8_SA(0, 1), a2 + hstep, voffA);
;             PG8_WAIT_V(8); PG8_WAIT_L(0); PG8_BAR; PG8_MMA(0, 0, At, B0); PG8_MMA(0, 1, At, B1); PG8_BAR; PG8_SCHED;
;             PG8_LDA(At, 1, 1); PG8_STAGE(PG8_SB(1, 0), b3, voffB); PG8_STAGE(PG8_SB(1, 1), b3 + hstep, voffB); PG8_STAGE(PG8_SA(1, 0), a3, voffA);
;             PG8_WAIT_V(8); PG8_WAIT_L(0); PG8_BAR; PG8_MMA(1, 0, At, B0); PG8_MMA(1, 1, At, B1); PG8_BAR; PG8_SCHED;
	s_add_i32 s86, 0, 0x18000
	s_add_i32 s87, 0, 0x1c000
	v_add_u32_e32 v142, s86, v212
	v_add_u32_e32 v158, s87, v212
	ds_read_b128 v[130:133], v142
	ds_read_b128 v[134:137], v142 offset:1024
	ds_read_b128 v[138:141], v142 offset:2048
	ds_read_b128 v[142:145], v142 offset:3072
	ds_read_b128 v[146:149], v158
	ds_read_b128 v[150:153], v158 offset:1024
	ds_read_b128 v[154:157], v158 offset:2048
	ds_read_b128 v[158:161], v158 offset:3072
	s_add_u32 s68, s68, 0x40000
	s_addc_u32 s69, s69, 0
	s_mov_b32 m0, s71
	v_lshl_add_u64 v[230:231], s[68:69], 0, v[178:179]
	ds_read_b128 v[162:165], v216 offset:32768
	ds_read_b128 v[166:169], v216 offset:33792
	ds_read_b128 v[170:173], v216 offset:34816
	ds_read_b128 v[174:177], v216 offset:35840
	ds_read_b128 v[194:197], v216 offset:36864
	ds_read_b128 v[198:201], v216 offset:37888
	ds_read_b128 v[202:205], v216 offset:38912
	ds_read_b128 v[218:221], v216 offset:39936
	global_load_lds_dwordx4 v[230:231], off
	v_lshl_add_u64 v[230:231], s[68:69], 0, v[182:183]
	s_mov_b32 m0, s72
	s_nop 0
	global_load_lds_dwordx4 v[230:231], off
	s_waitcnt vmcnt(8)
	s_waitcnt lgkmcnt(0)
	s_barrier
	s_waitcnt lgkmcnt(0)
	v_mfma_f32_16x16x32_bf16 v[126:129], v[130:133], v[162:165], v[126:129]
	v_mfma_f32_16x16x32_bf16 v[122:125], v[138:141], v[162:165], v[122:125]
	v_mfma_f32_16x16x32_bf16 v[110:113], v[130:133], v[170:173], v[110:113]
	v_mfma_f32_16x16x32_bf16 v[106:109], v[138:141], v[170:173], v[106:109]
	v_mfma_f32_16x16x32_bf16 v[94:97], v[130:133], v[194:197], v[94:97]
	v_mfma_f32_16x16x32_bf16 v[90:93], v[138:141], v[194:197], v[90:93]
	v_mfma_f32_16x16x32_bf16 v[78:81], v[130:133], v[202:205], v[78:81]
	v_mfma_f32_16x16x32_bf16 v[74:77], v[138:141], v[202:205], v[74:77]
	v_mfma_f32_16x16x32_bf16 v[126:129], v[134:137], v[166:169], v[126:129]
	v_mfma_f32_16x16x32_bf16 v[122:125], v[142:145], v[166:169], v[122:125]
	v_mfma_f32_16x16x32_bf16 v[110:113], v[134:137], v[174:177], v[110:113]
	v_mfma_f32_16x16x32_bf16 v[106:109], v[142:145], v[174:177], v[106:109]
	v_mfma_f32_16x16x32_bf16 v[94:97], v[134:137], v[198:201], v[94:97]
	v_mfma_f32_16x16x32_bf16 v[90:93], v[142:145], v[198:201], v[90:93]
	v_mfma_f32_16x16x32_bf16 v[78:81], v[134:137], v[218:221], v[78:81]
	v_mfma_f32_16x16x32_bf16 v[74:77], v[142:145], v[218:221], v[74:77]
	v_mfma_f32_16x16x32_bf16 v[118:121], v[146:149], v[162:165], v[118:121]
	v_mfma_f32_16x16x32_bf16 v[114:117], v[154:157], v[162:165], v[114:117]
	v_mfma_f32_16x16x32_bf16 v[102:105], v[146:149], v[170:173], v[102:105]
	v_mfma_f32_16x16x32_bf16 v[98:101], v[154:157], v[170:173], v[98:101]
	v_mfma_f32_16x16x32_bf16 v[86:89], v[146:149], v[194:197], v[86:89]
	v_mfma_f32_16x16x32_bf16 v[82:85], v[154:157], v[194:197], v[82:85]
	v_mfma_f32_16x16x32_bf16 v[70:73], v[146:149], v[202:205], v[70:73]
	v_mfma_f32_16x16x32_bf16 v[66:69], v[154:157], v[202:205], v[66:69]
	v_mfma_f32_16x16x32_bf16 v[118:121], v[150:153], v[166:169], v[118:121]
	v_mfma_f32_16x16x32_bf16 v[114:117], v[158:161], v[166:169], v[114:117]
	v_mfma_f32_16x16x32_bf16 v[102:105], v[150:153], v[174:177], v[102:105]
	v_mfma_f32_16x16x32_bf16 v[98:101], v[158:161], v[174:177], v[98:101]
	v_mfma_f32_16x16x32_bf16 v[86:89], v[150:153], v[198:201], v[86:89]
	v_mfma_f32_16x16x32_bf16 v[82:85], v[158:161], v[198:201], v[82:85]
	v_mfma_f32_16x16x32_bf16 v[70:73], v[150:153], v[218:221], v[70:73]
	v_mfma_f32_16x16x32_bf16 v[66:69], v[158:161], v[218:221], v[66:69]
	s_barrier
	s_add_i32 s68, s86, s33
	v_lshl_add_u64 v[222:223], v[222:223], 0, s[18:19]
	s_mov_b32 m0, s68
	ds_read_b128 v[162:165], v216 offset:49152
	ds_read_b128 v[166:169], v216 offset:50176
	ds_read_b128 v[170:173], v216 offset:51200
	ds_read_b128 v[174:177], v216 offset:52224
	ds_read_b128 v[194:197], v216 offset:53248
	ds_read_b128 v[198:201], v216 offset:54272
	ds_read_b128 v[202:205], v216 offset:55296
	ds_read_b128 v[218:221], v216 offset:56320
	global_load_lds_dwordx4 v[222:223], off
	s_add_i32 m0, s68, 0x2000
	s_add_u32 s66, s66, 0x40080
	v_lshl_add_u64 v[222:223], v[224:225], 0, s[18:19]
	s_addc_u32 s67, s67, 0
	s_add_i32 s68, s87, s33
	global_load_lds_dwordx4 v[222:223], off
	v_lshl_add_u64 v[222:223], s[66:67], 0, v[180:181]
	s_mov_b32 m0, s68
	s_nop 0
	global_load_lds_dwordx4 v[222:223], off
	v_lshl_add_u64 v[222:223], s[66:67], 0, v[184:185]
	s_add_i32 m0, s68, 0x2000
	s_nop 0
	global_load_lds_dwordx4 v[222:223], off
	v_lshl_add_u64 v[222:223], v[226:227], 0, s[18:19]
	s_mov_b32 m0, s78
	s_nop 0
	global_load_lds_dwordx4 v[222:223], off
	v_lshl_add_u64 v[222:223], v[228:229], 0, s[18:19]
	s_mov_b32 m0, s79
	s_nop 0
	global_load_lds_dwordx4 v[222:223], off
	s_waitcnt vmcnt(8)
	s_waitcnt lgkmcnt(0)
	s_barrier
	s_waitcnt lgkmcnt(0)
	v_mfma_f32_16x16x32_bf16 v[62:65], v[130:133], v[162:165], v[62:65]
	v_mfma_f32_16x16x32_bf16 v[58:61], v[138:141], v[162:165], v[58:61]
	v_mfma_f32_16x16x32_bf16 v[46:49], v[130:133], v[170:173], v[46:49]
	v_mfma_f32_16x16x32_bf16 v[42:45], v[138:141], v[170:173], v[42:45]
	v_mfma_f32_16x16x32_bf16 v[30:33], v[130:133], v[194:197], v[30:33]
	v_mfma_f32_16x16x32_bf16 v[26:29], v[138:141], v[194:197], v[26:29]
	v_mfma_f32_16x16x32_bf16 v[14:17], v[130:133], v[202:205], v[14:17]
	v_mfma_f32_16x16x32_bf16 v[10:13], v[138:141], v[202:205], v[10:13]
	v_mfma_f32_16x16x32_bf16 v[62:65], v[134:137], v[166:169], v[62:65]
	v_mfma_f32_16x16x32_bf16 v[58:61], v[142:145], v[166:169], v[58:61]
	v_mfma_f32_16x16x32_bf16 v[46:49], v[134:137], v[174:177], v[46:49]
	v_mfma_f32_16x16x32_bf16 v[42:45], v[142:145], v[174:177], v[42:45]
	v_mfma_f32_16x16x32_bf16 v[30:33], v[134:137], v[198:201], v[30:33]
	v_mfma_f32_16x16x32_bf16 v[26:29], v[142:145], v[198:201], v[26:29]
	v_mfma_f32_16x16x32_bf16 v[14:17], v[134:137], v[218:221], v[14:17]
	v_mfma_f32_16x16x32_bf16 v[10:13], v[142:145], v[218:221], v[10:13]
	v_mfma_f32_16x16x32_bf16 v[54:57], v[146:149], v[162:165], v[54:57]
	v_mfma_f32_16x16x32_bf16 v[50:53], v[154:157], v[162:165], v[50:53]
	v_mfma_f32_16x16x32_bf16 v[38:41], v[146:149], v[170:173], v[38:41]
	v_mfma_f32_16x16x32_bf16 v[34:37], v[154:157], v[170:173], v[34:37]
	v_mfma_f32_16x16x32_bf16 v[22:25], v[146:149], v[194:197], v[22:25]
	v_mfma_f32_16x16x32_bf16 v[18:21], v[154:157], v[194:197], v[18:21]
	v_mfma_f32_16x16x32_bf16 v[6:9], v[146:149], v[202:205], v[6:9]
	v_mfma_f32_16x16x32_bf16 v[2:5], v[154:157], v[202:205], v[2:5]
	v_mfma_f32_16x16x32_bf16 v[54:57], v[150:153], v[166:169], v[54:57]
	v_mfma_f32_16x16x32_bf16 v[50:53], v[158:161], v[166:169], v[50:53]
	v_mfma_f32_16x16x32_bf16 v[38:41], v[150:153], v[174:177], v[38:41]
	v_mfma_f32_16x16x32_bf16 v[34:37], v[158:161], v[174:177], v[34:37]
	v_mfma_f32_16x16x32_bf16 v[22:25], v[150:153], v[198:201], v[22:25]
	v_mfma_f32_16x16x32_bf16 v[18:21], v[158:161], v[198:201], v[18:21]
	v_mfma_f32_16x16x32_bf16 v[6:9], v[150:153], v[218:221], v[6:9]
	v_mfma_f32_16x16x32_bf16 v[2:5], v[158:161], v[218:221], v[2:5]
	s_barrier
	s_add_i32 s85, s85, 2
	s_add_u32 s64, s64, 0x100
	s_addc_u32 s65, s65, 0
	s_add_u32 s83, s83, 0x100
	s_addc_u32 s84, s84, 0
; #define PG8_STAGE(bufoff, gbase, voff) do { _Pragma("unroll") for (int _i = 0; _i < 2; ++_i) \
;         __builtin_amdgcn_global_load_lds((const unsigned*)((const char*)(gbase) + (voff)[_i]), (LAS unsigned*)(lds + (bufoff) + ldsw + _i * 8192), 16, 0, 0); } while (0)
; #define PG8_LDA(dst, b, h) do { _Pragma("unroll") for (int m = 0; m < 4; ++m) _Pragma("unroll") for (int k = 0; k < 2; ++k) dst[m][k] = *(const LAS bf16x8*)(lds + PG8_SA(b, h) + aoff + m * 2048 + k * 1024); } while (0)
; #define PG8_LDB(dst, b, h) do { _Pragma("unroll") for (int n = 0; n < 2; ++n) _Pragma("unroll") for (int k = 0; k < 2; ++k) dst[n][k] = *(const LAS bf16x8*)(lds + PG8_SB(b, h) + boff + n * 2048 + k * 1024); } while (0)
; #define PG8_MMA(ai, bj, At, Bt) do { __builtin_amdgcn_s_setprio(3); _Pragma("unroll") for (int m = 0; m < 4; ++m) _Pragma("unroll") for (int n = 0; n < 2; ++n) _Pragma("unroll") for (int k = 0; k < 2; ++k) \
;         acc[ai][bj][m][n] = __builtin_amdgcn_mfma_f32_16x16x32_bf16(Bt[n][k], At[m][k], acc[ai][bj][m][n], 0, 0, 0); __builtin_amdgcn_s_setprio(0); } while (0)
; #define PG8_WAIT_V(n) asm volatile("s_waitcnt vmcnt(" #n ")" ::: "memory")
; #define PG8_WAIT_L(n) asm volatile("s_waitcnt lgkmcnt(" #n ")" ::: "memory")
; #define PG8_BAR __builtin_amdgcn_s_barrier()
; #define PG8_SCHED __builtin_amdgcn_sched_barrier(0)
; template <class Epi, bool ALIGN_EPI>
; __device__ __forceinline__ void gemm_phase(LAS unsigned char* lds, const Gemm g, const StaticOrder& S, const Epi& E) {
;     ...
;             const bool last = (t == nt - 2);
;             const char* a1 = cA + (size_t)(t + 1) * kstep;
;             const char* a2 = last ? nA : cA + (size_t)(t + 2) * kstep; const char* b2 = last ? nB : cB + (size_t)(t + 2) * kstep;
;             const char* a3 = a2 + kstep; const char* b3 = b2 + kstep;
;             PG8_LDB(B0, 0, 0); PG8_LDB(B1, 0, 1); PG8_SCHED; PG8_LDA(At, 0, 0); PG8_STAGE(PG8_SA(1, 1), a1 + hstep, voffA);
;             PG8_WAIT_V(8); PG8_WAIT_L(0); PG8_BAR; PG8_MMA(0, 0, At, B0); PG8_MMA(0, 1, At, B1); PG8_BAR; PG8_SCHED;
;             PG8_LDA(At, 0, 1); PG8_STAGE(PG8_SB(0, 0), b2, voffB); PG8_STAGE(PG8_SB(0, 1), b2 + hstep, voffB); PG8_STAGE(PG8_SA(0, 0), a2, voffA);
.LBB0_520:
	ds_read_b128 v[130:133], v214
	ds_read_b128 v[134:137], v214 offset:1024
	ds_read_b128 v[138:141], v214 offset:2048
	ds_read_b128 v[142:145], v214 offset:3072
	ds_read_b128 v[146:149], v215
	ds_read_b128 v[150:153], v215 offset:1024
	ds_read_b128 v[154:157], v215 offset:2048
	ds_read_b128 v[158:161], v215 offset:3072
	s_add_u32 s66, s64, 0xfffc0080
	s_addc_u32 s67, s65, -1
	s_cmp_eq_u32 s85, 12
	s_cselect_b32 s69, s55, s67
	s_cselect_b32 s68, s61, s66
	s_cselect_b32 s67, s53, s84
	s_cselect_b32 s66, s82, s83
	v_lshl_add_u64 v[222:223], s[64:65], 0, v[186:187]
	s_add_i32 m0, s63, 0xc000
	ds_read_b128 v[162:165], v216
	ds_read_b128 v[166:169], v216 offset:1024
	ds_read_b128 v[170:173], v216 offset:2048
	ds_read_b128 v[174:177], v216 offset:3072
	ds_read_b128 v[194:197], v216 offset:4096
	ds_read_b128 v[198:201], v216 offset:5120
	ds_read_b128 v[202:205], v216 offset:6144
	ds_read_b128 v[218:221], v216 offset:7168
	global_load_lds_dwordx4 v[222:223], off
	v_lshl_add_u64 v[222:223], s[64:65], 0, v[188:189]
	s_add_i32 m0, s63, 0xe000
	s_nop 0
	global_load_lds_dwordx4 v[222:223], off
	s_waitcnt vmcnt(8)
	s_waitcnt lgkmcnt(0)
	s_barrier
	s_waitcnt lgkmcnt(0)
	v_mfma_f32_16x16x32_bf16 v[126:129], v[130:133], v[162:165], v[126:129]
	v_mfma_f32_16x16x32_bf16 v[122:125], v[138:141], v[162:165], v[122:125]
	v_mfma_f32_16x16x32_bf16 v[110:113], v[130:133], v[170:173], v[110:113]
	v_mfma_f32_16x16x32_bf16 v[106:109], v[138:141], v[170:173], v[106:109]
	v_mfma_f32_16x16x32_bf16 v[94:97], v[130:133], v[194:197], v[94:97]
	v_mfma_f32_16x16x32_bf16 v[90:93], v[138:141], v[194:197], v[90:93]
	v_mfma_f32_16x16x32_bf16 v[78:81], v[130:133], v[202:205], v[78:81]
	v_mfma_f32_16x16x32_bf16 v[74:77], v[138:141], v[202:205], v[74:77]
	v_mfma_f32_16x16x32_bf16 v[126:129], v[134:137], v[166:169], v[126:129]
	v_mfma_f32_16x16x32_bf16 v[122:125], v[142:145], v[166:169], v[122:125]
	v_mfma_f32_16x16x32_bf16 v[110:113], v[134:137], v[174:177], v[110:113]
	v_mfma_f32_16x16x32_bf16 v[106:109], v[142:145], v[174:177], v[106:109]
	v_mfma_f32_16x16x32_bf16 v[94:97], v[134:137], v[198:201], v[94:97]
	v_mfma_f32_16x16x32_bf16 v[90:93], v[142:145], v[198:201], v[90:93]
	v_mfma_f32_16x16x32_bf16 v[78:81], v[134:137], v[218:221], v[78:81]
	v_mfma_f32_16x16x32_bf16 v[74:77], v[142:145], v[218:221], v[74:77]
	v_mfma_f32_16x16x32_bf16 v[118:121], v[146:149], v[162:165], v[118:121]
	v_mfma_f32_16x16x32_bf16 v[114:117], v[154:157], v[162:165], v[114:117]
	v_mfma_f32_16x16x32_bf16 v[102:105], v[146:149], v[170:173], v[102:105]
	v_mfma_f32_16x16x32_bf16 v[98:101], v[154:157], v[170:173], v[98:101]
	v_mfma_f32_16x16x32_bf16 v[86:89], v[146:149], v[194:197], v[86:89]
	v_mfma_f32_16x16x32_bf16 v[82:85], v[154:157], v[194:197], v[82:85]
	v_mfma_f32_16x16x32_bf16 v[70:73], v[146:149], v[202:205], v[70:73]
	v_mfma_f32_16x16x32_bf16 v[66:69], v[154:157], v[202:205], v[66:69]
	v_mfma_f32_16x16x32_bf16 v[118:121], v[150:153], v[166:169], v[118:121]
	v_mfma_f32_16x16x32_bf16 v[114:117], v[158:161], v[166:169], v[114:117]
	v_mfma_f32_16x16x32_bf16 v[102:105], v[150:153], v[174:177], v[102:105]
	v_mfma_f32_16x16x32_bf16 v[98:101], v[158:161], v[174:177], v[98:101]
	v_mfma_f32_16x16x32_bf16 v[86:89], v[150:153], v[198:201], v[86:89]
	v_mfma_f32_16x16x32_bf16 v[82:85], v[158:161], v[198:201], v[82:85]
	v_mfma_f32_16x16x32_bf16 v[70:73], v[150:153], v[218:221], v[70:73]
	v_mfma_f32_16x16x32_bf16 v[66:69], v[158:161], v[218:221], v[66:69]
	s_barrier
	s_add_i32 s86, s80, s33
	v_lshl_add_u64 v[222:223], s[66:67], 0, v[180:181]
	s_mov_b32 m0, s86
	ds_read_b128 v[162:165], v216 offset:16384
	ds_read_b128 v[166:169], v216 offset:17408
	ds_read_b128 v[170:173], v216 offset:18432
	ds_read_b128 v[174:177], v216 offset:19456
	ds_read_b128 v[194:197], v216 offset:20480
	ds_read_b128 v[198:201], v216 offset:21504
	ds_read_b128 v[202:205], v216 offset:22528
	ds_read_b128 v[218:221], v216 offset:23552
	global_load_lds_dwordx4 v[222:223], off
	s_add_i32 m0, s86, 0x2000
	s_add_u32 s86, s66, 0x40000
	v_lshl_add_u64 v[224:225], s[66:67], 0, v[184:185]
	s_addc_u32 s87, s67, 0
	s_add_i32 s88, s81, s33
	global_load_lds_dwordx4 v[224:225], off
	v_lshl_add_u64 v[226:227], s[86:87], 0, v[180:181]
	s_mov_b32 m0, s88
	v_lshl_add_u64 v[228:229], s[68:69], 0, v[182:183]
	global_load_lds_dwordx4 v[226:227], off
	v_lshl_add_u64 v[226:227], s[86:87], 0, v[184:185]
	s_add_i32 m0, s88, 0x2000
	s_nop 0
	global_load_lds_dwordx4 v[226:227], off
	v_lshl_add_u64 v[226:227], s[68:69], 0, v[178:179]
	s_mov_b32 m0, s63
	s_nop 0
	global_load_lds_dwordx4 v[226:227], off
	s_mov_b32 m0, s70
	s_nop 0
	global_load_lds_dwordx4 v[228:229], off
	s_waitcnt vmcnt(8)
	s_waitcnt lgkmcnt(0)
	s_barrier
; #define PG8_STAGE(bufoff, gbase, voff) do { _Pragma("unroll") for (int _i = 0; _i < 2; ++_i) \
;         __builtin_amdgcn_global_load_lds((const unsigned*)((const char*)(gbase) + (voff)[_i]), (LAS unsigned*)(lds + (bufoff) + ldsw + _i * 8192), 16, 0, 0); } while (0)
; #define PG8_LDA(dst, b, h) do { _Pragma("unroll") for (int m = 0; m < 4; ++m) _Pragma("unroll") for (int k = 0; k < 2; ++k) dst[m][k] = *(const LAS bf16x8*)(lds + PG8_SA(b, h) + aoff + m * 2048 + k * 1024); } while (0)
; #define PG8_LDB(dst, b, h) do { _Pragma("unroll") for (int n = 0; n < 2; ++n) _Pragma("unroll") for (int k = 0; k < 2; ++k) dst[n][k] = *(const LAS bf16x8*)(lds + PG8_SB(b, h) + boff + n * 2048 + k * 1024); } while (0)
; #define PG8_MMA(ai, bj, At, Bt) do { __builtin_amdgcn_s_setprio(3); _Pragma("unroll") for (int m = 0; m < 4; ++m) _Pragma("unroll") for (int n = 0; n < 2; ++n) _Pragma("unroll") for (int k = 0; k < 2; ++k) \
;         acc[ai][bj][m][n] = __builtin_amdgcn_mfma_f32_16x16x32_bf16(Bt[n][k], At[m][k], acc[ai][bj][m][n], 0, 0, 0); __builtin_amdgcn_s_setprio(0); } while (0)
; #define PG8_WAIT_V(n) asm volatile("s_waitcnt vmcnt(" #n ")" ::: "memory")
; #define PG8_WAIT_L(n) asm volatile("s_waitcnt lgkmcnt(" #n ")" ::: "memory")
; #define PG8_BAR __builtin_amdgcn_s_barrier()
; #define PG8_SCHED __builtin_amdgcn_sched_barrier(0)
; template <class Epi, bool ALIGN_EPI>
; __device__ __forceinline__ void gemm_phase(LAS unsigned char* lds, const Gemm g, const StaticOrder& S, const Epi& E) {
;     ...
;             PG8_WAIT_V(8); PG8_WAIT_L(0); PG8_BAR; PG8_MMA(1, 0, At, B0); PG8_MMA(1, 1, At, B1); PG8_BAR; PG8_SCHED;
;             PG8_LDB(B0, 1, 0); PG8_LDB(B1, 1, 1); PG8_SCHED; PG8_LDA(At, 1, 0); PG8_STAGE(PG8_SA(0, 1), a2 + hstep, voffA);
;             PG8_WAIT_V(8); PG8_WAIT_L(0); PG8_BAR; PG8_MMA(0, 0, At, B0); PG8_MMA(0, 1, At, B1); PG8_BAR; PG8_SCHED;
	s_waitcnt lgkmcnt(0)
	v_mfma_f32_16x16x32_bf16 v[62:65], v[130:133], v[162:165], v[62:65]
	v_mfma_f32_16x16x32_bf16 v[58:61], v[138:141], v[162:165], v[58:61]
	v_mfma_f32_16x16x32_bf16 v[46:49], v[130:133], v[170:173], v[46:49]
	v_mfma_f32_16x16x32_bf16 v[42:45], v[138:141], v[170:173], v[42:45]
	v_mfma_f32_16x16x32_bf16 v[30:33], v[130:133], v[194:197], v[30:33]
	v_mfma_f32_16x16x32_bf16 v[26:29], v[138:141], v[194:197], v[26:29]
	v_mfma_f32_16x16x32_bf16 v[14:17], v[130:133], v[202:205], v[14:17]
	v_mfma_f32_16x16x32_bf16 v[10:13], v[138:141], v[202:205], v[10:13]
	v_mfma_f32_16x16x32_bf16 v[62:65], v[134:137], v[166:169], v[62:65]
	v_mfma_f32_16x16x32_bf16 v[58:61], v[142:145], v[166:169], v[58:61]
	v_mfma_f32_16x16x32_bf16 v[46:49], v[134:137], v[174:177], v[46:49]
	v_mfma_f32_16x16x32_bf16 v[42:45], v[142:145], v[174:177], v[42:45]
	v_mfma_f32_16x16x32_bf16 v[30:33], v[134:137], v[198:201], v[30:33]
	v_mfma_f32_16x16x32_bf16 v[26:29], v[142:145], v[198:201], v[26:29]
	v_mfma_f32_16x16x32_bf16 v[14:17], v[134:137], v[218:221], v[14:17]
	v_mfma_f32_16x16x32_bf16 v[10:13], v[142:145], v[218:221], v[10:13]
	v_mfma_f32_16x16x32_bf16 v[54:57], v[146:149], v[162:165], v[54:57]
	v_mfma_f32_16x16x32_bf16 v[50:53], v[154:157], v[162:165], v[50:53]
	v_mfma_f32_16x16x32_bf16 v[38:41], v[146:149], v[170:173], v[38:41]
	v_mfma_f32_16x16x32_bf16 v[34:37], v[154:157], v[170:173], v[34:37]
	v_mfma_f32_16x16x32_bf16 v[22:25], v[146:149], v[194:197], v[22:25]
	v_mfma_f32_16x16x32_bf16 v[18:21], v[154:157], v[194:197], v[18:21]
	v_mfma_f32_16x16x32_bf16 v[6:9], v[146:149], v[202:205], v[6:9]
	v_mfma_f32_16x16x32_bf16 v[2:5], v[154:157], v[202:205], v[2:5]
	v_mfma_f32_16x16x32_bf16 v[54:57], v[150:153], v[166:169], v[54:57]
	v_mfma_f32_16x16x32_bf16 v[50:53], v[158:161], v[166:169], v[50:53]
	v_mfma_f32_16x16x32_bf16 v[38:41], v[150:153], v[174:177], v[38:41]
	v_mfma_f32_16x16x32_bf16 v[34:37], v[158:161], v[174:177], v[34:37]
	v_mfma_f32_16x16x32_bf16 v[22:25], v[150:153], v[198:201], v[22:25]
	v_mfma_f32_16x16x32_bf16 v[18:21], v[158:161], v[198:201], v[18:21]
	v_mfma_f32_16x16x32_bf16 v[6:9], v[150:153], v[218:221], v[6:9]
	v_mfma_f32_16x16x32_bf16 v[2:5], v[158:161], v[218:221], v[2:5]
	s_barrier
	s_add_i32 s86, 0, 0x18000
	s_add_i32 s87, 0, 0x1c000
	v_add_u32_e32 v142, s86, v212
	v_add_u32_e32 v158, s87, v212
	ds_read_b128 v[130:133], v142
	ds_read_b128 v[134:137], v142 offset:1024
	ds_read_b128 v[138:141], v142 offset:2048
	ds_read_b128 v[142:145], v142 offset:3072
	ds_read_b128 v[146:149], v158
	ds_read_b128 v[150:153], v158 offset:1024
	ds_read_b128 v[154:157], v158 offset:2048
	ds_read_b128 v[158:161], v158 offset:3072
	s_add_u32 s68, s68, 0x40000
	s_addc_u32 s69, s69, 0
	s_mov_b32 m0, s71
	v_lshl_add_u64 v[230:231], s[68:69], 0, v[178:179]
	ds_read_b128 v[162:165], v216 offset:32768
	ds_read_b128 v[166:169], v216 offset:33792
	ds_read_b128 v[170:173], v216 offset:34816
	ds_read_b128 v[174:177], v216 offset:35840
	ds_read_b128 v[194:197], v216 offset:36864
	ds_read_b128 v[198:201], v216 offset:37888
	ds_read_b128 v[202:205], v216 offset:38912
	ds_read_b128 v[218:221], v216 offset:39936
	global_load_lds_dwordx4 v[230:231], off
	v_lshl_add_u64 v[230:231], s[68:69], 0, v[182:183]
	s_mov_b32 m0, s72
	s_nop 0
	global_load_lds_dwordx4 v[230:231], off
	s_waitcnt vmcnt(8)
	s_waitcnt lgkmcnt(0)
	s_barrier
	s_waitcnt lgkmcnt(0)
	v_mfma_f32_16x16x32_bf16 v[126:129], v[130:133], v[162:165], v[126:129]
	v_mfma_f32_16x16x32_bf16 v[122:125], v[138:141], v[162:165], v[122:125]
	v_mfma_f32_16x16x32_bf16 v[110:113], v[130:133], v[170:173], v[110:113]
	v_mfma_f32_16x16x32_bf16 v[106:109], v[138:141], v[170:173], v[106:109]
	v_mfma_f32_16x16x32_bf16 v[94:97], v[130:133], v[194:197], v[94:97]
	v_mfma_f32_16x16x32_bf16 v[90:93], v[138:141], v[194:197], v[90:93]
	v_mfma_f32_16x16x32_bf16 v[78:81], v[130:133], v[202:205], v[78:81]
	v_mfma_f32_16x16x32_bf16 v[74:77], v[138:141], v[202:205], v[74:77]
	v_mfma_f32_16x16x32_bf16 v[126:129], v[134:137], v[166:169], v[126:129]
	v_mfma_f32_16x16x32_bf16 v[122:125], v[142:145], v[166:169], v[122:125]
	v_mfma_f32_16x16x32_bf16 v[110:113], v[134:137], v[174:177], v[110:113]
	v_mfma_f32_16x16x32_bf16 v[106:109], v[142:145], v[174:177], v[106:109]
	v_mfma_f32_16x16x32_bf16 v[94:97], v[134:137], v[198:201], v[94:97]
	v_mfma_f32_16x16x32_bf16 v[90:93], v[142:145], v[198:201], v[90:93]
	v_mfma_f32_16x16x32_bf16 v[78:81], v[134:137], v[218:221], v[78:81]
	v_mfma_f32_16x16x32_bf16 v[74:77], v[142:145], v[218:221], v[74:77]
	v_mfma_f32_16x16x32_bf16 v[118:121], v[146:149], v[162:165], v[118:121]
	v_mfma_f32_16x16x32_bf16 v[114:117], v[154:157], v[162:165], v[114:117]
	v_mfma_f32_16x16x32_bf16 v[102:105], v[146:149], v[170:173], v[102:105]
	v_mfma_f32_16x16x32_bf16 v[98:101], v[154:157], v[170:173], v[98:101]
	v_mfma_f32_16x16x32_bf16 v[86:89], v[146:149], v[194:197], v[86:89]
	v_mfma_f32_16x16x32_bf16 v[82:85], v[154:157], v[194:197], v[82:85]
	v_mfma_f32_16x16x32_bf16 v[70:73], v[146:149], v[202:205], v[70:73]
	v_mfma_f32_16x16x32_bf16 v[66:69], v[154:157], v[202:205], v[66:69]
	v_mfma_f32_16x16x32_bf16 v[118:121], v[150:153], v[166:169], v[118:121]
	v_mfma_f32_16x16x32_bf16 v[114:117], v[158:161], v[166:169], v[114:117]
	v_mfma_f32_16x16x32_bf16 v[102:105], v[150:153], v[174:177], v[102:105]
	v_mfma_f32_16x16x32_bf16 v[98:101], v[158:161], v[174:177], v[98:101]
	v_mfma_f32_16x16x32_bf16 v[86:89], v[150:153], v[198:201], v[86:89]
	v_mfma_f32_16x16x32_bf16 v[82:85], v[158:161], v[198:201], v[82:85]
	v_mfma_f32_16x16x32_bf16 v[70:73], v[150:153], v[218:221], v[70:73]
	v_mfma_f32_16x16x32_bf16 v[66:69], v[158:161], v[218:221], v[66:69]
	s_barrier
; #define PG8_STAGE(bufoff, gbase, voff) do { _Pragma("unroll") for (int _i = 0; _i < 2; ++_i) \
;         __builtin_amdgcn_global_load_lds((const unsigned*)((const char*)(gbase) + (voff)[_i]), (LAS unsigned*)(lds + (bufoff) + ldsw + _i * 8192), 16, 0, 0); } while (0)
; #define PG8_LDA(dst, b, h) do { _Pragma("unroll") for (int m = 0; m < 4; ++m) _Pragma("unroll") for (int k = 0; k < 2; ++k) dst[m][k] = *(const LAS bf16x8*)(lds + PG8_SA(b, h) + aoff + m * 2048 + k * 1024); } while (0)
; #define PG8_MMA(ai, bj, At, Bt) do { __builtin_amdgcn_s_setprio(3); _Pragma("unroll") for (int m = 0; m < 4; ++m) _Pragma("unroll") for (int n = 0; n < 2; ++n) _Pragma("unroll") for (int k = 0; k < 2; ++k) \
;         acc[ai][bj][m][n] = __builtin_amdgcn_mfma_f32_16x16x32_bf16(Bt[n][k], At[m][k], acc[ai][bj][m][n], 0, 0, 0); __builtin_amdgcn_s_setprio(0); } while (0)
; #define PG8_WAIT_V(n) asm volatile("s_waitcnt vmcnt(" #n ")" ::: "memory")
; #define PG8_WAIT_L(n) asm volatile("s_waitcnt lgkmcnt(" #n ")" ::: "memory")
; #define PG8_BAR __builtin_amdgcn_s_barrier()
; #define PG8_SCHED __builtin_amdgcn_sched_barrier(0)
; template <class Epi, bool ALIGN_EPI>
; __device__ __forceinline__ void gemm_phase(LAS unsigned char* lds, const Gemm g, const StaticOrder& S, const Epi& E) {
;     ...
;             PG8_LDA(At, 1, 1); PG8_STAGE(PG8_SB(1, 0), b3, voffB); PG8_STAGE(PG8_SB(1, 1), b3 + hstep, voffB); PG8_STAGE(PG8_SA(1, 0), a3, voffA);
;             PG8_WAIT_V(8); PG8_WAIT_L(0); PG8_BAR; PG8_MMA(1, 0, At, B0); PG8_MMA(1, 1, At, B1); PG8_BAR; PG8_SCHED;
;         }
;         if constexpr (ALIGN_EPI) { if (wr == 0) PG8_BAR; }
;         E(acc, cur, wr, wc, fr, fq);
;         if (!has_next) break;
	s_add_i32 s68, s86, s33
	v_lshl_add_u64 v[222:223], v[222:223], 0, s[18:19]
	s_mov_b32 m0, s68
	ds_read_b128 v[162:165], v216 offset:49152
	ds_read_b128 v[166:169], v216 offset:50176
	ds_read_b128 v[170:173], v216 offset:51200
	ds_read_b128 v[174:177], v216 offset:52224
	ds_read_b128 v[194:197], v216 offset:53248
	ds_read_b128 v[198:201], v216 offset:54272
	ds_read_b128 v[202:205], v216 offset:55296
	ds_read_b128 v[218:221], v216 offset:56320
	global_load_lds_dwordx4 v[222:223], off
	s_add_i32 m0, s68, 0x2000
	s_add_u32 s66, s66, 0x40080
	v_lshl_add_u64 v[222:223], v[224:225], 0, s[18:19]
	s_addc_u32 s67, s67, 0
	s_add_i32 s68, s87, s33
	global_load_lds_dwordx4 v[222:223], off
	v_lshl_add_u64 v[222:223], s[66:67], 0, v[180:181]
	s_mov_b32 m0, s68
	s_nop 0
	global_load_lds_dwordx4 v[222:223], off
	v_lshl_add_u64 v[222:223], s[66:67], 0, v[184:185]
	s_add_i32 m0, s68, 0x2000
	s_nop 0
	global_load_lds_dwordx4 v[222:223], off
	v_lshl_add_u64 v[222:223], v[226:227], 0, s[18:19]
	s_mov_b32 m0, s78
	s_nop 0
	global_load_lds_dwordx4 v[222:223], off
	v_lshl_add_u64 v[222:223], v[228:229], 0, s[18:19]
	s_mov_b32 m0, s79
	s_nop 0
	global_load_lds_dwordx4 v[222:223], off
	s_waitcnt vmcnt(8)
	s_waitcnt lgkmcnt(0)
	s_barrier
	s_waitcnt lgkmcnt(0)
	v_mfma_f32_16x16x32_bf16 v[62:65], v[130:133], v[162:165], v[62:65]
	v_mfma_f32_16x16x32_bf16 v[58:61], v[138:141], v[162:165], v[58:61]
	v_mfma_f32_16x16x32_bf16 v[46:49], v[130:133], v[170:173], v[46:49]
	v_mfma_f32_16x16x32_bf16 v[42:45], v[138:141], v[170:173], v[42:45]
	v_mfma_f32_16x16x32_bf16 v[30:33], v[130:133], v[194:197], v[30:33]
	v_mfma_f32_16x16x32_bf16 v[26:29], v[138:141], v[194:197], v[26:29]
	v_mfma_f32_16x16x32_bf16 v[14:17], v[130:133], v[202:205], v[14:17]
	v_mfma_f32_16x16x32_bf16 v[10:13], v[138:141], v[202:205], v[10:13]
	v_mfma_f32_16x16x32_bf16 v[62:65], v[134:137], v[166:169], v[62:65]
	v_mfma_f32_16x16x32_bf16 v[58:61], v[142:145], v[166:169], v[58:61]
	v_mfma_f32_16x16x32_bf16 v[46:49], v[134:137], v[174:177], v[46:49]
	v_mfma_f32_16x16x32_bf16 v[42:45], v[142:145], v[174:177], v[42:45]
	v_mfma_f32_16x16x32_bf16 v[30:33], v[134:137], v[198:201], v[30:33]
	v_mfma_f32_16x16x32_bf16 v[26:29], v[142:145], v[198:201], v[26:29]
	v_mfma_f32_16x16x32_bf16 v[14:17], v[134:137], v[218:221], v[14:17]
	v_mfma_f32_16x16x32_bf16 v[10:13], v[142:145], v[218:221], v[10:13]
	v_mfma_f32_16x16x32_bf16 v[54:57], v[146:149], v[162:165], v[54:57]
	v_mfma_f32_16x16x32_bf16 v[50:53], v[154:157], v[162:165], v[50:53]
	v_mfma_f32_16x16x32_bf16 v[38:41], v[146:149], v[170:173], v[38:41]
	v_mfma_f32_16x16x32_bf16 v[34:37], v[154:157], v[170:173], v[34:37]
	v_mfma_f32_16x16x32_bf16 v[22:25], v[146:149], v[194:197], v[22:25]
	v_mfma_f32_16x16x32_bf16 v[18:21], v[154:157], v[194:197], v[18:21]
	v_mfma_f32_16x16x32_bf16 v[6:9], v[146:149], v[202:205], v[6:9]
	v_mfma_f32_16x16x32_bf16 v[2:5], v[154:157], v[202:205], v[2:5]
	v_mfma_f32_16x16x32_bf16 v[54:57], v[150:153], v[166:169], v[54:57]
	v_mfma_f32_16x16x32_bf16 v[50:53], v[158:161], v[166:169], v[50:53]
	v_mfma_f32_16x16x32_bf16 v[38:41], v[150:153], v[174:177], v[38:41]
	v_mfma_f32_16x16x32_bf16 v[34:37], v[158:161], v[174:177], v[34:37]
	v_mfma_f32_16x16x32_bf16 v[22:25], v[150:153], v[198:201], v[22:25]
	v_mfma_f32_16x16x32_bf16 v[18:21], v[158:161], v[198:201], v[18:21]
	v_mfma_f32_16x16x32_bf16 v[6:9], v[150:153], v[218:221], v[6:9]
	v_mfma_f32_16x16x32_bf16 v[2:5], v[158:161], v[218:221], v[2:5]
	s_barrier
	s_add_i32 s85, s85, 2
	s_add_u32 s64, s64, 0x100
	s_addc_u32 s65, s65, 0
	s_add_u32 s83, s83, 0x100
	s_addc_u32 s84, s84, 0
	s_cmp_gt_u32 s85, 13
	s_cbranch_scc0 .LBB0_520
	s_and_b64 vcc, exec, s[50:51]
	s_cbranch_vccz .LBB0_523
	s_barrier

; #define PG8_STAGE(bufoff, gbase, voff) do { _Pragma("unroll") for (int _i = 0; _i < 2; ++_i) \
;         __builtin_amdgcn_global_load_lds((const unsigned*)((const char*)(gbase) + (voff)[_i]), (LAS unsigned*)(lds + (bufoff) + ldsw + _i * 8192), 16, 0, 0); } while (0)
; #define PG8_LDA(dst, b, h) do { _Pragma("unroll") for (int m = 0; m < 4; ++m) _Pragma("unroll") for (int k = 0; k < 2; ++k) dst[m][k] = *(const LAS bf16x8*)(lds + PG8_SA(b, h) + aoff + m * 2048 + k * 1024); } while (0)
; #define PG8_LDB(dst, b, h) do { _Pragma("unroll") for (int n = 0; n < 2; ++n) _Pragma("unroll") for (int k = 0; k < 2; ++k) dst[n][k] = *(const LAS bf16x8*)(lds + PG8_SB(b, h) + boff + n * 2048 + k * 1024); } while (0)
; #define PG8_MMA(ai, bj, At, Bt) do { __builtin_amdgcn_s_setprio(3); _Pragma("unroll") for (int m = 0; m < 4; ++m) _Pragma("unroll") for (int n = 0; n < 2; ++n) _Pragma("unroll") for (int k = 0; k < 2; ++k) \
;         acc[ai][bj][m][n] = __builtin_amdgcn_mfma_f32_16x16x32_bf16(Bt[n][k], At[m][k], acc[ai][bj][m][n], 0, 0, 0); __builtin_amdgcn_s_setprio(0); } while (0)
; #define PG8_WAIT_V(n) asm volatile("s_waitcnt vmcnt(" #n ")" ::: "memory")
; #define PG8_WAIT_L(n) asm volatile("s_waitcnt lgkmcnt(" #n ")" ::: "memory")
; #define PG8_BAR __builtin_amdgcn_s_barrier()
; #define PG8_SCHED __builtin_amdgcn_sched_barrier(0)
; template <class Epi, bool ALIGN_EPI>
; __device__ __forceinline__ void gemm_phase(LAS unsigned char* lds, const Gemm g, const StaticOrder& S, const Epi& E) {
;     ...
;             PG8_LDB(B0, 0, 0); PG8_LDB(B1, 0, 1); PG8_SCHED; PG8_LDA(At, 0, 0); PG8_STAGE(PG8_SA(1, 1), a1 + hstep, voffA);
;             PG8_WAIT_V(8); PG8_WAIT_L(0); PG8_BAR; PG8_MMA(0, 0, At, B0); PG8_MMA(0, 1, At, B1); PG8_BAR; PG8_SCHED;
;             PG8_LDA(At, 0, 1); PG8_STAGE(PG8_SB(0, 0), b2, voffB); PG8_STAGE(PG8_SB(0, 1), b2 + hstep, voffB); PG8_STAGE(PG8_SA(0, 0), a2, voffA);
;             PG8_WAIT_V(8); PG8_WAIT_L(0); PG8_BAR; PG8_MMA(1, 0, At, B0); PG8_MMA(1, 1, At, B1); PG8_BAR; PG8_SCHED;
.Lmy_rw_609_0:
	s_waitcnt lgkmcnt(0)
	s_barrier
	s_waitcnt lgkmcnt(0)
	v_mfma_f32_16x16x32_bf16 v[126:129], v[146:149], v[188:191], 0
	v_mfma_f32_16x16x32_bf16 v[118:121], v[154:157], v[188:191], 0
	v_mfma_f32_16x16x32_bf16 v[110:113], v[146:149], v[196:199], 0
	v_mfma_f32_16x16x32_bf16 v[102:105], v[154:157], v[196:199], 0
	v_mfma_f32_16x16x32_bf16 v[94:97], v[146:149], v[204:207], 0
	v_mfma_f32_16x16x32_bf16 v[86:89], v[154:157], v[204:207], 0
	v_mfma_f32_16x16x32_bf16 v[78:81], v[146:149], v[212:215], 0
	v_mfma_f32_16x16x32_bf16 v[70:73], v[154:157], v[212:215], 0
	v_mfma_f32_16x16x32_bf16 v[126:129], v[150:153], v[192:195], v[126:129]
	v_mfma_f32_16x16x32_bf16 v[118:121], v[158:161], v[192:195], v[118:121]
	v_mfma_f32_16x16x32_bf16 v[110:113], v[150:153], v[200:203], v[110:113]
	v_mfma_f32_16x16x32_bf16 v[102:105], v[158:161], v[200:203], v[102:105]
	v_mfma_f32_16x16x32_bf16 v[94:97], v[150:153], v[208:211], v[94:97]
	v_mfma_f32_16x16x32_bf16 v[86:89], v[158:161], v[208:211], v[86:89]
	v_mfma_f32_16x16x32_bf16 v[78:81], v[150:153], v[216:219], v[78:81]
	v_mfma_f32_16x16x32_bf16 v[70:73], v[158:161], v[216:219], v[70:73]
	v_mfma_f32_16x16x32_bf16 v[122:125], v[172:175], v[188:191], 0
	v_mfma_f32_16x16x32_bf16 v[114:117], v[180:183], v[188:191], 0
	v_mfma_f32_16x16x32_bf16 v[106:109], v[172:175], v[196:199], 0
	v_mfma_f32_16x16x32_bf16 v[98:101], v[180:183], v[196:199], 0
	v_mfma_f32_16x16x32_bf16 v[90:93], v[172:175], v[204:207], 0
	v_mfma_f32_16x16x32_bf16 v[82:85], v[180:183], v[204:207], 0
	v_mfma_f32_16x16x32_bf16 v[74:77], v[172:175], v[212:215], 0
	v_mfma_f32_16x16x32_bf16 v[66:69], v[180:183], v[212:215], 0
	v_mfma_f32_16x16x32_bf16 v[122:125], v[176:179], v[192:195], v[122:125]
	v_mfma_f32_16x16x32_bf16 v[114:117], v[184:187], v[192:195], v[114:117]
	v_mfma_f32_16x16x32_bf16 v[106:109], v[176:179], v[200:203], v[106:109]
	v_mfma_f32_16x16x32_bf16 v[98:101], v[184:187], v[200:203], v[98:101]
	v_mfma_f32_16x16x32_bf16 v[90:93], v[176:179], v[208:211], v[90:93]
	v_mfma_f32_16x16x32_bf16 v[82:85], v[184:187], v[208:211], v[82:85]
	v_mfma_f32_16x16x32_bf16 v[74:77], v[176:179], v[216:219], v[74:77]
	v_mfma_f32_16x16x32_bf16 v[66:69], v[184:187], v[216:219], v[66:69]
	s_barrier
	s_add_i32 s63, s80, s33
	v_lshl_add_u64 v[220:221], s[8:9], 0, v[132:133]
	s_mov_b32 m0, s63
	ds_read_b128 v[188:191], v170 offset:16384
	ds_read_b128 v[192:195], v170 offset:17408
	ds_read_b128 v[196:199], v170 offset:18432
	ds_read_b128 v[200:203], v170 offset:19456
	ds_read_b128 v[204:207], v170 offset:20480
	ds_read_b128 v[208:211], v170 offset:21504
	ds_read_b128 v[212:215], v170 offset:22528
	ds_read_b128 v[216:219], v170 offset:23552
	global_load_lds_dwordx4 v[220:221], off
	s_add_i32 m0, s63, 0x2000
	s_add_u32 s84, s8, 0x40000
	v_lshl_add_u64 v[222:223], s[8:9], 0, v[136:137]
	s_addc_u32 s85, s9, 0
	s_add_i32 s63, s81, s33
	global_load_lds_dwordx4 v[222:223], off
	v_lshl_add_u64 v[224:225], s[84:85], 0, v[132:133]
	s_mov_b32 m0, s63
	v_lshl_add_u64 v[226:227], s[10:11], 0, v[134:135]
	global_load_lds_dwordx4 v[224:225], off
	v_lshl_add_u64 v[224:225], s[84:85], 0, v[136:137]
	s_add_i32 m0, s63, 0x2000
	s_nop 0
	global_load_lds_dwordx4 v[224:225], off
	v_lshl_add_u64 v[224:225], s[10:11], 0, v[130:131]
	s_mov_b32 m0, s70
	s_nop 0
	global_load_lds_dwordx4 v[224:225], off
	s_mov_b32 m0, s71
	s_nop 0
	global_load_lds_dwordx4 v[226:227], off
	s_cmp_lg_u32 s98, 0
	s_cbranch_scc1 .Lmy_rw_609_1
	s_waitcnt vmcnt(8)
.Lmy_rw_609_1:
	s_waitcnt lgkmcnt(0)
	s_barrier
	s_waitcnt lgkmcnt(0)
	v_mfma_f32_16x16x32_bf16 v[62:65], v[146:149], v[188:191], 0
	v_mfma_f32_16x16x32_bf16 v[54:57], v[154:157], v[188:191], 0
	v_mfma_f32_16x16x32_bf16 v[46:49], v[146:149], v[196:199], 0
	v_mfma_f32_16x16x32_bf16 v[38:41], v[154:157], v[196:199], 0
	v_mfma_f32_16x16x32_bf16 v[30:33], v[146:149], v[204:207], 0
	v_mfma_f32_16x16x32_bf16 v[22:25], v[154:157], v[204:207], 0
	v_mfma_f32_16x16x32_bf16 v[14:17], v[146:149], v[212:215], 0
	v_mfma_f32_16x16x32_bf16 v[6:9], v[154:157], v[212:215], 0
	v_mfma_f32_16x16x32_bf16 v[62:65], v[150:153], v[192:195], v[62:65]
	v_mfma_f32_16x16x32_bf16 v[54:57], v[158:161], v[192:195], v[54:57]
	v_mfma_f32_16x16x32_bf16 v[46:49], v[150:153], v[200:203], v[46:49]
	v_mfma_f32_16x16x32_bf16 v[38:41], v[158:161], v[200:203], v[38:41]
	v_mfma_f32_16x16x32_bf16 v[30:33], v[150:153], v[208:211], v[30:33]
	v_mfma_f32_16x16x32_bf16 v[22:25], v[158:161], v[208:211], v[22:25]
	v_mfma_f32_16x16x32_bf16 v[14:17], v[150:153], v[216:219], v[14:17]
	v_mfma_f32_16x16x32_bf16 v[6:9], v[158:161], v[216:219], v[6:9]
	v_mfma_f32_16x16x32_bf16 v[58:61], v[172:175], v[188:191], 0
	v_mfma_f32_16x16x32_bf16 v[50:53], v[180:183], v[188:191], 0
	v_mfma_f32_16x16x32_bf16 v[42:45], v[172:175], v[196:199], 0
	v_mfma_f32_16x16x32_bf16 v[34:37], v[180:183], v[196:199], 0
	v_mfma_f32_16x16x32_bf16 v[26:29], v[172:175], v[204:207], 0
	v_mfma_f32_16x16x32_bf16 v[18:21], v[180:183], v[204:207], 0
	v_mfma_f32_16x16x32_bf16 v[10:13], v[172:175], v[212:215], 0
	v_mfma_f32_16x16x32_bf16 v[2:5], v[180:183], v[212:215], 0
	v_mfma_f32_16x16x32_bf16 v[58:61], v[176:179], v[192:195], v[58:61]
	v_mfma_f32_16x16x32_bf16 v[50:53], v[184:187], v[192:195], v[50:53]
	v_mfma_f32_16x16x32_bf16 v[42:45], v[176:179], v[200:203], v[42:45]
	v_mfma_f32_16x16x32_bf16 v[34:37], v[184:187], v[200:203], v[34:37]
	v_mfma_f32_16x16x32_bf16 v[26:29], v[176:179], v[208:211], v[26:29]
	v_mfma_f32_16x16x32_bf16 v[18:21], v[184:187], v[208:211], v[18:21]
	v_mfma_f32_16x16x32_bf16 v[10:13], v[176:179], v[216:219], v[10:13]
	v_mfma_f32_16x16x32_bf16 v[2:5], v[184:187], v[216:219], v[2:5]
	s_barrier
; #define PG8_STAGE(bufoff, gbase, voff) do { _Pragma("unroll") for (int _i = 0; _i < 2; ++_i) \
;         __builtin_amdgcn_global_load_lds((const unsigned*)((const char*)(gbase) + (voff)[_i]), (LAS unsigned*)(lds + (bufoff) + ldsw + _i * 8192), 16, 0, 0); } while (0)
; #define PG8_LDA(dst, b, h) do { _Pragma("unroll") for (int m = 0; m < 4; ++m) _Pragma("unroll") for (int k = 0; k < 2; ++k) dst[m][k] = *(const LAS bf16x8*)(lds + PG8_SA(b, h) + aoff + m * 2048 + k * 1024); } while (0)
; #define PG8_LDB(dst, b, h) do { _Pragma("unroll") for (int n = 0; n < 2; ++n) _Pragma("unroll") for (int k = 0; k < 2; ++k) dst[n][k] = *(const LAS bf16x8*)(lds + PG8_SB(b, h) + boff + n * 2048 + k * 1024); } while (0)
; #define PG8_MMA(ai, bj, At, Bt) do { __builtin_amdgcn_s_setprio(3); _Pragma("unroll") for (int m = 0; m < 4; ++m) _Pragma("unroll") for (int n = 0; n < 2; ++n) _Pragma("unroll") for (int k = 0; k < 2; ++k) \
;         acc[ai][bj][m][n] = __builtin_amdgcn_mfma_f32_16x16x32_bf16(Bt[n][k], At[m][k], acc[ai][bj][m][n], 0, 0, 0); __builtin_amdgcn_s_setprio(0); } while (0)
; #define PG8_WAIT_V(n) asm volatile("s_waitcnt vmcnt(" #n ")" ::: "memory")
; #define PG8_WAIT_L(n) asm volatile("s_waitcnt lgkmcnt(" #n ")" ::: "memory")
; #define PG8_BAR __builtin_amdgcn_s_barrier()
; #define PG8_SCHED __builtin_amdgcn_sched_barrier(0)
; template <class Epi, bool ALIGN_EPI>
; __device__ __forceinline__ void gemm_phase(LAS unsigned char* lds, const Gemm g, const StaticOrder& S, const Epi& E) {
;     ...
;             PG8_LDB(B0, 1, 0); PG8_LDB(B1, 1, 1); PG8_SCHED; PG8_LDA(At, 1, 0); PG8_STAGE(PG8_SA(0, 1), a2 + hstep, voffA);
;             PG8_WAIT_V(8); PG8_WAIT_L(0); PG8_BAR; PG8_MMA(0, 0, At, B0); PG8_MMA(0, 1, At, B1); PG8_BAR; PG8_SCHED;
;             PG8_LDA(At, 1, 1); PG8_STAGE(PG8_SB(1, 0), b3, voffB); PG8_STAGE(PG8_SB(1, 1), b3 + hstep, voffB); PG8_STAGE(PG8_SA(1, 0), a3, voffA);
;             PG8_WAIT_V(8); PG8_WAIT_L(0); PG8_BAR; PG8_MMA(1, 0, At, B0); PG8_MMA(1, 1, At, B1); PG8_BAR; PG8_SCHED;
	s_add_i32 s63, 0, 0x18000
	s_add_i32 s84, 0, 0x1c000
	v_add_u32_e32 v158, s63, v166
	v_add_u32_e32 v184, s84, v166
	ds_read_b128 v[146:149], v158
	ds_read_b128 v[150:153], v158 offset:1024
	ds_read_b128 v[154:157], v158 offset:2048
	ds_read_b128 v[158:161], v158 offset:3072
	ds_read_b128 v[172:175], v184
	ds_read_b128 v[176:179], v184 offset:1024
	ds_read_b128 v[180:183], v184 offset:2048
	ds_read_b128 v[184:187], v184 offset:3072
	s_add_u32 s10, s10, 0x40000
	s_addc_u32 s11, s11, 0
	s_mov_b32 m0, s72
	v_lshl_add_u64 v[228:229], s[10:11], 0, v[130:131]
	ds_read_b128 v[188:191], v170 offset:32768
	ds_read_b128 v[192:195], v170 offset:33792
	ds_read_b128 v[196:199], v170 offset:34816
	ds_read_b128 v[200:203], v170 offset:35840
	ds_read_b128 v[204:207], v170 offset:36864
	ds_read_b128 v[208:211], v170 offset:37888
	ds_read_b128 v[212:215], v170 offset:38912
	ds_read_b128 v[216:219], v170 offset:39936
	global_load_lds_dwordx4 v[228:229], off
	v_lshl_add_u64 v[228:229], s[10:11], 0, v[134:135]
	s_mov_b32 m0, s73
	s_nop 0
	global_load_lds_dwordx4 v[228:229], off
	s_waitcnt vmcnt(8)
	s_waitcnt lgkmcnt(0)
	s_barrier
	s_waitcnt lgkmcnt(0)
	v_mfma_f32_16x16x32_bf16 v[126:129], v[146:149], v[188:191], v[126:129]
	v_mfma_f32_16x16x32_bf16 v[118:121], v[154:157], v[188:191], v[118:121]
	v_mfma_f32_16x16x32_bf16 v[110:113], v[146:149], v[196:199], v[110:113]
	v_mfma_f32_16x16x32_bf16 v[102:105], v[154:157], v[196:199], v[102:105]
	v_mfma_f32_16x16x32_bf16 v[94:97], v[146:149], v[204:207], v[94:97]
	v_mfma_f32_16x16x32_bf16 v[86:89], v[154:157], v[204:207], v[86:89]
	v_mfma_f32_16x16x32_bf16 v[78:81], v[146:149], v[212:215], v[78:81]
	v_mfma_f32_16x16x32_bf16 v[70:73], v[154:157], v[212:215], v[70:73]
	v_mfma_f32_16x16x32_bf16 v[126:129], v[150:153], v[192:195], v[126:129]
	v_mfma_f32_16x16x32_bf16 v[118:121], v[158:161], v[192:195], v[118:121]
	v_mfma_f32_16x16x32_bf16 v[110:113], v[150:153], v[200:203], v[110:113]
	v_mfma_f32_16x16x32_bf16 v[102:105], v[158:161], v[200:203], v[102:105]
	v_mfma_f32_16x16x32_bf16 v[94:97], v[150:153], v[208:211], v[94:97]
	v_mfma_f32_16x16x32_bf16 v[86:89], v[158:161], v[208:211], v[86:89]
	v_mfma_f32_16x16x32_bf16 v[78:81], v[150:153], v[216:219], v[78:81]
	v_mfma_f32_16x16x32_bf16 v[70:73], v[158:161], v[216:219], v[70:73]
	v_mfma_f32_16x16x32_bf16 v[122:125], v[172:175], v[188:191], v[122:125]
	v_mfma_f32_16x16x32_bf16 v[114:117], v[180:183], v[188:191], v[114:117]
	v_mfma_f32_16x16x32_bf16 v[106:109], v[172:175], v[196:199], v[106:109]
	v_mfma_f32_16x16x32_bf16 v[98:101], v[180:183], v[196:199], v[98:101]
	v_mfma_f32_16x16x32_bf16 v[90:93], v[172:175], v[204:207], v[90:93]
	v_mfma_f32_16x16x32_bf16 v[82:85], v[180:183], v[204:207], v[82:85]
	v_mfma_f32_16x16x32_bf16 v[74:77], v[172:175], v[212:215], v[74:77]
	v_mfma_f32_16x16x32_bf16 v[66:69], v[180:183], v[212:215], v[66:69]
	v_mfma_f32_16x16x32_bf16 v[122:125], v[176:179], v[192:195], v[122:125]
	v_mfma_f32_16x16x32_bf16 v[114:117], v[184:187], v[192:195], v[114:117]
	v_mfma_f32_16x16x32_bf16 v[106:109], v[176:179], v[200:203], v[106:109]
	v_mfma_f32_16x16x32_bf16 v[98:101], v[184:187], v[200:203], v[98:101]
	v_mfma_f32_16x16x32_bf16 v[90:93], v[176:179], v[208:211], v[90:93]
	v_mfma_f32_16x16x32_bf16 v[82:85], v[184:187], v[208:211], v[82:85]
	v_mfma_f32_16x16x32_bf16 v[74:77], v[176:179], v[216:219], v[74:77]
	v_mfma_f32_16x16x32_bf16 v[66:69], v[184:187], v[216:219], v[66:69]
	s_barrier
	s_add_i32 s10, s63, s33
	v_lshl_add_u64 v[220:221], v[220:221], 0, s[56:57]
	s_mov_b32 m0, s10
	ds_read_b128 v[188:191], v170 offset:49152
	ds_read_b128 v[192:195], v170 offset:50176
	ds_read_b128 v[196:199], v170 offset:51200
	ds_read_b128 v[200:203], v170 offset:52224
	ds_read_b128 v[204:207], v170 offset:53248
	ds_read_b128 v[208:211], v170 offset:54272
	ds_read_b128 v[212:215], v170 offset:55296
	ds_read_b128 v[216:219], v170 offset:56320
	global_load_lds_dwordx4 v[220:221], off
	s_add_i32 m0, s10, 0x2000
	s_add_u32 s8, s8, 0x40080
	v_lshl_add_u64 v[220:221], v[222:223], 0, s[56:57]
	s_addc_u32 s9, s9, 0
	s_add_i32 s10, s84, s33
	global_load_lds_dwordx4 v[220:221], off
	v_lshl_add_u64 v[220:221], s[8:9], 0, v[132:133]
	s_mov_b32 m0, s10
	s_nop 0
	global_load_lds_dwordx4 v[220:221], off
	v_lshl_add_u64 v[220:221], s[8:9], 0, v[136:137]
	s_add_i32 m0, s10, 0x2000
	s_nop 0
	global_load_lds_dwordx4 v[220:221], off
	v_lshl_add_u64 v[220:221], v[224:225], 0, s[56:57]
	s_mov_b32 m0, s78
	s_nop 0
	global_load_lds_dwordx4 v[220:221], off
	v_lshl_add_u64 v[220:221], v[226:227], 0, s[56:57]
	s_mov_b32 m0, s79
	s_nop 0
	global_load_lds_dwordx4 v[220:221], off
	s_waitcnt vmcnt(8)
	s_waitcnt lgkmcnt(0)
	s_barrier
	s_waitcnt lgkmcnt(0)
	v_mfma_f32_16x16x32_bf16 v[62:65], v[146:149], v[188:191], v[62:65]
	v_mfma_f32_16x16x32_bf16 v[54:57], v[154:157], v[188:191], v[54:57]
	v_mfma_f32_16x16x32_bf16 v[46:49], v[146:149], v[196:199], v[46:49]
	v_mfma_f32_16x16x32_bf16 v[38:41], v[154:157], v[196:199], v[38:41]
	v_mfma_f32_16x16x32_bf16 v[30:33], v[146:149], v[204:207], v[30:33]
	v_mfma_f32_16x16x32_bf16 v[22:25], v[154:157], v[204:207], v[22:25]
	v_mfma_f32_16x16x32_bf16 v[14:17], v[146:149], v[212:215], v[14:17]
	v_mfma_f32_16x16x32_bf16 v[6:9], v[154:157], v[212:215], v[6:9]
	v_mfma_f32_16x16x32_bf16 v[62:65], v[150:153], v[192:195], v[62:65]
	v_mfma_f32_16x16x32_bf16 v[54:57], v[158:161], v[192:195], v[54:57]
	v_mfma_f32_16x16x32_bf16 v[46:49], v[150:153], v[200:203], v[46:49]
	v_mfma_f32_16x16x32_bf16 v[38:41], v[158:161], v[200:203], v[38:41]
	v_mfma_f32_16x16x32_bf16 v[30:33], v[150:153], v[208:211], v[30:33]
	v_mfma_f32_16x16x32_bf16 v[22:25], v[158:161], v[208:211], v[22:25]
	v_mfma_f32_16x16x32_bf16 v[14:17], v[150:153], v[216:219], v[14:17]
	v_mfma_f32_16x16x32_bf16 v[6:9], v[158:161], v[216:219], v[6:9]
	v_mfma_f32_16x16x32_bf16 v[58:61], v[172:175], v[188:191], v[58:61]
	v_mfma_f32_16x16x32_bf16 v[50:53], v[180:183], v[188:191], v[50:53]
	v_mfma_f32_16x16x32_bf16 v[42:45], v[172:175], v[196:199], v[42:45]
	v_mfma_f32_16x16x32_bf16 v[34:37], v[180:183], v[196:199], v[34:37]
	v_mfma_f32_16x16x32_bf16 v[26:29], v[172:175], v[204:207], v[26:29]
	v_mfma_f32_16x16x32_bf16 v[18:21], v[180:183], v[204:207], v[18:21]
	v_mfma_f32_16x16x32_bf16 v[10:13], v[172:175], v[212:215], v[10:13]
	v_mfma_f32_16x16x32_bf16 v[2:5], v[180:183], v[212:215], v[2:5]
	v_mfma_f32_16x16x32_bf16 v[58:61], v[176:179], v[192:195], v[58:61]
	v_mfma_f32_16x16x32_bf16 v[50:53], v[184:187], v[192:195], v[50:53]
	v_mfma_f32_16x16x32_bf16 v[42:45], v[176:179], v[200:203], v[42:45]
	v_mfma_f32_16x16x32_bf16 v[34:37], v[184:187], v[200:203], v[34:37]
	v_mfma_f32_16x16x32_bf16 v[26:29], v[176:179], v[208:211], v[26:29]
	v_mfma_f32_16x16x32_bf16 v[18:21], v[184:187], v[208:211], v[18:21]
	v_mfma_f32_16x16x32_bf16 v[10:13], v[176:179], v[216:219], v[10:13]
	v_mfma_f32_16x16x32_bf16 v[2:5], v[184:187], v[216:219], v[2:5]
	s_barrier
	s_add_i32 s61, s61, 2
	s_add_u32 s6, s6, 0x100
	s_addc_u32 s7, s7, 0
	s_add_u32 s16, s16, 0x100
	s_addc_u32 s17, s17, 0
; #define PG8_STAGE(bufoff, gbase, voff) do { _Pragma("unroll") for (int _i = 0; _i < 2; ++_i) \
;         __builtin_amdgcn_global_load_lds((const unsigned*)((const char*)(gbase) + (voff)[_i]), (LAS unsigned*)(lds + (bufoff) + ldsw + _i * 8192), 16, 0, 0); } while (0)
; #define PG8_LDA(dst, b, h) do { _Pragma("unroll") for (int m = 0; m < 4; ++m) _Pragma("unroll") for (int k = 0; k < 2; ++k) dst[m][k] = *(const LAS bf16x8*)(lds + PG8_SA(b, h) + aoff + m * 2048 + k * 1024); } while (0)
; #define PG8_LDB(dst, b, h) do { _Pragma("unroll") for (int n = 0; n < 2; ++n) _Pragma("unroll") for (int k = 0; k < 2; ++k) dst[n][k] = *(const LAS bf16x8*)(lds + PG8_SB(b, h) + boff + n * 2048 + k * 1024); } while (0)
; #define PG8_MMA(ai, bj, At, Bt) do { __builtin_amdgcn_s_setprio(3); _Pragma("unroll") for (int m = 0; m < 4; ++m) _Pragma("unroll") for (int n = 0; n < 2; ++n) _Pragma("unroll") for (int k = 0; k < 2; ++k) \
;         acc[ai][bj][m][n] = __builtin_amdgcn_mfma_f32_16x16x32_bf16(Bt[n][k], At[m][k], acc[ai][bj][m][n], 0, 0, 0); __builtin_amdgcn_s_setprio(0); } while (0)
; #define PG8_WAIT_V(n) asm volatile("s_waitcnt vmcnt(" #n ")" ::: "memory")
; #define PG8_WAIT_L(n) asm volatile("s_waitcnt lgkmcnt(" #n ")" ::: "memory")
; #define PG8_BAR __builtin_amdgcn_s_barrier()
; #define PG8_SCHED __builtin_amdgcn_sched_barrier(0)
; template <class Epi, bool ALIGN_EPI>
; __device__ __forceinline__ void gemm_phase(LAS unsigned char* lds, const Gemm g, const StaticOrder& S, const Epi& E) {
;     ...
;             const bool last = (t == nt - 2);
;             const char* a1 = cA + (size_t)(t + 1) * kstep;
;             const char* a2 = last ? nA : cA + (size_t)(t + 2) * kstep; const char* b2 = last ? nB : cB + (size_t)(t + 2) * kstep;
;             const char* a3 = a2 + kstep; const char* b3 = b2 + kstep;
;             PG8_LDB(B0, 0, 0); PG8_LDB(B1, 0, 1); PG8_SCHED; PG8_LDA(At, 0, 0); PG8_STAGE(PG8_SA(1, 1), a1 + hstep, voffA);
;             PG8_WAIT_V(8); PG8_WAIT_L(0); PG8_BAR; PG8_MMA(0, 0, At, B0); PG8_MMA(0, 1, At, B1); PG8_BAR; PG8_SCHED;
;             PG8_LDA(At, 0, 1); PG8_STAGE(PG8_SB(0, 0), b2, voffB); PG8_STAGE(PG8_SB(0, 1), b2 + hstep, voffB); PG8_STAGE(PG8_SA(0, 0), a2, voffA);
.LBB0_609:
	ds_read_b128 v[146:149], v168
	ds_read_b128 v[150:153], v168 offset:1024
	ds_read_b128 v[154:157], v168 offset:2048
	ds_read_b128 v[158:161], v168 offset:3072
	ds_read_b128 v[172:175], v169
	ds_read_b128 v[176:179], v169 offset:1024
	ds_read_b128 v[180:183], v169 offset:2048
	ds_read_b128 v[184:187], v169 offset:3072
	s_add_u32 s8, s6, 0xfffc0080
	s_addc_u32 s9, s7, -1
	s_cmp_eq_u32 s61, 12
	s_cselect_b32 s11, s12, s9
	s_cselect_b32 s10, s13, s8
	s_cselect_b32 s9, s14, s17
	s_cselect_b32 s8, s15, s16
	v_lshl_add_u64 v[220:221], s[6:7], 0, v[138:139]
	s_add_i32 m0, s70, 0xc000
	ds_read_b128 v[188:191], v170
	ds_read_b128 v[192:195], v170 offset:1024
	ds_read_b128 v[196:199], v170 offset:2048
	ds_read_b128 v[200:203], v170 offset:3072
	ds_read_b128 v[204:207], v170 offset:4096
	ds_read_b128 v[208:211], v170 offset:5120
	ds_read_b128 v[212:215], v170 offset:6144
	ds_read_b128 v[216:219], v170 offset:7168
	global_load_lds_dwordx4 v[220:221], off
	v_lshl_add_u64 v[220:221], s[6:7], 0, v[140:141]
	s_add_i32 m0, s70, 0xe000
	s_nop 0
	global_load_lds_dwordx4 v[220:221], off
	s_waitcnt vmcnt(8)
	s_waitcnt lgkmcnt(0)
	s_barrier
	s_waitcnt lgkmcnt(0)
	v_mfma_f32_16x16x32_bf16 v[126:129], v[146:149], v[188:191], v[126:129]
	v_mfma_f32_16x16x32_bf16 v[118:121], v[154:157], v[188:191], v[118:121]
	v_mfma_f32_16x16x32_bf16 v[110:113], v[146:149], v[196:199], v[110:113]
	v_mfma_f32_16x16x32_bf16 v[102:105], v[154:157], v[196:199], v[102:105]
	v_mfma_f32_16x16x32_bf16 v[94:97], v[146:149], v[204:207], v[94:97]
	v_mfma_f32_16x16x32_bf16 v[86:89], v[154:157], v[204:207], v[86:89]
	v_mfma_f32_16x16x32_bf16 v[78:81], v[146:149], v[212:215], v[78:81]
	v_mfma_f32_16x16x32_bf16 v[70:73], v[154:157], v[212:215], v[70:73]
	v_mfma_f32_16x16x32_bf16 v[126:129], v[150:153], v[192:195], v[126:129]
	v_mfma_f32_16x16x32_bf16 v[118:121], v[158:161], v[192:195], v[118:121]
	v_mfma_f32_16x16x32_bf16 v[110:113], v[150:153], v[200:203], v[110:113]
	v_mfma_f32_16x16x32_bf16 v[102:105], v[158:161], v[200:203], v[102:105]
	v_mfma_f32_16x16x32_bf16 v[94:97], v[150:153], v[208:211], v[94:97]
	v_mfma_f32_16x16x32_bf16 v[86:89], v[158:161], v[208:211], v[86:89]
	v_mfma_f32_16x16x32_bf16 v[78:81], v[150:153], v[216:219], v[78:81]
	v_mfma_f32_16x16x32_bf16 v[70:73], v[158:161], v[216:219], v[70:73]
	v_mfma_f32_16x16x32_bf16 v[122:125], v[172:175], v[188:191], v[122:125]
	v_mfma_f32_16x16x32_bf16 v[114:117], v[180:183], v[188:191], v[114:117]
	v_mfma_f32_16x16x32_bf16 v[106:109], v[172:175], v[196:199], v[106:109]
	v_mfma_f32_16x16x32_bf16 v[98:101], v[180:183], v[196:199], v[98:101]
	v_mfma_f32_16x16x32_bf16 v[90:93], v[172:175], v[204:207], v[90:93]
	v_mfma_f32_16x16x32_bf16 v[82:85], v[180:183], v[204:207], v[82:85]
	v_mfma_f32_16x16x32_bf16 v[74:77], v[172:175], v[212:215], v[74:77]
	v_mfma_f32_16x16x32_bf16 v[66:69], v[180:183], v[212:215], v[66:69]
	v_mfma_f32_16x16x32_bf16 v[122:125], v[176:179], v[192:195], v[122:125]
	v_mfma_f32_16x16x32_bf16 v[114:117], v[184:187], v[192:195], v[114:117]
	v_mfma_f32_16x16x32_bf16 v[106:109], v[176:179], v[200:203], v[106:109]
	v_mfma_f32_16x16x32_bf16 v[98:101], v[184:187], v[200:203], v[98:101]
	v_mfma_f32_16x16x32_bf16 v[90:93], v[176:179], v[208:211], v[90:93]
	v_mfma_f32_16x16x32_bf16 v[82:85], v[184:187], v[208:211], v[82:85]
	v_mfma_f32_16x16x32_bf16 v[74:77], v[176:179], v[216:219], v[74:77]
	v_mfma_f32_16x16x32_bf16 v[66:69], v[184:187], v[216:219], v[66:69]
	s_barrier
	s_add_i32 s63, s80, s33
	v_lshl_add_u64 v[220:221], s[8:9], 0, v[132:133]
	s_mov_b32 m0, s63
	ds_read_b128 v[188:191], v170 offset:16384
	ds_read_b128 v[192:195], v170 offset:17408
	ds_read_b128 v[196:199], v170 offset:18432
	ds_read_b128 v[200:203], v170 offset:19456
	ds_read_b128 v[204:207], v170 offset:20480
	ds_read_b128 v[208:211], v170 offset:21504
	ds_read_b128 v[212:215], v170 offset:22528
	ds_read_b128 v[216:219], v170 offset:23552
	global_load_lds_dwordx4 v[220:221], off
	s_add_i32 m0, s63, 0x2000
	s_add_u32 s84, s8, 0x40000
	v_lshl_add_u64 v[222:223], s[8:9], 0, v[136:137]
	s_addc_u32 s85, s9, 0
	s_add_i32 s63, s81, s33
	global_load_lds_dwordx4 v[222:223], off
	v_lshl_add_u64 v[224:225], s[84:85], 0, v[132:133]
	s_mov_b32 m0, s63
	v_lshl_add_u64 v[226:227], s[10:11], 0, v[134:135]
	global_load_lds_dwordx4 v[224:225], off
	v_lshl_add_u64 v[224:225], s[84:85], 0, v[136:137]
	s_add_i32 m0, s63, 0x2000
	s_nop 0
	global_load_lds_dwordx4 v[224:225], off
	v_lshl_add_u64 v[224:225], s[10:11], 0, v[130:131]
	s_mov_b32 m0, s70
	s_nop 0
	global_load_lds_dwordx4 v[224:225], off
	s_mov_b32 m0, s71
	s_nop 0
	global_load_lds_dwordx4 v[226:227], off
	s_waitcnt vmcnt(8)
	s_waitcnt lgkmcnt(0)
	s_barrier
; #define PG8_STAGE(bufoff, gbase, voff) do { _Pragma("unroll") for (int _i = 0; _i < 2; ++_i) \
;         __builtin_amdgcn_global_load_lds((const unsigned*)((const char*)(gbase) + (voff)[_i]), (LAS unsigned*)(lds + (bufoff) + ldsw + _i * 8192), 16, 0, 0); } while (0)
; #define PG8_LDA(dst, b, h) do { _Pragma("unroll") for (int m = 0; m < 4; ++m) _Pragma("unroll") for (int k = 0; k < 2; ++k) dst[m][k] = *(const LAS bf16x8*)(lds + PG8_SA(b, h) + aoff + m * 2048 + k * 1024); } while (0)
; #define PG8_LDB(dst, b, h) do { _Pragma("unroll") for (int n = 0; n < 2; ++n) _Pragma("unroll") for (int k = 0; k < 2; ++k) dst[n][k] = *(const LAS bf16x8*)(lds + PG8_SB(b, h) + boff + n * 2048 + k * 1024); } while (0)
; #define PG8_MMA(ai, bj, At, Bt) do { __builtin_amdgcn_s_setprio(3); _Pragma("unroll") for (int m = 0; m < 4; ++m) _Pragma("unroll") for (int n = 0; n < 2; ++n) _Pragma("unroll") for (int k = 0; k < 2; ++k) \
;         acc[ai][bj][m][n] = __builtin_amdgcn_mfma_f32_16x16x32_bf16(Bt[n][k], At[m][k], acc[ai][bj][m][n], 0, 0, 0); __builtin_amdgcn_s_setprio(0); } while (0)
; #define PG8_WAIT_V(n) asm volatile("s_waitcnt vmcnt(" #n ")" ::: "memory")
; #define PG8_WAIT_L(n) asm volatile("s_waitcnt lgkmcnt(" #n ")" ::: "memory")
; #define PG8_BAR __builtin_amdgcn_s_barrier()
; #define PG8_SCHED __builtin_amdgcn_sched_barrier(0)
; template <class Epi, bool ALIGN_EPI>
; __device__ __forceinline__ void gemm_phase(LAS unsigned char* lds, const Gemm g, const StaticOrder& S, const Epi& E) {
;     ...
;             PG8_WAIT_V(8); PG8_WAIT_L(0); PG8_BAR; PG8_MMA(1, 0, At, B0); PG8_MMA(1, 1, At, B1); PG8_BAR; PG8_SCHED;
;             PG8_LDB(B0, 1, 0); PG8_LDB(B1, 1, 1); PG8_SCHED; PG8_LDA(At, 1, 0); PG8_STAGE(PG8_SA(0, 1), a2 + hstep, voffA);
;             PG8_WAIT_V(8); PG8_WAIT_L(0); PG8_BAR; PG8_MMA(0, 0, At, B0); PG8_MMA(0, 1, At, B1); PG8_BAR; PG8_SCHED;
	s_waitcnt lgkmcnt(0)
	v_mfma_f32_16x16x32_bf16 v[62:65], v[146:149], v[188:191], v[62:65]
	v_mfma_f32_16x16x32_bf16 v[54:57], v[154:157], v[188:191], v[54:57]
	v_mfma_f32_16x16x32_bf16 v[46:49], v[146:149], v[196:199], v[46:49]
	v_mfma_f32_16x16x32_bf16 v[38:41], v[154:157], v[196:199], v[38:41]
	v_mfma_f32_16x16x32_bf16 v[30:33], v[146:149], v[204:207], v[30:33]
	v_mfma_f32_16x16x32_bf16 v[22:25], v[154:157], v[204:207], v[22:25]
	v_mfma_f32_16x16x32_bf16 v[14:17], v[146:149], v[212:215], v[14:17]
	v_mfma_f32_16x16x32_bf16 v[6:9], v[154:157], v[212:215], v[6:9]
	v_mfma_f32_16x16x32_bf16 v[62:65], v[150:153], v[192:195], v[62:65]
	v_mfma_f32_16x16x32_bf16 v[54:57], v[158:161], v[192:195], v[54:57]
	v_mfma_f32_16x16x32_bf16 v[46:49], v[150:153], v[200:203], v[46:49]
	v_mfma_f32_16x16x32_bf16 v[38:41], v[158:161], v[200:203], v[38:41]
	v_mfma_f32_16x16x32_bf16 v[30:33], v[150:153], v[208:211], v[30:33]
	v_mfma_f32_16x16x32_bf16 v[22:25], v[158:161], v[208:211], v[22:25]
	v_mfma_f32_16x16x32_bf16 v[14:17], v[150:153], v[216:219], v[14:17]
	v_mfma_f32_16x16x32_bf16 v[6:9], v[158:161], v[216:219], v[6:9]
	v_mfma_f32_16x16x32_bf16 v[58:61], v[172:175], v[188:191], v[58:61]
	v_mfma_f32_16x16x32_bf16 v[50:53], v[180:183], v[188:191], v[50:53]
	v_mfma_f32_16x16x32_bf16 v[42:45], v[172:175], v[196:199], v[42:45]
	v_mfma_f32_16x16x32_bf16 v[34:37], v[180:183], v[196:199], v[34:37]
	v_mfma_f32_16x16x32_bf16 v[26:29], v[172:175], v[204:207], v[26:29]
	v_mfma_f32_16x16x32_bf16 v[18:21], v[180:183], v[204:207], v[18:21]
	v_mfma_f32_16x16x32_bf16 v[10:13], v[172:175], v[212:215], v[10:13]
	v_mfma_f32_16x16x32_bf16 v[2:5], v[180:183], v[212:215], v[2:5]
	v_mfma_f32_16x16x32_bf16 v[58:61], v[176:179], v[192:195], v[58:61]
	v_mfma_f32_16x16x32_bf16 v[50:53], v[184:187], v[192:195], v[50:53]
	v_mfma_f32_16x16x32_bf16 v[42:45], v[176:179], v[200:203], v[42:45]
	v_mfma_f32_16x16x32_bf16 v[34:37], v[184:187], v[200:203], v[34:37]
	v_mfma_f32_16x16x32_bf16 v[26:29], v[176:179], v[208:211], v[26:29]
	v_mfma_f32_16x16x32_bf16 v[18:21], v[184:187], v[208:211], v[18:21]
	v_mfma_f32_16x16x32_bf16 v[10:13], v[176:179], v[216:219], v[10:13]
	v_mfma_f32_16x16x32_bf16 v[2:5], v[184:187], v[216:219], v[2:5]
	s_barrier
	s_add_i32 s63, 0, 0x18000
	s_add_i32 s84, 0, 0x1c000
	v_add_u32_e32 v158, s63, v166
	v_add_u32_e32 v184, s84, v166
	ds_read_b128 v[146:149], v158
	ds_read_b128 v[150:153], v158 offset:1024
	ds_read_b128 v[154:157], v158 offset:2048
	ds_read_b128 v[158:161], v158 offset:3072
	ds_read_b128 v[172:175], v184
	ds_read_b128 v[176:179], v184 offset:1024
	ds_read_b128 v[180:183], v184 offset:2048
	ds_read_b128 v[184:187], v184 offset:3072
	s_add_u32 s10, s10, 0x40000
	s_addc_u32 s11, s11, 0
	s_mov_b32 m0, s72
	v_lshl_add_u64 v[228:229], s[10:11], 0, v[130:131]
	ds_read_b128 v[188:191], v170 offset:32768
	ds_read_b128 v[192:195], v170 offset:33792
	ds_read_b128 v[196:199], v170 offset:34816
	ds_read_b128 v[200:203], v170 offset:35840
	ds_read_b128 v[204:207], v170 offset:36864
	ds_read_b128 v[208:211], v170 offset:37888
	ds_read_b128 v[212:215], v170 offset:38912
	ds_read_b128 v[216:219], v170 offset:39936
	global_load_lds_dwordx4 v[228:229], off
	v_lshl_add_u64 v[228:229], s[10:11], 0, v[134:135]
	s_mov_b32 m0, s73
	s_nop 0
	global_load_lds_dwordx4 v[228:229], off
	s_waitcnt vmcnt(8)
	s_waitcnt lgkmcnt(0)
	s_barrier
	s_waitcnt lgkmcnt(0)
	v_mfma_f32_16x16x32_bf16 v[126:129], v[146:149], v[188:191], v[126:129]
	v_mfma_f32_16x16x32_bf16 v[118:121], v[154:157], v[188:191], v[118:121]
	v_mfma_f32_16x16x32_bf16 v[110:113], v[146:149], v[196:199], v[110:113]
	v_mfma_f32_16x16x32_bf16 v[102:105], v[154:157], v[196:199], v[102:105]
	v_mfma_f32_16x16x32_bf16 v[94:97], v[146:149], v[204:207], v[94:97]
	v_mfma_f32_16x16x32_bf16 v[86:89], v[154:157], v[204:207], v[86:89]
	v_mfma_f32_16x16x32_bf16 v[78:81], v[146:149], v[212:215], v[78:81]
	v_mfma_f32_16x16x32_bf16 v[70:73], v[154:157], v[212:215], v[70:73]
	v_mfma_f32_16x16x32_bf16 v[126:129], v[150:153], v[192:195], v[126:129]
	v_mfma_f32_16x16x32_bf16 v[118:121], v[158:161], v[192:195], v[118:121]
	v_mfma_f32_16x16x32_bf16 v[110:113], v[150:153], v[200:203], v[110:113]
	v_mfma_f32_16x16x32_bf16 v[102:105], v[158:161], v[200:203], v[102:105]
	v_mfma_f32_16x16x32_bf16 v[94:97], v[150:153], v[208:211], v[94:97]
	v_mfma_f32_16x16x32_bf16 v[86:89], v[158:161], v[208:211], v[86:89]
	v_mfma_f32_16x16x32_bf16 v[78:81], v[150:153], v[216:219], v[78:81]
	v_mfma_f32_16x16x32_bf16 v[70:73], v[158:161], v[216:219], v[70:73]
	v_mfma_f32_16x16x32_bf16 v[122:125], v[172:175], v[188:191], v[122:125]
	v_mfma_f32_16x16x32_bf16 v[114:117], v[180:183], v[188:191], v[114:117]
	v_mfma_f32_16x16x32_bf16 v[106:109], v[172:175], v[196:199], v[106:109]
	v_mfma_f32_16x16x32_bf16 v[98:101], v[180:183], v[196:199], v[98:101]
	v_mfma_f32_16x16x32_bf16 v[90:93], v[172:175], v[204:207], v[90:93]
	v_mfma_f32_16x16x32_bf16 v[82:85], v[180:183], v[204:207], v[82:85]
	v_mfma_f32_16x16x32_bf16 v[74:77], v[172:175], v[212:215], v[74:77]
	v_mfma_f32_16x16x32_bf16 v[66:69], v[180:183], v[212:215], v[66:69]
	v_mfma_f32_16x16x32_bf16 v[122:125], v[176:179], v[192:195], v[122:125]
	v_mfma_f32_16x16x32_bf16 v[114:117], v[184:187], v[192:195], v[114:117]
	v_mfma_f32_16x16x32_bf16 v[106:109], v[176:179], v[200:203], v[106:109]
	v_mfma_f32_16x16x32_bf16 v[98:101], v[184:187], v[200:203], v[98:101]
	v_mfma_f32_16x16x32_bf16 v[90:93], v[176:179], v[208:211], v[90:93]
	v_mfma_f32_16x16x32_bf16 v[82:85], v[184:187], v[208:211], v[82:85]
	v_mfma_f32_16x16x32_bf16 v[74:77], v[176:179], v[216:219], v[74:77]
	v_mfma_f32_16x16x32_bf16 v[66:69], v[184:187], v[216:219], v[66:69]
	s_barrier
; #define PG8_STAGE(bufoff, gbase, voff) do { _Pragma("unroll") for (int _i = 0; _i < 2; ++_i) \
;         __builtin_amdgcn_global_load_lds((const unsigned*)((const char*)(gbase) + (voff)[_i]), (LAS unsigned*)(lds + (bufoff) + ldsw + _i * 8192), 16, 0, 0); } while (0)
; #define PG8_LDA(dst, b, h) do { _Pragma("unroll") for (int m = 0; m < 4; ++m) _Pragma("unroll") for (int k = 0; k < 2; ++k) dst[m][k] = *(const LAS bf16x8*)(lds + PG8_SA(b, h) + aoff + m * 2048 + k * 1024); } while (0)
; #define PG8_MMA(ai, bj, At, Bt) do { __builtin_amdgcn_s_setprio(3); _Pragma("unroll") for (int m = 0; m < 4; ++m) _Pragma("unroll") for (int n = 0; n < 2; ++n) _Pragma("unroll") for (int k = 0; k < 2; ++k) \
;         acc[ai][bj][m][n] = __builtin_amdgcn_mfma_f32_16x16x32_bf16(Bt[n][k], At[m][k], acc[ai][bj][m][n], 0, 0, 0); __builtin_amdgcn_s_setprio(0); } while (0)
; #define PG8_WAIT_V(n) asm volatile("s_waitcnt vmcnt(" #n ")" ::: "memory")
; #define PG8_WAIT_L(n) asm volatile("s_waitcnt lgkmcnt(" #n ")" ::: "memory")
; #define PG8_BAR __builtin_amdgcn_s_barrier()
; #define PG8_SCHED __builtin_amdgcn_sched_barrier(0)
; template <class Epi, bool ALIGN_EPI>
; __device__ __forceinline__ void gemm_phase(LAS unsigned char* lds, const Gemm g, const StaticOrder& S, const Epi& E) {
;     ...
;             PG8_LDA(At, 1, 1); PG8_STAGE(PG8_SB(1, 0), b3, voffB); PG8_STAGE(PG8_SB(1, 1), b3 + hstep, voffB); PG8_STAGE(PG8_SA(1, 0), a3, voffA);
;             PG8_WAIT_V(8); PG8_WAIT_L(0); PG8_BAR; PG8_MMA(1, 0, At, B0); PG8_MMA(1, 1, At, B1); PG8_BAR; PG8_SCHED;
;         }
;         if constexpr (ALIGN_EPI) { if (wr == 0) PG8_BAR; }
;         E(acc, cur, wr, wc, fr, fq);
;         if (!has_next) break;
	s_add_i32 s10, s63, s33
	v_lshl_add_u64 v[220:221], v[220:221], 0, s[56:57]
	s_mov_b32 m0, s10
	ds_read_b128 v[188:191], v170 offset:49152
	ds_read_b128 v[192:195], v170 offset:50176
	ds_read_b128 v[196:199], v170 offset:51200
	ds_read_b128 v[200:203], v170 offset:52224
	ds_read_b128 v[204:207], v170 offset:53248
	ds_read_b128 v[208:211], v170 offset:54272
	ds_read_b128 v[212:215], v170 offset:55296
	ds_read_b128 v[216:219], v170 offset:56320
	global_load_lds_dwordx4 v[220:221], off
	s_add_i32 m0, s10, 0x2000
	s_add_u32 s8, s8, 0x40080
	v_lshl_add_u64 v[220:221], v[222:223], 0, s[56:57]
	s_addc_u32 s9, s9, 0
	s_add_i32 s10, s84, s33
	global_load_lds_dwordx4 v[220:221], off
	v_lshl_add_u64 v[220:221], s[8:9], 0, v[132:133]
	s_mov_b32 m0, s10
	s_nop 0
	global_load_lds_dwordx4 v[220:221], off
	v_lshl_add_u64 v[220:221], s[8:9], 0, v[136:137]
	s_add_i32 m0, s10, 0x2000
	s_nop 0
	global_load_lds_dwordx4 v[220:221], off
	v_lshl_add_u64 v[220:221], v[224:225], 0, s[56:57]
	s_mov_b32 m0, s78
	s_nop 0
	global_load_lds_dwordx4 v[220:221], off
	v_lshl_add_u64 v[220:221], v[226:227], 0, s[56:57]
	s_mov_b32 m0, s79
	s_nop 0
	global_load_lds_dwordx4 v[220:221], off
	s_waitcnt vmcnt(8)
	s_waitcnt lgkmcnt(0)
	s_barrier
	s_waitcnt lgkmcnt(0)
	v_mfma_f32_16x16x32_bf16 v[62:65], v[146:149], v[188:191], v[62:65]
	v_mfma_f32_16x16x32_bf16 v[54:57], v[154:157], v[188:191], v[54:57]
	v_mfma_f32_16x16x32_bf16 v[46:49], v[146:149], v[196:199], v[46:49]
	v_mfma_f32_16x16x32_bf16 v[38:41], v[154:157], v[196:199], v[38:41]
	v_mfma_f32_16x16x32_bf16 v[30:33], v[146:149], v[204:207], v[30:33]
	v_mfma_f32_16x16x32_bf16 v[22:25], v[154:157], v[204:207], v[22:25]
	v_mfma_f32_16x16x32_bf16 v[14:17], v[146:149], v[212:215], v[14:17]
	v_mfma_f32_16x16x32_bf16 v[6:9], v[154:157], v[212:215], v[6:9]
	v_mfma_f32_16x16x32_bf16 v[62:65], v[150:153], v[192:195], v[62:65]
	v_mfma_f32_16x16x32_bf16 v[54:57], v[158:161], v[192:195], v[54:57]
	v_mfma_f32_16x16x32_bf16 v[46:49], v[150:153], v[200:203], v[46:49]
	v_mfma_f32_16x16x32_bf16 v[38:41], v[158:161], v[200:203], v[38:41]
	v_mfma_f32_16x16x32_bf16 v[30:33], v[150:153], v[208:211], v[30:33]
	v_mfma_f32_16x16x32_bf16 v[22:25], v[158:161], v[208:211], v[22:25]
	v_mfma_f32_16x16x32_bf16 v[14:17], v[150:153], v[216:219], v[14:17]
	v_mfma_f32_16x16x32_bf16 v[6:9], v[158:161], v[216:219], v[6:9]
	v_mfma_f32_16x16x32_bf16 v[58:61], v[172:175], v[188:191], v[58:61]
	v_mfma_f32_16x16x32_bf16 v[50:53], v[180:183], v[188:191], v[50:53]
	v_mfma_f32_16x16x32_bf16 v[42:45], v[172:175], v[196:199], v[42:45]
	v_mfma_f32_16x16x32_bf16 v[34:37], v[180:183], v[196:199], v[34:37]
	v_mfma_f32_16x16x32_bf16 v[26:29], v[172:175], v[204:207], v[26:29]
	v_mfma_f32_16x16x32_bf16 v[18:21], v[180:183], v[204:207], v[18:21]
	v_mfma_f32_16x16x32_bf16 v[10:13], v[172:175], v[212:215], v[10:13]
	v_mfma_f32_16x16x32_bf16 v[2:5], v[180:183], v[212:215], v[2:5]
	v_mfma_f32_16x16x32_bf16 v[58:61], v[176:179], v[192:195], v[58:61]
	v_mfma_f32_16x16x32_bf16 v[50:53], v[184:187], v[192:195], v[50:53]
	v_mfma_f32_16x16x32_bf16 v[42:45], v[176:179], v[200:203], v[42:45]
	v_mfma_f32_16x16x32_bf16 v[34:37], v[184:187], v[200:203], v[34:37]
	v_mfma_f32_16x16x32_bf16 v[26:29], v[176:179], v[208:211], v[26:29]
	v_mfma_f32_16x16x32_bf16 v[18:21], v[184:187], v[208:211], v[18:21]
	v_mfma_f32_16x16x32_bf16 v[10:13], v[176:179], v[216:219], v[10:13]
	v_mfma_f32_16x16x32_bf16 v[2:5], v[184:187], v[216:219], v[2:5]
	s_barrier
	s_add_i32 s61, s61, 2
	s_add_u32 s6, s6, 0x100
	s_addc_u32 s7, s7, 0
	s_add_u32 s16, s16, 0x100
	s_addc_u32 s17, s17, 0
	s_cmp_gt_u32 s61, 13
	s_cbranch_scc0 .LBB0_609
	s_and_b64 vcc, exec, s[58:59]
	s_cbranch_vccz .LBB0_612
	s_barrier

; #define PG8_STAGE(bufoff, gbase, voff) do { _Pragma("unroll") for (int _i = 0; _i < 2; ++_i) \
;         __builtin_amdgcn_global_load_lds((const unsigned*)((const char*)(gbase) + (voff)[_i]), (LAS unsigned*)(lds + (bufoff) + ldsw + _i * 8192), 16, 0, 0); } while (0)
; #define PG8_LDA(dst, b, h) do { _Pragma("unroll") for (int m = 0; m < 4; ++m) _Pragma("unroll") for (int k = 0; k < 2; ++k) dst[m][k] = *(const LAS bf16x8*)(lds + PG8_SA(b, h) + aoff + m * 2048 + k * 1024); } while (0)
; #define PG8_LDB(dst, b, h) do { _Pragma("unroll") for (int n = 0; n < 2; ++n) _Pragma("unroll") for (int k = 0; k < 2; ++k) dst[n][k] = *(const LAS bf16x8*)(lds + PG8_SB(b, h) + boff + n * 2048 + k * 1024); } while (0)
; #define PG8_MMA(ai, bj, At, Bt) do { __builtin_amdgcn_s_setprio(3); _Pragma("unroll") for (int m = 0; m < 4; ++m) _Pragma("unroll") for (int n = 0; n < 2; ++n) _Pragma("unroll") for (int k = 0; k < 2; ++k) \
;         acc[ai][bj][m][n] = __builtin_amdgcn_mfma_f32_16x16x32_bf16(Bt[n][k], At[m][k], acc[ai][bj][m][n], 0, 0, 0); __builtin_amdgcn_s_setprio(0); } while (0)
; #define PG8_WAIT_V(n) asm volatile("s_waitcnt vmcnt(" #n ")" ::: "memory")
; #define PG8_WAIT_L(n) asm volatile("s_waitcnt lgkmcnt(" #n ")" ::: "memory")
; #define PG8_BAR __builtin_amdgcn_s_barrier()
; #define PG8_SCHED __builtin_amdgcn_sched_barrier(0)
; template <class Epi, bool ALIGN_EPI>
; __device__ __forceinline__ void gemm_phase(LAS unsigned char* lds, const Gemm g, const StaticOrder& S, const Epi& E) {
;     ...
;             PG8_LDB(B0, 0, 0); PG8_LDB(B1, 0, 1); PG8_SCHED; PG8_LDA(At, 0, 0); PG8_STAGE(PG8_SA(1, 1), a1 + hstep, voffA);
;             PG8_WAIT_V(8); PG8_WAIT_L(0); PG8_BAR; PG8_MMA(0, 0, At, B0); PG8_MMA(0, 1, At, B1); PG8_BAR; PG8_SCHED;
;             PG8_LDA(At, 0, 1); PG8_STAGE(PG8_SB(0, 0), b2, voffB); PG8_STAGE(PG8_SB(0, 1), b2 + hstep, voffB); PG8_STAGE(PG8_SA(0, 0), a2, voffA);
;             PG8_WAIT_V(8); PG8_WAIT_L(0); PG8_BAR; PG8_MMA(1, 0, At, B0); PG8_MMA(1, 1, At, B1); PG8_BAR; PG8_SCHED;
.Lmy_rw_696_0:
	s_waitcnt lgkmcnt(0)
	s_barrier
	s_waitcnt lgkmcnt(0)
	v_mfma_f32_16x16x32_bf16 v[126:129], v[130:133], v[178:181], 0
	v_mfma_f32_16x16x32_bf16 v[122:125], v[138:141], v[178:181], 0
	v_mfma_f32_16x16x32_bf16 v[110:113], v[130:133], v[200:203], 0
	v_mfma_f32_16x16x32_bf16 v[106:109], v[138:141], v[200:203], 0
	v_mfma_f32_16x16x32_bf16 v[94:97], v[130:133], v[208:211], 0
	v_mfma_f32_16x16x32_bf16 v[90:93], v[138:141], v[208:211], 0
	v_mfma_f32_16x16x32_bf16 v[78:81], v[130:133], v[216:219], 0
	v_mfma_f32_16x16x32_bf16 v[74:77], v[138:141], v[216:219], 0
	v_mfma_f32_16x16x32_bf16 v[126:129], v[134:137], v[182:185], v[126:129]
	v_mfma_f32_16x16x32_bf16 v[122:125], v[142:145], v[182:185], v[122:125]
	v_mfma_f32_16x16x32_bf16 v[110:113], v[134:137], v[204:207], v[110:113]
	v_mfma_f32_16x16x32_bf16 v[106:109], v[142:145], v[204:207], v[106:109]
	v_mfma_f32_16x16x32_bf16 v[94:97], v[134:137], v[212:215], v[94:97]
	v_mfma_f32_16x16x32_bf16 v[90:93], v[142:145], v[212:215], v[90:93]
	v_mfma_f32_16x16x32_bf16 v[78:81], v[134:137], v[220:223], v[78:81]
	v_mfma_f32_16x16x32_bf16 v[74:77], v[142:145], v[220:223], v[74:77]
	v_mfma_f32_16x16x32_bf16 v[118:121], v[146:149], v[178:181], 0
	v_mfma_f32_16x16x32_bf16 v[114:117], v[170:173], v[178:181], 0
	v_mfma_f32_16x16x32_bf16 v[102:105], v[146:149], v[200:203], 0
	v_mfma_f32_16x16x32_bf16 v[98:101], v[170:173], v[200:203], 0
	v_mfma_f32_16x16x32_bf16 v[86:89], v[146:149], v[208:211], 0
	v_mfma_f32_16x16x32_bf16 v[82:85], v[170:173], v[208:211], 0
	v_mfma_f32_16x16x32_bf16 v[70:73], v[146:149], v[216:219], 0
	v_mfma_f32_16x16x32_bf16 v[66:69], v[170:173], v[216:219], 0
	v_mfma_f32_16x16x32_bf16 v[118:121], v[150:153], v[182:185], v[118:121]
	v_mfma_f32_16x16x32_bf16 v[114:117], v[174:177], v[182:185], v[114:117]
	v_mfma_f32_16x16x32_bf16 v[102:105], v[150:153], v[204:207], v[102:105]
	v_mfma_f32_16x16x32_bf16 v[98:101], v[174:177], v[204:207], v[98:101]
	v_mfma_f32_16x16x32_bf16 v[86:89], v[150:153], v[212:215], v[86:89]
	v_mfma_f32_16x16x32_bf16 v[82:85], v[174:177], v[212:215], v[82:85]
	v_mfma_f32_16x16x32_bf16 v[70:73], v[150:153], v[220:223], v[70:73]
	v_mfma_f32_16x16x32_bf16 v[66:69], v[174:177], v[220:223], v[66:69]
	s_barrier
	s_add_i32 s78, s67, s57
	v_lshl_add_u64 v[186:187], s[52:53], 0, v[156:157]
	s_mov_b32 m0, s78
	ds_read_b128 v[178:181], v198 offset:16384
	ds_read_b128 v[182:185], v198 offset:17408
	ds_read_b128 v[200:203], v198 offset:18432
	ds_read_b128 v[204:207], v198 offset:19456
	ds_read_b128 v[208:211], v198 offset:20480
	ds_read_b128 v[212:215], v198 offset:21504
	ds_read_b128 v[216:219], v198 offset:22528
	ds_read_b128 v[220:223], v198 offset:23552
	global_load_lds_dwordx4 v[186:187], off
	s_add_i32 m0, s78, 0x2000
	s_add_u32 s78, s52, 0xb0000
	v_lshl_add_u64 v[224:225], s[52:53], 0, v[160:161]
	s_addc_u32 s79, s53, 0
	s_add_i32 s80, s68, s57
	global_load_lds_dwordx4 v[224:225], off
	v_lshl_add_u64 v[226:227], s[78:79], 0, v[156:157]
	s_mov_b32 m0, s80
	v_lshl_add_u64 v[228:229], s[54:55], 0, v[158:159]
	global_load_lds_dwordx4 v[226:227], off
	v_lshl_add_u64 v[226:227], s[78:79], 0, v[160:161]
	s_add_i32 m0, s80, 0x2000
	s_nop 0
	global_load_lds_dwordx4 v[226:227], off
	v_lshl_add_u64 v[226:227], s[54:55], 0, v[154:155]
	s_mov_b32 m0, s58
	s_nop 0
	global_load_lds_dwordx4 v[226:227], off
	s_mov_b32 m0, s59
	s_nop 0
	global_load_lds_dwordx4 v[228:229], off
	s_cmp_lg_u32 s98, 0
	s_cbranch_scc1 .Lmy_rw_696_1
	s_waitcnt vmcnt(8)
.Lmy_rw_696_1:
	s_waitcnt lgkmcnt(0)
	s_barrier
	s_waitcnt lgkmcnt(0)
	v_mfma_f32_16x16x32_bf16 v[62:65], v[130:133], v[178:181], 0
	v_mfma_f32_16x16x32_bf16 v[58:61], v[138:141], v[178:181], 0
	v_mfma_f32_16x16x32_bf16 v[46:49], v[130:133], v[200:203], 0
	v_mfma_f32_16x16x32_bf16 v[42:45], v[138:141], v[200:203], 0
	v_mfma_f32_16x16x32_bf16 v[30:33], v[130:133], v[208:211], 0
	v_mfma_f32_16x16x32_bf16 v[26:29], v[138:141], v[208:211], 0
	v_mfma_f32_16x16x32_bf16 v[14:17], v[130:133], v[216:219], 0
	v_mfma_f32_16x16x32_bf16 v[10:13], v[138:141], v[216:219], 0
	v_mfma_f32_16x16x32_bf16 v[62:65], v[134:137], v[182:185], v[62:65]
	v_mfma_f32_16x16x32_bf16 v[58:61], v[142:145], v[182:185], v[58:61]
	v_mfma_f32_16x16x32_bf16 v[46:49], v[134:137], v[204:207], v[46:49]
	v_mfma_f32_16x16x32_bf16 v[42:45], v[142:145], v[204:207], v[42:45]
	v_mfma_f32_16x16x32_bf16 v[30:33], v[134:137], v[212:215], v[30:33]
	v_mfma_f32_16x16x32_bf16 v[26:29], v[142:145], v[212:215], v[26:29]
	v_mfma_f32_16x16x32_bf16 v[14:17], v[134:137], v[220:223], v[14:17]
	v_mfma_f32_16x16x32_bf16 v[10:13], v[142:145], v[220:223], v[10:13]
	v_mfma_f32_16x16x32_bf16 v[54:57], v[146:149], v[178:181], 0
	v_mfma_f32_16x16x32_bf16 v[50:53], v[170:173], v[178:181], 0
	v_mfma_f32_16x16x32_bf16 v[38:41], v[146:149], v[200:203], 0
	v_mfma_f32_16x16x32_bf16 v[34:37], v[170:173], v[200:203], 0
	v_mfma_f32_16x16x32_bf16 v[22:25], v[146:149], v[208:211], 0
	v_mfma_f32_16x16x32_bf16 v[18:21], v[170:173], v[208:211], 0
	v_mfma_f32_16x16x32_bf16 v[6:9], v[146:149], v[216:219], 0
	v_mfma_f32_16x16x32_bf16 v[2:5], v[170:173], v[216:219], 0
	v_mfma_f32_16x16x32_bf16 v[54:57], v[150:153], v[182:185], v[54:57]
	v_mfma_f32_16x16x32_bf16 v[50:53], v[174:177], v[182:185], v[50:53]
	v_mfma_f32_16x16x32_bf16 v[38:41], v[150:153], v[204:207], v[38:41]
	v_mfma_f32_16x16x32_bf16 v[34:37], v[174:177], v[204:207], v[34:37]
	v_mfma_f32_16x16x32_bf16 v[22:25], v[150:153], v[212:215], v[22:25]
	v_mfma_f32_16x16x32_bf16 v[18:21], v[174:177], v[212:215], v[18:21]
	v_mfma_f32_16x16x32_bf16 v[6:9], v[150:153], v[220:223], v[6:9]
	v_mfma_f32_16x16x32_bf16 v[2:5], v[174:177], v[220:223], v[2:5]
	s_barrier
; #define PG8_STAGE(bufoff, gbase, voff) do { _Pragma("unroll") for (int _i = 0; _i < 2; ++_i) \
;         __builtin_amdgcn_global_load_lds((const unsigned*)((const char*)(gbase) + (voff)[_i]), (LAS unsigned*)(lds + (bufoff) + ldsw + _i * 8192), 16, 0, 0); } while (0)
; #define PG8_LDA(dst, b, h) do { _Pragma("unroll") for (int m = 0; m < 4; ++m) _Pragma("unroll") for (int k = 0; k < 2; ++k) dst[m][k] = *(const LAS bf16x8*)(lds + PG8_SA(b, h) + aoff + m * 2048 + k * 1024); } while (0)
; #define PG8_LDB(dst, b, h) do { _Pragma("unroll") for (int n = 0; n < 2; ++n) _Pragma("unroll") for (int k = 0; k < 2; ++k) dst[n][k] = *(const LAS bf16x8*)(lds + PG8_SB(b, h) + boff + n * 2048 + k * 1024); } while (0)
; #define PG8_MMA(ai, bj, At, Bt) do { __builtin_amdgcn_s_setprio(3); _Pragma("unroll") for (int m = 0; m < 4; ++m) _Pragma("unroll") for (int n = 0; n < 2; ++n) _Pragma("unroll") for (int k = 0; k < 2; ++k) \
;         acc[ai][bj][m][n] = __builtin_amdgcn_mfma_f32_16x16x32_bf16(Bt[n][k], At[m][k], acc[ai][bj][m][n], 0, 0, 0); __builtin_amdgcn_s_setprio(0); } while (0)
; #define PG8_WAIT_V(n) asm volatile("s_waitcnt vmcnt(" #n ")" ::: "memory")
; #define PG8_WAIT_L(n) asm volatile("s_waitcnt lgkmcnt(" #n ")" ::: "memory")
; #define PG8_BAR __builtin_amdgcn_s_barrier()
; #define PG8_SCHED __builtin_amdgcn_sched_barrier(0)
; template <class Epi, bool ALIGN_EPI>
; __device__ __forceinline__ void gemm_phase(LAS unsigned char* lds, const Gemm g, const StaticOrder& S, const Epi& E) {
;     ...
;             PG8_LDB(B0, 1, 0); PG8_LDB(B1, 1, 1); PG8_SCHED; PG8_LDA(At, 1, 0); PG8_STAGE(PG8_SA(0, 1), a2 + hstep, voffA);
;             PG8_WAIT_V(8); PG8_WAIT_L(0); PG8_BAR; PG8_MMA(0, 0, At, B0); PG8_MMA(0, 1, At, B1); PG8_BAR; PG8_SCHED;
;             PG8_LDA(At, 1, 1); PG8_STAGE(PG8_SB(1, 0), b3, voffB); PG8_STAGE(PG8_SB(1, 1), b3 + hstep, voffB); PG8_STAGE(PG8_SA(1, 0), a3, voffA);
;             PG8_WAIT_V(8); PG8_WAIT_L(0); PG8_BAR; PG8_MMA(1, 0, At, B0); PG8_MMA(1, 1, At, B1); PG8_BAR; PG8_SCHED;
	s_add_i32 s78, 0, 0x18000
	s_add_i32 s79, 0, 0x1c000
	v_add_u32_e32 v142, s78, v194
	v_add_u32_e32 v174, s79, v194
	ds_read_b128 v[130:133], v142
	ds_read_b128 v[134:137], v142 offset:1024
	ds_read_b128 v[138:141], v142 offset:2048
	ds_read_b128 v[142:145], v142 offset:3072
	ds_read_b128 v[146:149], v174
	ds_read_b128 v[150:153], v174 offset:1024
	ds_read_b128 v[170:173], v174 offset:2048
	ds_read_b128 v[174:177], v174 offset:3072
	s_add_u32 s54, s54, 0xb0000
	s_addc_u32 s55, s55, 0
	s_mov_b32 m0, s60
	v_lshl_add_u64 v[230:231], s[54:55], 0, v[154:155]
	ds_read_b128 v[178:181], v198 offset:32768
	ds_read_b128 v[182:185], v198 offset:33792
	ds_read_b128 v[200:203], v198 offset:34816
	ds_read_b128 v[204:207], v198 offset:35840
	ds_read_b128 v[208:211], v198 offset:36864
	ds_read_b128 v[212:215], v198 offset:37888
	ds_read_b128 v[216:219], v198 offset:38912
	ds_read_b128 v[220:223], v198 offset:39936
	global_load_lds_dwordx4 v[230:231], off
	v_lshl_add_u64 v[230:231], s[54:55], 0, v[158:159]
	s_mov_b32 m0, s61
	s_nop 0
	global_load_lds_dwordx4 v[230:231], off
	s_waitcnt vmcnt(8)
	s_waitcnt lgkmcnt(0)
	s_barrier
	s_waitcnt lgkmcnt(0)
	v_mfma_f32_16x16x32_bf16 v[126:129], v[130:133], v[178:181], v[126:129]
	v_mfma_f32_16x16x32_bf16 v[122:125], v[138:141], v[178:181], v[122:125]
	v_mfma_f32_16x16x32_bf16 v[110:113], v[130:133], v[200:203], v[110:113]
	v_mfma_f32_16x16x32_bf16 v[106:109], v[138:141], v[200:203], v[106:109]
	v_mfma_f32_16x16x32_bf16 v[94:97], v[130:133], v[208:211], v[94:97]
	v_mfma_f32_16x16x32_bf16 v[90:93], v[138:141], v[208:211], v[90:93]
	v_mfma_f32_16x16x32_bf16 v[78:81], v[130:133], v[216:219], v[78:81]
	v_mfma_f32_16x16x32_bf16 v[74:77], v[138:141], v[216:219], v[74:77]
	v_mfma_f32_16x16x32_bf16 v[126:129], v[134:137], v[182:185], v[126:129]
	v_mfma_f32_16x16x32_bf16 v[122:125], v[142:145], v[182:185], v[122:125]
	v_mfma_f32_16x16x32_bf16 v[110:113], v[134:137], v[204:207], v[110:113]
	v_mfma_f32_16x16x32_bf16 v[106:109], v[142:145], v[204:207], v[106:109]
	v_mfma_f32_16x16x32_bf16 v[94:97], v[134:137], v[212:215], v[94:97]
	v_mfma_f32_16x16x32_bf16 v[90:93], v[142:145], v[212:215], v[90:93]
	v_mfma_f32_16x16x32_bf16 v[78:81], v[134:137], v[220:223], v[78:81]
	v_mfma_f32_16x16x32_bf16 v[74:77], v[142:145], v[220:223], v[74:77]
	v_mfma_f32_16x16x32_bf16 v[118:121], v[146:149], v[178:181], v[118:121]
	v_mfma_f32_16x16x32_bf16 v[114:117], v[170:173], v[178:181], v[114:117]
	v_mfma_f32_16x16x32_bf16 v[102:105], v[146:149], v[200:203], v[102:105]
	v_mfma_f32_16x16x32_bf16 v[98:101], v[170:173], v[200:203], v[98:101]
	v_mfma_f32_16x16x32_bf16 v[86:89], v[146:149], v[208:211], v[86:89]
	v_mfma_f32_16x16x32_bf16 v[82:85], v[170:173], v[208:211], v[82:85]
	v_mfma_f32_16x16x32_bf16 v[70:73], v[146:149], v[216:219], v[70:73]
	v_mfma_f32_16x16x32_bf16 v[66:69], v[170:173], v[216:219], v[66:69]
	v_mfma_f32_16x16x32_bf16 v[118:121], v[150:153], v[182:185], v[118:121]
	v_mfma_f32_16x16x32_bf16 v[114:117], v[174:177], v[182:185], v[114:117]
	v_mfma_f32_16x16x32_bf16 v[102:105], v[150:153], v[204:207], v[102:105]
	v_mfma_f32_16x16x32_bf16 v[98:101], v[174:177], v[204:207], v[98:101]
	v_mfma_f32_16x16x32_bf16 v[86:89], v[150:153], v[212:215], v[86:89]
	v_mfma_f32_16x16x32_bf16 v[82:85], v[174:177], v[212:215], v[82:85]
	v_mfma_f32_16x16x32_bf16 v[70:73], v[150:153], v[220:223], v[70:73]
	v_mfma_f32_16x16x32_bf16 v[66:69], v[174:177], v[220:223], v[66:69]
	s_barrier
	s_add_i32 s54, s78, s57
	v_lshl_add_u64 v[186:187], v[186:187], 0, s[14:15]
	s_mov_b32 m0, s54
	ds_read_b128 v[178:181], v198 offset:49152
	ds_read_b128 v[182:185], v198 offset:50176
	ds_read_b128 v[200:203], v198 offset:51200
	ds_read_b128 v[204:207], v198 offset:52224
	ds_read_b128 v[208:211], v198 offset:53248
	ds_read_b128 v[212:215], v198 offset:54272
	ds_read_b128 v[216:219], v198 offset:55296
	ds_read_b128 v[220:223], v198 offset:56320
	global_load_lds_dwordx4 v[186:187], off
	s_add_i32 m0, s54, 0x2000
	s_add_u32 s52, s52, 0xb0080
	v_lshl_add_u64 v[186:187], v[224:225], 0, s[14:15]
	s_addc_u32 s53, s53, 0
	s_add_i32 s54, s79, s57
	global_load_lds_dwordx4 v[186:187], off
	v_lshl_add_u64 v[186:187], s[52:53], 0, v[156:157]
	s_mov_b32 m0, s54
	s_nop 0
	global_load_lds_dwordx4 v[186:187], off
	v_lshl_add_u64 v[186:187], s[52:53], 0, v[160:161]
	s_add_i32 m0, s54, 0x2000
	s_nop 0
	global_load_lds_dwordx4 v[186:187], off
	v_lshl_add_u64 v[186:187], v[226:227], 0, s[14:15]
	s_mov_b32 m0, s63
	s_nop 0
	global_load_lds_dwordx4 v[186:187], off
	v_lshl_add_u64 v[186:187], v[228:229], 0, s[14:15]
	s_mov_b32 m0, s64
	s_nop 0
	global_load_lds_dwordx4 v[186:187], off
	s_waitcnt vmcnt(8)
	s_waitcnt lgkmcnt(0)
	s_barrier
	s_waitcnt lgkmcnt(0)
	v_mfma_f32_16x16x32_bf16 v[62:65], v[130:133], v[178:181], v[62:65]
	v_mfma_f32_16x16x32_bf16 v[58:61], v[138:141], v[178:181], v[58:61]
	v_mfma_f32_16x16x32_bf16 v[46:49], v[130:133], v[200:203], v[46:49]
	v_mfma_f32_16x16x32_bf16 v[42:45], v[138:141], v[200:203], v[42:45]
	v_mfma_f32_16x16x32_bf16 v[30:33], v[130:133], v[208:211], v[30:33]
	v_mfma_f32_16x16x32_bf16 v[26:29], v[138:141], v[208:211], v[26:29]
	v_mfma_f32_16x16x32_bf16 v[14:17], v[130:133], v[216:219], v[14:17]
	v_mfma_f32_16x16x32_bf16 v[10:13], v[138:141], v[216:219], v[10:13]
	v_mfma_f32_16x16x32_bf16 v[62:65], v[134:137], v[182:185], v[62:65]
	v_mfma_f32_16x16x32_bf16 v[58:61], v[142:145], v[182:185], v[58:61]
	v_mfma_f32_16x16x32_bf16 v[46:49], v[134:137], v[204:207], v[46:49]
	v_mfma_f32_16x16x32_bf16 v[42:45], v[142:145], v[204:207], v[42:45]
	v_mfma_f32_16x16x32_bf16 v[30:33], v[134:137], v[212:215], v[30:33]
	v_mfma_f32_16x16x32_bf16 v[26:29], v[142:145], v[212:215], v[26:29]
	v_mfma_f32_16x16x32_bf16 v[14:17], v[134:137], v[220:223], v[14:17]
	v_mfma_f32_16x16x32_bf16 v[10:13], v[142:145], v[220:223], v[10:13]
	v_mfma_f32_16x16x32_bf16 v[54:57], v[146:149], v[178:181], v[54:57]
	v_mfma_f32_16x16x32_bf16 v[50:53], v[170:173], v[178:181], v[50:53]
	v_mfma_f32_16x16x32_bf16 v[38:41], v[146:149], v[200:203], v[38:41]
	v_mfma_f32_16x16x32_bf16 v[34:37], v[170:173], v[200:203], v[34:37]
	v_mfma_f32_16x16x32_bf16 v[22:25], v[146:149], v[208:211], v[22:25]
	v_mfma_f32_16x16x32_bf16 v[18:21], v[170:173], v[208:211], v[18:21]
	v_mfma_f32_16x16x32_bf16 v[6:9], v[146:149], v[216:219], v[6:9]
	v_mfma_f32_16x16x32_bf16 v[2:5], v[170:173], v[216:219], v[2:5]
	v_mfma_f32_16x16x32_bf16 v[54:57], v[150:153], v[182:185], v[54:57]
	v_mfma_f32_16x16x32_bf16 v[50:53], v[174:177], v[182:185], v[50:53]
	v_mfma_f32_16x16x32_bf16 v[38:41], v[150:153], v[204:207], v[38:41]
	v_mfma_f32_16x16x32_bf16 v[34:37], v[174:177], v[204:207], v[34:37]
	v_mfma_f32_16x16x32_bf16 v[22:25], v[150:153], v[212:215], v[22:25]
	v_mfma_f32_16x16x32_bf16 v[18:21], v[174:177], v[212:215], v[18:21]
	v_mfma_f32_16x16x32_bf16 v[6:9], v[150:153], v[220:223], v[6:9]
	v_mfma_f32_16x16x32_bf16 v[2:5], v[174:177], v[220:223], v[2:5]
	s_barrier
	s_add_i32 s77, s77, 2
	s_add_u32 s50, s50, 0x100
	s_addc_u32 s51, s51, 0
	s_add_u32 s73, s73, 0x100
	s_addc_u32 s76, s76, 0
; #define PG8_STAGE(bufoff, gbase, voff) do { _Pragma("unroll") for (int _i = 0; _i < 2; ++_i) \
;         __builtin_amdgcn_global_load_lds((const unsigned*)((const char*)(gbase) + (voff)[_i]), (LAS unsigned*)(lds + (bufoff) + ldsw + _i * 8192), 16, 0, 0); } while (0)
; #define PG8_LDA(dst, b, h) do { _Pragma("unroll") for (int m = 0; m < 4; ++m) _Pragma("unroll") for (int k = 0; k < 2; ++k) dst[m][k] = *(const LAS bf16x8*)(lds + PG8_SA(b, h) + aoff + m * 2048 + k * 1024); } while (0)
; #define PG8_LDB(dst, b, h) do { _Pragma("unroll") for (int n = 0; n < 2; ++n) _Pragma("unroll") for (int k = 0; k < 2; ++k) dst[n][k] = *(const LAS bf16x8*)(lds + PG8_SB(b, h) + boff + n * 2048 + k * 1024); } while (0)
; #define PG8_MMA(ai, bj, At, Bt) do { __builtin_amdgcn_s_setprio(3); _Pragma("unroll") for (int m = 0; m < 4; ++m) _Pragma("unroll") for (int n = 0; n < 2; ++n) _Pragma("unroll") for (int k = 0; k < 2; ++k) \
;         acc[ai][bj][m][n] = __builtin_amdgcn_mfma_f32_16x16x32_bf16(Bt[n][k], At[m][k], acc[ai][bj][m][n], 0, 0, 0); __builtin_amdgcn_s_setprio(0); } while (0)
; #define PG8_WAIT_V(n) asm volatile("s_waitcnt vmcnt(" #n ")" ::: "memory")
; #define PG8_WAIT_L(n) asm volatile("s_waitcnt lgkmcnt(" #n ")" ::: "memory")
; #define PG8_BAR __builtin_amdgcn_s_barrier()
; #define PG8_SCHED __builtin_amdgcn_sched_barrier(0)
; template <class Epi, bool ALIGN_EPI>
; __device__ __forceinline__ void gemm_phase(LAS unsigned char* lds, const Gemm g, const StaticOrder& S, const Epi& E) {
;     ...
;             const bool last = (t == nt - 2);
;             const char* a1 = cA + (size_t)(t + 1) * kstep;
;             const char* a2 = last ? nA : cA + (size_t)(t + 2) * kstep; const char* b2 = last ? nB : cB + (size_t)(t + 2) * kstep;
;             const char* a3 = a2 + kstep; const char* b3 = b2 + kstep;
;             PG8_LDB(B0, 0, 0); PG8_LDB(B1, 0, 1); PG8_SCHED; PG8_LDA(At, 0, 0); PG8_STAGE(PG8_SA(1, 1), a1 + hstep, voffA);
;             PG8_WAIT_V(8); PG8_WAIT_L(0); PG8_BAR; PG8_MMA(0, 0, At, B0); PG8_MMA(0, 1, At, B1); PG8_BAR; PG8_SCHED;
;             PG8_LDA(At, 0, 1); PG8_STAGE(PG8_SB(0, 0), b2, voffB); PG8_STAGE(PG8_SB(0, 1), b2 + hstep, voffB); PG8_STAGE(PG8_SA(0, 0), a2, voffA);
.LBB0_696:
	ds_read_b128 v[130:133], v196
	ds_read_b128 v[134:137], v196 offset:1024
	ds_read_b128 v[138:141], v196 offset:2048
	ds_read_b128 v[142:145], v196 offset:3072
	ds_read_b128 v[146:149], v197
	ds_read_b128 v[150:153], v197 offset:1024
	ds_read_b128 v[170:173], v197 offset:2048
	ds_read_b128 v[174:177], v197 offset:3072
	s_add_u32 s52, s50, 0xfff50080
	s_addc_u32 s53, s51, -1
	s_cmp_eq_u32 s77, 40
	s_cselect_b32 s55, s5, s53
	s_cselect_b32 s54, s4, s52
	s_cselect_b32 s53, s19, s76
	s_cselect_b32 s52, s18, s73
	v_lshl_add_u64 v[186:187], s[50:51], 0, v[162:163]
	s_add_i32 m0, s58, 0xc000
	ds_read_b128 v[178:181], v198
	ds_read_b128 v[182:185], v198 offset:1024
	ds_read_b128 v[200:203], v198 offset:2048
	ds_read_b128 v[204:207], v198 offset:3072
	ds_read_b128 v[208:211], v198 offset:4096
	ds_read_b128 v[212:215], v198 offset:5120
	ds_read_b128 v[216:219], v198 offset:6144
	ds_read_b128 v[220:223], v198 offset:7168
	global_load_lds_dwordx4 v[186:187], off
	v_lshl_add_u64 v[186:187], s[50:51], 0, v[164:165]
	s_add_i32 m0, s58, 0xe000
	s_nop 0
	global_load_lds_dwordx4 v[186:187], off
	s_waitcnt vmcnt(8)
	s_waitcnt lgkmcnt(0)
	s_barrier
	s_waitcnt lgkmcnt(0)
	v_mfma_f32_16x16x32_bf16 v[126:129], v[130:133], v[178:181], v[126:129]
	v_mfma_f32_16x16x32_bf16 v[122:125], v[138:141], v[178:181], v[122:125]
	v_mfma_f32_16x16x32_bf16 v[110:113], v[130:133], v[200:203], v[110:113]
	v_mfma_f32_16x16x32_bf16 v[106:109], v[138:141], v[200:203], v[106:109]
	v_mfma_f32_16x16x32_bf16 v[94:97], v[130:133], v[208:211], v[94:97]
	v_mfma_f32_16x16x32_bf16 v[90:93], v[138:141], v[208:211], v[90:93]
	v_mfma_f32_16x16x32_bf16 v[78:81], v[130:133], v[216:219], v[78:81]
	v_mfma_f32_16x16x32_bf16 v[74:77], v[138:141], v[216:219], v[74:77]
	v_mfma_f32_16x16x32_bf16 v[126:129], v[134:137], v[182:185], v[126:129]
	v_mfma_f32_16x16x32_bf16 v[122:125], v[142:145], v[182:185], v[122:125]
	v_mfma_f32_16x16x32_bf16 v[110:113], v[134:137], v[204:207], v[110:113]
	v_mfma_f32_16x16x32_bf16 v[106:109], v[142:145], v[204:207], v[106:109]
	v_mfma_f32_16x16x32_bf16 v[94:97], v[134:137], v[212:215], v[94:97]
	v_mfma_f32_16x16x32_bf16 v[90:93], v[142:145], v[212:215], v[90:93]
	v_mfma_f32_16x16x32_bf16 v[78:81], v[134:137], v[220:223], v[78:81]
	v_mfma_f32_16x16x32_bf16 v[74:77], v[142:145], v[220:223], v[74:77]
	v_mfma_f32_16x16x32_bf16 v[118:121], v[146:149], v[178:181], v[118:121]
	v_mfma_f32_16x16x32_bf16 v[114:117], v[170:173], v[178:181], v[114:117]
	v_mfma_f32_16x16x32_bf16 v[102:105], v[146:149], v[200:203], v[102:105]
	v_mfma_f32_16x16x32_bf16 v[98:101], v[170:173], v[200:203], v[98:101]
	v_mfma_f32_16x16x32_bf16 v[86:89], v[146:149], v[208:211], v[86:89]
	v_mfma_f32_16x16x32_bf16 v[82:85], v[170:173], v[208:211], v[82:85]
	v_mfma_f32_16x16x32_bf16 v[70:73], v[146:149], v[216:219], v[70:73]
	v_mfma_f32_16x16x32_bf16 v[66:69], v[170:173], v[216:219], v[66:69]
	v_mfma_f32_16x16x32_bf16 v[118:121], v[150:153], v[182:185], v[118:121]
	v_mfma_f32_16x16x32_bf16 v[114:117], v[174:177], v[182:185], v[114:117]
	v_mfma_f32_16x16x32_bf16 v[102:105], v[150:153], v[204:207], v[102:105]
	v_mfma_f32_16x16x32_bf16 v[98:101], v[174:177], v[204:207], v[98:101]
	v_mfma_f32_16x16x32_bf16 v[86:89], v[150:153], v[212:215], v[86:89]
	v_mfma_f32_16x16x32_bf16 v[82:85], v[174:177], v[212:215], v[82:85]
	v_mfma_f32_16x16x32_bf16 v[70:73], v[150:153], v[220:223], v[70:73]
	v_mfma_f32_16x16x32_bf16 v[66:69], v[174:177], v[220:223], v[66:69]
	s_barrier
	s_add_i32 s78, s67, s57
	v_lshl_add_u64 v[186:187], s[52:53], 0, v[156:157]
	s_mov_b32 m0, s78
	ds_read_b128 v[178:181], v198 offset:16384
	ds_read_b128 v[182:185], v198 offset:17408
	ds_read_b128 v[200:203], v198 offset:18432
	ds_read_b128 v[204:207], v198 offset:19456
	ds_read_b128 v[208:211], v198 offset:20480
	ds_read_b128 v[212:215], v198 offset:21504
	ds_read_b128 v[216:219], v198 offset:22528
	ds_read_b128 v[220:223], v198 offset:23552
	global_load_lds_dwordx4 v[186:187], off
	s_add_i32 m0, s78, 0x2000
	s_add_u32 s78, s52, 0xb0000
	v_lshl_add_u64 v[224:225], s[52:53], 0, v[160:161]
	s_addc_u32 s79, s53, 0
	s_add_i32 s80, s68, s57
	global_load_lds_dwordx4 v[224:225], off
	v_lshl_add_u64 v[226:227], s[78:79], 0, v[156:157]
	s_mov_b32 m0, s80
	v_lshl_add_u64 v[228:229], s[54:55], 0, v[158:159]
	global_load_lds_dwordx4 v[226:227], off
	v_lshl_add_u64 v[226:227], s[78:79], 0, v[160:161]
	s_add_i32 m0, s80, 0x2000
	s_nop 0
	global_load_lds_dwordx4 v[226:227], off
	v_lshl_add_u64 v[226:227], s[54:55], 0, v[154:155]
	s_mov_b32 m0, s58
	s_nop 0
	global_load_lds_dwordx4 v[226:227], off
	s_mov_b32 m0, s59
	s_nop 0
	global_load_lds_dwordx4 v[228:229], off
	s_waitcnt vmcnt(8)
	s_waitcnt lgkmcnt(0)
	s_barrier
; #define PG8_STAGE(bufoff, gbase, voff) do { _Pragma("unroll") for (int _i = 0; _i < 2; ++_i) \
;         __builtin_amdgcn_global_load_lds((const unsigned*)((const char*)(gbase) + (voff)[_i]), (LAS unsigned*)(lds + (bufoff) + ldsw + _i * 8192), 16, 0, 0); } while (0)
; #define PG8_LDA(dst, b, h) do { _Pragma("unroll") for (int m = 0; m < 4; ++m) _Pragma("unroll") for (int k = 0; k < 2; ++k) dst[m][k] = *(const LAS bf16x8*)(lds + PG8_SA(b, h) + aoff + m * 2048 + k * 1024); } while (0)
; #define PG8_LDB(dst, b, h) do { _Pragma("unroll") for (int n = 0; n < 2; ++n) _Pragma("unroll") for (int k = 0; k < 2; ++k) dst[n][k] = *(const LAS bf16x8*)(lds + PG8_SB(b, h) + boff + n * 2048 + k * 1024); } while (0)
; #define PG8_MMA(ai, bj, At, Bt) do { __builtin_amdgcn_s_setprio(3); _Pragma("unroll") for (int m = 0; m < 4; ++m) _Pragma("unroll") for (int n = 0; n < 2; ++n) _Pragma("unroll") for (int k = 0; k < 2; ++k) \
;         acc[ai][bj][m][n] = __builtin_amdgcn_mfma_f32_16x16x32_bf16(Bt[n][k], At[m][k], acc[ai][bj][m][n], 0, 0, 0); __builtin_amdgcn_s_setprio(0); } while (0)
; #define PG8_WAIT_V(n) asm volatile("s_waitcnt vmcnt(" #n ")" ::: "memory")
; #define PG8_WAIT_L(n) asm volatile("s_waitcnt lgkmcnt(" #n ")" ::: "memory")
; #define PG8_BAR __builtin_amdgcn_s_barrier()
; #define PG8_SCHED __builtin_amdgcn_sched_barrier(0)
; template <class Epi, bool ALIGN_EPI>
; __device__ __forceinline__ void gemm_phase(LAS unsigned char* lds, const Gemm g, const StaticOrder& S, const Epi& E) {
;     ...
;             PG8_WAIT_V(8); PG8_WAIT_L(0); PG8_BAR; PG8_MMA(1, 0, At, B0); PG8_MMA(1, 1, At, B1); PG8_BAR; PG8_SCHED;
;             PG8_LDB(B0, 1, 0); PG8_LDB(B1, 1, 1); PG8_SCHED; PG8_LDA(At, 1, 0); PG8_STAGE(PG8_SA(0, 1), a2 + hstep, voffA);
;             PG8_WAIT_V(8); PG8_WAIT_L(0); PG8_BAR; PG8_MMA(0, 0, At, B0); PG8_MMA(0, 1, At, B1); PG8_BAR; PG8_SCHED;
	s_waitcnt lgkmcnt(0)
	v_mfma_f32_16x16x32_bf16 v[62:65], v[130:133], v[178:181], v[62:65]
	v_mfma_f32_16x16x32_bf16 v[58:61], v[138:141], v[178:181], v[58:61]
	v_mfma_f32_16x16x32_bf16 v[46:49], v[130:133], v[200:203], v[46:49]
	v_mfma_f32_16x16x32_bf16 v[42:45], v[138:141], v[200:203], v[42:45]
	v_mfma_f32_16x16x32_bf16 v[30:33], v[130:133], v[208:211], v[30:33]
	v_mfma_f32_16x16x32_bf16 v[26:29], v[138:141], v[208:211], v[26:29]
	v_mfma_f32_16x16x32_bf16 v[14:17], v[130:133], v[216:219], v[14:17]
	v_mfma_f32_16x16x32_bf16 v[10:13], v[138:141], v[216:219], v[10:13]
	v_mfma_f32_16x16x32_bf16 v[62:65], v[134:137], v[182:185], v[62:65]
	v_mfma_f32_16x16x32_bf16 v[58:61], v[142:145], v[182:185], v[58:61]
	v_mfma_f32_16x16x32_bf16 v[46:49], v[134:137], v[204:207], v[46:49]
	v_mfma_f32_16x16x32_bf16 v[42:45], v[142:145], v[204:207], v[42:45]
	v_mfma_f32_16x16x32_bf16 v[30:33], v[134:137], v[212:215], v[30:33]
	v_mfma_f32_16x16x32_bf16 v[26:29], v[142:145], v[212:215], v[26:29]
	v_mfma_f32_16x16x32_bf16 v[14:17], v[134:137], v[220:223], v[14:17]
	v_mfma_f32_16x16x32_bf16 v[10:13], v[142:145], v[220:223], v[10:13]
	v_mfma_f32_16x16x32_bf16 v[54:57], v[146:149], v[178:181], v[54:57]
	v_mfma_f32_16x16x32_bf16 v[50:53], v[170:173], v[178:181], v[50:53]
	v_mfma_f32_16x16x32_bf16 v[38:41], v[146:149], v[200:203], v[38:41]
	v_mfma_f32_16x16x32_bf16 v[34:37], v[170:173], v[200:203], v[34:37]
	v_mfma_f32_16x16x32_bf16 v[22:25], v[146:149], v[208:211], v[22:25]
	v_mfma_f32_16x16x32_bf16 v[18:21], v[170:173], v[208:211], v[18:21]
	v_mfma_f32_16x16x32_bf16 v[6:9], v[146:149], v[216:219], v[6:9]
	v_mfma_f32_16x16x32_bf16 v[2:5], v[170:173], v[216:219], v[2:5]
	v_mfma_f32_16x16x32_bf16 v[54:57], v[150:153], v[182:185], v[54:57]
	v_mfma_f32_16x16x32_bf16 v[50:53], v[174:177], v[182:185], v[50:53]
	v_mfma_f32_16x16x32_bf16 v[38:41], v[150:153], v[204:207], v[38:41]
	v_mfma_f32_16x16x32_bf16 v[34:37], v[174:177], v[204:207], v[34:37]
	v_mfma_f32_16x16x32_bf16 v[22:25], v[150:153], v[212:215], v[22:25]
	v_mfma_f32_16x16x32_bf16 v[18:21], v[174:177], v[212:215], v[18:21]
	v_mfma_f32_16x16x32_bf16 v[6:9], v[150:153], v[220:223], v[6:9]
	v_mfma_f32_16x16x32_bf16 v[2:5], v[174:177], v[220:223], v[2:5]
	s_barrier
	s_add_i32 s78, 0, 0x18000
	s_add_i32 s79, 0, 0x1c000
	v_add_u32_e32 v142, s78, v194
	v_add_u32_e32 v174, s79, v194
	ds_read_b128 v[130:133], v142
	ds_read_b128 v[134:137], v142 offset:1024
	ds_read_b128 v[138:141], v142 offset:2048
	ds_read_b128 v[142:145], v142 offset:3072
	ds_read_b128 v[146:149], v174
	ds_read_b128 v[150:153], v174 offset:1024
	ds_read_b128 v[170:173], v174 offset:2048
	ds_read_b128 v[174:177], v174 offset:3072
	s_add_u32 s54, s54, 0xb0000
	s_addc_u32 s55, s55, 0
	s_mov_b32 m0, s60
	v_lshl_add_u64 v[230:231], s[54:55], 0, v[154:155]
	ds_read_b128 v[178:181], v198 offset:32768
	ds_read_b128 v[182:185], v198 offset:33792
	ds_read_b128 v[200:203], v198 offset:34816
	ds_read_b128 v[204:207], v198 offset:35840
	ds_read_b128 v[208:211], v198 offset:36864
	ds_read_b128 v[212:215], v198 offset:37888
	ds_read_b128 v[216:219], v198 offset:38912
	ds_read_b128 v[220:223], v198 offset:39936
	global_load_lds_dwordx4 v[230:231], off
	v_lshl_add_u64 v[230:231], s[54:55], 0, v[158:159]
	s_mov_b32 m0, s61
	s_nop 0
	global_load_lds_dwordx4 v[230:231], off
	s_waitcnt vmcnt(8)
	s_waitcnt lgkmcnt(0)
	s_barrier
	s_waitcnt lgkmcnt(0)
	v_mfma_f32_16x16x32_bf16 v[126:129], v[130:133], v[178:181], v[126:129]
	v_mfma_f32_16x16x32_bf16 v[122:125], v[138:141], v[178:181], v[122:125]
	v_mfma_f32_16x16x32_bf16 v[110:113], v[130:133], v[200:203], v[110:113]
	v_mfma_f32_16x16x32_bf16 v[106:109], v[138:141], v[200:203], v[106:109]
	v_mfma_f32_16x16x32_bf16 v[94:97], v[130:133], v[208:211], v[94:97]
	v_mfma_f32_16x16x32_bf16 v[90:93], v[138:141], v[208:211], v[90:93]
	v_mfma_f32_16x16x32_bf16 v[78:81], v[130:133], v[216:219], v[78:81]
	v_mfma_f32_16x16x32_bf16 v[74:77], v[138:141], v[216:219], v[74:77]
	v_mfma_f32_16x16x32_bf16 v[126:129], v[134:137], v[182:185], v[126:129]
	v_mfma_f32_16x16x32_bf16 v[122:125], v[142:145], v[182:185], v[122:125]
	v_mfma_f32_16x16x32_bf16 v[110:113], v[134:137], v[204:207], v[110:113]
	v_mfma_f32_16x16x32_bf16 v[106:109], v[142:145], v[204:207], v[106:109]
	v_mfma_f32_16x16x32_bf16 v[94:97], v[134:137], v[212:215], v[94:97]
	v_mfma_f32_16x16x32_bf16 v[90:93], v[142:145], v[212:215], v[90:93]
	v_mfma_f32_16x16x32_bf16 v[78:81], v[134:137], v[220:223], v[78:81]
	v_mfma_f32_16x16x32_bf16 v[74:77], v[142:145], v[220:223], v[74:77]
	v_mfma_f32_16x16x32_bf16 v[118:121], v[146:149], v[178:181], v[118:121]
	v_mfma_f32_16x16x32_bf16 v[114:117], v[170:173], v[178:181], v[114:117]
	v_mfma_f32_16x16x32_bf16 v[102:105], v[146:149], v[200:203], v[102:105]
	v_mfma_f32_16x16x32_bf16 v[98:101], v[170:173], v[200:203], v[98:101]
	v_mfma_f32_16x16x32_bf16 v[86:89], v[146:149], v[208:211], v[86:89]
	v_mfma_f32_16x16x32_bf16 v[82:85], v[170:173], v[208:211], v[82:85]
	v_mfma_f32_16x16x32_bf16 v[70:73], v[146:149], v[216:219], v[70:73]
	v_mfma_f32_16x16x32_bf16 v[66:69], v[170:173], v[216:219], v[66:69]
	v_mfma_f32_16x16x32_bf16 v[118:121], v[150:153], v[182:185], v[118:121]
	v_mfma_f32_16x16x32_bf16 v[114:117], v[174:177], v[182:185], v[114:117]
	v_mfma_f32_16x16x32_bf16 v[102:105], v[150:153], v[204:207], v[102:105]
	v_mfma_f32_16x16x32_bf16 v[98:101], v[174:177], v[204:207], v[98:101]
	v_mfma_f32_16x16x32_bf16 v[86:89], v[150:153], v[212:215], v[86:89]
	v_mfma_f32_16x16x32_bf16 v[82:85], v[174:177], v[212:215], v[82:85]
	v_mfma_f32_16x16x32_bf16 v[70:73], v[150:153], v[220:223], v[70:73]
	v_mfma_f32_16x16x32_bf16 v[66:69], v[174:177], v[220:223], v[66:69]
	s_barrier
; #define PG8_STAGE(bufoff, gbase, voff) do { _Pragma("unroll") for (int _i = 0; _i < 2; ++_i) \
;         __builtin_amdgcn_global_load_lds((const unsigned*)((const char*)(gbase) + (voff)[_i]), (LAS unsigned*)(lds + (bufoff) + ldsw + _i * 8192), 16, 0, 0); } while (0)
; #define PG8_LDA(dst, b, h) do { _Pragma("unroll") for (int m = 0; m < 4; ++m) _Pragma("unroll") for (int k = 0; k < 2; ++k) dst[m][k] = *(const LAS bf16x8*)(lds + PG8_SA(b, h) + aoff + m * 2048 + k * 1024); } while (0)
; #define PG8_MMA(ai, bj, At, Bt) do { __builtin_amdgcn_s_setprio(3); _Pragma("unroll") for (int m = 0; m < 4; ++m) _Pragma("unroll") for (int n = 0; n < 2; ++n) _Pragma("unroll") for (int k = 0; k < 2; ++k) \
;         acc[ai][bj][m][n] = __builtin_amdgcn_mfma_f32_16x16x32_bf16(Bt[n][k], At[m][k], acc[ai][bj][m][n], 0, 0, 0); __builtin_amdgcn_s_setprio(0); } while (0)
; #define PG8_WAIT_V(n) asm volatile("s_waitcnt vmcnt(" #n ")" ::: "memory")
; #define PG8_WAIT_L(n) asm volatile("s_waitcnt lgkmcnt(" #n ")" ::: "memory")
; #define PG8_BAR __builtin_amdgcn_s_barrier()
; #define PG8_SCHED __builtin_amdgcn_sched_barrier(0)
; template <class Epi, bool ALIGN_EPI>
; __device__ __forceinline__ void gemm_phase(LAS unsigned char* lds, const Gemm g, const StaticOrder& S, const Epi& E) {
;     ...
;             PG8_LDA(At, 1, 1); PG8_STAGE(PG8_SB(1, 0), b3, voffB); PG8_STAGE(PG8_SB(1, 1), b3 + hstep, voffB); PG8_STAGE(PG8_SA(1, 0), a3, voffA);
;             PG8_WAIT_V(8); PG8_WAIT_L(0); PG8_BAR; PG8_MMA(1, 0, At, B0); PG8_MMA(1, 1, At, B1); PG8_BAR; PG8_SCHED;
;         }
;         if constexpr (ALIGN_EPI) { if (wr == 0) PG8_BAR; }
;         E(acc, cur, wr, wc, fr, fq);
;         if (!has_next) break;
	s_add_i32 s54, s78, s57
	v_lshl_add_u64 v[186:187], v[186:187], 0, s[14:15]
	s_mov_b32 m0, s54
	ds_read_b128 v[178:181], v198 offset:49152
	ds_read_b128 v[182:185], v198 offset:50176
	ds_read_b128 v[200:203], v198 offset:51200
	ds_read_b128 v[204:207], v198 offset:52224
	ds_read_b128 v[208:211], v198 offset:53248
	ds_read_b128 v[212:215], v198 offset:54272
	ds_read_b128 v[216:219], v198 offset:55296
	ds_read_b128 v[220:223], v198 offset:56320
	global_load_lds_dwordx4 v[186:187], off
	s_add_i32 m0, s54, 0x2000
	s_add_u32 s52, s52, 0xb0080
	v_lshl_add_u64 v[186:187], v[224:225], 0, s[14:15]
	s_addc_u32 s53, s53, 0
	s_add_i32 s54, s79, s57
	global_load_lds_dwordx4 v[186:187], off
	v_lshl_add_u64 v[186:187], s[52:53], 0, v[156:157]
	s_mov_b32 m0, s54
	s_nop 0
	global_load_lds_dwordx4 v[186:187], off
	v_lshl_add_u64 v[186:187], s[52:53], 0, v[160:161]
	s_add_i32 m0, s54, 0x2000
	s_nop 0
	global_load_lds_dwordx4 v[186:187], off
	v_lshl_add_u64 v[186:187], v[226:227], 0, s[14:15]
	s_mov_b32 m0, s63
	s_nop 0
	global_load_lds_dwordx4 v[186:187], off
	v_lshl_add_u64 v[186:187], v[228:229], 0, s[14:15]
	s_mov_b32 m0, s64
	s_nop 0
	global_load_lds_dwordx4 v[186:187], off
	s_waitcnt vmcnt(8)
	s_waitcnt lgkmcnt(0)
	s_barrier
	s_waitcnt lgkmcnt(0)
	v_mfma_f32_16x16x32_bf16 v[62:65], v[130:133], v[178:181], v[62:65]
	v_mfma_f32_16x16x32_bf16 v[58:61], v[138:141], v[178:181], v[58:61]
	v_mfma_f32_16x16x32_bf16 v[46:49], v[130:133], v[200:203], v[46:49]
	v_mfma_f32_16x16x32_bf16 v[42:45], v[138:141], v[200:203], v[42:45]
	v_mfma_f32_16x16x32_bf16 v[30:33], v[130:133], v[208:211], v[30:33]
	v_mfma_f32_16x16x32_bf16 v[26:29], v[138:141], v[208:211], v[26:29]
	v_mfma_f32_16x16x32_bf16 v[14:17], v[130:133], v[216:219], v[14:17]
	v_mfma_f32_16x16x32_bf16 v[10:13], v[138:141], v[216:219], v[10:13]
	v_mfma_f32_16x16x32_bf16 v[62:65], v[134:137], v[182:185], v[62:65]
	v_mfma_f32_16x16x32_bf16 v[58:61], v[142:145], v[182:185], v[58:61]
	v_mfma_f32_16x16x32_bf16 v[46:49], v[134:137], v[204:207], v[46:49]
	v_mfma_f32_16x16x32_bf16 v[42:45], v[142:145], v[204:207], v[42:45]
	v_mfma_f32_16x16x32_bf16 v[30:33], v[134:137], v[212:215], v[30:33]
	v_mfma_f32_16x16x32_bf16 v[26:29], v[142:145], v[212:215], v[26:29]
	v_mfma_f32_16x16x32_bf16 v[14:17], v[134:137], v[220:223], v[14:17]
	v_mfma_f32_16x16x32_bf16 v[10:13], v[142:145], v[220:223], v[10:13]
	v_mfma_f32_16x16x32_bf16 v[54:57], v[146:149], v[178:181], v[54:57]
	v_mfma_f32_16x16x32_bf16 v[50:53], v[170:173], v[178:181], v[50:53]
	v_mfma_f32_16x16x32_bf16 v[38:41], v[146:149], v[200:203], v[38:41]
	v_mfma_f32_16x16x32_bf16 v[34:37], v[170:173], v[200:203], v[34:37]
	v_mfma_f32_16x16x32_bf16 v[22:25], v[146:149], v[208:211], v[22:25]
	v_mfma_f32_16x16x32_bf16 v[18:21], v[170:173], v[208:211], v[18:21]
	v_mfma_f32_16x16x32_bf16 v[6:9], v[146:149], v[216:219], v[6:9]
	v_mfma_f32_16x16x32_bf16 v[2:5], v[170:173], v[216:219], v[2:5]
	v_mfma_f32_16x16x32_bf16 v[54:57], v[150:153], v[182:185], v[54:57]
	v_mfma_f32_16x16x32_bf16 v[50:53], v[174:177], v[182:185], v[50:53]
	v_mfma_f32_16x16x32_bf16 v[38:41], v[150:153], v[204:207], v[38:41]
	v_mfma_f32_16x16x32_bf16 v[34:37], v[174:177], v[204:207], v[34:37]
	v_mfma_f32_16x16x32_bf16 v[22:25], v[150:153], v[212:215], v[22:25]
	v_mfma_f32_16x16x32_bf16 v[18:21], v[174:177], v[212:215], v[18:21]
	v_mfma_f32_16x16x32_bf16 v[6:9], v[150:153], v[220:223], v[6:9]
	v_mfma_f32_16x16x32_bf16 v[2:5], v[174:177], v[220:223], v[2:5]
	s_barrier
	s_add_i32 s77, s77, 2
	s_add_u32 s50, s50, 0x100
	s_addc_u32 s51, s51, 0
	s_add_u32 s73, s73, 0x100
	s_addc_u32 s76, s76, 0
	s_cmp_gt_u32 s77, 41
	s_cbranch_scc0 .LBB0_696
	s_and_b64 vcc, exec, s[16:17]
	s_cbranch_vccz .LBB0_699
	s_barrier

; #define PG8_STAGE(bufoff, gbase, voff) do { _Pragma("unroll") for (int _i = 0; _i < 2; ++_i) \
;         __builtin_amdgcn_global_load_lds((const unsigned*)((const char*)(gbase) + (voff)[_i]), (LAS unsigned*)(lds + (bufoff) + ldsw + _i * 8192), 16, 0, 0); } while (0)
; #define PG8_LDA(dst, b, h) do { _Pragma("unroll") for (int m = 0; m < 4; ++m) _Pragma("unroll") for (int k = 0; k < 2; ++k) dst[m][k] = *(const LAS bf16x8*)(lds + PG8_SA(b, h) + aoff + m * 2048 + k * 1024); } while (0)
; #define PG8_LDB(dst, b, h) do { _Pragma("unroll") for (int n = 0; n < 2; ++n) _Pragma("unroll") for (int k = 0; k < 2; ++k) dst[n][k] = *(const LAS bf16x8*)(lds + PG8_SB(b, h) + boff + n * 2048 + k * 1024); } while (0)
; #define PG8_MMA(ai, bj, At, Bt) do { __builtin_amdgcn_s_setprio(3); _Pragma("unroll") for (int m = 0; m < 4; ++m) _Pragma("unroll") for (int n = 0; n < 2; ++n) _Pragma("unroll") for (int k = 0; k < 2; ++k) \
;         acc[ai][bj][m][n] = __builtin_amdgcn_mfma_f32_16x16x32_bf16(Bt[n][k], At[m][k], acc[ai][bj][m][n], 0, 0, 0); __builtin_amdgcn_s_setprio(0); } while (0)
; #define PG8_WAIT_V(n) asm volatile("s_waitcnt vmcnt(" #n ")" ::: "memory")
; #define PG8_WAIT_L(n) asm volatile("s_waitcnt lgkmcnt(" #n ")" ::: "memory")
; #define PG8_BAR __builtin_amdgcn_s_barrier()
; #define PG8_SCHED __builtin_amdgcn_sched_barrier(0)
; template <class Epi, bool ALIGN_EPI>
; __device__ __forceinline__ void gemm_phase(LAS unsigned char* lds, const Gemm g, const StaticOrder& S, const Epi& E) {
;     ...
;             PG8_LDB(B0, 0, 0); PG8_LDB(B1, 0, 1); PG8_SCHED; PG8_LDA(At, 0, 0); PG8_STAGE(PG8_SA(1, 1), a1 + hstep, voffA);
;             PG8_WAIT_V(8); PG8_WAIT_L(0); PG8_BAR; PG8_MMA(0, 0, At, B0); PG8_MMA(0, 1, At, B1); PG8_BAR; PG8_SCHED;
;             PG8_LDA(At, 0, 1); PG8_STAGE(PG8_SB(0, 0), b2, voffB); PG8_STAGE(PG8_SB(0, 1), b2 + hstep, voffB); PG8_STAGE(PG8_SA(0, 0), a2, voffA);
;             PG8_WAIT_V(8); PG8_WAIT_L(0); PG8_BAR; PG8_MMA(1, 0, At, B0); PG8_MMA(1, 1, At, B1); PG8_BAR; PG8_SCHED;
.Lmy_rw_787_0:
	s_waitcnt lgkmcnt(0)
	s_barrier
	s_waitcnt lgkmcnt(0)
	v_mfma_f32_16x16x32_bf16 v[126:129], v[130:133], v[182:185], 0
	v_mfma_f32_16x16x32_bf16 v[122:125], v[138:141], v[182:185], 0
	v_mfma_f32_16x16x32_bf16 v[110:113], v[130:133], v[190:193], 0
	v_mfma_f32_16x16x32_bf16 v[106:109], v[138:141], v[190:193], 0
	v_mfma_f32_16x16x32_bf16 v[94:97], v[130:133], v[198:201], 0
	v_mfma_f32_16x16x32_bf16 v[90:93], v[138:141], v[198:201], 0
	v_mfma_f32_16x16x32_bf16 v[78:81], v[130:133], v[206:209], 0
	v_mfma_f32_16x16x32_bf16 v[74:77], v[138:141], v[206:209], 0
	v_mfma_f32_16x16x32_bf16 v[126:129], v[134:137], v[186:189], v[126:129]
	v_mfma_f32_16x16x32_bf16 v[122:125], v[142:145], v[186:189], v[122:125]
	v_mfma_f32_16x16x32_bf16 v[110:113], v[134:137], v[194:197], v[110:113]
	v_mfma_f32_16x16x32_bf16 v[106:109], v[142:145], v[194:197], v[106:109]
	v_mfma_f32_16x16x32_bf16 v[94:97], v[134:137], v[202:205], v[94:97]
	v_mfma_f32_16x16x32_bf16 v[90:93], v[142:145], v[202:205], v[90:93]
	v_mfma_f32_16x16x32_bf16 v[78:81], v[134:137], v[226:229], v[78:81]
	v_mfma_f32_16x16x32_bf16 v[74:77], v[142:145], v[226:229], v[74:77]
	v_mfma_f32_16x16x32_bf16 v[118:121], v[166:169], v[182:185], 0
	v_mfma_f32_16x16x32_bf16 v[114:117], v[174:177], v[182:185], 0
	v_mfma_f32_16x16x32_bf16 v[102:105], v[166:169], v[190:193], 0
	v_mfma_f32_16x16x32_bf16 v[98:101], v[174:177], v[190:193], 0
	v_mfma_f32_16x16x32_bf16 v[86:89], v[166:169], v[198:201], 0
	v_mfma_f32_16x16x32_bf16 v[82:85], v[174:177], v[198:201], 0
	v_mfma_f32_16x16x32_bf16 v[70:73], v[166:169], v[206:209], 0
	v_mfma_f32_16x16x32_bf16 v[66:69], v[174:177], v[206:209], 0
	v_mfma_f32_16x16x32_bf16 v[118:121], v[170:173], v[186:189], v[118:121]
	v_mfma_f32_16x16x32_bf16 v[114:117], v[178:181], v[186:189], v[114:117]
	v_mfma_f32_16x16x32_bf16 v[102:105], v[170:173], v[194:197], v[102:105]
	v_mfma_f32_16x16x32_bf16 v[98:101], v[178:181], v[194:197], v[98:101]
	v_mfma_f32_16x16x32_bf16 v[86:89], v[170:173], v[202:205], v[86:89]
	v_mfma_f32_16x16x32_bf16 v[82:85], v[178:181], v[202:205], v[82:85]
	v_mfma_f32_16x16x32_bf16 v[70:73], v[170:173], v[226:229], v[70:73]
	v_mfma_f32_16x16x32_bf16 v[66:69], v[178:181], v[226:229], v[66:69]
	s_barrier
	s_add_i32 s90, s69, s76
	v_lshl_add_u64 v[230:231], s[6:7], 0, v[148:149]
	s_mov_b32 m0, s90
	ds_read_b128 v[182:185], v222 offset:16384
	ds_read_b128 v[186:189], v222 offset:17408
	ds_read_b128 v[190:193], v222 offset:18432
	ds_read_b128 v[194:197], v222 offset:19456
	ds_read_b128 v[198:201], v222 offset:20480
	ds_read_b128 v[202:205], v222 offset:21504
	ds_read_b128 v[206:209], v222 offset:22528
	ds_read_b128 v[226:229], v222 offset:23552
	global_load_lds_dwordx4 v[230:231], off
	s_add_i32 m0, s90, 0x2000
	s_add_u32 s90, s6, 0x40000
	v_lshl_add_u64 v[232:233], s[6:7], 0, v[152:153]
	s_addc_u32 s91, s7, 0
	s_add_i32 s92, s70, s76
	global_load_lds_dwordx4 v[232:233], off
	v_lshl_add_u64 v[234:235], s[90:91], 0, v[148:149]
	s_mov_b32 m0, s92
	v_lshl_add_u64 v[236:237], s[8:9], 0, v[150:151]
	global_load_lds_dwordx4 v[234:235], off
	v_lshl_add_u64 v[234:235], s[90:91], 0, v[152:153]
	s_add_i32 m0, s92, 0x2000
	s_nop 0
	global_load_lds_dwordx4 v[234:235], off
	v_lshl_add_u64 v[234:235], s[8:9], 0, v[146:147]
	s_mov_b32 m0, s77
	s_nop 0
	global_load_lds_dwordx4 v[234:235], off
	s_mov_b32 m0, s87
	s_nop 0
	global_load_lds_dwordx4 v[236:237], off
	s_cmp_lg_u32 s98, 0
	s_cbranch_scc1 .Lmy_rw_787_1
	s_waitcnt vmcnt(8)
.Lmy_rw_787_1:
	s_waitcnt lgkmcnt(0)
	s_barrier
	s_waitcnt lgkmcnt(0)
	v_mfma_f32_16x16x32_bf16 v[62:65], v[130:133], v[182:185], 0
	v_mfma_f32_16x16x32_bf16 v[58:61], v[138:141], v[182:185], 0
	v_mfma_f32_16x16x32_bf16 v[46:49], v[130:133], v[190:193], 0
	v_mfma_f32_16x16x32_bf16 v[42:45], v[138:141], v[190:193], 0
	v_mfma_f32_16x16x32_bf16 v[30:33], v[130:133], v[198:201], 0
	v_mfma_f32_16x16x32_bf16 v[26:29], v[138:141], v[198:201], 0
	v_mfma_f32_16x16x32_bf16 v[14:17], v[130:133], v[206:209], 0
	v_mfma_f32_16x16x32_bf16 v[10:13], v[138:141], v[206:209], 0
	v_mfma_f32_16x16x32_bf16 v[62:65], v[134:137], v[186:189], v[62:65]
	v_mfma_f32_16x16x32_bf16 v[58:61], v[142:145], v[186:189], v[58:61]
	v_mfma_f32_16x16x32_bf16 v[46:49], v[134:137], v[194:197], v[46:49]
	v_mfma_f32_16x16x32_bf16 v[42:45], v[142:145], v[194:197], v[42:45]
	v_mfma_f32_16x16x32_bf16 v[30:33], v[134:137], v[202:205], v[30:33]
	v_mfma_f32_16x16x32_bf16 v[26:29], v[142:145], v[202:205], v[26:29]
	v_mfma_f32_16x16x32_bf16 v[14:17], v[134:137], v[226:229], v[14:17]
	v_mfma_f32_16x16x32_bf16 v[10:13], v[142:145], v[226:229], v[10:13]
	v_mfma_f32_16x16x32_bf16 v[54:57], v[166:169], v[182:185], 0
	v_mfma_f32_16x16x32_bf16 v[50:53], v[174:177], v[182:185], 0
	v_mfma_f32_16x16x32_bf16 v[38:41], v[166:169], v[190:193], 0
	v_mfma_f32_16x16x32_bf16 v[34:37], v[174:177], v[190:193], 0
	v_mfma_f32_16x16x32_bf16 v[22:25], v[166:169], v[198:201], 0
	v_mfma_f32_16x16x32_bf16 v[18:21], v[174:177], v[198:201], 0
	v_mfma_f32_16x16x32_bf16 v[6:9], v[166:169], v[206:209], 0
	v_mfma_f32_16x16x32_bf16 v[2:5], v[174:177], v[206:209], 0
	v_mfma_f32_16x16x32_bf16 v[54:57], v[170:173], v[186:189], v[54:57]
	v_mfma_f32_16x16x32_bf16 v[50:53], v[178:181], v[186:189], v[50:53]
	v_mfma_f32_16x16x32_bf16 v[38:41], v[170:173], v[194:197], v[38:41]
	v_mfma_f32_16x16x32_bf16 v[34:37], v[178:181], v[194:197], v[34:37]
	v_mfma_f32_16x16x32_bf16 v[22:25], v[170:173], v[202:205], v[22:25]
	v_mfma_f32_16x16x32_bf16 v[18:21], v[178:181], v[202:205], v[18:21]
	v_mfma_f32_16x16x32_bf16 v[6:9], v[170:173], v[226:229], v[6:9]
	v_mfma_f32_16x16x32_bf16 v[2:5], v[178:181], v[226:229], v[2:5]
	s_barrier
; #define PG8_STAGE(bufoff, gbase, voff) do { _Pragma("unroll") for (int _i = 0; _i < 2; ++_i) \
;         __builtin_amdgcn_global_load_lds((const unsigned*)((const char*)(gbase) + (voff)[_i]), (LAS unsigned*)(lds + (bufoff) + ldsw + _i * 8192), 16, 0, 0); } while (0)
; #define PG8_LDA(dst, b, h) do { _Pragma("unroll") for (int m = 0; m < 4; ++m) _Pragma("unroll") for (int k = 0; k < 2; ++k) dst[m][k] = *(const LAS bf16x8*)(lds + PG8_SA(b, h) + aoff + m * 2048 + k * 1024); } while (0)
; #define PG8_LDB(dst, b, h) do { _Pragma("unroll") for (int n = 0; n < 2; ++n) _Pragma("unroll") for (int k = 0; k < 2; ++k) dst[n][k] = *(const LAS bf16x8*)(lds + PG8_SB(b, h) + boff + n * 2048 + k * 1024); } while (0)
; #define PG8_MMA(ai, bj, At, Bt) do { __builtin_amdgcn_s_setprio(3); _Pragma("unroll") for (int m = 0; m < 4; ++m) _Pragma("unroll") for (int n = 0; n < 2; ++n) _Pragma("unroll") for (int k = 0; k < 2; ++k) \
;         acc[ai][bj][m][n] = __builtin_amdgcn_mfma_f32_16x16x32_bf16(Bt[n][k], At[m][k], acc[ai][bj][m][n], 0, 0, 0); __builtin_amdgcn_s_setprio(0); } while (0)
; #define PG8_WAIT_V(n) asm volatile("s_waitcnt vmcnt(" #n ")" ::: "memory")
; #define PG8_WAIT_L(n) asm volatile("s_waitcnt lgkmcnt(" #n ")" ::: "memory")
; #define PG8_BAR __builtin_amdgcn_s_barrier()
; #define PG8_SCHED __builtin_amdgcn_sched_barrier(0)
; template <class Epi, bool ALIGN_EPI>
; __device__ __forceinline__ void gemm_phase(LAS unsigned char* lds, const Gemm g, const StaticOrder& S, const Epi& E) {
;     ...
;             PG8_LDB(B0, 1, 0); PG8_LDB(B1, 1, 1); PG8_SCHED; PG8_LDA(At, 1, 0); PG8_STAGE(PG8_SA(0, 1), a2 + hstep, voffA);
;             PG8_WAIT_V(8); PG8_WAIT_L(0); PG8_BAR; PG8_MMA(0, 0, At, B0); PG8_MMA(0, 1, At, B1); PG8_BAR; PG8_SCHED;
;             PG8_LDA(At, 1, 1); PG8_STAGE(PG8_SB(1, 0), b3, voffB); PG8_STAGE(PG8_SB(1, 1), b3 + hstep, voffB); PG8_STAGE(PG8_SA(1, 0), a3, voffA);
;             PG8_WAIT_V(8); PG8_WAIT_L(0); PG8_BAR; PG8_MMA(1, 0, At, B0); PG8_MMA(1, 1, At, B1); PG8_BAR; PG8_SCHED;
	s_add_i32 s90, 0, 0x18000
	s_add_i32 s91, 0, 0x1c000
	v_add_u32_e32 v142, s90, v217
	v_add_u32_e32 v154, s91, v217
	ds_read_b128 v[130:133], v142
	ds_read_b128 v[134:137], v142 offset:1024
	ds_read_b128 v[138:141], v142 offset:2048
	ds_read_b128 v[142:145], v142 offset:3072
	ds_read_b128 v[166:169], v154
	ds_read_b128 v[170:173], v154 offset:1024
	ds_read_b128 v[174:177], v154 offset:2048
	ds_read_b128 v[178:181], v154 offset:3072
	s_add_u32 s8, s8, 0x40000
	s_addc_u32 s9, s9, 0
	s_mov_b32 m0, s33
	v_lshl_add_u64 v[238:239], s[8:9], 0, v[146:147]
	ds_read_b128 v[182:185], v222 offset:32768
	ds_read_b128 v[186:189], v222 offset:33792
	ds_read_b128 v[190:193], v222 offset:34816
	ds_read_b128 v[194:197], v222 offset:35840
	ds_read_b128 v[198:201], v222 offset:36864
	ds_read_b128 v[202:205], v222 offset:37888
	ds_read_b128 v[206:209], v222 offset:38912
	ds_read_b128 v[226:229], v222 offset:39936
	global_load_lds_dwordx4 v[238:239], off
	v_lshl_add_u64 v[238:239], s[8:9], 0, v[150:151]
	s_mov_b32 m0, s14
	s_nop 0
	global_load_lds_dwordx4 v[238:239], off
	s_waitcnt vmcnt(8)
	s_waitcnt lgkmcnt(0)
	s_barrier
	s_waitcnt lgkmcnt(0)
	v_mfma_f32_16x16x32_bf16 v[126:129], v[130:133], v[182:185], v[126:129]
	v_mfma_f32_16x16x32_bf16 v[122:125], v[138:141], v[182:185], v[122:125]
	v_mfma_f32_16x16x32_bf16 v[110:113], v[130:133], v[190:193], v[110:113]
	v_mfma_f32_16x16x32_bf16 v[106:109], v[138:141], v[190:193], v[106:109]
	v_mfma_f32_16x16x32_bf16 v[94:97], v[130:133], v[198:201], v[94:97]
	v_mfma_f32_16x16x32_bf16 v[90:93], v[138:141], v[198:201], v[90:93]
	v_mfma_f32_16x16x32_bf16 v[78:81], v[130:133], v[206:209], v[78:81]
	v_mfma_f32_16x16x32_bf16 v[74:77], v[138:141], v[206:209], v[74:77]
	v_mfma_f32_16x16x32_bf16 v[126:129], v[134:137], v[186:189], v[126:129]
	v_mfma_f32_16x16x32_bf16 v[122:125], v[142:145], v[186:189], v[122:125]
	v_mfma_f32_16x16x32_bf16 v[110:113], v[134:137], v[194:197], v[110:113]
	v_mfma_f32_16x16x32_bf16 v[106:109], v[142:145], v[194:197], v[106:109]
	v_mfma_f32_16x16x32_bf16 v[94:97], v[134:137], v[202:205], v[94:97]
	v_mfma_f32_16x16x32_bf16 v[90:93], v[142:145], v[202:205], v[90:93]
	v_mfma_f32_16x16x32_bf16 v[78:81], v[134:137], v[226:229], v[78:81]
	v_mfma_f32_16x16x32_bf16 v[74:77], v[142:145], v[226:229], v[74:77]
	v_mfma_f32_16x16x32_bf16 v[118:121], v[166:169], v[182:185], v[118:121]
	v_mfma_f32_16x16x32_bf16 v[114:117], v[174:177], v[182:185], v[114:117]
	v_mfma_f32_16x16x32_bf16 v[102:105], v[166:169], v[190:193], v[102:105]
	v_mfma_f32_16x16x32_bf16 v[98:101], v[174:177], v[190:193], v[98:101]
	v_mfma_f32_16x16x32_bf16 v[86:89], v[166:169], v[198:201], v[86:89]
	v_mfma_f32_16x16x32_bf16 v[82:85], v[174:177], v[198:201], v[82:85]
	v_mfma_f32_16x16x32_bf16 v[70:73], v[166:169], v[206:209], v[70:73]
	v_mfma_f32_16x16x32_bf16 v[66:69], v[174:177], v[206:209], v[66:69]
	v_mfma_f32_16x16x32_bf16 v[118:121], v[170:173], v[186:189], v[118:121]
	v_mfma_f32_16x16x32_bf16 v[114:117], v[178:181], v[186:189], v[114:117]
	v_mfma_f32_16x16x32_bf16 v[102:105], v[170:173], v[194:197], v[102:105]
	v_mfma_f32_16x16x32_bf16 v[98:101], v[178:181], v[194:197], v[98:101]
	v_mfma_f32_16x16x32_bf16 v[86:89], v[170:173], v[202:205], v[86:89]
	v_mfma_f32_16x16x32_bf16 v[82:85], v[178:181], v[202:205], v[82:85]
	v_mfma_f32_16x16x32_bf16 v[70:73], v[170:173], v[226:229], v[70:73]
	v_mfma_f32_16x16x32_bf16 v[66:69], v[178:181], v[226:229], v[66:69]
	s_barrier
	s_add_i32 s8, s90, s76
	v_lshl_add_u64 v[230:231], v[230:231], 0, s[60:61]
	s_mov_b32 m0, s8
	ds_read_b128 v[182:185], v222 offset:49152
	ds_read_b128 v[186:189], v222 offset:50176
	ds_read_b128 v[190:193], v222 offset:51200
	ds_read_b128 v[194:197], v222 offset:52224
	ds_read_b128 v[198:201], v222 offset:53248
	ds_read_b128 v[202:205], v222 offset:54272
	ds_read_b128 v[206:209], v222 offset:55296
	ds_read_b128 v[226:229], v222 offset:56320
	global_load_lds_dwordx4 v[230:231], off
	s_add_i32 m0, s8, 0x2000
	s_add_u32 s6, s6, 0x40080
	v_lshl_add_u64 v[230:231], v[232:233], 0, s[60:61]
	s_addc_u32 s7, s7, 0
	s_add_i32 s8, s91, s76
	global_load_lds_dwordx4 v[230:231], off
	v_lshl_add_u64 v[230:231], s[6:7], 0, v[148:149]
	s_mov_b32 m0, s8
	s_nop 0
	global_load_lds_dwordx4 v[230:231], off
	v_lshl_add_u64 v[230:231], s[6:7], 0, v[152:153]
	s_add_i32 m0, s8, 0x2000
	s_nop 0
	global_load_lds_dwordx4 v[230:231], off
	v_lshl_add_u64 v[230:231], v[234:235], 0, s[60:61]
	s_mov_b32 m0, s65
	s_nop 0
	global_load_lds_dwordx4 v[230:231], off
	v_lshl_add_u64 v[230:231], v[236:237], 0, s[60:61]
	s_mov_b32 m0, s66
	s_nop 0
	global_load_lds_dwordx4 v[230:231], off
	s_waitcnt vmcnt(8)
	s_waitcnt lgkmcnt(0)
	s_barrier
	s_waitcnt lgkmcnt(0)
	v_mfma_f32_16x16x32_bf16 v[62:65], v[130:133], v[182:185], v[62:65]
	v_mfma_f32_16x16x32_bf16 v[58:61], v[138:141], v[182:185], v[58:61]
	v_mfma_f32_16x16x32_bf16 v[46:49], v[130:133], v[190:193], v[46:49]
	v_mfma_f32_16x16x32_bf16 v[42:45], v[138:141], v[190:193], v[42:45]
	v_mfma_f32_16x16x32_bf16 v[30:33], v[130:133], v[198:201], v[30:33]
	v_mfma_f32_16x16x32_bf16 v[26:29], v[138:141], v[198:201], v[26:29]
	v_mfma_f32_16x16x32_bf16 v[14:17], v[130:133], v[206:209], v[14:17]
	v_mfma_f32_16x16x32_bf16 v[10:13], v[138:141], v[206:209], v[10:13]
	v_mfma_f32_16x16x32_bf16 v[62:65], v[134:137], v[186:189], v[62:65]
	v_mfma_f32_16x16x32_bf16 v[58:61], v[142:145], v[186:189], v[58:61]
	v_mfma_f32_16x16x32_bf16 v[46:49], v[134:137], v[194:197], v[46:49]
	v_mfma_f32_16x16x32_bf16 v[42:45], v[142:145], v[194:197], v[42:45]
	v_mfma_f32_16x16x32_bf16 v[30:33], v[134:137], v[202:205], v[30:33]
	v_mfma_f32_16x16x32_bf16 v[26:29], v[142:145], v[202:205], v[26:29]
	v_mfma_f32_16x16x32_bf16 v[14:17], v[134:137], v[226:229], v[14:17]
	v_mfma_f32_16x16x32_bf16 v[10:13], v[142:145], v[226:229], v[10:13]
	v_mfma_f32_16x16x32_bf16 v[54:57], v[166:169], v[182:185], v[54:57]
	v_mfma_f32_16x16x32_bf16 v[50:53], v[174:177], v[182:185], v[50:53]
	v_mfma_f32_16x16x32_bf16 v[38:41], v[166:169], v[190:193], v[38:41]
	v_mfma_f32_16x16x32_bf16 v[34:37], v[174:177], v[190:193], v[34:37]
	v_mfma_f32_16x16x32_bf16 v[22:25], v[166:169], v[198:201], v[22:25]
	v_mfma_f32_16x16x32_bf16 v[18:21], v[174:177], v[198:201], v[18:21]
	v_mfma_f32_16x16x32_bf16 v[6:9], v[166:169], v[206:209], v[6:9]
	v_mfma_f32_16x16x32_bf16 v[2:5], v[174:177], v[206:209], v[2:5]
	v_mfma_f32_16x16x32_bf16 v[54:57], v[170:173], v[186:189], v[54:57]
	v_mfma_f32_16x16x32_bf16 v[50:53], v[178:181], v[186:189], v[50:53]
	v_mfma_f32_16x16x32_bf16 v[38:41], v[170:173], v[194:197], v[38:41]
	v_mfma_f32_16x16x32_bf16 v[34:37], v[178:181], v[194:197], v[34:37]
	v_mfma_f32_16x16x32_bf16 v[22:25], v[170:173], v[202:205], v[22:25]
	v_mfma_f32_16x16x32_bf16 v[18:21], v[178:181], v[202:205], v[18:21]
	v_mfma_f32_16x16x32_bf16 v[6:9], v[170:173], v[226:229], v[6:9]
	v_mfma_f32_16x16x32_bf16 v[2:5], v[178:181], v[226:229], v[2:5]
	s_barrier
	s_add_i32 s89, s89, 2
	s_add_u32 s4, s4, 0x100
	s_addc_u32 s5, s5, 0
	s_add_u32 s85, s85, 0x100
	s_addc_u32 s88, s88, 0
; #define PG8_STAGE(bufoff, gbase, voff) do { _Pragma("unroll") for (int _i = 0; _i < 2; ++_i) \
;         __builtin_amdgcn_global_load_lds((const unsigned*)((const char*)(gbase) + (voff)[_i]), (LAS unsigned*)(lds + (bufoff) + ldsw + _i * 8192), 16, 0, 0); } while (0)
; #define PG8_LDA(dst, b, h) do { _Pragma("unroll") for (int m = 0; m < 4; ++m) _Pragma("unroll") for (int k = 0; k < 2; ++k) dst[m][k] = *(const LAS bf16x8*)(lds + PG8_SA(b, h) + aoff + m * 2048 + k * 1024); } while (0)
; #define PG8_LDB(dst, b, h) do { _Pragma("unroll") for (int n = 0; n < 2; ++n) _Pragma("unroll") for (int k = 0; k < 2; ++k) dst[n][k] = *(const LAS bf16x8*)(lds + PG8_SB(b, h) + boff + n * 2048 + k * 1024); } while (0)
; #define PG8_MMA(ai, bj, At, Bt) do { __builtin_amdgcn_s_setprio(3); _Pragma("unroll") for (int m = 0; m < 4; ++m) _Pragma("unroll") for (int n = 0; n < 2; ++n) _Pragma("unroll") for (int k = 0; k < 2; ++k) \
;         acc[ai][bj][m][n] = __builtin_amdgcn_mfma_f32_16x16x32_bf16(Bt[n][k], At[m][k], acc[ai][bj][m][n], 0, 0, 0); __builtin_amdgcn_s_setprio(0); } while (0)
; #define PG8_WAIT_V(n) asm volatile("s_waitcnt vmcnt(" #n ")" ::: "memory")
; #define PG8_WAIT_L(n) asm volatile("s_waitcnt lgkmcnt(" #n ")" ::: "memory")
; #define PG8_BAR __builtin_amdgcn_s_barrier()
; #define PG8_SCHED __builtin_amdgcn_sched_barrier(0)
; template <class Epi, bool ALIGN_EPI>
; __device__ __forceinline__ void gemm_phase(LAS unsigned char* lds, const Gemm g, const StaticOrder& S, const Epi& E) {
;     ...
;             const bool last = (t == nt - 2);
;             const char* a1 = cA + (size_t)(t + 1) * kstep;
;             const char* a2 = last ? nA : cA + (size_t)(t + 2) * kstep; const char* b2 = last ? nB : cB + (size_t)(t + 2) * kstep;
;             const char* a3 = a2 + kstep; const char* b3 = b2 + kstep;
;             PG8_LDB(B0, 0, 0); PG8_LDB(B1, 0, 1); PG8_SCHED; PG8_LDA(At, 0, 0); PG8_STAGE(PG8_SA(1, 1), a1 + hstep, voffA);
;             PG8_WAIT_V(8); PG8_WAIT_L(0); PG8_BAR; PG8_MMA(0, 0, At, B0); PG8_MMA(0, 1, At, B1); PG8_BAR; PG8_SCHED;
;             PG8_LDA(At, 0, 1); PG8_STAGE(PG8_SB(0, 0), b2, voffB); PG8_STAGE(PG8_SB(0, 1), b2 + hstep, voffB); PG8_STAGE(PG8_SA(0, 0), a2, voffA);
.LBB0_787:
	s_waitcnt lgkmcnt(0)
	ds_read_b128 v[130:133], v220
	ds_read_b128 v[134:137], v220 offset:1024
	ds_read_b128 v[138:141], v220 offset:2048
	ds_read_b128 v[142:145], v220 offset:3072
	ds_read_b128 v[166:169], v221
	ds_read_b128 v[170:173], v221 offset:1024
	ds_read_b128 v[174:177], v221 offset:2048
	ds_read_b128 v[178:181], v221 offset:3072
	s_add_u32 s6, s4, 0xfffc0080
	s_addc_u32 s7, s5, -1
	s_cmp_eq_u32 s89, 12
	s_cselect_b32 s9, s50, s7
	s_cselect_b32 s8, s55, s6
	s_cselect_b32 s7, s73, s88
	s_cselect_b32 s6, s79, s85
	v_lshl_add_u64 v[230:231], s[4:5], 0, v[158:159]
	s_add_i32 m0, s77, 0xc000
	ds_read_b128 v[182:185], v222
	ds_read_b128 v[186:189], v222 offset:1024
	ds_read_b128 v[190:193], v222 offset:2048
	ds_read_b128 v[194:197], v222 offset:3072
	ds_read_b128 v[198:201], v222 offset:4096
	ds_read_b128 v[202:205], v222 offset:5120
	ds_read_b128 v[206:209], v222 offset:6144
	ds_read_b128 v[226:229], v222 offset:7168
	global_load_lds_dwordx4 v[230:231], off
	v_lshl_add_u64 v[230:231], s[4:5], 0, v[160:161]
	s_add_i32 m0, s77, 0xe000
	s_nop 0
	global_load_lds_dwordx4 v[230:231], off
	s_waitcnt vmcnt(8)
	s_waitcnt lgkmcnt(0)
	s_barrier
	s_waitcnt lgkmcnt(0)
	v_mfma_f32_16x16x32_bf16 v[126:129], v[130:133], v[182:185], v[126:129]
	v_mfma_f32_16x16x32_bf16 v[122:125], v[138:141], v[182:185], v[122:125]
	v_mfma_f32_16x16x32_bf16 v[110:113], v[130:133], v[190:193], v[110:113]
	v_mfma_f32_16x16x32_bf16 v[106:109], v[138:141], v[190:193], v[106:109]
	v_mfma_f32_16x16x32_bf16 v[94:97], v[130:133], v[198:201], v[94:97]
	v_mfma_f32_16x16x32_bf16 v[90:93], v[138:141], v[198:201], v[90:93]
	v_mfma_f32_16x16x32_bf16 v[78:81], v[130:133], v[206:209], v[78:81]
	v_mfma_f32_16x16x32_bf16 v[74:77], v[138:141], v[206:209], v[74:77]
	v_mfma_f32_16x16x32_bf16 v[126:129], v[134:137], v[186:189], v[126:129]
	v_mfma_f32_16x16x32_bf16 v[122:125], v[142:145], v[186:189], v[122:125]
	v_mfma_f32_16x16x32_bf16 v[110:113], v[134:137], v[194:197], v[110:113]
	v_mfma_f32_16x16x32_bf16 v[106:109], v[142:145], v[194:197], v[106:109]
	v_mfma_f32_16x16x32_bf16 v[94:97], v[134:137], v[202:205], v[94:97]
	v_mfma_f32_16x16x32_bf16 v[90:93], v[142:145], v[202:205], v[90:93]
	v_mfma_f32_16x16x32_bf16 v[78:81], v[134:137], v[226:229], v[78:81]
	v_mfma_f32_16x16x32_bf16 v[74:77], v[142:145], v[226:229], v[74:77]
	v_mfma_f32_16x16x32_bf16 v[118:121], v[166:169], v[182:185], v[118:121]
	v_mfma_f32_16x16x32_bf16 v[114:117], v[174:177], v[182:185], v[114:117]
	v_mfma_f32_16x16x32_bf16 v[102:105], v[166:169], v[190:193], v[102:105]
	v_mfma_f32_16x16x32_bf16 v[98:101], v[174:177], v[190:193], v[98:101]
	v_mfma_f32_16x16x32_bf16 v[86:89], v[166:169], v[198:201], v[86:89]
	v_mfma_f32_16x16x32_bf16 v[82:85], v[174:177], v[198:201], v[82:85]
	v_mfma_f32_16x16x32_bf16 v[70:73], v[166:169], v[206:209], v[70:73]
	v_mfma_f32_16x16x32_bf16 v[66:69], v[174:177], v[206:209], v[66:69]
	v_mfma_f32_16x16x32_bf16 v[118:121], v[170:173], v[186:189], v[118:121]
	v_mfma_f32_16x16x32_bf16 v[114:117], v[178:181], v[186:189], v[114:117]
	v_mfma_f32_16x16x32_bf16 v[102:105], v[170:173], v[194:197], v[102:105]
	v_mfma_f32_16x16x32_bf16 v[98:101], v[178:181], v[194:197], v[98:101]
	v_mfma_f32_16x16x32_bf16 v[86:89], v[170:173], v[202:205], v[86:89]
	v_mfma_f32_16x16x32_bf16 v[82:85], v[178:181], v[202:205], v[82:85]
	v_mfma_f32_16x16x32_bf16 v[70:73], v[170:173], v[226:229], v[70:73]
	v_mfma_f32_16x16x32_bf16 v[66:69], v[178:181], v[226:229], v[66:69]
	s_barrier
	s_add_i32 s90, s69, s76
	v_lshl_add_u64 v[230:231], s[6:7], 0, v[148:149]
	s_mov_b32 m0, s90
	ds_read_b128 v[182:185], v222 offset:16384
	ds_read_b128 v[186:189], v222 offset:17408
	ds_read_b128 v[190:193], v222 offset:18432
	ds_read_b128 v[194:197], v222 offset:19456
	ds_read_b128 v[198:201], v222 offset:20480
	ds_read_b128 v[202:205], v222 offset:21504
	ds_read_b128 v[206:209], v222 offset:22528
	ds_read_b128 v[226:229], v222 offset:23552
	global_load_lds_dwordx4 v[230:231], off
	s_add_i32 m0, s90, 0x2000
	s_add_u32 s90, s6, 0x40000
	v_lshl_add_u64 v[232:233], s[6:7], 0, v[152:153]
	s_addc_u32 s91, s7, 0
	s_add_i32 s92, s70, s76
	global_load_lds_dwordx4 v[232:233], off
	v_lshl_add_u64 v[234:235], s[90:91], 0, v[148:149]
	s_mov_b32 m0, s92
	v_lshl_add_u64 v[236:237], s[8:9], 0, v[150:151]
	global_load_lds_dwordx4 v[234:235], off
	v_lshl_add_u64 v[234:235], s[90:91], 0, v[152:153]
	s_add_i32 m0, s92, 0x2000
	s_nop 0
	global_load_lds_dwordx4 v[234:235], off
	v_lshl_add_u64 v[234:235], s[8:9], 0, v[146:147]
	s_mov_b32 m0, s77
	s_nop 0
	global_load_lds_dwordx4 v[234:235], off
	s_mov_b32 m0, s87
	s_nop 0
	global_load_lds_dwordx4 v[236:237], off
	s_waitcnt vmcnt(8)
	s_waitcnt lgkmcnt(0)
	s_barrier
; #define PG8_STAGE(bufoff, gbase, voff) do { _Pragma("unroll") for (int _i = 0; _i < 2; ++_i) \
;         __builtin_amdgcn_global_load_lds((const unsigned*)((const char*)(gbase) + (voff)[_i]), (LAS unsigned*)(lds + (bufoff) + ldsw + _i * 8192), 16, 0, 0); } while (0)
; #define PG8_LDA(dst, b, h) do { _Pragma("unroll") for (int m = 0; m < 4; ++m) _Pragma("unroll") for (int k = 0; k < 2; ++k) dst[m][k] = *(const LAS bf16x8*)(lds + PG8_SA(b, h) + aoff + m * 2048 + k * 1024); } while (0)
; #define PG8_LDB(dst, b, h) do { _Pragma("unroll") for (int n = 0; n < 2; ++n) _Pragma("unroll") for (int k = 0; k < 2; ++k) dst[n][k] = *(const LAS bf16x8*)(lds + PG8_SB(b, h) + boff + n * 2048 + k * 1024); } while (0)
; #define PG8_MMA(ai, bj, At, Bt) do { __builtin_amdgcn_s_setprio(3); _Pragma("unroll") for (int m = 0; m < 4; ++m) _Pragma("unroll") for (int n = 0; n < 2; ++n) _Pragma("unroll") for (int k = 0; k < 2; ++k) \
;         acc[ai][bj][m][n] = __builtin_amdgcn_mfma_f32_16x16x32_bf16(Bt[n][k], At[m][k], acc[ai][bj][m][n], 0, 0, 0); __builtin_amdgcn_s_setprio(0); } while (0)
; #define PG8_WAIT_V(n) asm volatile("s_waitcnt vmcnt(" #n ")" ::: "memory")
; #define PG8_WAIT_L(n) asm volatile("s_waitcnt lgkmcnt(" #n ")" ::: "memory")
; #define PG8_BAR __builtin_amdgcn_s_barrier()
; #define PG8_SCHED __builtin_amdgcn_sched_barrier(0)
; template <class Epi, bool ALIGN_EPI>
; __device__ __forceinline__ void gemm_phase(LAS unsigned char* lds, const Gemm g, const StaticOrder& S, const Epi& E) {
;     ...
;             PG8_WAIT_V(8); PG8_WAIT_L(0); PG8_BAR; PG8_MMA(1, 0, At, B0); PG8_MMA(1, 1, At, B1); PG8_BAR; PG8_SCHED;
;             PG8_LDB(B0, 1, 0); PG8_LDB(B1, 1, 1); PG8_SCHED; PG8_LDA(At, 1, 0); PG8_STAGE(PG8_SA(0, 1), a2 + hstep, voffA);
;             PG8_WAIT_V(8); PG8_WAIT_L(0); PG8_BAR; PG8_MMA(0, 0, At, B0); PG8_MMA(0, 1, At, B1); PG8_BAR; PG8_SCHED;
	s_waitcnt lgkmcnt(0)
	v_mfma_f32_16x16x32_bf16 v[62:65], v[130:133], v[182:185], v[62:65]
	v_mfma_f32_16x16x32_bf16 v[58:61], v[138:141], v[182:185], v[58:61]
	v_mfma_f32_16x16x32_bf16 v[46:49], v[130:133], v[190:193], v[46:49]
	v_mfma_f32_16x16x32_bf16 v[42:45], v[138:141], v[190:193], v[42:45]
	v_mfma_f32_16x16x32_bf16 v[30:33], v[130:133], v[198:201], v[30:33]
	v_mfma_f32_16x16x32_bf16 v[26:29], v[138:141], v[198:201], v[26:29]
	v_mfma_f32_16x16x32_bf16 v[14:17], v[130:133], v[206:209], v[14:17]
	v_mfma_f32_16x16x32_bf16 v[10:13], v[138:141], v[206:209], v[10:13]
	v_mfma_f32_16x16x32_bf16 v[62:65], v[134:137], v[186:189], v[62:65]
	v_mfma_f32_16x16x32_bf16 v[58:61], v[142:145], v[186:189], v[58:61]
	v_mfma_f32_16x16x32_bf16 v[46:49], v[134:137], v[194:197], v[46:49]
	v_mfma_f32_16x16x32_bf16 v[42:45], v[142:145], v[194:197], v[42:45]
	v_mfma_f32_16x16x32_bf16 v[30:33], v[134:137], v[202:205], v[30:33]
	v_mfma_f32_16x16x32_bf16 v[26:29], v[142:145], v[202:205], v[26:29]
	v_mfma_f32_16x16x32_bf16 v[14:17], v[134:137], v[226:229], v[14:17]
	v_mfma_f32_16x16x32_bf16 v[10:13], v[142:145], v[226:229], v[10:13]
	v_mfma_f32_16x16x32_bf16 v[54:57], v[166:169], v[182:185], v[54:57]
	v_mfma_f32_16x16x32_bf16 v[50:53], v[174:177], v[182:185], v[50:53]
	v_mfma_f32_16x16x32_bf16 v[38:41], v[166:169], v[190:193], v[38:41]
	v_mfma_f32_16x16x32_bf16 v[34:37], v[174:177], v[190:193], v[34:37]
	v_mfma_f32_16x16x32_bf16 v[22:25], v[166:169], v[198:201], v[22:25]
	v_mfma_f32_16x16x32_bf16 v[18:21], v[174:177], v[198:201], v[18:21]
	v_mfma_f32_16x16x32_bf16 v[6:9], v[166:169], v[206:209], v[6:9]
	v_mfma_f32_16x16x32_bf16 v[2:5], v[174:177], v[206:209], v[2:5]
	v_mfma_f32_16x16x32_bf16 v[54:57], v[170:173], v[186:189], v[54:57]
	v_mfma_f32_16x16x32_bf16 v[50:53], v[178:181], v[186:189], v[50:53]
	v_mfma_f32_16x16x32_bf16 v[38:41], v[170:173], v[194:197], v[38:41]
	v_mfma_f32_16x16x32_bf16 v[34:37], v[178:181], v[194:197], v[34:37]
	v_mfma_f32_16x16x32_bf16 v[22:25], v[170:173], v[202:205], v[22:25]
	v_mfma_f32_16x16x32_bf16 v[18:21], v[178:181], v[202:205], v[18:21]
	v_mfma_f32_16x16x32_bf16 v[6:9], v[170:173], v[226:229], v[6:9]
	v_mfma_f32_16x16x32_bf16 v[2:5], v[178:181], v[226:229], v[2:5]
	s_barrier
	s_add_i32 s90, 0, 0x18000
	s_add_i32 s91, 0, 0x1c000
	v_add_u32_e32 v142, s90, v217
	v_add_u32_e32 v154, s91, v217
	ds_read_b128 v[130:133], v142
	ds_read_b128 v[134:137], v142 offset:1024
	ds_read_b128 v[138:141], v142 offset:2048
	ds_read_b128 v[142:145], v142 offset:3072
	ds_read_b128 v[166:169], v154
	ds_read_b128 v[170:173], v154 offset:1024
	ds_read_b128 v[174:177], v154 offset:2048
	ds_read_b128 v[178:181], v154 offset:3072
	s_add_u32 s8, s8, 0x40000
	s_addc_u32 s9, s9, 0
	s_mov_b32 m0, s33
	v_lshl_add_u64 v[238:239], s[8:9], 0, v[146:147]
	ds_read_b128 v[182:185], v222 offset:32768
	ds_read_b128 v[186:189], v222 offset:33792
	ds_read_b128 v[190:193], v222 offset:34816
	ds_read_b128 v[194:197], v222 offset:35840
	ds_read_b128 v[198:201], v222 offset:36864
	ds_read_b128 v[202:205], v222 offset:37888
	ds_read_b128 v[206:209], v222 offset:38912
	ds_read_b128 v[226:229], v222 offset:39936
	global_load_lds_dwordx4 v[238:239], off
	v_lshl_add_u64 v[238:239], s[8:9], 0, v[150:151]
	s_mov_b32 m0, s14
	s_nop 0
	global_load_lds_dwordx4 v[238:239], off
	s_waitcnt vmcnt(8)
	s_waitcnt lgkmcnt(0)
	s_barrier
	s_waitcnt lgkmcnt(0)
	v_mfma_f32_16x16x32_bf16 v[126:129], v[130:133], v[182:185], v[126:129]
	v_mfma_f32_16x16x32_bf16 v[122:125], v[138:141], v[182:185], v[122:125]
	v_mfma_f32_16x16x32_bf16 v[110:113], v[130:133], v[190:193], v[110:113]
	v_mfma_f32_16x16x32_bf16 v[106:109], v[138:141], v[190:193], v[106:109]
	v_mfma_f32_16x16x32_bf16 v[94:97], v[130:133], v[198:201], v[94:97]
	v_mfma_f32_16x16x32_bf16 v[90:93], v[138:141], v[198:201], v[90:93]
	v_mfma_f32_16x16x32_bf16 v[78:81], v[130:133], v[206:209], v[78:81]
	v_mfma_f32_16x16x32_bf16 v[74:77], v[138:141], v[206:209], v[74:77]
	v_mfma_f32_16x16x32_bf16 v[126:129], v[134:137], v[186:189], v[126:129]
	v_mfma_f32_16x16x32_bf16 v[122:125], v[142:145], v[186:189], v[122:125]
	v_mfma_f32_16x16x32_bf16 v[110:113], v[134:137], v[194:197], v[110:113]
	v_mfma_f32_16x16x32_bf16 v[106:109], v[142:145], v[194:197], v[106:109]
	v_mfma_f32_16x16x32_bf16 v[94:97], v[134:137], v[202:205], v[94:97]
	v_mfma_f32_16x16x32_bf16 v[90:93], v[142:145], v[202:205], v[90:93]
	v_mfma_f32_16x16x32_bf16 v[78:81], v[134:137], v[226:229], v[78:81]
	v_mfma_f32_16x16x32_bf16 v[74:77], v[142:145], v[226:229], v[74:77]
	v_mfma_f32_16x16x32_bf16 v[118:121], v[166:169], v[182:185], v[118:121]
	v_mfma_f32_16x16x32_bf16 v[114:117], v[174:177], v[182:185], v[114:117]
	v_mfma_f32_16x16x32_bf16 v[102:105], v[166:169], v[190:193], v[102:105]
	v_mfma_f32_16x16x32_bf16 v[98:101], v[174:177], v[190:193], v[98:101]
	v_mfma_f32_16x16x32_bf16 v[86:89], v[166:169], v[198:201], v[86:89]
	v_mfma_f32_16x16x32_bf16 v[82:85], v[174:177], v[198:201], v[82:85]
	v_mfma_f32_16x16x32_bf16 v[70:73], v[166:169], v[206:209], v[70:73]
	v_mfma_f32_16x16x32_bf16 v[66:69], v[174:177], v[206:209], v[66:69]
	v_mfma_f32_16x16x32_bf16 v[118:121], v[170:173], v[186:189], v[118:121]
	v_mfma_f32_16x16x32_bf16 v[114:117], v[178:181], v[186:189], v[114:117]
	v_mfma_f32_16x16x32_bf16 v[102:105], v[170:173], v[194:197], v[102:105]
	v_mfma_f32_16x16x32_bf16 v[98:101], v[178:181], v[194:197], v[98:101]
	v_mfma_f32_16x16x32_bf16 v[86:89], v[170:173], v[202:205], v[86:89]
	v_mfma_f32_16x16x32_bf16 v[82:85], v[178:181], v[202:205], v[82:85]
	v_mfma_f32_16x16x32_bf16 v[70:73], v[170:173], v[226:229], v[70:73]
	v_mfma_f32_16x16x32_bf16 v[66:69], v[178:181], v[226:229], v[66:69]
	s_barrier
; #define PG8_STAGE(bufoff, gbase, voff) do { _Pragma("unroll") for (int _i = 0; _i < 2; ++_i) \
;         __builtin_amdgcn_global_load_lds((const unsigned*)((const char*)(gbase) + (voff)[_i]), (LAS unsigned*)(lds + (bufoff) + ldsw + _i * 8192), 16, 0, 0); } while (0)
; #define PG8_LDA(dst, b, h) do { _Pragma("unroll") for (int m = 0; m < 4; ++m) _Pragma("unroll") for (int k = 0; k < 2; ++k) dst[m][k] = *(const LAS bf16x8*)(lds + PG8_SA(b, h) + aoff + m * 2048 + k * 1024); } while (0)
; #define PG8_MMA(ai, bj, At, Bt) do { __builtin_amdgcn_s_setprio(3); _Pragma("unroll") for (int m = 0; m < 4; ++m) _Pragma("unroll") for (int n = 0; n < 2; ++n) _Pragma("unroll") for (int k = 0; k < 2; ++k) \
;         acc[ai][bj][m][n] = __builtin_amdgcn_mfma_f32_16x16x32_bf16(Bt[n][k], At[m][k], acc[ai][bj][m][n], 0, 0, 0); __builtin_amdgcn_s_setprio(0); } while (0)
; #define PG8_WAIT_V(n) asm volatile("s_waitcnt vmcnt(" #n ")" ::: "memory")
; #define PG8_WAIT_L(n) asm volatile("s_waitcnt lgkmcnt(" #n ")" ::: "memory")
; #define PG8_BAR __builtin_amdgcn_s_barrier()
; #define PG8_SCHED __builtin_amdgcn_sched_barrier(0)
; template <class Epi, bool ALIGN_EPI>
; __device__ __forceinline__ void gemm_phase(LAS unsigned char* lds, const Gemm g, const StaticOrder& S, const Epi& E) {
;     ...
;             PG8_LDA(At, 1, 1); PG8_STAGE(PG8_SB(1, 0), b3, voffB); PG8_STAGE(PG8_SB(1, 1), b3 + hstep, voffB); PG8_STAGE(PG8_SA(1, 0), a3, voffA);
;             PG8_WAIT_V(8); PG8_WAIT_L(0); PG8_BAR; PG8_MMA(1, 0, At, B0); PG8_MMA(1, 1, At, B1); PG8_BAR; PG8_SCHED;
;         }
;         if constexpr (ALIGN_EPI) { if (wr == 0) PG8_BAR; }
;         E(acc, cur, wr, wc, fr, fq);
;         if (!has_next) break;
	s_add_i32 s8, s90, s76
	v_lshl_add_u64 v[230:231], v[230:231], 0, s[60:61]
	s_mov_b32 m0, s8
	ds_read_b128 v[182:185], v222 offset:49152
	ds_read_b128 v[186:189], v222 offset:50176
	ds_read_b128 v[190:193], v222 offset:51200
	ds_read_b128 v[194:197], v222 offset:52224
	ds_read_b128 v[198:201], v222 offset:53248
	ds_read_b128 v[202:205], v222 offset:54272
	ds_read_b128 v[206:209], v222 offset:55296
	ds_read_b128 v[226:229], v222 offset:56320
	global_load_lds_dwordx4 v[230:231], off
	s_add_i32 m0, s8, 0x2000
	s_add_u32 s6, s6, 0x40080
	v_lshl_add_u64 v[230:231], v[232:233], 0, s[60:61]
	s_addc_u32 s7, s7, 0
	s_add_i32 s8, s91, s76
	global_load_lds_dwordx4 v[230:231], off
	v_lshl_add_u64 v[230:231], s[6:7], 0, v[148:149]
	s_mov_b32 m0, s8
	s_nop 0
	global_load_lds_dwordx4 v[230:231], off
	v_lshl_add_u64 v[230:231], s[6:7], 0, v[152:153]
	s_add_i32 m0, s8, 0x2000
	s_nop 0
	global_load_lds_dwordx4 v[230:231], off
	v_lshl_add_u64 v[230:231], v[234:235], 0, s[60:61]
	s_mov_b32 m0, s65
	s_nop 0
	global_load_lds_dwordx4 v[230:231], off
	v_lshl_add_u64 v[230:231], v[236:237], 0, s[60:61]
	s_mov_b32 m0, s66
	s_nop 0
	global_load_lds_dwordx4 v[230:231], off
	s_waitcnt vmcnt(8)
	s_waitcnt lgkmcnt(0)
	s_barrier
	s_waitcnt lgkmcnt(0)
	v_mfma_f32_16x16x32_bf16 v[62:65], v[130:133], v[182:185], v[62:65]
	v_mfma_f32_16x16x32_bf16 v[58:61], v[138:141], v[182:185], v[58:61]
	v_mfma_f32_16x16x32_bf16 v[46:49], v[130:133], v[190:193], v[46:49]
	v_mfma_f32_16x16x32_bf16 v[42:45], v[138:141], v[190:193], v[42:45]
	v_mfma_f32_16x16x32_bf16 v[30:33], v[130:133], v[198:201], v[30:33]
	v_mfma_f32_16x16x32_bf16 v[26:29], v[138:141], v[198:201], v[26:29]
	v_mfma_f32_16x16x32_bf16 v[14:17], v[130:133], v[206:209], v[14:17]
	v_mfma_f32_16x16x32_bf16 v[10:13], v[138:141], v[206:209], v[10:13]
	v_mfma_f32_16x16x32_bf16 v[62:65], v[134:137], v[186:189], v[62:65]
	v_mfma_f32_16x16x32_bf16 v[58:61], v[142:145], v[186:189], v[58:61]
	v_mfma_f32_16x16x32_bf16 v[46:49], v[134:137], v[194:197], v[46:49]
	v_mfma_f32_16x16x32_bf16 v[42:45], v[142:145], v[194:197], v[42:45]
	v_mfma_f32_16x16x32_bf16 v[30:33], v[134:137], v[202:205], v[30:33]
	v_mfma_f32_16x16x32_bf16 v[26:29], v[142:145], v[202:205], v[26:29]
	v_mfma_f32_16x16x32_bf16 v[14:17], v[134:137], v[226:229], v[14:17]
	v_mfma_f32_16x16x32_bf16 v[10:13], v[142:145], v[226:229], v[10:13]
	v_mfma_f32_16x16x32_bf16 v[54:57], v[166:169], v[182:185], v[54:57]
	v_mfma_f32_16x16x32_bf16 v[50:53], v[174:177], v[182:185], v[50:53]
	v_mfma_f32_16x16x32_bf16 v[38:41], v[166:169], v[190:193], v[38:41]
	v_mfma_f32_16x16x32_bf16 v[34:37], v[174:177], v[190:193], v[34:37]
	v_mfma_f32_16x16x32_bf16 v[22:25], v[166:169], v[198:201], v[22:25]
	v_mfma_f32_16x16x32_bf16 v[18:21], v[174:177], v[198:201], v[18:21]
	v_mfma_f32_16x16x32_bf16 v[6:9], v[166:169], v[206:209], v[6:9]
	v_mfma_f32_16x16x32_bf16 v[2:5], v[174:177], v[206:209], v[2:5]
	v_mfma_f32_16x16x32_bf16 v[54:57], v[170:173], v[186:189], v[54:57]
	v_mfma_f32_16x16x32_bf16 v[50:53], v[178:181], v[186:189], v[50:53]
	v_mfma_f32_16x16x32_bf16 v[38:41], v[170:173], v[194:197], v[38:41]
	v_mfma_f32_16x16x32_bf16 v[34:37], v[178:181], v[194:197], v[34:37]
	v_mfma_f32_16x16x32_bf16 v[22:25], v[170:173], v[202:205], v[22:25]
	v_mfma_f32_16x16x32_bf16 v[18:21], v[178:181], v[202:205], v[18:21]
	v_mfma_f32_16x16x32_bf16 v[6:9], v[170:173], v[226:229], v[6:9]
	v_mfma_f32_16x16x32_bf16 v[2:5], v[178:181], v[226:229], v[2:5]
	s_barrier
	s_add_i32 s89, s89, 2
	s_add_u32 s4, s4, 0x100
	s_addc_u32 s5, s5, 0
	s_add_u32 s85, s85, 0x100
	s_addc_u32 s88, s88, 0
	s_cmp_gt_u32 s89, 13
	s_cbranch_scc0 .LBB0_787
	s_and_b64 vcc, exec, s[62:63]
	s_cbranch_vccz .LBB0_790
	s_barrier

; #define PG8_STAGE(bufoff, gbase, voff) do { _Pragma("unroll") for (int _i = 0; _i < 2; ++_i) \
;         __builtin_amdgcn_global_load_lds((const unsigned*)((const char*)(gbase) + (voff)[_i]), (LAS unsigned*)(lds + (bufoff) + ldsw + _i * 8192), 16, 0, 0); } while (0)
; #define PG8_LDA(dst, b, h) do { _Pragma("unroll") for (int m = 0; m < 4; ++m) _Pragma("unroll") for (int k = 0; k < 2; ++k) dst[m][k] = *(const LAS bf16x8*)(lds + PG8_SA(b, h) + aoff + m * 2048 + k * 1024); } while (0)
; #define PG8_LDB(dst, b, h) do { _Pragma("unroll") for (int n = 0; n < 2; ++n) _Pragma("unroll") for (int k = 0; k < 2; ++k) dst[n][k] = *(const LAS bf16x8*)(lds + PG8_SB(b, h) + boff + n * 2048 + k * 1024); } while (0)
; #define PG8_MMA(ai, bj, At, Bt) do { __builtin_amdgcn_s_setprio(3); _Pragma("unroll") for (int m = 0; m < 4; ++m) _Pragma("unroll") for (int n = 0; n < 2; ++n) _Pragma("unroll") for (int k = 0; k < 2; ++k) \
;         acc[ai][bj][m][n] = __builtin_amdgcn_mfma_f32_16x16x32_bf16(Bt[n][k], At[m][k], acc[ai][bj][m][n], 0, 0, 0); __builtin_amdgcn_s_setprio(0); } while (0)
; #define PG8_WAIT_V(n) asm volatile("s_waitcnt vmcnt(" #n ")" ::: "memory")
; #define PG8_WAIT_L(n) asm volatile("s_waitcnt lgkmcnt(" #n ")" ::: "memory")
; #define PG8_BAR __builtin_amdgcn_s_barrier()
; #define PG8_SCHED __builtin_amdgcn_sched_barrier(0)
; template <class Epi, bool ALIGN_EPI>
; __device__ __forceinline__ void gemm_phase(LAS unsigned char* lds, const Gemm g, const StaticOrder& S, const Epi& E) {
;     ...
;             PG8_LDB(B0, 0, 0); PG8_LDB(B1, 0, 1); PG8_SCHED; PG8_LDA(At, 0, 0); PG8_STAGE(PG8_SA(1, 1), a1 + hstep, voffA);
;             PG8_WAIT_V(8); PG8_WAIT_L(0); PG8_BAR; PG8_MMA(0, 0, At, B0); PG8_MMA(0, 1, At, B1); PG8_BAR; PG8_SCHED;
;             PG8_LDA(At, 0, 1); PG8_STAGE(PG8_SB(0, 0), b2, voffB); PG8_STAGE(PG8_SB(0, 1), b2 + hstep, voffB); PG8_STAGE(PG8_SA(0, 0), a2, voffA);
;             PG8_WAIT_V(8); PG8_WAIT_L(0); PG8_BAR; PG8_MMA(1, 0, At, B0); PG8_MMA(1, 1, At, B1); PG8_BAR; PG8_SCHED;
.Lmy_rw_1339_0:
	s_waitcnt lgkmcnt(0)
	s_barrier
	s_waitcnt lgkmcnt(0)
	v_mfma_f32_16x16x32_bf16 v[126:129], v[130:133], v[178:181], 0
	v_mfma_f32_16x16x32_bf16 v[122:125], v[138:141], v[178:181], 0
	v_mfma_f32_16x16x32_bf16 v[110:113], v[130:133], v[200:203], 0
	v_mfma_f32_16x16x32_bf16 v[106:109], v[138:141], v[200:203], 0
	v_mfma_f32_16x16x32_bf16 v[94:97], v[130:133], v[208:211], 0
	v_mfma_f32_16x16x32_bf16 v[90:93], v[138:141], v[208:211], 0
	v_mfma_f32_16x16x32_bf16 v[78:81], v[130:133], v[216:219], 0
	v_mfma_f32_16x16x32_bf16 v[74:77], v[138:141], v[216:219], 0
	v_mfma_f32_16x16x32_bf16 v[126:129], v[134:137], v[182:185], v[126:129]
	v_mfma_f32_16x16x32_bf16 v[122:125], v[142:145], v[182:185], v[122:125]
	v_mfma_f32_16x16x32_bf16 v[110:113], v[134:137], v[204:207], v[110:113]
	v_mfma_f32_16x16x32_bf16 v[106:109], v[142:145], v[204:207], v[106:109]
	v_mfma_f32_16x16x32_bf16 v[94:97], v[134:137], v[212:215], v[94:97]
	v_mfma_f32_16x16x32_bf16 v[90:93], v[142:145], v[212:215], v[90:93]
	v_mfma_f32_16x16x32_bf16 v[78:81], v[134:137], v[220:223], v[78:81]
	v_mfma_f32_16x16x32_bf16 v[74:77], v[142:145], v[220:223], v[74:77]
	v_mfma_f32_16x16x32_bf16 v[118:121], v[146:149], v[178:181], 0
	v_mfma_f32_16x16x32_bf16 v[114:117], v[170:173], v[178:181], 0
	v_mfma_f32_16x16x32_bf16 v[102:105], v[146:149], v[200:203], 0
	v_mfma_f32_16x16x32_bf16 v[98:101], v[170:173], v[200:203], 0
	v_mfma_f32_16x16x32_bf16 v[86:89], v[146:149], v[208:211], 0
	v_mfma_f32_16x16x32_bf16 v[82:85], v[170:173], v[208:211], 0
	v_mfma_f32_16x16x32_bf16 v[70:73], v[146:149], v[216:219], 0
	v_mfma_f32_16x16x32_bf16 v[66:69], v[170:173], v[216:219], 0
	v_mfma_f32_16x16x32_bf16 v[118:121], v[150:153], v[182:185], v[118:121]
	v_mfma_f32_16x16x32_bf16 v[114:117], v[174:177], v[182:185], v[114:117]
	v_mfma_f32_16x16x32_bf16 v[102:105], v[150:153], v[204:207], v[102:105]
	v_mfma_f32_16x16x32_bf16 v[98:101], v[174:177], v[204:207], v[98:101]
	v_mfma_f32_16x16x32_bf16 v[86:89], v[150:153], v[212:215], v[86:89]
	v_mfma_f32_16x16x32_bf16 v[82:85], v[174:177], v[212:215], v[82:85]
	v_mfma_f32_16x16x32_bf16 v[70:73], v[150:153], v[220:223], v[70:73]
	v_mfma_f32_16x16x32_bf16 v[66:69], v[174:177], v[220:223], v[66:69]
	s_barrier
	s_add_i32 s62, s56, s47
	v_lshl_add_u64 v[186:187], s[42:43], 0, v[156:157]
	s_mov_b32 m0, s62
	ds_read_b128 v[178:181], v198 offset:16384
	ds_read_b128 v[182:185], v198 offset:17408
	ds_read_b128 v[200:203], v198 offset:18432
	ds_read_b128 v[204:207], v198 offset:19456
	ds_read_b128 v[208:211], v198 offset:20480
	ds_read_b128 v[212:215], v198 offset:21504
	ds_read_b128 v[216:219], v198 offset:22528
	ds_read_b128 v[220:223], v198 offset:23552
	global_load_lds_dwordx4 v[186:187], off
	s_add_i32 m0, s62, 0x2000
	s_add_u32 s62, s42, 0x40000
	v_lshl_add_u64 v[224:225], s[42:43], 0, v[160:161]
	s_addc_u32 s63, s43, 0
	s_add_i32 s64, s57, s47
	global_load_lds_dwordx4 v[224:225], off
	v_lshl_add_u64 v[226:227], s[62:63], 0, v[156:157]
	s_mov_b32 m0, s64
	v_lshl_add_u64 v[228:229], s[44:45], 0, v[158:159]
	global_load_lds_dwordx4 v[226:227], off
	v_lshl_add_u64 v[226:227], s[62:63], 0, v[160:161]
	s_add_i32 m0, s64, 0x2000
	s_nop 0
	global_load_lds_dwordx4 v[226:227], off
	v_lshl_add_u64 v[226:227], s[44:45], 0, v[154:155]
	s_mov_b32 m0, s39
	s_nop 0
	global_load_lds_dwordx4 v[226:227], off
	s_mov_b32 m0, s48
	s_nop 0
	global_load_lds_dwordx4 v[228:229], off
	s_cmp_lg_u32 s98, 0
	s_cbranch_scc1 .Lmy_rw_1339_1
	s_waitcnt vmcnt(8)
.Lmy_rw_1339_1:
	s_waitcnt lgkmcnt(0)
	s_barrier
	s_waitcnt lgkmcnt(0)
	v_mfma_f32_16x16x32_bf16 v[62:65], v[130:133], v[178:181], 0
	v_mfma_f32_16x16x32_bf16 v[58:61], v[138:141], v[178:181], 0
	v_mfma_f32_16x16x32_bf16 v[46:49], v[130:133], v[200:203], 0
	v_mfma_f32_16x16x32_bf16 v[42:45], v[138:141], v[200:203], 0
	v_mfma_f32_16x16x32_bf16 v[30:33], v[130:133], v[208:211], 0
	v_mfma_f32_16x16x32_bf16 v[26:29], v[138:141], v[208:211], 0
	v_mfma_f32_16x16x32_bf16 v[14:17], v[130:133], v[216:219], 0
	v_mfma_f32_16x16x32_bf16 v[10:13], v[138:141], v[216:219], 0
	v_mfma_f32_16x16x32_bf16 v[62:65], v[134:137], v[182:185], v[62:65]
	v_mfma_f32_16x16x32_bf16 v[58:61], v[142:145], v[182:185], v[58:61]
	v_mfma_f32_16x16x32_bf16 v[46:49], v[134:137], v[204:207], v[46:49]
	v_mfma_f32_16x16x32_bf16 v[42:45], v[142:145], v[204:207], v[42:45]
	v_mfma_f32_16x16x32_bf16 v[30:33], v[134:137], v[212:215], v[30:33]
	v_mfma_f32_16x16x32_bf16 v[26:29], v[142:145], v[212:215], v[26:29]
	v_mfma_f32_16x16x32_bf16 v[14:17], v[134:137], v[220:223], v[14:17]
	v_mfma_f32_16x16x32_bf16 v[10:13], v[142:145], v[220:223], v[10:13]
	v_mfma_f32_16x16x32_bf16 v[54:57], v[146:149], v[178:181], 0
	v_mfma_f32_16x16x32_bf16 v[50:53], v[170:173], v[178:181], 0
	v_mfma_f32_16x16x32_bf16 v[38:41], v[146:149], v[200:203], 0
	v_mfma_f32_16x16x32_bf16 v[34:37], v[170:173], v[200:203], 0
	v_mfma_f32_16x16x32_bf16 v[22:25], v[146:149], v[208:211], 0
	v_mfma_f32_16x16x32_bf16 v[18:21], v[170:173], v[208:211], 0
	v_mfma_f32_16x16x32_bf16 v[6:9], v[146:149], v[216:219], 0
	v_mfma_f32_16x16x32_bf16 v[2:5], v[170:173], v[216:219], 0
	v_mfma_f32_16x16x32_bf16 v[54:57], v[150:153], v[182:185], v[54:57]
	v_mfma_f32_16x16x32_bf16 v[50:53], v[174:177], v[182:185], v[50:53]
	v_mfma_f32_16x16x32_bf16 v[38:41], v[150:153], v[204:207], v[38:41]
	v_mfma_f32_16x16x32_bf16 v[34:37], v[174:177], v[204:207], v[34:37]
	v_mfma_f32_16x16x32_bf16 v[22:25], v[150:153], v[212:215], v[22:25]
	v_mfma_f32_16x16x32_bf16 v[18:21], v[174:177], v[212:215], v[18:21]
	v_mfma_f32_16x16x32_bf16 v[6:9], v[150:153], v[220:223], v[6:9]
	v_mfma_f32_16x16x32_bf16 v[2:5], v[174:177], v[220:223], v[2:5]
	s_barrier
; #define PG8_STAGE(bufoff, gbase, voff) do { _Pragma("unroll") for (int _i = 0; _i < 2; ++_i) \
;         __builtin_amdgcn_global_load_lds((const unsigned*)((const char*)(gbase) + (voff)[_i]), (LAS unsigned*)(lds + (bufoff) + ldsw + _i * 8192), 16, 0, 0); } while (0)
; #define PG8_LDA(dst, b, h) do { _Pragma("unroll") for (int m = 0; m < 4; ++m) _Pragma("unroll") for (int k = 0; k < 2; ++k) dst[m][k] = *(const LAS bf16x8*)(lds + PG8_SA(b, h) + aoff + m * 2048 + k * 1024); } while (0)
; #define PG8_LDB(dst, b, h) do { _Pragma("unroll") for (int n = 0; n < 2; ++n) _Pragma("unroll") for (int k = 0; k < 2; ++k) dst[n][k] = *(const LAS bf16x8*)(lds + PG8_SB(b, h) + boff + n * 2048 + k * 1024); } while (0)
; #define PG8_MMA(ai, bj, At, Bt) do { __builtin_amdgcn_s_setprio(3); _Pragma("unroll") for (int m = 0; m < 4; ++m) _Pragma("unroll") for (int n = 0; n < 2; ++n) _Pragma("unroll") for (int k = 0; k < 2; ++k) \
;         acc[ai][bj][m][n] = __builtin_amdgcn_mfma_f32_16x16x32_bf16(Bt[n][k], At[m][k], acc[ai][bj][m][n], 0, 0, 0); __builtin_amdgcn_s_setprio(0); } while (0)
; #define PG8_WAIT_V(n) asm volatile("s_waitcnt vmcnt(" #n ")" ::: "memory")
; #define PG8_WAIT_L(n) asm volatile("s_waitcnt lgkmcnt(" #n ")" ::: "memory")
; #define PG8_BAR __builtin_amdgcn_s_barrier()
; #define PG8_SCHED __builtin_amdgcn_sched_barrier(0)
; template <class Epi, bool ALIGN_EPI>
; __device__ __forceinline__ void gemm_phase(LAS unsigned char* lds, const Gemm g, const StaticOrder& S, const Epi& E) {
;     ...
;             PG8_LDB(B0, 1, 0); PG8_LDB(B1, 1, 1); PG8_SCHED; PG8_LDA(At, 1, 0); PG8_STAGE(PG8_SA(0, 1), a2 + hstep, voffA);
;             PG8_WAIT_V(8); PG8_WAIT_L(0); PG8_BAR; PG8_MMA(0, 0, At, B0); PG8_MMA(0, 1, At, B1); PG8_BAR; PG8_SCHED;
;             PG8_LDA(At, 1, 1); PG8_STAGE(PG8_SB(1, 0), b3, voffB); PG8_STAGE(PG8_SB(1, 1), b3 + hstep, voffB); PG8_STAGE(PG8_SA(1, 0), a3, voffA);
;             PG8_WAIT_V(8); PG8_WAIT_L(0); PG8_BAR; PG8_MMA(1, 0, At, B0); PG8_MMA(1, 1, At, B1); PG8_BAR; PG8_SCHED;
	s_add_i32 s62, 0, 0x18000
	s_add_i32 s63, 0, 0x1c000
	v_add_u32_e32 v142, s62, v194
	v_add_u32_e32 v174, s63, v194
	ds_read_b128 v[130:133], v142
	ds_read_b128 v[134:137], v142 offset:1024
	ds_read_b128 v[138:141], v142 offset:2048
	ds_read_b128 v[142:145], v142 offset:3072
	ds_read_b128 v[146:149], v174
	ds_read_b128 v[150:153], v174 offset:1024
	ds_read_b128 v[170:173], v174 offset:2048
	ds_read_b128 v[174:177], v174 offset:3072
	s_add_u32 s44, s44, 0x40000
	s_addc_u32 s45, s45, 0
	s_mov_b32 m0, s49
	v_lshl_add_u64 v[230:231], s[44:45], 0, v[154:155]
	ds_read_b128 v[178:181], v198 offset:32768
	ds_read_b128 v[182:185], v198 offset:33792
	ds_read_b128 v[200:203], v198 offset:34816
	ds_read_b128 v[204:207], v198 offset:35840
	ds_read_b128 v[208:211], v198 offset:36864
	ds_read_b128 v[212:215], v198 offset:37888
	ds_read_b128 v[216:219], v198 offset:38912
	ds_read_b128 v[220:223], v198 offset:39936
	global_load_lds_dwordx4 v[230:231], off
	v_lshl_add_u64 v[230:231], s[44:45], 0, v[158:159]
	s_mov_b32 m0, s50
	s_nop 0
	global_load_lds_dwordx4 v[230:231], off
	s_waitcnt vmcnt(8)
	s_waitcnt lgkmcnt(0)
	s_barrier
	s_waitcnt lgkmcnt(0)
	v_mfma_f32_16x16x32_bf16 v[126:129], v[130:133], v[178:181], v[126:129]
	v_mfma_f32_16x16x32_bf16 v[122:125], v[138:141], v[178:181], v[122:125]
	v_mfma_f32_16x16x32_bf16 v[110:113], v[130:133], v[200:203], v[110:113]
	v_mfma_f32_16x16x32_bf16 v[106:109], v[138:141], v[200:203], v[106:109]
	v_mfma_f32_16x16x32_bf16 v[94:97], v[130:133], v[208:211], v[94:97]
	v_mfma_f32_16x16x32_bf16 v[90:93], v[138:141], v[208:211], v[90:93]
	v_mfma_f32_16x16x32_bf16 v[78:81], v[130:133], v[216:219], v[78:81]
	v_mfma_f32_16x16x32_bf16 v[74:77], v[138:141], v[216:219], v[74:77]
	v_mfma_f32_16x16x32_bf16 v[126:129], v[134:137], v[182:185], v[126:129]
	v_mfma_f32_16x16x32_bf16 v[122:125], v[142:145], v[182:185], v[122:125]
	v_mfma_f32_16x16x32_bf16 v[110:113], v[134:137], v[204:207], v[110:113]
	v_mfma_f32_16x16x32_bf16 v[106:109], v[142:145], v[204:207], v[106:109]
	v_mfma_f32_16x16x32_bf16 v[94:97], v[134:137], v[212:215], v[94:97]
	v_mfma_f32_16x16x32_bf16 v[90:93], v[142:145], v[212:215], v[90:93]
	v_mfma_f32_16x16x32_bf16 v[78:81], v[134:137], v[220:223], v[78:81]
	v_mfma_f32_16x16x32_bf16 v[74:77], v[142:145], v[220:223], v[74:77]
	v_mfma_f32_16x16x32_bf16 v[118:121], v[146:149], v[178:181], v[118:121]
	v_mfma_f32_16x16x32_bf16 v[114:117], v[170:173], v[178:181], v[114:117]
	v_mfma_f32_16x16x32_bf16 v[102:105], v[146:149], v[200:203], v[102:105]
	v_mfma_f32_16x16x32_bf16 v[98:101], v[170:173], v[200:203], v[98:101]
	v_mfma_f32_16x16x32_bf16 v[86:89], v[146:149], v[208:211], v[86:89]
	v_mfma_f32_16x16x32_bf16 v[82:85], v[170:173], v[208:211], v[82:85]
	v_mfma_f32_16x16x32_bf16 v[70:73], v[146:149], v[216:219], v[70:73]
	v_mfma_f32_16x16x32_bf16 v[66:69], v[170:173], v[216:219], v[66:69]
	v_mfma_f32_16x16x32_bf16 v[118:121], v[150:153], v[182:185], v[118:121]
	v_mfma_f32_16x16x32_bf16 v[114:117], v[174:177], v[182:185], v[114:117]
	v_mfma_f32_16x16x32_bf16 v[102:105], v[150:153], v[204:207], v[102:105]
	v_mfma_f32_16x16x32_bf16 v[98:101], v[174:177], v[204:207], v[98:101]
	v_mfma_f32_16x16x32_bf16 v[86:89], v[150:153], v[212:215], v[86:89]
	v_mfma_f32_16x16x32_bf16 v[82:85], v[174:177], v[212:215], v[82:85]
	v_mfma_f32_16x16x32_bf16 v[70:73], v[150:153], v[220:223], v[70:73]
	v_mfma_f32_16x16x32_bf16 v[66:69], v[174:177], v[220:223], v[66:69]
	s_barrier
	s_add_i32 s44, s62, s47
	v_lshl_add_u64 v[186:187], v[186:187], 0, s[12:13]
	s_mov_b32 m0, s44
	ds_read_b128 v[178:181], v198 offset:49152
	ds_read_b128 v[182:185], v198 offset:50176
	ds_read_b128 v[200:203], v198 offset:51200
	ds_read_b128 v[204:207], v198 offset:52224
	ds_read_b128 v[208:211], v198 offset:53248
	ds_read_b128 v[212:215], v198 offset:54272
	ds_read_b128 v[216:219], v198 offset:55296
	ds_read_b128 v[220:223], v198 offset:56320
	global_load_lds_dwordx4 v[186:187], off
	s_add_i32 m0, s44, 0x2000
	s_add_u32 s42, s42, 0x40080
	v_lshl_add_u64 v[186:187], v[224:225], 0, s[12:13]
	s_addc_u32 s43, s43, 0
	s_add_i32 s44, s63, s47
	global_load_lds_dwordx4 v[186:187], off
	v_lshl_add_u64 v[186:187], s[42:43], 0, v[156:157]
	s_mov_b32 m0, s44
	s_nop 0
	global_load_lds_dwordx4 v[186:187], off
	v_lshl_add_u64 v[186:187], s[42:43], 0, v[160:161]
	s_add_i32 m0, s44, 0x2000
	s_nop 0
	global_load_lds_dwordx4 v[186:187], off
	v_lshl_add_u64 v[186:187], v[226:227], 0, s[12:13]
	s_mov_b32 m0, s52
	s_nop 0
	global_load_lds_dwordx4 v[186:187], off
	v_lshl_add_u64 v[186:187], v[228:229], 0, s[12:13]
	s_mov_b32 m0, s53
	s_nop 0
	global_load_lds_dwordx4 v[186:187], off
	s_waitcnt vmcnt(8)
	s_waitcnt lgkmcnt(0)
	s_barrier
	s_waitcnt lgkmcnt(0)
	v_mfma_f32_16x16x32_bf16 v[62:65], v[130:133], v[178:181], v[62:65]
	v_mfma_f32_16x16x32_bf16 v[58:61], v[138:141], v[178:181], v[58:61]
	v_mfma_f32_16x16x32_bf16 v[46:49], v[130:133], v[200:203], v[46:49]
	v_mfma_f32_16x16x32_bf16 v[42:45], v[138:141], v[200:203], v[42:45]
	v_mfma_f32_16x16x32_bf16 v[30:33], v[130:133], v[208:211], v[30:33]
	v_mfma_f32_16x16x32_bf16 v[26:29], v[138:141], v[208:211], v[26:29]
	v_mfma_f32_16x16x32_bf16 v[14:17], v[130:133], v[216:219], v[14:17]
	v_mfma_f32_16x16x32_bf16 v[10:13], v[138:141], v[216:219], v[10:13]
	v_mfma_f32_16x16x32_bf16 v[62:65], v[134:137], v[182:185], v[62:65]
	v_mfma_f32_16x16x32_bf16 v[58:61], v[142:145], v[182:185], v[58:61]
	v_mfma_f32_16x16x32_bf16 v[46:49], v[134:137], v[204:207], v[46:49]
	v_mfma_f32_16x16x32_bf16 v[42:45], v[142:145], v[204:207], v[42:45]
	v_mfma_f32_16x16x32_bf16 v[30:33], v[134:137], v[212:215], v[30:33]
	v_mfma_f32_16x16x32_bf16 v[26:29], v[142:145], v[212:215], v[26:29]
	v_mfma_f32_16x16x32_bf16 v[14:17], v[134:137], v[220:223], v[14:17]
	v_mfma_f32_16x16x32_bf16 v[10:13], v[142:145], v[220:223], v[10:13]
	v_mfma_f32_16x16x32_bf16 v[54:57], v[146:149], v[178:181], v[54:57]
	v_mfma_f32_16x16x32_bf16 v[50:53], v[170:173], v[178:181], v[50:53]
	v_mfma_f32_16x16x32_bf16 v[38:41], v[146:149], v[200:203], v[38:41]
	v_mfma_f32_16x16x32_bf16 v[34:37], v[170:173], v[200:203], v[34:37]
	v_mfma_f32_16x16x32_bf16 v[22:25], v[146:149], v[208:211], v[22:25]
	v_mfma_f32_16x16x32_bf16 v[18:21], v[170:173], v[208:211], v[18:21]
	v_mfma_f32_16x16x32_bf16 v[6:9], v[146:149], v[216:219], v[6:9]
	v_mfma_f32_16x16x32_bf16 v[2:5], v[170:173], v[216:219], v[2:5]
	v_mfma_f32_16x16x32_bf16 v[54:57], v[150:153], v[182:185], v[54:57]
	v_mfma_f32_16x16x32_bf16 v[50:53], v[174:177], v[182:185], v[50:53]
	v_mfma_f32_16x16x32_bf16 v[38:41], v[150:153], v[204:207], v[38:41]
	v_mfma_f32_16x16x32_bf16 v[34:37], v[174:177], v[204:207], v[34:37]
	v_mfma_f32_16x16x32_bf16 v[22:25], v[150:153], v[212:215], v[22:25]
	v_mfma_f32_16x16x32_bf16 v[18:21], v[174:177], v[212:215], v[18:21]
	v_mfma_f32_16x16x32_bf16 v[6:9], v[150:153], v[220:223], v[6:9]
	v_mfma_f32_16x16x32_bf16 v[2:5], v[174:177], v[220:223], v[2:5]
	s_barrier
	s_add_i32 s61, s61, 2
	s_add_u32 s40, s40, 0x100
	s_addc_u32 s41, s41, 0
	s_add_u32 s59, s59, 0x100
	s_addc_u32 s60, s60, 0
; #define PG8_STAGE(bufoff, gbase, voff) do { _Pragma("unroll") for (int _i = 0; _i < 2; ++_i) \
;         __builtin_amdgcn_global_load_lds((const unsigned*)((const char*)(gbase) + (voff)[_i]), (LAS unsigned*)(lds + (bufoff) + ldsw + _i * 8192), 16, 0, 0); } while (0)
; #define PG8_LDA(dst, b, h) do { _Pragma("unroll") for (int m = 0; m < 4; ++m) _Pragma("unroll") for (int k = 0; k < 2; ++k) dst[m][k] = *(const LAS bf16x8*)(lds + PG8_SA(b, h) + aoff + m * 2048 + k * 1024); } while (0)
; #define PG8_LDB(dst, b, h) do { _Pragma("unroll") for (int n = 0; n < 2; ++n) _Pragma("unroll") for (int k = 0; k < 2; ++k) dst[n][k] = *(const LAS bf16x8*)(lds + PG8_SB(b, h) + boff + n * 2048 + k * 1024); } while (0)
; #define PG8_MMA(ai, bj, At, Bt) do { __builtin_amdgcn_s_setprio(3); _Pragma("unroll") for (int m = 0; m < 4; ++m) _Pragma("unroll") for (int n = 0; n < 2; ++n) _Pragma("unroll") for (int k = 0; k < 2; ++k) \
;         acc[ai][bj][m][n] = __builtin_amdgcn_mfma_f32_16x16x32_bf16(Bt[n][k], At[m][k], acc[ai][bj][m][n], 0, 0, 0); __builtin_amdgcn_s_setprio(0); } while (0)
; #define PG8_WAIT_V(n) asm volatile("s_waitcnt vmcnt(" #n ")" ::: "memory")
; #define PG8_WAIT_L(n) asm volatile("s_waitcnt lgkmcnt(" #n ")" ::: "memory")
; #define PG8_BAR __builtin_amdgcn_s_barrier()
; #define PG8_SCHED __builtin_amdgcn_sched_barrier(0)
; template <class Epi, bool ALIGN_EPI>
; __device__ __forceinline__ void gemm_phase(LAS unsigned char* lds, const Gemm g, const StaticOrder& S, const Epi& E) {
;     ...
;             PG8_LDB(B0, 0, 0); PG8_LDB(B1, 0, 1); PG8_SCHED; PG8_LDA(At, 0, 0); PG8_STAGE(PG8_SA(1, 1), a1 + hstep, voffA);
;             PG8_WAIT_V(8); PG8_WAIT_L(0); PG8_BAR; PG8_MMA(0, 0, At, B0); PG8_MMA(0, 1, At, B1); PG8_BAR; PG8_SCHED;
;             PG8_LDA(At, 0, 1); PG8_STAGE(PG8_SB(0, 0), b2, voffB); PG8_STAGE(PG8_SB(0, 1), b2 + hstep, voffB); PG8_STAGE(PG8_SA(0, 0), a2, voffA);
;             PG8_WAIT_V(8); PG8_WAIT_L(0); PG8_BAR; PG8_MMA(1, 0, At, B0); PG8_MMA(1, 1, At, B1); PG8_BAR; PG8_SCHED;
.LBB0_1339:
	ds_read_b128 v[130:133], v196
	ds_read_b128 v[134:137], v196 offset:1024
	ds_read_b128 v[138:141], v196 offset:2048
	ds_read_b128 v[142:145], v196 offset:3072
	ds_read_b128 v[146:149], v197
	ds_read_b128 v[150:153], v197 offset:1024
	ds_read_b128 v[170:173], v197 offset:2048
	ds_read_b128 v[174:177], v197 offset:3072
	s_add_u32 s42, s40, 0xfffc0080
	s_addc_u32 s43, s41, -1
	s_cmp_eq_u32 s61, 12
	s_cselect_b32 s45, s19, s43
	s_cselect_b32 s44, s37, s42
	s_cselect_b32 s43, s17, s60
	s_cselect_b32 s42, s58, s59
	v_lshl_add_u64 v[186:187], s[40:41], 0, v[162:163]
	s_add_i32 m0, s39, 0xc000
	ds_read_b128 v[178:181], v198
	ds_read_b128 v[182:185], v198 offset:1024
	ds_read_b128 v[200:203], v198 offset:2048
	ds_read_b128 v[204:207], v198 offset:3072
	ds_read_b128 v[208:211], v198 offset:4096
	ds_read_b128 v[212:215], v198 offset:5120
	ds_read_b128 v[216:219], v198 offset:6144
	ds_read_b128 v[220:223], v198 offset:7168
	global_load_lds_dwordx4 v[186:187], off
	v_lshl_add_u64 v[186:187], s[40:41], 0, v[164:165]
	s_add_i32 m0, s39, 0xe000
	s_nop 0
	global_load_lds_dwordx4 v[186:187], off
	s_waitcnt vmcnt(8)
	s_waitcnt lgkmcnt(0)
	s_barrier
	s_waitcnt lgkmcnt(0)
	v_mfma_f32_16x16x32_bf16 v[126:129], v[130:133], v[178:181], v[126:129]
	v_mfma_f32_16x16x32_bf16 v[122:125], v[138:141], v[178:181], v[122:125]
	v_mfma_f32_16x16x32_bf16 v[110:113], v[130:133], v[200:203], v[110:113]
	v_mfma_f32_16x16x32_bf16 v[106:109], v[138:141], v[200:203], v[106:109]
	v_mfma_f32_16x16x32_bf16 v[94:97], v[130:133], v[208:211], v[94:97]
	v_mfma_f32_16x16x32_bf16 v[90:93], v[138:141], v[208:211], v[90:93]
	v_mfma_f32_16x16x32_bf16 v[78:81], v[130:133], v[216:219], v[78:81]
	v_mfma_f32_16x16x32_bf16 v[74:77], v[138:141], v[216:219], v[74:77]
	v_mfma_f32_16x16x32_bf16 v[126:129], v[134:137], v[182:185], v[126:129]
	v_mfma_f32_16x16x32_bf16 v[122:125], v[142:145], v[182:185], v[122:125]
	v_mfma_f32_16x16x32_bf16 v[110:113], v[134:137], v[204:207], v[110:113]
	v_mfma_f32_16x16x32_bf16 v[106:109], v[142:145], v[204:207], v[106:109]
	v_mfma_f32_16x16x32_bf16 v[94:97], v[134:137], v[212:215], v[94:97]
	v_mfma_f32_16x16x32_bf16 v[90:93], v[142:145], v[212:215], v[90:93]
	v_mfma_f32_16x16x32_bf16 v[78:81], v[134:137], v[220:223], v[78:81]
	v_mfma_f32_16x16x32_bf16 v[74:77], v[142:145], v[220:223], v[74:77]
	v_mfma_f32_16x16x32_bf16 v[118:121], v[146:149], v[178:181], v[118:121]
	v_mfma_f32_16x16x32_bf16 v[114:117], v[170:173], v[178:181], v[114:117]
	v_mfma_f32_16x16x32_bf16 v[102:105], v[146:149], v[200:203], v[102:105]
	v_mfma_f32_16x16x32_bf16 v[98:101], v[170:173], v[200:203], v[98:101]
	v_mfma_f32_16x16x32_bf16 v[86:89], v[146:149], v[208:211], v[86:89]
	v_mfma_f32_16x16x32_bf16 v[82:85], v[170:173], v[208:211], v[82:85]
	v_mfma_f32_16x16x32_bf16 v[70:73], v[146:149], v[216:219], v[70:73]
	v_mfma_f32_16x16x32_bf16 v[66:69], v[170:173], v[216:219], v[66:69]
	v_mfma_f32_16x16x32_bf16 v[118:121], v[150:153], v[182:185], v[118:121]
	v_mfma_f32_16x16x32_bf16 v[114:117], v[174:177], v[182:185], v[114:117]
	v_mfma_f32_16x16x32_bf16 v[102:105], v[150:153], v[204:207], v[102:105]
	v_mfma_f32_16x16x32_bf16 v[98:101], v[174:177], v[204:207], v[98:101]
	v_mfma_f32_16x16x32_bf16 v[86:89], v[150:153], v[212:215], v[86:89]
	v_mfma_f32_16x16x32_bf16 v[82:85], v[174:177], v[212:215], v[82:85]
	v_mfma_f32_16x16x32_bf16 v[70:73], v[150:153], v[220:223], v[70:73]
	v_mfma_f32_16x16x32_bf16 v[66:69], v[174:177], v[220:223], v[66:69]
	s_barrier
	s_add_i32 s62, s56, s47
	v_lshl_add_u64 v[186:187], s[42:43], 0, v[156:157]
	s_mov_b32 m0, s62
	ds_read_b128 v[178:181], v198 offset:16384
	ds_read_b128 v[182:185], v198 offset:17408
	ds_read_b128 v[200:203], v198 offset:18432
	ds_read_b128 v[204:207], v198 offset:19456
	ds_read_b128 v[208:211], v198 offset:20480
	ds_read_b128 v[212:215], v198 offset:21504
	ds_read_b128 v[216:219], v198 offset:22528
	ds_read_b128 v[220:223], v198 offset:23552
	global_load_lds_dwordx4 v[186:187], off
	s_add_i32 m0, s62, 0x2000
	s_add_u32 s62, s42, 0x40000
	v_lshl_add_u64 v[224:225], s[42:43], 0, v[160:161]
	s_addc_u32 s63, s43, 0
	s_add_i32 s64, s57, s47
	global_load_lds_dwordx4 v[224:225], off
	v_lshl_add_u64 v[226:227], s[62:63], 0, v[156:157]
	s_mov_b32 m0, s64
	v_lshl_add_u64 v[228:229], s[44:45], 0, v[158:159]
	global_load_lds_dwordx4 v[226:227], off
	v_lshl_add_u64 v[226:227], s[62:63], 0, v[160:161]
	s_add_i32 m0, s64, 0x2000
	s_nop 0
	global_load_lds_dwordx4 v[226:227], off
	v_lshl_add_u64 v[226:227], s[44:45], 0, v[154:155]
	s_mov_b32 m0, s39
	s_nop 0
	global_load_lds_dwordx4 v[226:227], off
	s_mov_b32 m0, s48
	s_nop 0
	global_load_lds_dwordx4 v[228:229], off
	s_waitcnt vmcnt(8)
	s_waitcnt lgkmcnt(0)
	s_barrier
; #define PG8_STAGE(bufoff, gbase, voff) do { _Pragma("unroll") for (int _i = 0; _i < 2; ++_i) \
;         __builtin_amdgcn_global_load_lds((const unsigned*)((const char*)(gbase) + (voff)[_i]), (LAS unsigned*)(lds + (bufoff) + ldsw + _i * 8192), 16, 0, 0); } while (0)
; #define PG8_LDA(dst, b, h) do { _Pragma("unroll") for (int m = 0; m < 4; ++m) _Pragma("unroll") for (int k = 0; k < 2; ++k) dst[m][k] = *(const LAS bf16x8*)(lds + PG8_SA(b, h) + aoff + m * 2048 + k * 1024); } while (0)
; #define PG8_LDB(dst, b, h) do { _Pragma("unroll") for (int n = 0; n < 2; ++n) _Pragma("unroll") for (int k = 0; k < 2; ++k) dst[n][k] = *(const LAS bf16x8*)(lds + PG8_SB(b, h) + boff + n * 2048 + k * 1024); } while (0)
; #define PG8_MMA(ai, bj, At, Bt) do { __builtin_amdgcn_s_setprio(3); _Pragma("unroll") for (int m = 0; m < 4; ++m) _Pragma("unroll") for (int n = 0; n < 2; ++n) _Pragma("unroll") for (int k = 0; k < 2; ++k) \
;         acc[ai][bj][m][n] = __builtin_amdgcn_mfma_f32_16x16x32_bf16(Bt[n][k], At[m][k], acc[ai][bj][m][n], 0, 0, 0); __builtin_amdgcn_s_setprio(0); } while (0)
; #define PG8_WAIT_V(n) asm volatile("s_waitcnt vmcnt(" #n ")" ::: "memory")
; #define PG8_WAIT_L(n) asm volatile("s_waitcnt lgkmcnt(" #n ")" ::: "memory")
; #define PG8_BAR __builtin_amdgcn_s_barrier()
; #define PG8_SCHED __builtin_amdgcn_sched_barrier(0)
; template <class Epi, bool ALIGN_EPI>
; __device__ __forceinline__ void gemm_phase(LAS unsigned char* lds, const Gemm g, const StaticOrder& S, const Epi& E) {
;     ...
;             PG8_WAIT_V(8); PG8_WAIT_L(0); PG8_BAR; PG8_MMA(1, 0, At, B0); PG8_MMA(1, 1, At, B1); PG8_BAR; PG8_SCHED;
;             PG8_LDB(B0, 1, 0); PG8_LDB(B1, 1, 1); PG8_SCHED; PG8_LDA(At, 1, 0); PG8_STAGE(PG8_SA(0, 1), a2 + hstep, voffA);
;             PG8_WAIT_V(8); PG8_WAIT_L(0); PG8_BAR; PG8_MMA(0, 0, At, B0); PG8_MMA(0, 1, At, B1); PG8_BAR; PG8_SCHED;
	s_waitcnt lgkmcnt(0)
	v_mfma_f32_16x16x32_bf16 v[62:65], v[130:133], v[178:181], v[62:65]
	v_mfma_f32_16x16x32_bf16 v[58:61], v[138:141], v[178:181], v[58:61]
	v_mfma_f32_16x16x32_bf16 v[46:49], v[130:133], v[200:203], v[46:49]
	v_mfma_f32_16x16x32_bf16 v[42:45], v[138:141], v[200:203], v[42:45]
	v_mfma_f32_16x16x32_bf16 v[30:33], v[130:133], v[208:211], v[30:33]
	v_mfma_f32_16x16x32_bf16 v[26:29], v[138:141], v[208:211], v[26:29]
	v_mfma_f32_16x16x32_bf16 v[14:17], v[130:133], v[216:219], v[14:17]
	v_mfma_f32_16x16x32_bf16 v[10:13], v[138:141], v[216:219], v[10:13]
	v_mfma_f32_16x16x32_bf16 v[62:65], v[134:137], v[182:185], v[62:65]
	v_mfma_f32_16x16x32_bf16 v[58:61], v[142:145], v[182:185], v[58:61]
	v_mfma_f32_16x16x32_bf16 v[46:49], v[134:137], v[204:207], v[46:49]
	v_mfma_f32_16x16x32_bf16 v[42:45], v[142:145], v[204:207], v[42:45]
	v_mfma_f32_16x16x32_bf16 v[30:33], v[134:137], v[212:215], v[30:33]
	v_mfma_f32_16x16x32_bf16 v[26:29], v[142:145], v[212:215], v[26:29]
	v_mfma_f32_16x16x32_bf16 v[14:17], v[134:137], v[220:223], v[14:17]
	v_mfma_f32_16x16x32_bf16 v[10:13], v[142:145], v[220:223], v[10:13]
	v_mfma_f32_16x16x32_bf16 v[54:57], v[146:149], v[178:181], v[54:57]
	v_mfma_f32_16x16x32_bf16 v[50:53], v[170:173], v[178:181], v[50:53]
	v_mfma_f32_16x16x32_bf16 v[38:41], v[146:149], v[200:203], v[38:41]
	v_mfma_f32_16x16x32_bf16 v[34:37], v[170:173], v[200:203], v[34:37]
	v_mfma_f32_16x16x32_bf16 v[22:25], v[146:149], v[208:211], v[22:25]
	v_mfma_f32_16x16x32_bf16 v[18:21], v[170:173], v[208:211], v[18:21]
	v_mfma_f32_16x16x32_bf16 v[6:9], v[146:149], v[216:219], v[6:9]
	v_mfma_f32_16x16x32_bf16 v[2:5], v[170:173], v[216:219], v[2:5]
	v_mfma_f32_16x16x32_bf16 v[54:57], v[150:153], v[182:185], v[54:57]
	v_mfma_f32_16x16x32_bf16 v[50:53], v[174:177], v[182:185], v[50:53]
	v_mfma_f32_16x16x32_bf16 v[38:41], v[150:153], v[204:207], v[38:41]
	v_mfma_f32_16x16x32_bf16 v[34:37], v[174:177], v[204:207], v[34:37]
	v_mfma_f32_16x16x32_bf16 v[22:25], v[150:153], v[212:215], v[22:25]
	v_mfma_f32_16x16x32_bf16 v[18:21], v[174:177], v[212:215], v[18:21]
	v_mfma_f32_16x16x32_bf16 v[6:9], v[150:153], v[220:223], v[6:9]
	v_mfma_f32_16x16x32_bf16 v[2:5], v[174:177], v[220:223], v[2:5]
	s_barrier
	s_add_i32 s62, 0, 0x18000
	s_add_i32 s63, 0, 0x1c000
	v_add_u32_e32 v142, s62, v194
	v_add_u32_e32 v174, s63, v194
	ds_read_b128 v[130:133], v142
	ds_read_b128 v[134:137], v142 offset:1024
	ds_read_b128 v[138:141], v142 offset:2048
	ds_read_b128 v[142:145], v142 offset:3072
	ds_read_b128 v[146:149], v174
	ds_read_b128 v[150:153], v174 offset:1024
	ds_read_b128 v[170:173], v174 offset:2048
	ds_read_b128 v[174:177], v174 offset:3072
	s_add_u32 s44, s44, 0x40000
	s_addc_u32 s45, s45, 0
	s_mov_b32 m0, s49
	v_lshl_add_u64 v[230:231], s[44:45], 0, v[154:155]
	ds_read_b128 v[178:181], v198 offset:32768
	ds_read_b128 v[182:185], v198 offset:33792
	ds_read_b128 v[200:203], v198 offset:34816
	ds_read_b128 v[204:207], v198 offset:35840
	ds_read_b128 v[208:211], v198 offset:36864
	ds_read_b128 v[212:215], v198 offset:37888
	ds_read_b128 v[216:219], v198 offset:38912
	ds_read_b128 v[220:223], v198 offset:39936
	global_load_lds_dwordx4 v[230:231], off
	v_lshl_add_u64 v[230:231], s[44:45], 0, v[158:159]
	s_mov_b32 m0, s50
	s_nop 0
	global_load_lds_dwordx4 v[230:231], off
	s_waitcnt vmcnt(8)
	s_waitcnt lgkmcnt(0)
	s_barrier
	s_waitcnt lgkmcnt(0)
	v_mfma_f32_16x16x32_bf16 v[126:129], v[130:133], v[178:181], v[126:129]
	v_mfma_f32_16x16x32_bf16 v[122:125], v[138:141], v[178:181], v[122:125]
	v_mfma_f32_16x16x32_bf16 v[110:113], v[130:133], v[200:203], v[110:113]
	v_mfma_f32_16x16x32_bf16 v[106:109], v[138:141], v[200:203], v[106:109]
	v_mfma_f32_16x16x32_bf16 v[94:97], v[130:133], v[208:211], v[94:97]
	v_mfma_f32_16x16x32_bf16 v[90:93], v[138:141], v[208:211], v[90:93]
	v_mfma_f32_16x16x32_bf16 v[78:81], v[130:133], v[216:219], v[78:81]
	v_mfma_f32_16x16x32_bf16 v[74:77], v[138:141], v[216:219], v[74:77]
	v_mfma_f32_16x16x32_bf16 v[126:129], v[134:137], v[182:185], v[126:129]
	v_mfma_f32_16x16x32_bf16 v[122:125], v[142:145], v[182:185], v[122:125]
	v_mfma_f32_16x16x32_bf16 v[110:113], v[134:137], v[204:207], v[110:113]
	v_mfma_f32_16x16x32_bf16 v[106:109], v[142:145], v[204:207], v[106:109]
	v_mfma_f32_16x16x32_bf16 v[94:97], v[134:137], v[212:215], v[94:97]
	v_mfma_f32_16x16x32_bf16 v[90:93], v[142:145], v[212:215], v[90:93]
	v_mfma_f32_16x16x32_bf16 v[78:81], v[134:137], v[220:223], v[78:81]
	v_mfma_f32_16x16x32_bf16 v[74:77], v[142:145], v[220:223], v[74:77]
	v_mfma_f32_16x16x32_bf16 v[118:121], v[146:149], v[178:181], v[118:121]
	v_mfma_f32_16x16x32_bf16 v[114:117], v[170:173], v[178:181], v[114:117]
	v_mfma_f32_16x16x32_bf16 v[102:105], v[146:149], v[200:203], v[102:105]
	v_mfma_f32_16x16x32_bf16 v[98:101], v[170:173], v[200:203], v[98:101]
	v_mfma_f32_16x16x32_bf16 v[86:89], v[146:149], v[208:211], v[86:89]
	v_mfma_f32_16x16x32_bf16 v[82:85], v[170:173], v[208:211], v[82:85]
	v_mfma_f32_16x16x32_bf16 v[70:73], v[146:149], v[216:219], v[70:73]
	v_mfma_f32_16x16x32_bf16 v[66:69], v[170:173], v[216:219], v[66:69]
	v_mfma_f32_16x16x32_bf16 v[118:121], v[150:153], v[182:185], v[118:121]
	v_mfma_f32_16x16x32_bf16 v[114:117], v[174:177], v[182:185], v[114:117]
	v_mfma_f32_16x16x32_bf16 v[102:105], v[150:153], v[204:207], v[102:105]
	v_mfma_f32_16x16x32_bf16 v[98:101], v[174:177], v[204:207], v[98:101]
	v_mfma_f32_16x16x32_bf16 v[86:89], v[150:153], v[212:215], v[86:89]
	v_mfma_f32_16x16x32_bf16 v[82:85], v[174:177], v[212:215], v[82:85]
	v_mfma_f32_16x16x32_bf16 v[70:73], v[150:153], v[220:223], v[70:73]
	v_mfma_f32_16x16x32_bf16 v[66:69], v[174:177], v[220:223], v[66:69]
	s_barrier
; #define PG8_STAGE(bufoff, gbase, voff) do { _Pragma("unroll") for (int _i = 0; _i < 2; ++_i) \
;         __builtin_amdgcn_global_load_lds((const unsigned*)((const char*)(gbase) + (voff)[_i]), (LAS unsigned*)(lds + (bufoff) + ldsw + _i * 8192), 16, 0, 0); } while (0)
; #define PG8_LDA(dst, b, h) do { _Pragma("unroll") for (int m = 0; m < 4; ++m) _Pragma("unroll") for (int k = 0; k < 2; ++k) dst[m][k] = *(const LAS bf16x8*)(lds + PG8_SA(b, h) + aoff + m * 2048 + k * 1024); } while (0)
; #define PG8_MMA(ai, bj, At, Bt) do { __builtin_amdgcn_s_setprio(3); _Pragma("unroll") for (int m = 0; m < 4; ++m) _Pragma("unroll") for (int n = 0; n < 2; ++n) _Pragma("unroll") for (int k = 0; k < 2; ++k) \
;         acc[ai][bj][m][n] = __builtin_amdgcn_mfma_f32_16x16x32_bf16(Bt[n][k], At[m][k], acc[ai][bj][m][n], 0, 0, 0); __builtin_amdgcn_s_setprio(0); } while (0)
; #define PG8_WAIT_V(n) asm volatile("s_waitcnt vmcnt(" #n ")" ::: "memory")
; #define PG8_WAIT_L(n) asm volatile("s_waitcnt lgkmcnt(" #n ")" ::: "memory")
; #define PG8_BAR __builtin_amdgcn_s_barrier()
; #define PG8_SCHED __builtin_amdgcn_sched_barrier(0)
; template <class Epi, bool ALIGN_EPI>
; __device__ __forceinline__ void gemm_phase(LAS unsigned char* lds, const Gemm g, const StaticOrder& S, const Epi& E) {
;     ...
;         for (int t = 0; t < nt; t += 2) {
;     ...
;             PG8_LDA(At, 1, 1); PG8_STAGE(PG8_SB(1, 0), b3, voffB); PG8_STAGE(PG8_SB(1, 1), b3 + hstep, voffB); PG8_STAGE(PG8_SA(1, 0), a3, voffA);
;             PG8_WAIT_V(8); PG8_WAIT_L(0); PG8_BAR; PG8_MMA(1, 0, At, B0); PG8_MMA(1, 1, At, B1); PG8_BAR; PG8_SCHED;
;         }
	s_add_i32 s44, s62, s47
	v_lshl_add_u64 v[186:187], v[186:187], 0, s[12:13]
	s_mov_b32 m0, s44
	ds_read_b128 v[178:181], v198 offset:49152
	ds_read_b128 v[182:185], v198 offset:50176
	ds_read_b128 v[200:203], v198 offset:51200
	ds_read_b128 v[204:207], v198 offset:52224
	ds_read_b128 v[208:211], v198 offset:53248
	ds_read_b128 v[212:215], v198 offset:54272
	ds_read_b128 v[216:219], v198 offset:55296
	ds_read_b128 v[220:223], v198 offset:56320
	global_load_lds_dwordx4 v[186:187], off
	s_add_i32 m0, s44, 0x2000
	s_add_u32 s42, s42, 0x40080
	v_lshl_add_u64 v[186:187], v[224:225], 0, s[12:13]
	s_addc_u32 s43, s43, 0
	s_add_i32 s44, s63, s47
	global_load_lds_dwordx4 v[186:187], off
	v_lshl_add_u64 v[186:187], s[42:43], 0, v[156:157]
	s_mov_b32 m0, s44
	s_nop 0
	global_load_lds_dwordx4 v[186:187], off
	v_lshl_add_u64 v[186:187], s[42:43], 0, v[160:161]
	s_add_i32 m0, s44, 0x2000
	s_nop 0
	global_load_lds_dwordx4 v[186:187], off
	v_lshl_add_u64 v[186:187], v[226:227], 0, s[12:13]
	s_mov_b32 m0, s52
	s_nop 0
	global_load_lds_dwordx4 v[186:187], off
	v_lshl_add_u64 v[186:187], v[228:229], 0, s[12:13]
	s_mov_b32 m0, s53
	s_nop 0
	global_load_lds_dwordx4 v[186:187], off
	s_waitcnt vmcnt(8)
	s_waitcnt lgkmcnt(0)
	s_barrier
	s_waitcnt lgkmcnt(0)
	v_mfma_f32_16x16x32_bf16 v[62:65], v[130:133], v[178:181], v[62:65]
	v_mfma_f32_16x16x32_bf16 v[58:61], v[138:141], v[178:181], v[58:61]
	v_mfma_f32_16x16x32_bf16 v[46:49], v[130:133], v[200:203], v[46:49]
	v_mfma_f32_16x16x32_bf16 v[42:45], v[138:141], v[200:203], v[42:45]
	v_mfma_f32_16x16x32_bf16 v[30:33], v[130:133], v[208:211], v[30:33]
	v_mfma_f32_16x16x32_bf16 v[26:29], v[138:141], v[208:211], v[26:29]
	v_mfma_f32_16x16x32_bf16 v[14:17], v[130:133], v[216:219], v[14:17]
	v_mfma_f32_16x16x32_bf16 v[10:13], v[138:141], v[216:219], v[10:13]
	v_mfma_f32_16x16x32_bf16 v[62:65], v[134:137], v[182:185], v[62:65]
	v_mfma_f32_16x16x32_bf16 v[58:61], v[142:145], v[182:185], v[58:61]
	v_mfma_f32_16x16x32_bf16 v[46:49], v[134:137], v[204:207], v[46:49]
	v_mfma_f32_16x16x32_bf16 v[42:45], v[142:145], v[204:207], v[42:45]
	v_mfma_f32_16x16x32_bf16 v[30:33], v[134:137], v[212:215], v[30:33]
	v_mfma_f32_16x16x32_bf16 v[26:29], v[142:145], v[212:215], v[26:29]
	v_mfma_f32_16x16x32_bf16 v[14:17], v[134:137], v[220:223], v[14:17]
	v_mfma_f32_16x16x32_bf16 v[10:13], v[142:145], v[220:223], v[10:13]
	v_mfma_f32_16x16x32_bf16 v[54:57], v[146:149], v[178:181], v[54:57]
	v_mfma_f32_16x16x32_bf16 v[50:53], v[170:173], v[178:181], v[50:53]
	v_mfma_f32_16x16x32_bf16 v[38:41], v[146:149], v[200:203], v[38:41]
	v_mfma_f32_16x16x32_bf16 v[34:37], v[170:173], v[200:203], v[34:37]
	v_mfma_f32_16x16x32_bf16 v[22:25], v[146:149], v[208:211], v[22:25]
	v_mfma_f32_16x16x32_bf16 v[18:21], v[170:173], v[208:211], v[18:21]
	v_mfma_f32_16x16x32_bf16 v[6:9], v[146:149], v[216:219], v[6:9]
	v_mfma_f32_16x16x32_bf16 v[2:5], v[170:173], v[216:219], v[2:5]
	v_mfma_f32_16x16x32_bf16 v[54:57], v[150:153], v[182:185], v[54:57]
	v_mfma_f32_16x16x32_bf16 v[50:53], v[174:177], v[182:185], v[50:53]
	v_mfma_f32_16x16x32_bf16 v[38:41], v[150:153], v[204:207], v[38:41]
	v_mfma_f32_16x16x32_bf16 v[34:37], v[174:177], v[204:207], v[34:37]
	v_mfma_f32_16x16x32_bf16 v[22:25], v[150:153], v[212:215], v[22:25]
	v_mfma_f32_16x16x32_bf16 v[18:21], v[174:177], v[212:215], v[18:21]
	v_mfma_f32_16x16x32_bf16 v[6:9], v[150:153], v[220:223], v[6:9]
	v_mfma_f32_16x16x32_bf16 v[2:5], v[174:177], v[220:223], v[2:5]
	s_barrier
	s_add_i32 s61, s61, 2
	s_add_u32 s40, s40, 0x100
	s_addc_u32 s41, s41, 0
	s_add_u32 s59, s59, 0x100
	s_addc_u32 s60, s60, 0
	s_cmp_gt_u32 s61, 13
	s_cbranch_scc0 .LBB0_1339
	s_and_b64 vcc, exec, s[14:15]
	s_cbranch_vccz .LBB0_1342
	s_barrier

; #define PG8_STAGE(bufoff, gbase, voff) do { _Pragma("unroll") for (int _i = 0; _i < 2; ++_i) \
;         __builtin_amdgcn_global_load_lds((const unsigned*)((const char*)(gbase) + (voff)[_i]), (LAS unsigned*)(lds + (bufoff) + ldsw + _i * 8192), 16, 0, 0); } while (0)
; #define PG8_LDA(dst, b, h) do { _Pragma("unroll") for (int m = 0; m < 4; ++m) _Pragma("unroll") for (int k = 0; k < 2; ++k) dst[m][k] = *(const LAS bf16x8*)(lds + PG8_SA(b, h) + aoff + m * 2048 + k * 1024); } while (0)
; #define PG8_LDB(dst, b, h) do { _Pragma("unroll") for (int n = 0; n < 2; ++n) _Pragma("unroll") for (int k = 0; k < 2; ++k) dst[n][k] = *(const LAS bf16x8*)(lds + PG8_SB(b, h) + boff + n * 2048 + k * 1024); } while (0)
; #define PG8_MMA(ai, bj, At, Bt) do { __builtin_amdgcn_s_setprio(3); _Pragma("unroll") for (int m = 0; m < 4; ++m) _Pragma("unroll") for (int n = 0; n < 2; ++n) _Pragma("unroll") for (int k = 0; k < 2; ++k) \
;         acc[ai][bj][m][n] = __builtin_amdgcn_mfma_f32_16x16x32_bf16(Bt[n][k], At[m][k], acc[ai][bj][m][n], 0, 0, 0); __builtin_amdgcn_s_setprio(0); } while (0)
; #define PG8_WAIT_V(n) asm volatile("s_waitcnt vmcnt(" #n ")" ::: "memory")
; #define PG8_WAIT_L(n) asm volatile("s_waitcnt lgkmcnt(" #n ")" ::: "memory")
; #define PG8_BAR __builtin_amdgcn_s_barrier()
; #define PG8_SCHED __builtin_amdgcn_sched_barrier(0)
; template <class Epi, bool ALIGN_EPI>
; __device__ __forceinline__ void gemm_phase(LAS unsigned char* lds, const Gemm g, const StaticOrder& S, const Epi& E) {
;     ...
;                 for (int n = 0; n < 2; ++n) acc[a][b][m][n] = (f32x4){0.f, 0.f, 0.f, 0.f};
;     ...
;             PG8_LDB(B0, 0, 0); PG8_LDB(B1, 0, 1); PG8_SCHED; PG8_LDA(At, 0, 0); PG8_STAGE(PG8_SA(1, 1), a1 + hstep, voffA);
;             PG8_WAIT_V(8); PG8_WAIT_L(0); PG8_BAR; PG8_MMA(0, 0, At, B0); PG8_MMA(0, 1, At, B1); PG8_BAR; PG8_SCHED;
;             PG8_LDA(At, 0, 1); PG8_STAGE(PG8_SB(0, 0), b2, voffB); PG8_STAGE(PG8_SB(0, 1), b2 + hstep, voffB); PG8_STAGE(PG8_SA(0, 0), a2, voffA);
;             PG8_WAIT_V(8); PG8_WAIT_L(0); PG8_BAR; PG8_MMA(1, 0, At, B0); PG8_MMA(1, 1, At, B1); PG8_BAR; PG8_SCHED;
.Lmy_rw_1428_0:
	s_waitcnt lgkmcnt(0)
	s_barrier
	s_waitcnt lgkmcnt(0)
	v_mfma_f32_16x16x32_bf16 v[126:129], v[146:149], v[188:191], 0
	v_mfma_f32_16x16x32_bf16 v[118:121], v[154:157], v[188:191], 0
	v_mfma_f32_16x16x32_bf16 v[110:113], v[146:149], v[196:199], 0
	v_mfma_f32_16x16x32_bf16 v[102:105], v[154:157], v[196:199], 0
	v_mfma_f32_16x16x32_bf16 v[94:97], v[146:149], v[204:207], 0
	v_mfma_f32_16x16x32_bf16 v[86:89], v[154:157], v[204:207], 0
	v_mfma_f32_16x16x32_bf16 v[78:81], v[146:149], v[212:215], 0
	v_mfma_f32_16x16x32_bf16 v[70:73], v[154:157], v[212:215], 0
	v_mfma_f32_16x16x32_bf16 v[126:129], v[150:153], v[192:195], v[126:129]
	v_mfma_f32_16x16x32_bf16 v[118:121], v[158:161], v[192:195], v[118:121]
	v_mfma_f32_16x16x32_bf16 v[110:113], v[150:153], v[200:203], v[110:113]
	v_mfma_f32_16x16x32_bf16 v[102:105], v[158:161], v[200:203], v[102:105]
	v_mfma_f32_16x16x32_bf16 v[94:97], v[150:153], v[208:211], v[94:97]
	v_mfma_f32_16x16x32_bf16 v[86:89], v[158:161], v[208:211], v[86:89]
	v_mfma_f32_16x16x32_bf16 v[78:81], v[150:153], v[216:219], v[78:81]
	v_mfma_f32_16x16x32_bf16 v[70:73], v[158:161], v[216:219], v[70:73]
	v_mfma_f32_16x16x32_bf16 v[122:125], v[172:175], v[188:191], 0
	v_mfma_f32_16x16x32_bf16 v[114:117], v[180:183], v[188:191], 0
	v_mfma_f32_16x16x32_bf16 v[106:109], v[172:175], v[196:199], 0
	v_mfma_f32_16x16x32_bf16 v[98:101], v[180:183], v[196:199], 0
	v_mfma_f32_16x16x32_bf16 v[90:93], v[172:175], v[204:207], 0
	v_mfma_f32_16x16x32_bf16 v[82:85], v[180:183], v[204:207], 0
	v_mfma_f32_16x16x32_bf16 v[74:77], v[172:175], v[212:215], 0
	v_mfma_f32_16x16x32_bf16 v[66:69], v[180:183], v[212:215], 0
	v_mfma_f32_16x16x32_bf16 v[122:125], v[176:179], v[192:195], v[122:125]
	v_mfma_f32_16x16x32_bf16 v[114:117], v[184:187], v[192:195], v[114:117]
	v_mfma_f32_16x16x32_bf16 v[106:109], v[176:179], v[200:203], v[106:109]
	v_mfma_f32_16x16x32_bf16 v[98:101], v[184:187], v[200:203], v[98:101]
	v_mfma_f32_16x16x32_bf16 v[90:93], v[176:179], v[208:211], v[90:93]
	v_mfma_f32_16x16x32_bf16 v[82:85], v[184:187], v[208:211], v[82:85]
	v_mfma_f32_16x16x32_bf16 v[74:77], v[176:179], v[216:219], v[74:77]
	v_mfma_f32_16x16x32_bf16 v[66:69], v[184:187], v[216:219], v[66:69]
	s_barrier
	s_add_i32 s43, s58, s33
	v_lshl_add_u64 v[220:221], s[8:9], 0, v[132:133]
	s_mov_b32 m0, s43
	ds_read_b128 v[188:191], v170 offset:16384
	ds_read_b128 v[192:195], v170 offset:17408
	ds_read_b128 v[196:199], v170 offset:18432
	ds_read_b128 v[200:203], v170 offset:19456
	ds_read_b128 v[204:207], v170 offset:20480
	ds_read_b128 v[208:211], v170 offset:21504
	ds_read_b128 v[212:215], v170 offset:22528
	ds_read_b128 v[216:219], v170 offset:23552
	global_load_lds_dwordx4 v[220:221], off
	s_add_i32 m0, s43, 0x2000
	s_add_u32 s62, s8, 0x40000
	v_lshl_add_u64 v[222:223], s[8:9], 0, v[136:137]
	s_addc_u32 s63, s9, 0
	s_add_i32 s43, s59, s33
	global_load_lds_dwordx4 v[222:223], off
	v_lshl_add_u64 v[224:225], s[62:63], 0, v[132:133]
	s_mov_b32 m0, s43
	v_lshl_add_u64 v[226:227], s[10:11], 0, v[134:135]
	global_load_lds_dwordx4 v[224:225], off
	v_lshl_add_u64 v[224:225], s[62:63], 0, v[136:137]
	s_add_i32 m0, s43, 0x2000
	s_nop 0
	global_load_lds_dwordx4 v[224:225], off
	v_lshl_add_u64 v[224:225], s[10:11], 0, v[130:131]
	s_mov_b32 m0, s50
	s_nop 0
	global_load_lds_dwordx4 v[224:225], off
	s_mov_b32 m0, s51
	s_nop 0
	global_load_lds_dwordx4 v[226:227], off
	s_cmp_lg_u32 s98, 0
	s_cbranch_scc1 .Lmy_rw_1428_1
	s_waitcnt vmcnt(8)
.Lmy_rw_1428_1:
	s_waitcnt lgkmcnt(0)
	s_barrier
	s_waitcnt lgkmcnt(0)
	v_mfma_f32_16x16x32_bf16 v[62:65], v[146:149], v[188:191], 0
	v_mfma_f32_16x16x32_bf16 v[54:57], v[154:157], v[188:191], 0
	v_mfma_f32_16x16x32_bf16 v[46:49], v[146:149], v[196:199], 0
	v_mfma_f32_16x16x32_bf16 v[38:41], v[154:157], v[196:199], 0
	v_mfma_f32_16x16x32_bf16 v[30:33], v[146:149], v[204:207], 0
	v_mfma_f32_16x16x32_bf16 v[22:25], v[154:157], v[204:207], 0
	v_mfma_f32_16x16x32_bf16 v[14:17], v[146:149], v[212:215], 0
	v_mfma_f32_16x16x32_bf16 v[6:9], v[154:157], v[212:215], 0
	v_mfma_f32_16x16x32_bf16 v[62:65], v[150:153], v[192:195], v[62:65]
	v_mfma_f32_16x16x32_bf16 v[54:57], v[158:161], v[192:195], v[54:57]
	v_mfma_f32_16x16x32_bf16 v[46:49], v[150:153], v[200:203], v[46:49]
	v_mfma_f32_16x16x32_bf16 v[38:41], v[158:161], v[200:203], v[38:41]
	v_mfma_f32_16x16x32_bf16 v[30:33], v[150:153], v[208:211], v[30:33]
	v_mfma_f32_16x16x32_bf16 v[22:25], v[158:161], v[208:211], v[22:25]
	v_mfma_f32_16x16x32_bf16 v[14:17], v[150:153], v[216:219], v[14:17]
	v_mfma_f32_16x16x32_bf16 v[6:9], v[158:161], v[216:219], v[6:9]
	v_mfma_f32_16x16x32_bf16 v[58:61], v[172:175], v[188:191], 0
	v_mfma_f32_16x16x32_bf16 v[50:53], v[180:183], v[188:191], 0
	v_mfma_f32_16x16x32_bf16 v[42:45], v[172:175], v[196:199], 0
	v_mfma_f32_16x16x32_bf16 v[34:37], v[180:183], v[196:199], 0
	v_mfma_f32_16x16x32_bf16 v[26:29], v[172:175], v[204:207], 0
	v_mfma_f32_16x16x32_bf16 v[18:21], v[180:183], v[204:207], 0
	v_mfma_f32_16x16x32_bf16 v[10:13], v[172:175], v[212:215], 0
	v_mfma_f32_16x16x32_bf16 v[2:5], v[180:183], v[212:215], 0
	v_mfma_f32_16x16x32_bf16 v[58:61], v[176:179], v[192:195], v[58:61]
	v_mfma_f32_16x16x32_bf16 v[50:53], v[184:187], v[192:195], v[50:53]
	v_mfma_f32_16x16x32_bf16 v[42:45], v[176:179], v[200:203], v[42:45]
	v_mfma_f32_16x16x32_bf16 v[34:37], v[184:187], v[200:203], v[34:37]
	v_mfma_f32_16x16x32_bf16 v[26:29], v[176:179], v[208:211], v[26:29]
	v_mfma_f32_16x16x32_bf16 v[18:21], v[184:187], v[208:211], v[18:21]
	v_mfma_f32_16x16x32_bf16 v[10:13], v[176:179], v[216:219], v[10:13]
	v_mfma_f32_16x16x32_bf16 v[2:5], v[184:187], v[216:219], v[2:5]
	s_barrier
; #define PG8_STAGE(bufoff, gbase, voff) do { _Pragma("unroll") for (int _i = 0; _i < 2; ++_i) \
;         __builtin_amdgcn_global_load_lds((const unsigned*)((const char*)(gbase) + (voff)[_i]), (LAS unsigned*)(lds + (bufoff) + ldsw + _i * 8192), 16, 0, 0); } while (0)
; #define PG8_LDA(dst, b, h) do { _Pragma("unroll") for (int m = 0; m < 4; ++m) _Pragma("unroll") for (int k = 0; k < 2; ++k) dst[m][k] = *(const LAS bf16x8*)(lds + PG8_SA(b, h) + aoff + m * 2048 + k * 1024); } while (0)
; #define PG8_LDB(dst, b, h) do { _Pragma("unroll") for (int n = 0; n < 2; ++n) _Pragma("unroll") for (int k = 0; k < 2; ++k) dst[n][k] = *(const LAS bf16x8*)(lds + PG8_SB(b, h) + boff + n * 2048 + k * 1024); } while (0)
; #define PG8_MMA(ai, bj, At, Bt) do { __builtin_amdgcn_s_setprio(3); _Pragma("unroll") for (int m = 0; m < 4; ++m) _Pragma("unroll") for (int n = 0; n < 2; ++n) _Pragma("unroll") for (int k = 0; k < 2; ++k) \
;         acc[ai][bj][m][n] = __builtin_amdgcn_mfma_f32_16x16x32_bf16(Bt[n][k], At[m][k], acc[ai][bj][m][n], 0, 0, 0); __builtin_amdgcn_s_setprio(0); } while (0)
; #define PG8_WAIT_V(n) asm volatile("s_waitcnt vmcnt(" #n ")" ::: "memory")
; #define PG8_WAIT_L(n) asm volatile("s_waitcnt lgkmcnt(" #n ")" ::: "memory")
; #define PG8_BAR __builtin_amdgcn_s_barrier()
; #define PG8_SCHED __builtin_amdgcn_sched_barrier(0)
; template <class Epi, bool ALIGN_EPI>
; __device__ __forceinline__ void gemm_phase(LAS unsigned char* lds, const Gemm g, const StaticOrder& S, const Epi& E) {
;     ...
;             PG8_LDB(B0, 1, 0); PG8_LDB(B1, 1, 1); PG8_SCHED; PG8_LDA(At, 1, 0); PG8_STAGE(PG8_SA(0, 1), a2 + hstep, voffA);
;             PG8_WAIT_V(8); PG8_WAIT_L(0); PG8_BAR; PG8_MMA(0, 0, At, B0); PG8_MMA(0, 1, At, B1); PG8_BAR; PG8_SCHED;
;             PG8_LDA(At, 1, 1); PG8_STAGE(PG8_SB(1, 0), b3, voffB); PG8_STAGE(PG8_SB(1, 1), b3 + hstep, voffB); PG8_STAGE(PG8_SA(1, 0), a3, voffA);
;             PG8_WAIT_V(8); PG8_WAIT_L(0); PG8_BAR; PG8_MMA(1, 0, At, B0); PG8_MMA(1, 1, At, B1); PG8_BAR; PG8_SCHED;
	s_add_i32 s43, 0, 0x18000
	s_add_i32 s62, 0, 0x1c000
	v_add_u32_e32 v158, s43, v166
	v_add_u32_e32 v184, s62, v166
	ds_read_b128 v[146:149], v158
	ds_read_b128 v[150:153], v158 offset:1024
	ds_read_b128 v[154:157], v158 offset:2048
	ds_read_b128 v[158:161], v158 offset:3072
	ds_read_b128 v[172:175], v184
	ds_read_b128 v[176:179], v184 offset:1024
	ds_read_b128 v[180:183], v184 offset:2048
	ds_read_b128 v[184:187], v184 offset:3072
	s_add_u32 s10, s10, 0x40000
	s_addc_u32 s11, s11, 0
	s_mov_b32 m0, s52
	v_lshl_add_u64 v[228:229], s[10:11], 0, v[130:131]
	ds_read_b128 v[188:191], v170 offset:32768
	ds_read_b128 v[192:195], v170 offset:33792
	ds_read_b128 v[196:199], v170 offset:34816
	ds_read_b128 v[200:203], v170 offset:35840
	ds_read_b128 v[204:207], v170 offset:36864
	ds_read_b128 v[208:211], v170 offset:37888
	ds_read_b128 v[212:215], v170 offset:38912
	ds_read_b128 v[216:219], v170 offset:39936
	global_load_lds_dwordx4 v[228:229], off
	v_lshl_add_u64 v[228:229], s[10:11], 0, v[134:135]
	s_mov_b32 m0, s53
	s_nop 0
	global_load_lds_dwordx4 v[228:229], off
	s_waitcnt vmcnt(8)
	s_waitcnt lgkmcnt(0)
	s_barrier
	s_waitcnt lgkmcnt(0)
	v_mfma_f32_16x16x32_bf16 v[126:129], v[146:149], v[188:191], v[126:129]
	v_mfma_f32_16x16x32_bf16 v[118:121], v[154:157], v[188:191], v[118:121]
	v_mfma_f32_16x16x32_bf16 v[110:113], v[146:149], v[196:199], v[110:113]
	v_mfma_f32_16x16x32_bf16 v[102:105], v[154:157], v[196:199], v[102:105]
	v_mfma_f32_16x16x32_bf16 v[94:97], v[146:149], v[204:207], v[94:97]
	v_mfma_f32_16x16x32_bf16 v[86:89], v[154:157], v[204:207], v[86:89]
	v_mfma_f32_16x16x32_bf16 v[78:81], v[146:149], v[212:215], v[78:81]
	v_mfma_f32_16x16x32_bf16 v[70:73], v[154:157], v[212:215], v[70:73]
	v_mfma_f32_16x16x32_bf16 v[126:129], v[150:153], v[192:195], v[126:129]
	v_mfma_f32_16x16x32_bf16 v[118:121], v[158:161], v[192:195], v[118:121]
	v_mfma_f32_16x16x32_bf16 v[110:113], v[150:153], v[200:203], v[110:113]
	v_mfma_f32_16x16x32_bf16 v[102:105], v[158:161], v[200:203], v[102:105]
	v_mfma_f32_16x16x32_bf16 v[94:97], v[150:153], v[208:211], v[94:97]
	v_mfma_f32_16x16x32_bf16 v[86:89], v[158:161], v[208:211], v[86:89]
	v_mfma_f32_16x16x32_bf16 v[78:81], v[150:153], v[216:219], v[78:81]
	v_mfma_f32_16x16x32_bf16 v[70:73], v[158:161], v[216:219], v[70:73]
	v_mfma_f32_16x16x32_bf16 v[122:125], v[172:175], v[188:191], v[122:125]
	v_mfma_f32_16x16x32_bf16 v[114:117], v[180:183], v[188:191], v[114:117]
	v_mfma_f32_16x16x32_bf16 v[106:109], v[172:175], v[196:199], v[106:109]
	v_mfma_f32_16x16x32_bf16 v[98:101], v[180:183], v[196:199], v[98:101]
	v_mfma_f32_16x16x32_bf16 v[90:93], v[172:175], v[204:207], v[90:93]
	v_mfma_f32_16x16x32_bf16 v[82:85], v[180:183], v[204:207], v[82:85]
	v_mfma_f32_16x16x32_bf16 v[74:77], v[172:175], v[212:215], v[74:77]
	v_mfma_f32_16x16x32_bf16 v[66:69], v[180:183], v[212:215], v[66:69]
	v_mfma_f32_16x16x32_bf16 v[122:125], v[176:179], v[192:195], v[122:125]
	v_mfma_f32_16x16x32_bf16 v[114:117], v[184:187], v[192:195], v[114:117]
	v_mfma_f32_16x16x32_bf16 v[106:109], v[176:179], v[200:203], v[106:109]
	v_mfma_f32_16x16x32_bf16 v[98:101], v[184:187], v[200:203], v[98:101]
	v_mfma_f32_16x16x32_bf16 v[90:93], v[176:179], v[208:211], v[90:93]
	v_mfma_f32_16x16x32_bf16 v[82:85], v[184:187], v[208:211], v[82:85]
	v_mfma_f32_16x16x32_bf16 v[74:77], v[176:179], v[216:219], v[74:77]
	v_mfma_f32_16x16x32_bf16 v[66:69], v[184:187], v[216:219], v[66:69]
	s_barrier
	s_add_i32 s10, s43, s33
	v_lshl_add_u64 v[220:221], v[220:221], 0, s[36:37]
	s_mov_b32 m0, s10
	ds_read_b128 v[188:191], v170 offset:49152
	ds_read_b128 v[192:195], v170 offset:50176
	ds_read_b128 v[196:199], v170 offset:51200
	ds_read_b128 v[200:203], v170 offset:52224
	ds_read_b128 v[204:207], v170 offset:53248
	ds_read_b128 v[208:211], v170 offset:54272
	ds_read_b128 v[212:215], v170 offset:55296
	ds_read_b128 v[216:219], v170 offset:56320
	global_load_lds_dwordx4 v[220:221], off
	s_add_i32 m0, s10, 0x2000
	s_add_u32 s8, s8, 0x40080
	v_lshl_add_u64 v[220:221], v[222:223], 0, s[36:37]
	s_addc_u32 s9, s9, 0
	s_add_i32 s10, s62, s33
	global_load_lds_dwordx4 v[220:221], off
	v_lshl_add_u64 v[220:221], s[8:9], 0, v[132:133]
	s_mov_b32 m0, s10
	s_nop 0
	global_load_lds_dwordx4 v[220:221], off
	v_lshl_add_u64 v[220:221], s[8:9], 0, v[136:137]
	s_add_i32 m0, s10, 0x2000
	s_nop 0
	global_load_lds_dwordx4 v[220:221], off
	v_lshl_add_u64 v[220:221], v[224:225], 0, s[36:37]
	s_mov_b32 m0, s56
	s_nop 0
	global_load_lds_dwordx4 v[220:221], off
	v_lshl_add_u64 v[220:221], v[226:227], 0, s[36:37]
	s_mov_b32 m0, s57
	s_nop 0
	global_load_lds_dwordx4 v[220:221], off
	s_waitcnt vmcnt(8)
	s_waitcnt lgkmcnt(0)
	s_barrier
	s_waitcnt lgkmcnt(0)
	v_mfma_f32_16x16x32_bf16 v[62:65], v[146:149], v[188:191], v[62:65]
	v_mfma_f32_16x16x32_bf16 v[54:57], v[154:157], v[188:191], v[54:57]
	v_mfma_f32_16x16x32_bf16 v[46:49], v[146:149], v[196:199], v[46:49]
	v_mfma_f32_16x16x32_bf16 v[38:41], v[154:157], v[196:199], v[38:41]
	v_mfma_f32_16x16x32_bf16 v[30:33], v[146:149], v[204:207], v[30:33]
	v_mfma_f32_16x16x32_bf16 v[22:25], v[154:157], v[204:207], v[22:25]
	v_mfma_f32_16x16x32_bf16 v[14:17], v[146:149], v[212:215], v[14:17]
	v_mfma_f32_16x16x32_bf16 v[6:9], v[154:157], v[212:215], v[6:9]
	v_mfma_f32_16x16x32_bf16 v[62:65], v[150:153], v[192:195], v[62:65]
	v_mfma_f32_16x16x32_bf16 v[54:57], v[158:161], v[192:195], v[54:57]
	v_mfma_f32_16x16x32_bf16 v[46:49], v[150:153], v[200:203], v[46:49]
	v_mfma_f32_16x16x32_bf16 v[38:41], v[158:161], v[200:203], v[38:41]
	v_mfma_f32_16x16x32_bf16 v[30:33], v[150:153], v[208:211], v[30:33]
	v_mfma_f32_16x16x32_bf16 v[22:25], v[158:161], v[208:211], v[22:25]
	v_mfma_f32_16x16x32_bf16 v[14:17], v[150:153], v[216:219], v[14:17]
	v_mfma_f32_16x16x32_bf16 v[6:9], v[158:161], v[216:219], v[6:9]
	v_mfma_f32_16x16x32_bf16 v[58:61], v[172:175], v[188:191], v[58:61]
	v_mfma_f32_16x16x32_bf16 v[50:53], v[180:183], v[188:191], v[50:53]
	v_mfma_f32_16x16x32_bf16 v[42:45], v[172:175], v[196:199], v[42:45]
	v_mfma_f32_16x16x32_bf16 v[34:37], v[180:183], v[196:199], v[34:37]
	v_mfma_f32_16x16x32_bf16 v[26:29], v[172:175], v[204:207], v[26:29]
	v_mfma_f32_16x16x32_bf16 v[18:21], v[180:183], v[204:207], v[18:21]
	v_mfma_f32_16x16x32_bf16 v[10:13], v[172:175], v[212:215], v[10:13]
	v_mfma_f32_16x16x32_bf16 v[2:5], v[180:183], v[212:215], v[2:5]
	v_mfma_f32_16x16x32_bf16 v[58:61], v[176:179], v[192:195], v[58:61]
	v_mfma_f32_16x16x32_bf16 v[50:53], v[184:187], v[192:195], v[50:53]
	v_mfma_f32_16x16x32_bf16 v[42:45], v[176:179], v[200:203], v[42:45]
	v_mfma_f32_16x16x32_bf16 v[34:37], v[184:187], v[200:203], v[34:37]
	v_mfma_f32_16x16x32_bf16 v[26:29], v[176:179], v[208:211], v[26:29]
	v_mfma_f32_16x16x32_bf16 v[18:21], v[184:187], v[208:211], v[18:21]
	v_mfma_f32_16x16x32_bf16 v[10:13], v[176:179], v[216:219], v[10:13]
	v_mfma_f32_16x16x32_bf16 v[2:5], v[184:187], v[216:219], v[2:5]
	s_barrier
	s_add_i32 s41, s41, 2
	s_add_u32 s6, s6, 0x100
	s_addc_u32 s7, s7, 0
	s_add_u32 s16, s16, 0x100
	s_addc_u32 s17, s17, 0
; #define PG8_STAGE(bufoff, gbase, voff) do { _Pragma("unroll") for (int _i = 0; _i < 2; ++_i) \
;         __builtin_amdgcn_global_load_lds((const unsigned*)((const char*)(gbase) + (voff)[_i]), (LAS unsigned*)(lds + (bufoff) + ldsw + _i * 8192), 16, 0, 0); } while (0)
; #define PG8_LDA(dst, b, h) do { _Pragma("unroll") for (int m = 0; m < 4; ++m) _Pragma("unroll") for (int k = 0; k < 2; ++k) dst[m][k] = *(const LAS bf16x8*)(lds + PG8_SA(b, h) + aoff + m * 2048 + k * 1024); } while (0)
; #define PG8_LDB(dst, b, h) do { _Pragma("unroll") for (int n = 0; n < 2; ++n) _Pragma("unroll") for (int k = 0; k < 2; ++k) dst[n][k] = *(const LAS bf16x8*)(lds + PG8_SB(b, h) + boff + n * 2048 + k * 1024); } while (0)
; #define PG8_MMA(ai, bj, At, Bt) do { __builtin_amdgcn_s_setprio(3); _Pragma("unroll") for (int m = 0; m < 4; ++m) _Pragma("unroll") for (int n = 0; n < 2; ++n) _Pragma("unroll") for (int k = 0; k < 2; ++k) \
;         acc[ai][bj][m][n] = __builtin_amdgcn_mfma_f32_16x16x32_bf16(Bt[n][k], At[m][k], acc[ai][bj][m][n], 0, 0, 0); __builtin_amdgcn_s_setprio(0); } while (0)
; #define PG8_WAIT_V(n) asm volatile("s_waitcnt vmcnt(" #n ")" ::: "memory")
; #define PG8_WAIT_L(n) asm volatile("s_waitcnt lgkmcnt(" #n ")" ::: "memory")
; #define PG8_BAR __builtin_amdgcn_s_barrier()
; #define PG8_SCHED __builtin_amdgcn_sched_barrier(0)
; template <class Epi, bool ALIGN_EPI>
; __device__ __forceinline__ void gemm_phase(LAS unsigned char* lds, const Gemm g, const StaticOrder& S, const Epi& E) {
;     ...
;             PG8_LDB(B0, 0, 0); PG8_LDB(B1, 0, 1); PG8_SCHED; PG8_LDA(At, 0, 0); PG8_STAGE(PG8_SA(1, 1), a1 + hstep, voffA);
;             PG8_WAIT_V(8); PG8_WAIT_L(0); PG8_BAR; PG8_MMA(0, 0, At, B0); PG8_MMA(0, 1, At, B1); PG8_BAR; PG8_SCHED;
;             PG8_LDA(At, 0, 1); PG8_STAGE(PG8_SB(0, 0), b2, voffB); PG8_STAGE(PG8_SB(0, 1), b2 + hstep, voffB); PG8_STAGE(PG8_SA(0, 0), a2, voffA);
;             PG8_WAIT_V(8); PG8_WAIT_L(0); PG8_BAR; PG8_MMA(1, 0, At, B0); PG8_MMA(1, 1, At, B1); PG8_BAR; PG8_SCHED;
.LBB0_1428:
	ds_read_b128 v[146:149], v168
	ds_read_b128 v[150:153], v168 offset:1024
	ds_read_b128 v[154:157], v168 offset:2048
	ds_read_b128 v[158:161], v168 offset:3072
	ds_read_b128 v[172:175], v169
	ds_read_b128 v[176:179], v169 offset:1024
	ds_read_b128 v[180:183], v169 offset:2048
	ds_read_b128 v[184:187], v169 offset:3072
	s_add_u32 s8, s6, 0xfffc0080
	s_addc_u32 s9, s7, -1
	s_cmp_eq_u32 s41, 12
	s_cselect_b32 s11, s12, s9
	s_cselect_b32 s10, s13, s8
	s_cselect_b32 s9, s14, s17
	s_cselect_b32 s8, s15, s16
	v_lshl_add_u64 v[220:221], s[6:7], 0, v[138:139]
	s_add_i32 m0, s50, 0xc000
	ds_read_b128 v[188:191], v170
	ds_read_b128 v[192:195], v170 offset:1024
	ds_read_b128 v[196:199], v170 offset:2048
	ds_read_b128 v[200:203], v170 offset:3072
	ds_read_b128 v[204:207], v170 offset:4096
	ds_read_b128 v[208:211], v170 offset:5120
	ds_read_b128 v[212:215], v170 offset:6144
	ds_read_b128 v[216:219], v170 offset:7168
	global_load_lds_dwordx4 v[220:221], off
	v_lshl_add_u64 v[220:221], s[6:7], 0, v[140:141]
	s_add_i32 m0, s50, 0xe000
	s_nop 0
	global_load_lds_dwordx4 v[220:221], off
	s_waitcnt vmcnt(8)
	s_waitcnt lgkmcnt(0)
	s_barrier
	s_waitcnt lgkmcnt(0)
	v_mfma_f32_16x16x32_bf16 v[126:129], v[146:149], v[188:191], v[126:129]
	v_mfma_f32_16x16x32_bf16 v[118:121], v[154:157], v[188:191], v[118:121]
	v_mfma_f32_16x16x32_bf16 v[110:113], v[146:149], v[196:199], v[110:113]
	v_mfma_f32_16x16x32_bf16 v[102:105], v[154:157], v[196:199], v[102:105]
	v_mfma_f32_16x16x32_bf16 v[94:97], v[146:149], v[204:207], v[94:97]
	v_mfma_f32_16x16x32_bf16 v[86:89], v[154:157], v[204:207], v[86:89]
	v_mfma_f32_16x16x32_bf16 v[78:81], v[146:149], v[212:215], v[78:81]
	v_mfma_f32_16x16x32_bf16 v[70:73], v[154:157], v[212:215], v[70:73]
	v_mfma_f32_16x16x32_bf16 v[126:129], v[150:153], v[192:195], v[126:129]
	v_mfma_f32_16x16x32_bf16 v[118:121], v[158:161], v[192:195], v[118:121]
	v_mfma_f32_16x16x32_bf16 v[110:113], v[150:153], v[200:203], v[110:113]
	v_mfma_f32_16x16x32_bf16 v[102:105], v[158:161], v[200:203], v[102:105]
	v_mfma_f32_16x16x32_bf16 v[94:97], v[150:153], v[208:211], v[94:97]
	v_mfma_f32_16x16x32_bf16 v[86:89], v[158:161], v[208:211], v[86:89]
	v_mfma_f32_16x16x32_bf16 v[78:81], v[150:153], v[216:219], v[78:81]
	v_mfma_f32_16x16x32_bf16 v[70:73], v[158:161], v[216:219], v[70:73]
	v_mfma_f32_16x16x32_bf16 v[122:125], v[172:175], v[188:191], v[122:125]
	v_mfma_f32_16x16x32_bf16 v[114:117], v[180:183], v[188:191], v[114:117]
	v_mfma_f32_16x16x32_bf16 v[106:109], v[172:175], v[196:199], v[106:109]
	v_mfma_f32_16x16x32_bf16 v[98:101], v[180:183], v[196:199], v[98:101]
	v_mfma_f32_16x16x32_bf16 v[90:93], v[172:175], v[204:207], v[90:93]
	v_mfma_f32_16x16x32_bf16 v[82:85], v[180:183], v[204:207], v[82:85]
	v_mfma_f32_16x16x32_bf16 v[74:77], v[172:175], v[212:215], v[74:77]
	v_mfma_f32_16x16x32_bf16 v[66:69], v[180:183], v[212:215], v[66:69]
	v_mfma_f32_16x16x32_bf16 v[122:125], v[176:179], v[192:195], v[122:125]
	v_mfma_f32_16x16x32_bf16 v[114:117], v[184:187], v[192:195], v[114:117]
	v_mfma_f32_16x16x32_bf16 v[106:109], v[176:179], v[200:203], v[106:109]
	v_mfma_f32_16x16x32_bf16 v[98:101], v[184:187], v[200:203], v[98:101]
	v_mfma_f32_16x16x32_bf16 v[90:93], v[176:179], v[208:211], v[90:93]
	v_mfma_f32_16x16x32_bf16 v[82:85], v[184:187], v[208:211], v[82:85]
	v_mfma_f32_16x16x32_bf16 v[74:77], v[176:179], v[216:219], v[74:77]
	v_mfma_f32_16x16x32_bf16 v[66:69], v[184:187], v[216:219], v[66:69]
	s_barrier
	s_add_i32 s43, s58, s33
	v_lshl_add_u64 v[220:221], s[8:9], 0, v[132:133]
	s_mov_b32 m0, s43
	ds_read_b128 v[188:191], v170 offset:16384
	ds_read_b128 v[192:195], v170 offset:17408
	ds_read_b128 v[196:199], v170 offset:18432
	ds_read_b128 v[200:203], v170 offset:19456
	ds_read_b128 v[204:207], v170 offset:20480
	ds_read_b128 v[208:211], v170 offset:21504
	ds_read_b128 v[212:215], v170 offset:22528
	ds_read_b128 v[216:219], v170 offset:23552
	global_load_lds_dwordx4 v[220:221], off
	s_add_i32 m0, s43, 0x2000
	s_add_u32 s62, s8, 0x40000
	v_lshl_add_u64 v[222:223], s[8:9], 0, v[136:137]
	s_addc_u32 s63, s9, 0
	s_add_i32 s43, s59, s33
	global_load_lds_dwordx4 v[222:223], off
	v_lshl_add_u64 v[224:225], s[62:63], 0, v[132:133]
	s_mov_b32 m0, s43
	v_lshl_add_u64 v[226:227], s[10:11], 0, v[134:135]
	global_load_lds_dwordx4 v[224:225], off
	v_lshl_add_u64 v[224:225], s[62:63], 0, v[136:137]
	s_add_i32 m0, s43, 0x2000
	s_nop 0
	global_load_lds_dwordx4 v[224:225], off
	v_lshl_add_u64 v[224:225], s[10:11], 0, v[130:131]
	s_mov_b32 m0, s50
	s_nop 0
	global_load_lds_dwordx4 v[224:225], off
	s_mov_b32 m0, s51
	s_nop 0
	global_load_lds_dwordx4 v[226:227], off
	s_waitcnt vmcnt(8)
	s_waitcnt lgkmcnt(0)
	s_barrier
; #define PG8_STAGE(bufoff, gbase, voff) do { _Pragma("unroll") for (int _i = 0; _i < 2; ++_i) \
;         __builtin_amdgcn_global_load_lds((const unsigned*)((const char*)(gbase) + (voff)[_i]), (LAS unsigned*)(lds + (bufoff) + ldsw + _i * 8192), 16, 0, 0); } while (0)
; #define PG8_LDA(dst, b, h) do { _Pragma("unroll") for (int m = 0; m < 4; ++m) _Pragma("unroll") for (int k = 0; k < 2; ++k) dst[m][k] = *(const LAS bf16x8*)(lds + PG8_SA(b, h) + aoff + m * 2048 + k * 1024); } while (0)
; #define PG8_LDB(dst, b, h) do { _Pragma("unroll") for (int n = 0; n < 2; ++n) _Pragma("unroll") for (int k = 0; k < 2; ++k) dst[n][k] = *(const LAS bf16x8*)(lds + PG8_SB(b, h) + boff + n * 2048 + k * 1024); } while (0)
; #define PG8_MMA(ai, bj, At, Bt) do { __builtin_amdgcn_s_setprio(3); _Pragma("unroll") for (int m = 0; m < 4; ++m) _Pragma("unroll") for (int n = 0; n < 2; ++n) _Pragma("unroll") for (int k = 0; k < 2; ++k) \
;         acc[ai][bj][m][n] = __builtin_amdgcn_mfma_f32_16x16x32_bf16(Bt[n][k], At[m][k], acc[ai][bj][m][n], 0, 0, 0); __builtin_amdgcn_s_setprio(0); } while (0)
; #define PG8_WAIT_V(n) asm volatile("s_waitcnt vmcnt(" #n ")" ::: "memory")
; #define PG8_WAIT_L(n) asm volatile("s_waitcnt lgkmcnt(" #n ")" ::: "memory")
; #define PG8_BAR __builtin_amdgcn_s_barrier()
; #define PG8_SCHED __builtin_amdgcn_sched_barrier(0)
; template <class Epi, bool ALIGN_EPI>
; __device__ __forceinline__ void gemm_phase(LAS unsigned char* lds, const Gemm g, const StaticOrder& S, const Epi& E) {
;     ...
;             PG8_WAIT_V(8); PG8_WAIT_L(0); PG8_BAR; PG8_MMA(1, 0, At, B0); PG8_MMA(1, 1, At, B1); PG8_BAR; PG8_SCHED;
;             PG8_LDB(B0, 1, 0); PG8_LDB(B1, 1, 1); PG8_SCHED; PG8_LDA(At, 1, 0); PG8_STAGE(PG8_SA(0, 1), a2 + hstep, voffA);
;             PG8_WAIT_V(8); PG8_WAIT_L(0); PG8_BAR; PG8_MMA(0, 0, At, B0); PG8_MMA(0, 1, At, B1); PG8_BAR; PG8_SCHED;
	s_waitcnt lgkmcnt(0)
	v_mfma_f32_16x16x32_bf16 v[62:65], v[146:149], v[188:191], v[62:65]
	v_mfma_f32_16x16x32_bf16 v[54:57], v[154:157], v[188:191], v[54:57]
	v_mfma_f32_16x16x32_bf16 v[46:49], v[146:149], v[196:199], v[46:49]
	v_mfma_f32_16x16x32_bf16 v[38:41], v[154:157], v[196:199], v[38:41]
	v_mfma_f32_16x16x32_bf16 v[30:33], v[146:149], v[204:207], v[30:33]
	v_mfma_f32_16x16x32_bf16 v[22:25], v[154:157], v[204:207], v[22:25]
	v_mfma_f32_16x16x32_bf16 v[14:17], v[146:149], v[212:215], v[14:17]
	v_mfma_f32_16x16x32_bf16 v[6:9], v[154:157], v[212:215], v[6:9]
	v_mfma_f32_16x16x32_bf16 v[62:65], v[150:153], v[192:195], v[62:65]
	v_mfma_f32_16x16x32_bf16 v[54:57], v[158:161], v[192:195], v[54:57]
	v_mfma_f32_16x16x32_bf16 v[46:49], v[150:153], v[200:203], v[46:49]
	v_mfma_f32_16x16x32_bf16 v[38:41], v[158:161], v[200:203], v[38:41]
	v_mfma_f32_16x16x32_bf16 v[30:33], v[150:153], v[208:211], v[30:33]
	v_mfma_f32_16x16x32_bf16 v[22:25], v[158:161], v[208:211], v[22:25]
	v_mfma_f32_16x16x32_bf16 v[14:17], v[150:153], v[216:219], v[14:17]
	v_mfma_f32_16x16x32_bf16 v[6:9], v[158:161], v[216:219], v[6:9]
	v_mfma_f32_16x16x32_bf16 v[58:61], v[172:175], v[188:191], v[58:61]
	v_mfma_f32_16x16x32_bf16 v[50:53], v[180:183], v[188:191], v[50:53]
	v_mfma_f32_16x16x32_bf16 v[42:45], v[172:175], v[196:199], v[42:45]
	v_mfma_f32_16x16x32_bf16 v[34:37], v[180:183], v[196:199], v[34:37]
	v_mfma_f32_16x16x32_bf16 v[26:29], v[172:175], v[204:207], v[26:29]
	v_mfma_f32_16x16x32_bf16 v[18:21], v[180:183], v[204:207], v[18:21]
	v_mfma_f32_16x16x32_bf16 v[10:13], v[172:175], v[212:215], v[10:13]
	v_mfma_f32_16x16x32_bf16 v[2:5], v[180:183], v[212:215], v[2:5]
	v_mfma_f32_16x16x32_bf16 v[58:61], v[176:179], v[192:195], v[58:61]
	v_mfma_f32_16x16x32_bf16 v[50:53], v[184:187], v[192:195], v[50:53]
	v_mfma_f32_16x16x32_bf16 v[42:45], v[176:179], v[200:203], v[42:45]
	v_mfma_f32_16x16x32_bf16 v[34:37], v[184:187], v[200:203], v[34:37]
	v_mfma_f32_16x16x32_bf16 v[26:29], v[176:179], v[208:211], v[26:29]
	v_mfma_f32_16x16x32_bf16 v[18:21], v[184:187], v[208:211], v[18:21]
	v_mfma_f32_16x16x32_bf16 v[10:13], v[176:179], v[216:219], v[10:13]
	v_mfma_f32_16x16x32_bf16 v[2:5], v[184:187], v[216:219], v[2:5]
	s_barrier
	s_add_i32 s43, 0, 0x18000
	s_add_i32 s62, 0, 0x1c000
	v_add_u32_e32 v158, s43, v166
	v_add_u32_e32 v184, s62, v166
	ds_read_b128 v[146:149], v158
	ds_read_b128 v[150:153], v158 offset:1024
	ds_read_b128 v[154:157], v158 offset:2048
	ds_read_b128 v[158:161], v158 offset:3072
	ds_read_b128 v[172:175], v184
	ds_read_b128 v[176:179], v184 offset:1024
	ds_read_b128 v[180:183], v184 offset:2048
	ds_read_b128 v[184:187], v184 offset:3072
	s_add_u32 s10, s10, 0x40000
	s_addc_u32 s11, s11, 0
	s_mov_b32 m0, s52
	v_lshl_add_u64 v[228:229], s[10:11], 0, v[130:131]
	ds_read_b128 v[188:191], v170 offset:32768
	ds_read_b128 v[192:195], v170 offset:33792
	ds_read_b128 v[196:199], v170 offset:34816
	ds_read_b128 v[200:203], v170 offset:35840
	ds_read_b128 v[204:207], v170 offset:36864
	ds_read_b128 v[208:211], v170 offset:37888
	ds_read_b128 v[212:215], v170 offset:38912
	ds_read_b128 v[216:219], v170 offset:39936
	global_load_lds_dwordx4 v[228:229], off
	v_lshl_add_u64 v[228:229], s[10:11], 0, v[134:135]
	s_mov_b32 m0, s53
	s_nop 0
	global_load_lds_dwordx4 v[228:229], off
	s_waitcnt vmcnt(8)
	s_waitcnt lgkmcnt(0)
	s_barrier
	s_waitcnt lgkmcnt(0)
	v_mfma_f32_16x16x32_bf16 v[126:129], v[146:149], v[188:191], v[126:129]
	v_mfma_f32_16x16x32_bf16 v[118:121], v[154:157], v[188:191], v[118:121]
	v_mfma_f32_16x16x32_bf16 v[110:113], v[146:149], v[196:199], v[110:113]
	v_mfma_f32_16x16x32_bf16 v[102:105], v[154:157], v[196:199], v[102:105]
	v_mfma_f32_16x16x32_bf16 v[94:97], v[146:149], v[204:207], v[94:97]
	v_mfma_f32_16x16x32_bf16 v[86:89], v[154:157], v[204:207], v[86:89]
	v_mfma_f32_16x16x32_bf16 v[78:81], v[146:149], v[212:215], v[78:81]
	v_mfma_f32_16x16x32_bf16 v[70:73], v[154:157], v[212:215], v[70:73]
	v_mfma_f32_16x16x32_bf16 v[126:129], v[150:153], v[192:195], v[126:129]
	v_mfma_f32_16x16x32_bf16 v[118:121], v[158:161], v[192:195], v[118:121]
	v_mfma_f32_16x16x32_bf16 v[110:113], v[150:153], v[200:203], v[110:113]
	v_mfma_f32_16x16x32_bf16 v[102:105], v[158:161], v[200:203], v[102:105]
	v_mfma_f32_16x16x32_bf16 v[94:97], v[150:153], v[208:211], v[94:97]
	v_mfma_f32_16x16x32_bf16 v[86:89], v[158:161], v[208:211], v[86:89]
	v_mfma_f32_16x16x32_bf16 v[78:81], v[150:153], v[216:219], v[78:81]
	v_mfma_f32_16x16x32_bf16 v[70:73], v[158:161], v[216:219], v[70:73]
	v_mfma_f32_16x16x32_bf16 v[122:125], v[172:175], v[188:191], v[122:125]
	v_mfma_f32_16x16x32_bf16 v[114:117], v[180:183], v[188:191], v[114:117]
	v_mfma_f32_16x16x32_bf16 v[106:109], v[172:175], v[196:199], v[106:109]
	v_mfma_f32_16x16x32_bf16 v[98:101], v[180:183], v[196:199], v[98:101]
	v_mfma_f32_16x16x32_bf16 v[90:93], v[172:175], v[204:207], v[90:93]
	v_mfma_f32_16x16x32_bf16 v[82:85], v[180:183], v[204:207], v[82:85]
	v_mfma_f32_16x16x32_bf16 v[74:77], v[172:175], v[212:215], v[74:77]
	v_mfma_f32_16x16x32_bf16 v[66:69], v[180:183], v[212:215], v[66:69]
	v_mfma_f32_16x16x32_bf16 v[122:125], v[176:179], v[192:195], v[122:125]
	v_mfma_f32_16x16x32_bf16 v[114:117], v[184:187], v[192:195], v[114:117]
	v_mfma_f32_16x16x32_bf16 v[106:109], v[176:179], v[200:203], v[106:109]
	v_mfma_f32_16x16x32_bf16 v[98:101], v[184:187], v[200:203], v[98:101]
	v_mfma_f32_16x16x32_bf16 v[90:93], v[176:179], v[208:211], v[90:93]
	v_mfma_f32_16x16x32_bf16 v[82:85], v[184:187], v[208:211], v[82:85]
	v_mfma_f32_16x16x32_bf16 v[74:77], v[176:179], v[216:219], v[74:77]
	v_mfma_f32_16x16x32_bf16 v[66:69], v[184:187], v[216:219], v[66:69]
	s_barrier
; #define PG8_STAGE(bufoff, gbase, voff) do { _Pragma("unroll") for (int _i = 0; _i < 2; ++_i) \
;         __builtin_amdgcn_global_load_lds((const unsigned*)((const char*)(gbase) + (voff)[_i]), (LAS unsigned*)(lds + (bufoff) + ldsw + _i * 8192), 16, 0, 0); } while (0)
; #define PG8_LDA(dst, b, h) do { _Pragma("unroll") for (int m = 0; m < 4; ++m) _Pragma("unroll") for (int k = 0; k < 2; ++k) dst[m][k] = *(const LAS bf16x8*)(lds + PG8_SA(b, h) + aoff + m * 2048 + k * 1024); } while (0)
; #define PG8_MMA(ai, bj, At, Bt) do { __builtin_amdgcn_s_setprio(3); _Pragma("unroll") for (int m = 0; m < 4; ++m) _Pragma("unroll") for (int n = 0; n < 2; ++n) _Pragma("unroll") for (int k = 0; k < 2; ++k) \
;         acc[ai][bj][m][n] = __builtin_amdgcn_mfma_f32_16x16x32_bf16(Bt[n][k], At[m][k], acc[ai][bj][m][n], 0, 0, 0); __builtin_amdgcn_s_setprio(0); } while (0)
; #define PG8_WAIT_V(n) asm volatile("s_waitcnt vmcnt(" #n ")" ::: "memory")
; #define PG8_WAIT_L(n) asm volatile("s_waitcnt lgkmcnt(" #n ")" ::: "memory")
; #define PG8_BAR __builtin_amdgcn_s_barrier()
; #define PG8_SCHED __builtin_amdgcn_sched_barrier(0)
; template <class Epi, bool ALIGN_EPI>
; __device__ __forceinline__ void gemm_phase(LAS unsigned char* lds, const Gemm g, const StaticOrder& S, const Epi& E) {
;     ...
;         for (int t = 0; t < nt; t += 2) {
;     ...
;             PG8_LDA(At, 1, 1); PG8_STAGE(PG8_SB(1, 0), b3, voffB); PG8_STAGE(PG8_SB(1, 1), b3 + hstep, voffB); PG8_STAGE(PG8_SA(1, 0), a3, voffA);
;             PG8_WAIT_V(8); PG8_WAIT_L(0); PG8_BAR; PG8_MMA(1, 0, At, B0); PG8_MMA(1, 1, At, B1); PG8_BAR; PG8_SCHED;
;         }
	s_add_i32 s10, s43, s33
	v_lshl_add_u64 v[220:221], v[220:221], 0, s[36:37]
	s_mov_b32 m0, s10
	ds_read_b128 v[188:191], v170 offset:49152
	ds_read_b128 v[192:195], v170 offset:50176
	ds_read_b128 v[196:199], v170 offset:51200
	ds_read_b128 v[200:203], v170 offset:52224
	ds_read_b128 v[204:207], v170 offset:53248
	ds_read_b128 v[208:211], v170 offset:54272
	ds_read_b128 v[212:215], v170 offset:55296
	ds_read_b128 v[216:219], v170 offset:56320
	global_load_lds_dwordx4 v[220:221], off
	s_add_i32 m0, s10, 0x2000
	s_add_u32 s8, s8, 0x40080
	v_lshl_add_u64 v[220:221], v[222:223], 0, s[36:37]
	s_addc_u32 s9, s9, 0
	s_add_i32 s10, s62, s33
	global_load_lds_dwordx4 v[220:221], off
	v_lshl_add_u64 v[220:221], s[8:9], 0, v[132:133]
	s_mov_b32 m0, s10
	s_nop 0
	global_load_lds_dwordx4 v[220:221], off
	v_lshl_add_u64 v[220:221], s[8:9], 0, v[136:137]
	s_add_i32 m0, s10, 0x2000
	s_nop 0
	global_load_lds_dwordx4 v[220:221], off
	v_lshl_add_u64 v[220:221], v[224:225], 0, s[36:37]
	s_mov_b32 m0, s56
	s_nop 0
	global_load_lds_dwordx4 v[220:221], off
	v_lshl_add_u64 v[220:221], v[226:227], 0, s[36:37]
	s_mov_b32 m0, s57
	s_nop 0
	global_load_lds_dwordx4 v[220:221], off
	s_waitcnt vmcnt(8)
	s_waitcnt lgkmcnt(0)
	s_barrier
	s_waitcnt lgkmcnt(0)
	v_mfma_f32_16x16x32_bf16 v[62:65], v[146:149], v[188:191], v[62:65]
	v_mfma_f32_16x16x32_bf16 v[54:57], v[154:157], v[188:191], v[54:57]
	v_mfma_f32_16x16x32_bf16 v[46:49], v[146:149], v[196:199], v[46:49]
	v_mfma_f32_16x16x32_bf16 v[38:41], v[154:157], v[196:199], v[38:41]
	v_mfma_f32_16x16x32_bf16 v[30:33], v[146:149], v[204:207], v[30:33]
	v_mfma_f32_16x16x32_bf16 v[22:25], v[154:157], v[204:207], v[22:25]
	v_mfma_f32_16x16x32_bf16 v[14:17], v[146:149], v[212:215], v[14:17]
	v_mfma_f32_16x16x32_bf16 v[6:9], v[154:157], v[212:215], v[6:9]
	v_mfma_f32_16x16x32_bf16 v[62:65], v[150:153], v[192:195], v[62:65]
	v_mfma_f32_16x16x32_bf16 v[54:57], v[158:161], v[192:195], v[54:57]
	v_mfma_f32_16x16x32_bf16 v[46:49], v[150:153], v[200:203], v[46:49]
	v_mfma_f32_16x16x32_bf16 v[38:41], v[158:161], v[200:203], v[38:41]
	v_mfma_f32_16x16x32_bf16 v[30:33], v[150:153], v[208:211], v[30:33]
	v_mfma_f32_16x16x32_bf16 v[22:25], v[158:161], v[208:211], v[22:25]
	v_mfma_f32_16x16x32_bf16 v[14:17], v[150:153], v[216:219], v[14:17]
	v_mfma_f32_16x16x32_bf16 v[6:9], v[158:161], v[216:219], v[6:9]
	v_mfma_f32_16x16x32_bf16 v[58:61], v[172:175], v[188:191], v[58:61]
	v_mfma_f32_16x16x32_bf16 v[50:53], v[180:183], v[188:191], v[50:53]
	v_mfma_f32_16x16x32_bf16 v[42:45], v[172:175], v[196:199], v[42:45]
	v_mfma_f32_16x16x32_bf16 v[34:37], v[180:183], v[196:199], v[34:37]
	v_mfma_f32_16x16x32_bf16 v[26:29], v[172:175], v[204:207], v[26:29]
	v_mfma_f32_16x16x32_bf16 v[18:21], v[180:183], v[204:207], v[18:21]
	v_mfma_f32_16x16x32_bf16 v[10:13], v[172:175], v[212:215], v[10:13]
	v_mfma_f32_16x16x32_bf16 v[2:5], v[180:183], v[212:215], v[2:5]
	v_mfma_f32_16x16x32_bf16 v[58:61], v[176:179], v[192:195], v[58:61]
	v_mfma_f32_16x16x32_bf16 v[50:53], v[184:187], v[192:195], v[50:53]
	v_mfma_f32_16x16x32_bf16 v[42:45], v[176:179], v[200:203], v[42:45]
	v_mfma_f32_16x16x32_bf16 v[34:37], v[184:187], v[200:203], v[34:37]
	v_mfma_f32_16x16x32_bf16 v[26:29], v[176:179], v[208:211], v[26:29]
	v_mfma_f32_16x16x32_bf16 v[18:21], v[184:187], v[208:211], v[18:21]
	v_mfma_f32_16x16x32_bf16 v[10:13], v[176:179], v[216:219], v[10:13]
	v_mfma_f32_16x16x32_bf16 v[2:5], v[184:187], v[216:219], v[2:5]
	s_barrier
	s_add_i32 s41, s41, 2
	s_add_u32 s6, s6, 0x100
	s_addc_u32 s7, s7, 0
	s_add_u32 s16, s16, 0x100
	s_addc_u32 s17, s17, 0
	s_cmp_gt_u32 s41, 13
	s_cbranch_scc0 .LBB0_1428
	s_and_b64 vcc, exec, s[38:39]
	s_cbranch_vccz .LBB0_1431
	s_barrier

; #define PG8_STAGE(bufoff, gbase, voff) do { _Pragma("unroll") for (int _i = 0; _i < 2; ++_i) \
;         __builtin_amdgcn_global_load_lds((const unsigned*)((const char*)(gbase) + (voff)[_i]), (LAS unsigned*)(lds + (bufoff) + ldsw + _i * 8192), 16, 0, 0); } while (0)
; #define PG8_LDA(dst, b, h) do { _Pragma("unroll") for (int m = 0; m < 4; ++m) _Pragma("unroll") for (int k = 0; k < 2; ++k) dst[m][k] = *(const LAS bf16x8*)(lds + PG8_SA(b, h) + aoff + m * 2048 + k * 1024); } while (0)
; #define PG8_LDB(dst, b, h) do { _Pragma("unroll") for (int n = 0; n < 2; ++n) _Pragma("unroll") for (int k = 0; k < 2; ++k) dst[n][k] = *(const LAS bf16x8*)(lds + PG8_SB(b, h) + boff + n * 2048 + k * 1024); } while (0)
; #define PG8_MMA(ai, bj, At, Bt) do { __builtin_amdgcn_s_setprio(3); _Pragma("unroll") for (int m = 0; m < 4; ++m) _Pragma("unroll") for (int n = 0; n < 2; ++n) _Pragma("unroll") for (int k = 0; k < 2; ++k) \
;         acc[ai][bj][m][n] = __builtin_amdgcn_mfma_f32_16x16x32_bf16(Bt[n][k], At[m][k], acc[ai][bj][m][n], 0, 0, 0); __builtin_amdgcn_s_setprio(0); } while (0)
; #define PG8_WAIT_V(n) asm volatile("s_waitcnt vmcnt(" #n ")" ::: "memory")
; #define PG8_WAIT_L(n) asm volatile("s_waitcnt lgkmcnt(" #n ")" ::: "memory")
; #define PG8_BAR __builtin_amdgcn_s_barrier()
; #define PG8_SCHED __builtin_amdgcn_sched_barrier(0)
; template <class Epi, bool ALIGN_EPI>
; __device__ __forceinline__ void gemm_phase(LAS unsigned char* lds, const Gemm g, const StaticOrder& S, const Epi& E) {
;     ...
;                 for (int n = 0; n < 2; ++n) acc[a][b][m][n] = (f32x4){0.f, 0.f, 0.f, 0.f};
;     ...
;             PG8_LDB(B0, 0, 0); PG8_LDB(B1, 0, 1); PG8_SCHED; PG8_LDA(At, 0, 0); PG8_STAGE(PG8_SA(1, 1), a1 + hstep, voffA);
;             PG8_WAIT_V(8); PG8_WAIT_L(0); PG8_BAR; PG8_MMA(0, 0, At, B0); PG8_MMA(0, 1, At, B1); PG8_BAR; PG8_SCHED;
;             PG8_LDA(At, 0, 1); PG8_STAGE(PG8_SB(0, 0), b2, voffB); PG8_STAGE(PG8_SB(0, 1), b2 + hstep, voffB); PG8_STAGE(PG8_SA(0, 0), a2, voffA);
;             PG8_WAIT_V(8); PG8_WAIT_L(0); PG8_BAR; PG8_MMA(1, 0, At, B0); PG8_MMA(1, 1, At, B1); PG8_BAR; PG8_SCHED;
.Lmy_rw_1513_0:
	s_waitcnt lgkmcnt(0)
	s_barrier
	s_waitcnt lgkmcnt(0)
	v_mfma_f32_16x16x32_bf16 v[124:127], v[144:147], v[186:189], 0
	v_mfma_f32_16x16x32_bf16 v[120:123], v[162:165], v[186:189], 0
	v_mfma_f32_16x16x32_bf16 v[108:111], v[144:147], v[194:197], 0
	v_mfma_f32_16x16x32_bf16 v[104:107], v[162:165], v[194:197], 0
	v_mfma_f32_16x16x32_bf16 v[96:99], v[144:147], v[202:205], 0
	v_mfma_f32_16x16x32_bf16 v[88:91], v[162:165], v[202:205], 0
	v_mfma_f32_16x16x32_bf16 v[80:83], v[144:147], v[210:213], 0
	v_mfma_f32_16x16x32_bf16 v[72:75], v[162:165], v[210:213], 0
	v_mfma_f32_16x16x32_bf16 v[124:127], v[148:151], v[190:193], v[124:127]
	v_mfma_f32_16x16x32_bf16 v[120:123], v[166:169], v[190:193], v[120:123]
	v_mfma_f32_16x16x32_bf16 v[108:111], v[148:151], v[198:201], v[108:111]
	v_mfma_f32_16x16x32_bf16 v[104:107], v[166:169], v[198:201], v[104:107]
	v_mfma_f32_16x16x32_bf16 v[96:99], v[148:151], v[206:209], v[96:99]
	v_mfma_f32_16x16x32_bf16 v[88:91], v[166:169], v[206:209], v[88:91]
	v_mfma_f32_16x16x32_bf16 v[80:83], v[148:151], v[214:217], v[80:83]
	v_mfma_f32_16x16x32_bf16 v[72:75], v[166:169], v[214:217], v[72:75]
	v_mfma_f32_16x16x32_bf16 v[116:119], v[170:173], v[186:189], 0
	v_mfma_f32_16x16x32_bf16 v[112:115], v[178:181], v[186:189], 0
	v_mfma_f32_16x16x32_bf16 v[100:103], v[170:173], v[194:197], 0
	v_mfma_f32_16x16x32_bf16 v[92:95], v[178:181], v[194:197], 0
	v_mfma_f32_16x16x32_bf16 v[84:87], v[170:173], v[202:205], 0
	v_mfma_f32_16x16x32_bf16 v[76:79], v[178:181], v[202:205], 0
	v_mfma_f32_16x16x32_bf16 v[68:71], v[170:173], v[210:213], 0
	v_mfma_f32_16x16x32_bf16 v[64:67], v[178:181], v[210:213], 0
	v_mfma_f32_16x16x32_bf16 v[116:119], v[174:177], v[190:193], v[116:119]
	v_mfma_f32_16x16x32_bf16 v[112:115], v[182:185], v[190:193], v[112:115]
	v_mfma_f32_16x16x32_bf16 v[100:103], v[174:177], v[198:201], v[100:103]
	v_mfma_f32_16x16x32_bf16 v[92:95], v[182:185], v[198:201], v[92:95]
	v_mfma_f32_16x16x32_bf16 v[84:87], v[174:177], v[206:209], v[84:87]
	v_mfma_f32_16x16x32_bf16 v[76:79], v[182:185], v[206:209], v[76:79]
	v_mfma_f32_16x16x32_bf16 v[68:71], v[174:177], v[214:217], v[68:71]
	v_mfma_f32_16x16x32_bf16 v[64:67], v[182:185], v[214:217], v[64:67]
	s_barrier
	s_add_i32 s46, s37, s23
	v_lshl_add_u64 v[218:219], s[16:17], 0, v[130:131]
	s_mov_b32 m0, s46
	ds_read_b128 v[186:189], v160 offset:16384
	ds_read_b128 v[190:193], v160 offset:17408
	ds_read_b128 v[194:197], v160 offset:18432
	ds_read_b128 v[198:201], v160 offset:19456
	ds_read_b128 v[202:205], v160 offset:20480
	ds_read_b128 v[206:209], v160 offset:21504
	ds_read_b128 v[210:213], v160 offset:22528
	ds_read_b128 v[214:217], v160 offset:23552
	global_load_lds_dwordx4 v[218:219], off
	s_add_i32 m0, s46, 0x2000
	s_add_u32 s46, s16, 0xb0000
	v_lshl_add_u64 v[220:221], s[16:17], 0, v[134:135]
	s_addc_u32 s47, s17, 0
	s_add_i32 s48, s38, s23
	global_load_lds_dwordx4 v[220:221], off
	v_lshl_add_u64 v[222:223], s[46:47], 0, v[130:131]
	s_mov_b32 m0, s48
	v_lshl_add_u64 v[224:225], s[18:19], 0, v[132:133]
	global_load_lds_dwordx4 v[222:223], off
	v_lshl_add_u64 v[222:223], s[46:47], 0, v[134:135]
	s_add_i32 m0, s48, 0x2000
	s_nop 0
	global_load_lds_dwordx4 v[222:223], off
	v_lshl_add_u64 v[222:223], s[18:19], 0, v[128:129]
	s_mov_b32 m0, s26
	s_nop 0
	global_load_lds_dwordx4 v[222:223], off
	s_mov_b32 m0, s27
	s_nop 0
	global_load_lds_dwordx4 v[224:225], off
	s_cmp_lg_u32 s98, 0
	s_cbranch_scc1 .Lmy_rw_1513_1
	s_waitcnt vmcnt(8)
.Lmy_rw_1513_1:
	s_waitcnt lgkmcnt(0)
	s_barrier
	s_waitcnt lgkmcnt(0)
	v_mfma_f32_16x16x32_bf16 v[60:63], v[144:147], v[186:189], 0
	v_mfma_f32_16x16x32_bf16 v[56:59], v[162:165], v[186:189], 0
	v_mfma_f32_16x16x32_bf16 v[48:51], v[144:147], v[194:197], 0
	v_mfma_f32_16x16x32_bf16 v[40:43], v[162:165], v[194:197], 0
	v_mfma_f32_16x16x32_bf16 v[32:35], v[144:147], v[202:205], 0
	v_mfma_f32_16x16x32_bf16 v[24:27], v[162:165], v[202:205], 0
	v_mfma_f32_16x16x32_bf16 v[16:19], v[144:147], v[210:213], 0
	v_mfma_f32_16x16x32_bf16 v[8:11], v[162:165], v[210:213], 0
	v_mfma_f32_16x16x32_bf16 v[60:63], v[148:151], v[190:193], v[60:63]
	v_mfma_f32_16x16x32_bf16 v[56:59], v[166:169], v[190:193], v[56:59]
	v_mfma_f32_16x16x32_bf16 v[48:51], v[148:151], v[198:201], v[48:51]
	v_mfma_f32_16x16x32_bf16 v[40:43], v[166:169], v[198:201], v[40:43]
	v_mfma_f32_16x16x32_bf16 v[32:35], v[148:151], v[206:209], v[32:35]
	v_mfma_f32_16x16x32_bf16 v[24:27], v[166:169], v[206:209], v[24:27]
	v_mfma_f32_16x16x32_bf16 v[16:19], v[148:151], v[214:217], v[16:19]
	v_mfma_f32_16x16x32_bf16 v[8:11], v[166:169], v[214:217], v[8:11]
	v_mfma_f32_16x16x32_bf16 v[52:55], v[170:173], v[186:189], 0
	v_mfma_f32_16x16x32_bf16 v[44:47], v[178:181], v[186:189], 0
	v_mfma_f32_16x16x32_bf16 v[36:39], v[170:173], v[194:197], 0
	v_mfma_f32_16x16x32_bf16 v[28:31], v[178:181], v[194:197], 0
	v_mfma_f32_16x16x32_bf16 v[20:23], v[170:173], v[202:205], 0
	v_mfma_f32_16x16x32_bf16 v[12:15], v[178:181], v[202:205], 0
	v_mfma_f32_16x16x32_bf16 v[4:7], v[170:173], v[210:213], 0
	v_mfma_f32_16x16x32_bf16 v[0:3], v[178:181], v[210:213], 0
	v_mfma_f32_16x16x32_bf16 v[52:55], v[174:177], v[190:193], v[52:55]
	v_mfma_f32_16x16x32_bf16 v[44:47], v[182:185], v[190:193], v[44:47]
	v_mfma_f32_16x16x32_bf16 v[36:39], v[174:177], v[198:201], v[36:39]
	v_mfma_f32_16x16x32_bf16 v[28:31], v[182:185], v[198:201], v[28:31]
	v_mfma_f32_16x16x32_bf16 v[20:23], v[174:177], v[206:209], v[20:23]
	v_mfma_f32_16x16x32_bf16 v[12:15], v[182:185], v[206:209], v[12:15]
	v_mfma_f32_16x16x32_bf16 v[4:7], v[174:177], v[214:217], v[4:7]
	v_mfma_f32_16x16x32_bf16 v[0:3], v[182:185], v[214:217], v[0:3]
	s_barrier
; #define PG8_STAGE(bufoff, gbase, voff) do { _Pragma("unroll") for (int _i = 0; _i < 2; ++_i) \
;         __builtin_amdgcn_global_load_lds((const unsigned*)((const char*)(gbase) + (voff)[_i]), (LAS unsigned*)(lds + (bufoff) + ldsw + _i * 8192), 16, 0, 0); } while (0)
; #define PG8_LDA(dst, b, h) do { _Pragma("unroll") for (int m = 0; m < 4; ++m) _Pragma("unroll") for (int k = 0; k < 2; ++k) dst[m][k] = *(const LAS bf16x8*)(lds + PG8_SA(b, h) + aoff + m * 2048 + k * 1024); } while (0)
; #define PG8_LDB(dst, b, h) do { _Pragma("unroll") for (int n = 0; n < 2; ++n) _Pragma("unroll") for (int k = 0; k < 2; ++k) dst[n][k] = *(const LAS bf16x8*)(lds + PG8_SB(b, h) + boff + n * 2048 + k * 1024); } while (0)
; #define PG8_MMA(ai, bj, At, Bt) do { __builtin_amdgcn_s_setprio(3); _Pragma("unroll") for (int m = 0; m < 4; ++m) _Pragma("unroll") for (int n = 0; n < 2; ++n) _Pragma("unroll") for (int k = 0; k < 2; ++k) \
;         acc[ai][bj][m][n] = __builtin_amdgcn_mfma_f32_16x16x32_bf16(Bt[n][k], At[m][k], acc[ai][bj][m][n], 0, 0, 0); __builtin_amdgcn_s_setprio(0); } while (0)
; #define PG8_WAIT_V(n) asm volatile("s_waitcnt vmcnt(" #n ")" ::: "memory")
; #define PG8_WAIT_L(n) asm volatile("s_waitcnt lgkmcnt(" #n ")" ::: "memory")
; #define PG8_BAR __builtin_amdgcn_s_barrier()
; #define PG8_SCHED __builtin_amdgcn_sched_barrier(0)
; template <class Epi, bool ALIGN_EPI>
; __device__ __forceinline__ void gemm_phase(LAS unsigned char* lds, const Gemm g, const StaticOrder& S, const Epi& E) {
;     ...
;             PG8_LDB(B0, 1, 0); PG8_LDB(B1, 1, 1); PG8_SCHED; PG8_LDA(At, 1, 0); PG8_STAGE(PG8_SA(0, 1), a2 + hstep, voffA);
;             PG8_WAIT_V(8); PG8_WAIT_L(0); PG8_BAR; PG8_MMA(0, 0, At, B0); PG8_MMA(0, 1, At, B1); PG8_BAR; PG8_SCHED;
;             PG8_LDA(At, 1, 1); PG8_STAGE(PG8_SB(1, 0), b3, voffB); PG8_STAGE(PG8_SB(1, 1), b3 + hstep, voffB); PG8_STAGE(PG8_SA(1, 0), a3, voffA);
;             PG8_WAIT_V(8); PG8_WAIT_L(0); PG8_BAR; PG8_MMA(1, 0, At, B0); PG8_MMA(1, 1, At, B1); PG8_BAR; PG8_SCHED;
	s_add_i32 s46, 0, 0x18000
	v_add_u32_e32 v161, s46, v156
	s_add_i32 s47, 0, 0x1c000
	ds_read_b128 v[144:147], v161
	ds_read_b128 v[148:151], v161 offset:1024
	ds_read_b128 v[162:165], v161 offset:2048
	ds_read_b128 v[166:169], v161 offset:3072
	v_add_u32_e32 v161, s47, v156
	ds_read_b128 v[170:173], v161
	ds_read_b128 v[174:177], v161 offset:1024
	ds_read_b128 v[178:181], v161 offset:2048
	ds_read_b128 v[182:185], v161 offset:3072
	s_add_u32 s18, s18, 0xb0000
	s_addc_u32 s19, s19, 0
	s_mov_b32 m0, s28
	v_lshl_add_u64 v[226:227], s[18:19], 0, v[128:129]
	ds_read_b128 v[186:189], v160 offset:32768
	ds_read_b128 v[190:193], v160 offset:33792
	ds_read_b128 v[194:197], v160 offset:34816
	ds_read_b128 v[198:201], v160 offset:35840
	ds_read_b128 v[202:205], v160 offset:36864
	ds_read_b128 v[206:209], v160 offset:37888
	ds_read_b128 v[210:213], v160 offset:38912
	ds_read_b128 v[214:217], v160 offset:39936
	global_load_lds_dwordx4 v[226:227], off
	v_lshl_add_u64 v[226:227], s[18:19], 0, v[132:133]
	s_mov_b32 m0, s29
	s_nop 0
	global_load_lds_dwordx4 v[226:227], off
	s_waitcnt vmcnt(8)
	s_waitcnt lgkmcnt(0)
	s_barrier
	s_waitcnt lgkmcnt(0)
	v_mfma_f32_16x16x32_bf16 v[124:127], v[144:147], v[186:189], v[124:127]
	v_mfma_f32_16x16x32_bf16 v[120:123], v[162:165], v[186:189], v[120:123]
	v_mfma_f32_16x16x32_bf16 v[108:111], v[144:147], v[194:197], v[108:111]
	v_mfma_f32_16x16x32_bf16 v[104:107], v[162:165], v[194:197], v[104:107]
	v_mfma_f32_16x16x32_bf16 v[96:99], v[144:147], v[202:205], v[96:99]
	v_mfma_f32_16x16x32_bf16 v[88:91], v[162:165], v[202:205], v[88:91]
	v_mfma_f32_16x16x32_bf16 v[80:83], v[144:147], v[210:213], v[80:83]
	v_mfma_f32_16x16x32_bf16 v[72:75], v[162:165], v[210:213], v[72:75]
	v_mfma_f32_16x16x32_bf16 v[124:127], v[148:151], v[190:193], v[124:127]
	v_mfma_f32_16x16x32_bf16 v[120:123], v[166:169], v[190:193], v[120:123]
	v_mfma_f32_16x16x32_bf16 v[108:111], v[148:151], v[198:201], v[108:111]
	v_mfma_f32_16x16x32_bf16 v[104:107], v[166:169], v[198:201], v[104:107]
	v_mfma_f32_16x16x32_bf16 v[96:99], v[148:151], v[206:209], v[96:99]
	v_mfma_f32_16x16x32_bf16 v[88:91], v[166:169], v[206:209], v[88:91]
	v_mfma_f32_16x16x32_bf16 v[80:83], v[148:151], v[214:217], v[80:83]
	v_mfma_f32_16x16x32_bf16 v[72:75], v[166:169], v[214:217], v[72:75]
	v_mfma_f32_16x16x32_bf16 v[116:119], v[170:173], v[186:189], v[116:119]
	v_mfma_f32_16x16x32_bf16 v[112:115], v[178:181], v[186:189], v[112:115]
	v_mfma_f32_16x16x32_bf16 v[100:103], v[170:173], v[194:197], v[100:103]
	v_mfma_f32_16x16x32_bf16 v[92:95], v[178:181], v[194:197], v[92:95]
	v_mfma_f32_16x16x32_bf16 v[84:87], v[170:173], v[202:205], v[84:87]
	v_mfma_f32_16x16x32_bf16 v[76:79], v[178:181], v[202:205], v[76:79]
	v_mfma_f32_16x16x32_bf16 v[68:71], v[170:173], v[210:213], v[68:71]
	v_mfma_f32_16x16x32_bf16 v[64:67], v[178:181], v[210:213], v[64:67]
	v_mfma_f32_16x16x32_bf16 v[116:119], v[174:177], v[190:193], v[116:119]
	v_mfma_f32_16x16x32_bf16 v[112:115], v[182:185], v[190:193], v[112:115]
	v_mfma_f32_16x16x32_bf16 v[100:103], v[174:177], v[198:201], v[100:103]
	v_mfma_f32_16x16x32_bf16 v[92:95], v[182:185], v[198:201], v[92:95]
	v_mfma_f32_16x16x32_bf16 v[84:87], v[174:177], v[206:209], v[84:87]
	v_mfma_f32_16x16x32_bf16 v[76:79], v[182:185], v[206:209], v[76:79]
	v_mfma_f32_16x16x32_bf16 v[68:71], v[174:177], v[214:217], v[68:71]
	v_mfma_f32_16x16x32_bf16 v[64:67], v[182:185], v[214:217], v[64:67]
	s_barrier
	s_add_i32 s18, s46, s23
	v_lshl_add_u64 v[218:219], v[218:219], 0, s[8:9]
	s_mov_b32 m0, s18
	ds_read_b128 v[186:189], v160 offset:49152
	ds_read_b128 v[190:193], v160 offset:50176
	ds_read_b128 v[194:197], v160 offset:51200
	ds_read_b128 v[198:201], v160 offset:52224
	ds_read_b128 v[202:205], v160 offset:53248
	ds_read_b128 v[206:209], v160 offset:54272
	ds_read_b128 v[210:213], v160 offset:55296
	ds_read_b128 v[214:217], v160 offset:56320
	global_load_lds_dwordx4 v[218:219], off
	s_add_i32 m0, s18, 0x2000
	s_add_u32 s16, s16, 0xb0080
	v_lshl_add_u64 v[218:219], v[220:221], 0, s[8:9]
	s_addc_u32 s17, s17, 0
	s_add_i32 s18, s47, s23
	global_load_lds_dwordx4 v[218:219], off
	v_lshl_add_u64 v[218:219], s[16:17], 0, v[130:131]
	s_mov_b32 m0, s18
	s_nop 0
	global_load_lds_dwordx4 v[218:219], off
	v_lshl_add_u64 v[218:219], s[16:17], 0, v[134:135]
	s_add_i32 m0, s18, 0x2000
	s_nop 0
	global_load_lds_dwordx4 v[218:219], off
	v_lshl_add_u64 v[218:219], v[222:223], 0, s[8:9]
	s_mov_b32 m0, s31
	s_nop 0
	global_load_lds_dwordx4 v[218:219], off
	v_lshl_add_u64 v[218:219], v[224:225], 0, s[8:9]
	s_mov_b32 m0, s33
	s_nop 0
	global_load_lds_dwordx4 v[218:219], off
	s_waitcnt vmcnt(8)
	s_waitcnt lgkmcnt(0)
	s_barrier
	s_waitcnt lgkmcnt(0)
	v_mfma_f32_16x16x32_bf16 v[60:63], v[144:147], v[186:189], v[60:63]
	v_mfma_f32_16x16x32_bf16 v[56:59], v[162:165], v[186:189], v[56:59]
	v_mfma_f32_16x16x32_bf16 v[48:51], v[144:147], v[194:197], v[48:51]
	v_mfma_f32_16x16x32_bf16 v[40:43], v[162:165], v[194:197], v[40:43]
	v_mfma_f32_16x16x32_bf16 v[32:35], v[144:147], v[202:205], v[32:35]
	v_mfma_f32_16x16x32_bf16 v[24:27], v[162:165], v[202:205], v[24:27]
	v_mfma_f32_16x16x32_bf16 v[16:19], v[144:147], v[210:213], v[16:19]
	v_mfma_f32_16x16x32_bf16 v[8:11], v[162:165], v[210:213], v[8:11]
	v_mfma_f32_16x16x32_bf16 v[60:63], v[148:151], v[190:193], v[60:63]
	v_mfma_f32_16x16x32_bf16 v[56:59], v[166:169], v[190:193], v[56:59]
	v_mfma_f32_16x16x32_bf16 v[48:51], v[148:151], v[198:201], v[48:51]
	v_mfma_f32_16x16x32_bf16 v[40:43], v[166:169], v[198:201], v[40:43]
	v_mfma_f32_16x16x32_bf16 v[32:35], v[148:151], v[206:209], v[32:35]
	v_mfma_f32_16x16x32_bf16 v[24:27], v[166:169], v[206:209], v[24:27]
	v_mfma_f32_16x16x32_bf16 v[16:19], v[148:151], v[214:217], v[16:19]
	v_mfma_f32_16x16x32_bf16 v[8:11], v[166:169], v[214:217], v[8:11]
	v_mfma_f32_16x16x32_bf16 v[52:55], v[170:173], v[186:189], v[52:55]
	v_mfma_f32_16x16x32_bf16 v[44:47], v[178:181], v[186:189], v[44:47]
	v_mfma_f32_16x16x32_bf16 v[36:39], v[170:173], v[194:197], v[36:39]
	v_mfma_f32_16x16x32_bf16 v[28:31], v[178:181], v[194:197], v[28:31]
	v_mfma_f32_16x16x32_bf16 v[20:23], v[170:173], v[202:205], v[20:23]
	v_mfma_f32_16x16x32_bf16 v[12:15], v[178:181], v[202:205], v[12:15]
	v_mfma_f32_16x16x32_bf16 v[4:7], v[170:173], v[210:213], v[4:7]
	v_mfma_f32_16x16x32_bf16 v[0:3], v[178:181], v[210:213], v[0:3]
	v_mfma_f32_16x16x32_bf16 v[52:55], v[174:177], v[190:193], v[52:55]
	v_mfma_f32_16x16x32_bf16 v[44:47], v[182:185], v[190:193], v[44:47]
	v_mfma_f32_16x16x32_bf16 v[36:39], v[174:177], v[198:201], v[36:39]
	v_mfma_f32_16x16x32_bf16 v[28:31], v[182:185], v[198:201], v[28:31]
	v_mfma_f32_16x16x32_bf16 v[20:23], v[174:177], v[206:209], v[20:23]
	v_mfma_f32_16x16x32_bf16 v[12:15], v[182:185], v[206:209], v[12:15]
	v_mfma_f32_16x16x32_bf16 v[4:7], v[174:177], v[214:217], v[4:7]
	v_mfma_f32_16x16x32_bf16 v[0:3], v[182:185], v[214:217], v[0:3]
	s_barrier
	s_add_i32 s45, s45, 2
	s_add_u32 s14, s14, 0x100
	s_addc_u32 s15, s15, 0
	s_add_u32 s43, s43, 0x100
	s_addc_u32 s44, s44, 0
; #define PG8_STAGE(bufoff, gbase, voff) do { _Pragma("unroll") for (int _i = 0; _i < 2; ++_i) \
;         __builtin_amdgcn_global_load_lds((const unsigned*)((const char*)(gbase) + (voff)[_i]), (LAS unsigned*)(lds + (bufoff) + ldsw + _i * 8192), 16, 0, 0); } while (0)
; #define PG8_LDA(dst, b, h) do { _Pragma("unroll") for (int m = 0; m < 4; ++m) _Pragma("unroll") for (int k = 0; k < 2; ++k) dst[m][k] = *(const LAS bf16x8*)(lds + PG8_SA(b, h) + aoff + m * 2048 + k * 1024); } while (0)
; #define PG8_LDB(dst, b, h) do { _Pragma("unroll") for (int n = 0; n < 2; ++n) _Pragma("unroll") for (int k = 0; k < 2; ++k) dst[n][k] = *(const LAS bf16x8*)(lds + PG8_SB(b, h) + boff + n * 2048 + k * 1024); } while (0)
; #define PG8_MMA(ai, bj, At, Bt) do { __builtin_amdgcn_s_setprio(3); _Pragma("unroll") for (int m = 0; m < 4; ++m) _Pragma("unroll") for (int n = 0; n < 2; ++n) _Pragma("unroll") for (int k = 0; k < 2; ++k) \
;         acc[ai][bj][m][n] = __builtin_amdgcn_mfma_f32_16x16x32_bf16(Bt[n][k], At[m][k], acc[ai][bj][m][n], 0, 0, 0); __builtin_amdgcn_s_setprio(0); } while (0)
; #define PG8_WAIT_V(n) asm volatile("s_waitcnt vmcnt(" #n ")" ::: "memory")
; #define PG8_WAIT_L(n) asm volatile("s_waitcnt lgkmcnt(" #n ")" ::: "memory")
; #define PG8_BAR __builtin_amdgcn_s_barrier()
; #define PG8_SCHED __builtin_amdgcn_sched_barrier(0)
; template <class Epi, bool ALIGN_EPI>
; __device__ __forceinline__ void gemm_phase(LAS unsigned char* lds, const Gemm g, const StaticOrder& S, const Epi& E) {
;     ...
;             PG8_LDB(B0, 0, 0); PG8_LDB(B1, 0, 1); PG8_SCHED; PG8_LDA(At, 0, 0); PG8_STAGE(PG8_SA(1, 1), a1 + hstep, voffA);
;             PG8_WAIT_V(8); PG8_WAIT_L(0); PG8_BAR; PG8_MMA(0, 0, At, B0); PG8_MMA(0, 1, At, B1); PG8_BAR; PG8_SCHED;
;             PG8_LDA(At, 0, 1); PG8_STAGE(PG8_SB(0, 0), b2, voffB); PG8_STAGE(PG8_SB(0, 1), b2 + hstep, voffB); PG8_STAGE(PG8_SA(0, 0), a2, voffA);
;             PG8_WAIT_V(8); PG8_WAIT_L(0); PG8_BAR; PG8_MMA(1, 0, At, B0); PG8_MMA(1, 1, At, B1); PG8_BAR; PG8_SCHED;
.LBB0_1513:
	ds_read_b128 v[144:147], v158
	ds_read_b128 v[148:151], v158 offset:1024
	ds_read_b128 v[162:165], v158 offset:2048
	ds_read_b128 v[166:169], v158 offset:3072
	ds_read_b128 v[170:173], v159
	ds_read_b128 v[174:177], v159 offset:1024
	ds_read_b128 v[178:181], v159 offset:2048
	ds_read_b128 v[182:185], v159 offset:3072
	s_add_u32 s16, s14, 0xfff50080
	s_addc_u32 s17, s15, -1
	s_cmp_eq_u32 s45, 40
	s_cselect_b32 s19, s5, s17
	s_cselect_b32 s18, s4, s16
	s_cselect_b32 s17, s13, s44
	s_cselect_b32 s16, s12, s43
	v_lshl_add_u64 v[218:219], s[14:15], 0, v[136:137]
	s_add_i32 m0, s26, 0xc000
	ds_read_b128 v[186:189], v160
	ds_read_b128 v[190:193], v160 offset:1024
	ds_read_b128 v[194:197], v160 offset:2048
	ds_read_b128 v[198:201], v160 offset:3072
	ds_read_b128 v[202:205], v160 offset:4096
	ds_read_b128 v[206:209], v160 offset:5120
	ds_read_b128 v[210:213], v160 offset:6144
	ds_read_b128 v[214:217], v160 offset:7168
	global_load_lds_dwordx4 v[218:219], off
	v_lshl_add_u64 v[218:219], s[14:15], 0, v[138:139]
	s_add_i32 m0, s26, 0xe000
	s_nop 0
	global_load_lds_dwordx4 v[218:219], off
	s_waitcnt vmcnt(8)
	s_waitcnt lgkmcnt(0)
	s_barrier
	s_waitcnt lgkmcnt(0)
	v_mfma_f32_16x16x32_bf16 v[124:127], v[144:147], v[186:189], v[124:127]
	v_mfma_f32_16x16x32_bf16 v[120:123], v[162:165], v[186:189], v[120:123]
	v_mfma_f32_16x16x32_bf16 v[108:111], v[144:147], v[194:197], v[108:111]
	v_mfma_f32_16x16x32_bf16 v[104:107], v[162:165], v[194:197], v[104:107]
	v_mfma_f32_16x16x32_bf16 v[96:99], v[144:147], v[202:205], v[96:99]
	v_mfma_f32_16x16x32_bf16 v[88:91], v[162:165], v[202:205], v[88:91]
	v_mfma_f32_16x16x32_bf16 v[80:83], v[144:147], v[210:213], v[80:83]
	v_mfma_f32_16x16x32_bf16 v[72:75], v[162:165], v[210:213], v[72:75]
	v_mfma_f32_16x16x32_bf16 v[124:127], v[148:151], v[190:193], v[124:127]
	v_mfma_f32_16x16x32_bf16 v[120:123], v[166:169], v[190:193], v[120:123]
	v_mfma_f32_16x16x32_bf16 v[108:111], v[148:151], v[198:201], v[108:111]
	v_mfma_f32_16x16x32_bf16 v[104:107], v[166:169], v[198:201], v[104:107]
	v_mfma_f32_16x16x32_bf16 v[96:99], v[148:151], v[206:209], v[96:99]
	v_mfma_f32_16x16x32_bf16 v[88:91], v[166:169], v[206:209], v[88:91]
	v_mfma_f32_16x16x32_bf16 v[80:83], v[148:151], v[214:217], v[80:83]
	v_mfma_f32_16x16x32_bf16 v[72:75], v[166:169], v[214:217], v[72:75]
	v_mfma_f32_16x16x32_bf16 v[116:119], v[170:173], v[186:189], v[116:119]
	v_mfma_f32_16x16x32_bf16 v[112:115], v[178:181], v[186:189], v[112:115]
	v_mfma_f32_16x16x32_bf16 v[100:103], v[170:173], v[194:197], v[100:103]
	v_mfma_f32_16x16x32_bf16 v[92:95], v[178:181], v[194:197], v[92:95]
	v_mfma_f32_16x16x32_bf16 v[84:87], v[170:173], v[202:205], v[84:87]
	v_mfma_f32_16x16x32_bf16 v[76:79], v[178:181], v[202:205], v[76:79]
	v_mfma_f32_16x16x32_bf16 v[68:71], v[170:173], v[210:213], v[68:71]
	v_mfma_f32_16x16x32_bf16 v[64:67], v[178:181], v[210:213], v[64:67]
	v_mfma_f32_16x16x32_bf16 v[116:119], v[174:177], v[190:193], v[116:119]
	v_mfma_f32_16x16x32_bf16 v[112:115], v[182:185], v[190:193], v[112:115]
	v_mfma_f32_16x16x32_bf16 v[100:103], v[174:177], v[198:201], v[100:103]
	v_mfma_f32_16x16x32_bf16 v[92:95], v[182:185], v[198:201], v[92:95]
	v_mfma_f32_16x16x32_bf16 v[84:87], v[174:177], v[206:209], v[84:87]
	v_mfma_f32_16x16x32_bf16 v[76:79], v[182:185], v[206:209], v[76:79]
	v_mfma_f32_16x16x32_bf16 v[68:71], v[174:177], v[214:217], v[68:71]
	v_mfma_f32_16x16x32_bf16 v[64:67], v[182:185], v[214:217], v[64:67]
	s_barrier
	s_add_i32 s46, s37, s23
	v_lshl_add_u64 v[218:219], s[16:17], 0, v[130:131]
	s_mov_b32 m0, s46
	ds_read_b128 v[186:189], v160 offset:16384
	ds_read_b128 v[190:193], v160 offset:17408
	ds_read_b128 v[194:197], v160 offset:18432
	ds_read_b128 v[198:201], v160 offset:19456
	ds_read_b128 v[202:205], v160 offset:20480
	ds_read_b128 v[206:209], v160 offset:21504
	ds_read_b128 v[210:213], v160 offset:22528
	ds_read_b128 v[214:217], v160 offset:23552
	global_load_lds_dwordx4 v[218:219], off
	s_add_i32 m0, s46, 0x2000
	s_add_u32 s46, s16, 0xb0000
	v_lshl_add_u64 v[220:221], s[16:17], 0, v[134:135]
	s_addc_u32 s47, s17, 0
	s_add_i32 s48, s38, s23
	global_load_lds_dwordx4 v[220:221], off
	v_lshl_add_u64 v[222:223], s[46:47], 0, v[130:131]
	s_mov_b32 m0, s48
	v_lshl_add_u64 v[224:225], s[18:19], 0, v[132:133]
	global_load_lds_dwordx4 v[222:223], off
	v_lshl_add_u64 v[222:223], s[46:47], 0, v[134:135]
	s_add_i32 m0, s48, 0x2000
	s_nop 0
	global_load_lds_dwordx4 v[222:223], off
	v_lshl_add_u64 v[222:223], s[18:19], 0, v[128:129]
	s_mov_b32 m0, s26
	s_nop 0
	global_load_lds_dwordx4 v[222:223], off
	s_mov_b32 m0, s27
	s_nop 0
	global_load_lds_dwordx4 v[224:225], off
	s_waitcnt vmcnt(8)
	s_waitcnt lgkmcnt(0)
	s_barrier
; #define PG8_STAGE(bufoff, gbase, voff) do { _Pragma("unroll") for (int _i = 0; _i < 2; ++_i) \
;         __builtin_amdgcn_global_load_lds((const unsigned*)((const char*)(gbase) + (voff)[_i]), (LAS unsigned*)(lds + (bufoff) + ldsw + _i * 8192), 16, 0, 0); } while (0)
; #define PG8_LDA(dst, b, h) do { _Pragma("unroll") for (int m = 0; m < 4; ++m) _Pragma("unroll") for (int k = 0; k < 2; ++k) dst[m][k] = *(const LAS bf16x8*)(lds + PG8_SA(b, h) + aoff + m * 2048 + k * 1024); } while (0)
; #define PG8_LDB(dst, b, h) do { _Pragma("unroll") for (int n = 0; n < 2; ++n) _Pragma("unroll") for (int k = 0; k < 2; ++k) dst[n][k] = *(const LAS bf16x8*)(lds + PG8_SB(b, h) + boff + n * 2048 + k * 1024); } while (0)
; #define PG8_MMA(ai, bj, At, Bt) do { __builtin_amdgcn_s_setprio(3); _Pragma("unroll") for (int m = 0; m < 4; ++m) _Pragma("unroll") for (int n = 0; n < 2; ++n) _Pragma("unroll") for (int k = 0; k < 2; ++k) \
;         acc[ai][bj][m][n] = __builtin_amdgcn_mfma_f32_16x16x32_bf16(Bt[n][k], At[m][k], acc[ai][bj][m][n], 0, 0, 0); __builtin_amdgcn_s_setprio(0); } while (0)
; #define PG8_WAIT_V(n) asm volatile("s_waitcnt vmcnt(" #n ")" ::: "memory")
; #define PG8_WAIT_L(n) asm volatile("s_waitcnt lgkmcnt(" #n ")" ::: "memory")
; #define PG8_BAR __builtin_amdgcn_s_barrier()
; #define PG8_SCHED __builtin_amdgcn_sched_barrier(0)
; template <class Epi, bool ALIGN_EPI>
; __device__ __forceinline__ void gemm_phase(LAS unsigned char* lds, const Gemm g, const StaticOrder& S, const Epi& E) {
;     ...
;             PG8_WAIT_V(8); PG8_WAIT_L(0); PG8_BAR; PG8_MMA(1, 0, At, B0); PG8_MMA(1, 1, At, B1); PG8_BAR; PG8_SCHED;
;             PG8_LDB(B0, 1, 0); PG8_LDB(B1, 1, 1); PG8_SCHED; PG8_LDA(At, 1, 0); PG8_STAGE(PG8_SA(0, 1), a2 + hstep, voffA);
;             PG8_WAIT_V(8); PG8_WAIT_L(0); PG8_BAR; PG8_MMA(0, 0, At, B0); PG8_MMA(0, 1, At, B1); PG8_BAR; PG8_SCHED;
	s_waitcnt lgkmcnt(0)
	v_mfma_f32_16x16x32_bf16 v[60:63], v[144:147], v[186:189], v[60:63]
	v_mfma_f32_16x16x32_bf16 v[56:59], v[162:165], v[186:189], v[56:59]
	v_mfma_f32_16x16x32_bf16 v[48:51], v[144:147], v[194:197], v[48:51]
	v_mfma_f32_16x16x32_bf16 v[40:43], v[162:165], v[194:197], v[40:43]
	v_mfma_f32_16x16x32_bf16 v[32:35], v[144:147], v[202:205], v[32:35]
	v_mfma_f32_16x16x32_bf16 v[24:27], v[162:165], v[202:205], v[24:27]
	v_mfma_f32_16x16x32_bf16 v[16:19], v[144:147], v[210:213], v[16:19]
	v_mfma_f32_16x16x32_bf16 v[8:11], v[162:165], v[210:213], v[8:11]
	v_mfma_f32_16x16x32_bf16 v[60:63], v[148:151], v[190:193], v[60:63]
	v_mfma_f32_16x16x32_bf16 v[56:59], v[166:169], v[190:193], v[56:59]
	v_mfma_f32_16x16x32_bf16 v[48:51], v[148:151], v[198:201], v[48:51]
	v_mfma_f32_16x16x32_bf16 v[40:43], v[166:169], v[198:201], v[40:43]
	v_mfma_f32_16x16x32_bf16 v[32:35], v[148:151], v[206:209], v[32:35]
	v_mfma_f32_16x16x32_bf16 v[24:27], v[166:169], v[206:209], v[24:27]
	v_mfma_f32_16x16x32_bf16 v[16:19], v[148:151], v[214:217], v[16:19]
	v_mfma_f32_16x16x32_bf16 v[8:11], v[166:169], v[214:217], v[8:11]
	v_mfma_f32_16x16x32_bf16 v[52:55], v[170:173], v[186:189], v[52:55]
	v_mfma_f32_16x16x32_bf16 v[44:47], v[178:181], v[186:189], v[44:47]
	v_mfma_f32_16x16x32_bf16 v[36:39], v[170:173], v[194:197], v[36:39]
	v_mfma_f32_16x16x32_bf16 v[28:31], v[178:181], v[194:197], v[28:31]
	v_mfma_f32_16x16x32_bf16 v[20:23], v[170:173], v[202:205], v[20:23]
	v_mfma_f32_16x16x32_bf16 v[12:15], v[178:181], v[202:205], v[12:15]
	v_mfma_f32_16x16x32_bf16 v[4:7], v[170:173], v[210:213], v[4:7]
	v_mfma_f32_16x16x32_bf16 v[0:3], v[178:181], v[210:213], v[0:3]
	v_mfma_f32_16x16x32_bf16 v[52:55], v[174:177], v[190:193], v[52:55]
	v_mfma_f32_16x16x32_bf16 v[44:47], v[182:185], v[190:193], v[44:47]
	v_mfma_f32_16x16x32_bf16 v[36:39], v[174:177], v[198:201], v[36:39]
	v_mfma_f32_16x16x32_bf16 v[28:31], v[182:185], v[198:201], v[28:31]
	v_mfma_f32_16x16x32_bf16 v[20:23], v[174:177], v[206:209], v[20:23]
	v_mfma_f32_16x16x32_bf16 v[12:15], v[182:185], v[206:209], v[12:15]
	v_mfma_f32_16x16x32_bf16 v[4:7], v[174:177], v[214:217], v[4:7]
	v_mfma_f32_16x16x32_bf16 v[0:3], v[182:185], v[214:217], v[0:3]
	s_barrier
	s_add_i32 s46, 0, 0x18000
	v_add_u32_e32 v161, s46, v156
	s_add_i32 s47, 0, 0x1c000
	ds_read_b128 v[144:147], v161
	ds_read_b128 v[148:151], v161 offset:1024
	ds_read_b128 v[162:165], v161 offset:2048
	ds_read_b128 v[166:169], v161 offset:3072
	v_add_u32_e32 v161, s47, v156
	ds_read_b128 v[170:173], v161
	ds_read_b128 v[174:177], v161 offset:1024
	ds_read_b128 v[178:181], v161 offset:2048
	ds_read_b128 v[182:185], v161 offset:3072
	s_add_u32 s18, s18, 0xb0000
	s_addc_u32 s19, s19, 0
	s_mov_b32 m0, s28
	v_lshl_add_u64 v[226:227], s[18:19], 0, v[128:129]
	ds_read_b128 v[186:189], v160 offset:32768
	ds_read_b128 v[190:193], v160 offset:33792
	ds_read_b128 v[194:197], v160 offset:34816
	ds_read_b128 v[198:201], v160 offset:35840
	ds_read_b128 v[202:205], v160 offset:36864
	ds_read_b128 v[206:209], v160 offset:37888
	ds_read_b128 v[210:213], v160 offset:38912
	ds_read_b128 v[214:217], v160 offset:39936
	global_load_lds_dwordx4 v[226:227], off
	v_lshl_add_u64 v[226:227], s[18:19], 0, v[132:133]
	s_mov_b32 m0, s29
	s_nop 0
	global_load_lds_dwordx4 v[226:227], off
	s_waitcnt vmcnt(8)
	s_waitcnt lgkmcnt(0)
	s_barrier
	s_waitcnt lgkmcnt(0)
	v_mfma_f32_16x16x32_bf16 v[124:127], v[144:147], v[186:189], v[124:127]
	v_mfma_f32_16x16x32_bf16 v[120:123], v[162:165], v[186:189], v[120:123]
	v_mfma_f32_16x16x32_bf16 v[108:111], v[144:147], v[194:197], v[108:111]
	v_mfma_f32_16x16x32_bf16 v[104:107], v[162:165], v[194:197], v[104:107]
	v_mfma_f32_16x16x32_bf16 v[96:99], v[144:147], v[202:205], v[96:99]
	v_mfma_f32_16x16x32_bf16 v[88:91], v[162:165], v[202:205], v[88:91]
	v_mfma_f32_16x16x32_bf16 v[80:83], v[144:147], v[210:213], v[80:83]
	v_mfma_f32_16x16x32_bf16 v[72:75], v[162:165], v[210:213], v[72:75]
	v_mfma_f32_16x16x32_bf16 v[124:127], v[148:151], v[190:193], v[124:127]
	v_mfma_f32_16x16x32_bf16 v[120:123], v[166:169], v[190:193], v[120:123]
	v_mfma_f32_16x16x32_bf16 v[108:111], v[148:151], v[198:201], v[108:111]
	v_mfma_f32_16x16x32_bf16 v[104:107], v[166:169], v[198:201], v[104:107]
	v_mfma_f32_16x16x32_bf16 v[96:99], v[148:151], v[206:209], v[96:99]
	v_mfma_f32_16x16x32_bf16 v[88:91], v[166:169], v[206:209], v[88:91]
	v_mfma_f32_16x16x32_bf16 v[80:83], v[148:151], v[214:217], v[80:83]
	v_mfma_f32_16x16x32_bf16 v[72:75], v[166:169], v[214:217], v[72:75]
	v_mfma_f32_16x16x32_bf16 v[116:119], v[170:173], v[186:189], v[116:119]
	v_mfma_f32_16x16x32_bf16 v[112:115], v[178:181], v[186:189], v[112:115]
	v_mfma_f32_16x16x32_bf16 v[100:103], v[170:173], v[194:197], v[100:103]
	v_mfma_f32_16x16x32_bf16 v[92:95], v[178:181], v[194:197], v[92:95]
	v_mfma_f32_16x16x32_bf16 v[84:87], v[170:173], v[202:205], v[84:87]
	v_mfma_f32_16x16x32_bf16 v[76:79], v[178:181], v[202:205], v[76:79]
	v_mfma_f32_16x16x32_bf16 v[68:71], v[170:173], v[210:213], v[68:71]
	v_mfma_f32_16x16x32_bf16 v[64:67], v[178:181], v[210:213], v[64:67]
	v_mfma_f32_16x16x32_bf16 v[116:119], v[174:177], v[190:193], v[116:119]
	v_mfma_f32_16x16x32_bf16 v[112:115], v[182:185], v[190:193], v[112:115]
	v_mfma_f32_16x16x32_bf16 v[100:103], v[174:177], v[198:201], v[100:103]
	v_mfma_f32_16x16x32_bf16 v[92:95], v[182:185], v[198:201], v[92:95]
	v_mfma_f32_16x16x32_bf16 v[84:87], v[174:177], v[206:209], v[84:87]
	v_mfma_f32_16x16x32_bf16 v[76:79], v[182:185], v[206:209], v[76:79]
	v_mfma_f32_16x16x32_bf16 v[68:71], v[174:177], v[214:217], v[68:71]
	v_mfma_f32_16x16x32_bf16 v[64:67], v[182:185], v[214:217], v[64:67]
	s_barrier
; #define PG8_STAGE(bufoff, gbase, voff) do { _Pragma("unroll") for (int _i = 0; _i < 2; ++_i) \
;         __builtin_amdgcn_global_load_lds((const unsigned*)((const char*)(gbase) + (voff)[_i]), (LAS unsigned*)(lds + (bufoff) + ldsw + _i * 8192), 16, 0, 0); } while (0)
; #define PG8_LDA(dst, b, h) do { _Pragma("unroll") for (int m = 0; m < 4; ++m) _Pragma("unroll") for (int k = 0; k < 2; ++k) dst[m][k] = *(const LAS bf16x8*)(lds + PG8_SA(b, h) + aoff + m * 2048 + k * 1024); } while (0)
; #define PG8_MMA(ai, bj, At, Bt) do { __builtin_amdgcn_s_setprio(3); _Pragma("unroll") for (int m = 0; m < 4; ++m) _Pragma("unroll") for (int n = 0; n < 2; ++n) _Pragma("unroll") for (int k = 0; k < 2; ++k) \
;         acc[ai][bj][m][n] = __builtin_amdgcn_mfma_f32_16x16x32_bf16(Bt[n][k], At[m][k], acc[ai][bj][m][n], 0, 0, 0); __builtin_amdgcn_s_setprio(0); } while (0)
; #define PG8_WAIT_V(n) asm volatile("s_waitcnt vmcnt(" #n ")" ::: "memory")
; #define PG8_WAIT_L(n) asm volatile("s_waitcnt lgkmcnt(" #n ")" ::: "memory")
; #define PG8_BAR __builtin_amdgcn_s_barrier()
; #define PG8_SCHED __builtin_amdgcn_sched_barrier(0)
; template <class Epi, bool ALIGN_EPI>
; __device__ __forceinline__ void gemm_phase(LAS unsigned char* lds, const Gemm g, const StaticOrder& S, const Epi& E) {
;     ...
;         for (int t = 0; t < nt; t += 2) {
;     ...
;             PG8_LDA(At, 1, 1); PG8_STAGE(PG8_SB(1, 0), b3, voffB); PG8_STAGE(PG8_SB(1, 1), b3 + hstep, voffB); PG8_STAGE(PG8_SA(1, 0), a3, voffA);
;             PG8_WAIT_V(8); PG8_WAIT_L(0); PG8_BAR; PG8_MMA(1, 0, At, B0); PG8_MMA(1, 1, At, B1); PG8_BAR; PG8_SCHED;
;         }
	s_add_i32 s18, s46, s23
	v_lshl_add_u64 v[218:219], v[218:219], 0, s[8:9]
	s_mov_b32 m0, s18
	ds_read_b128 v[186:189], v160 offset:49152
	ds_read_b128 v[190:193], v160 offset:50176
	ds_read_b128 v[194:197], v160 offset:51200
	ds_read_b128 v[198:201], v160 offset:52224
	ds_read_b128 v[202:205], v160 offset:53248
	ds_read_b128 v[206:209], v160 offset:54272
	ds_read_b128 v[210:213], v160 offset:55296
	ds_read_b128 v[214:217], v160 offset:56320
	global_load_lds_dwordx4 v[218:219], off
	s_add_i32 m0, s18, 0x2000
	s_add_u32 s16, s16, 0xb0080
	v_lshl_add_u64 v[218:219], v[220:221], 0, s[8:9]
	s_addc_u32 s17, s17, 0
	s_add_i32 s18, s47, s23
	global_load_lds_dwordx4 v[218:219], off
	v_lshl_add_u64 v[218:219], s[16:17], 0, v[130:131]
	s_mov_b32 m0, s18
	s_nop 0
	global_load_lds_dwordx4 v[218:219], off
	v_lshl_add_u64 v[218:219], s[16:17], 0, v[134:135]
	s_add_i32 m0, s18, 0x2000
	s_nop 0
	global_load_lds_dwordx4 v[218:219], off
	v_lshl_add_u64 v[218:219], v[222:223], 0, s[8:9]
	s_mov_b32 m0, s31
	s_nop 0
	global_load_lds_dwordx4 v[218:219], off
	v_lshl_add_u64 v[218:219], v[224:225], 0, s[8:9]
	s_mov_b32 m0, s33
	s_nop 0
	global_load_lds_dwordx4 v[218:219], off
	s_waitcnt vmcnt(8)
	s_waitcnt lgkmcnt(0)
	s_barrier
	s_waitcnt lgkmcnt(0)
	v_mfma_f32_16x16x32_bf16 v[60:63], v[144:147], v[186:189], v[60:63]
	v_mfma_f32_16x16x32_bf16 v[56:59], v[162:165], v[186:189], v[56:59]
	v_mfma_f32_16x16x32_bf16 v[48:51], v[144:147], v[194:197], v[48:51]
	v_mfma_f32_16x16x32_bf16 v[40:43], v[162:165], v[194:197], v[40:43]
	v_mfma_f32_16x16x32_bf16 v[32:35], v[144:147], v[202:205], v[32:35]
	v_mfma_f32_16x16x32_bf16 v[24:27], v[162:165], v[202:205], v[24:27]
	v_mfma_f32_16x16x32_bf16 v[16:19], v[144:147], v[210:213], v[16:19]
	v_mfma_f32_16x16x32_bf16 v[8:11], v[162:165], v[210:213], v[8:11]
	v_mfma_f32_16x16x32_bf16 v[60:63], v[148:151], v[190:193], v[60:63]
	v_mfma_f32_16x16x32_bf16 v[56:59], v[166:169], v[190:193], v[56:59]
	v_mfma_f32_16x16x32_bf16 v[48:51], v[148:151], v[198:201], v[48:51]
	v_mfma_f32_16x16x32_bf16 v[40:43], v[166:169], v[198:201], v[40:43]
	v_mfma_f32_16x16x32_bf16 v[32:35], v[148:151], v[206:209], v[32:35]
	v_mfma_f32_16x16x32_bf16 v[24:27], v[166:169], v[206:209], v[24:27]
	v_mfma_f32_16x16x32_bf16 v[16:19], v[148:151], v[214:217], v[16:19]
	v_mfma_f32_16x16x32_bf16 v[8:11], v[166:169], v[214:217], v[8:11]
	v_mfma_f32_16x16x32_bf16 v[52:55], v[170:173], v[186:189], v[52:55]
	v_mfma_f32_16x16x32_bf16 v[44:47], v[178:181], v[186:189], v[44:47]
	v_mfma_f32_16x16x32_bf16 v[36:39], v[170:173], v[194:197], v[36:39]
	v_mfma_f32_16x16x32_bf16 v[28:31], v[178:181], v[194:197], v[28:31]
	v_mfma_f32_16x16x32_bf16 v[20:23], v[170:173], v[202:205], v[20:23]
	v_mfma_f32_16x16x32_bf16 v[12:15], v[178:181], v[202:205], v[12:15]
	v_mfma_f32_16x16x32_bf16 v[4:7], v[170:173], v[210:213], v[4:7]
	v_mfma_f32_16x16x32_bf16 v[0:3], v[178:181], v[210:213], v[0:3]
	v_mfma_f32_16x16x32_bf16 v[52:55], v[174:177], v[190:193], v[52:55]
	v_mfma_f32_16x16x32_bf16 v[44:47], v[182:185], v[190:193], v[44:47]
	v_mfma_f32_16x16x32_bf16 v[36:39], v[174:177], v[198:201], v[36:39]
	v_mfma_f32_16x16x32_bf16 v[28:31], v[182:185], v[198:201], v[28:31]
	v_mfma_f32_16x16x32_bf16 v[20:23], v[174:177], v[206:209], v[20:23]
	v_mfma_f32_16x16x32_bf16 v[12:15], v[182:185], v[206:209], v[12:15]
	v_mfma_f32_16x16x32_bf16 v[4:7], v[174:177], v[214:217], v[4:7]
	v_mfma_f32_16x16x32_bf16 v[0:3], v[182:185], v[214:217], v[0:3]
	s_barrier
	s_add_i32 s45, s45, 2
	s_add_u32 s14, s14, 0x100
	s_addc_u32 s15, s15, 0
	s_add_u32 s43, s43, 0x100
	s_addc_u32 s44, s44, 0
	s_cmp_gt_u32 s45, 41
	s_cbranch_scc0 .LBB0_1513
	s_and_b64 vcc, exec, s[10:11]
	s_cbranch_vccz .LBB0_1516
	s_barrier
